# speedup vs baseline: 1.0492x; 1.0188x over previous
; #define P8_STAGE(P,BASE,br,kt) do{const bfr* _ub=(BASE)+((long)(br)*K+(long)(kt)*BK); \
;     __builtin_amdgcn_global_load_lds((const unsigned*)(_ub+so0),(unsigned*)((char*)(P)+wid*1024),16,0,0); \
;     __builtin_amdgcn_global_load_lds((const unsigned*)(_ub+so1),(unsigned*)((char*)(P)+wid*1024+8192),16,0,0);}while(0)
; #define P8_WAIT_V(n) asm volatile("s_waitcnt vmcnt(" #n ")":::"memory")
; #define P8_BAR __builtin_amdgcn_s_barrier()
; template <class EPI>
; DEVI void gemm8_tile(const bfr* __restrict__ A, const bfr* __restrict__ Bt, int K, int brow, int bcol, int nbrow, int nbcol, char* shmc, EPI epi) {
;     ...
;   unsigned so0, so1;
;   { int _r, _c; stage_rc(tid * 16, _r, _c); so0 = (unsigned)(_r * K + _c); stage_rc(tid * 16 + 8192, _r, _c); so1 = (unsigned)(_r * K + _c); }
;   f32x4 acc[2][2][4][2];
; #pragma unroll
;   for (int a = 0; a < 2; ++a)
; #pragma unroll
;     for (int b = 0; b < 2; ++b)
; #pragma unroll
;       for (int m = 0; m < 4; ++m)
; #pragma unroll
;         for (int n = 0; n < 2; ++n) acc[a][b][m][n] = f32x4{0.f, 0.f, 0.f, 0.f};
;   bf16x8 At[4][2], B0[2][2], B1[2][2];
;   const int nt = K / BK;
;   if(wr==1)P8_BAR;
;   P8_WAIT_V(4); P8_BAR;
;   P8_STAGE(P8_SB(1,0),Bt,bcol,1); P8_STAGE(P8_SA(1,0),A,brow,1); P8_STAGE(P8_SB(1,1),Bt,bcol+128,1);
;   P8_WAIT_V(6); P8_BAR;
.LBB0_65:
	s_or_b64 exec, exec, s[0:1]
	v_lshlrev_b32_e32 v2, 4, v142
	v_and_b32_e32 v3, 32, v142
	s_lshl_b32 s10, s9, 8
	v_lshrrev_b32_e32 v7, 1, v142
	v_bitop3_b32 v3, v2, v3, 48 bitop3:0x6c
	v_add_u32_e32 v2, 0x2000, v2
	v_ashrrev_i32_e32 v4, 3, v142
	v_bfe_u32 v5, v142, 2, 4
	s_mov_b32 s0, 0x1ffff0
	v_lshrrev_b32_e32 v8, 1, v3
	v_ashrrev_i32_e32 v9, 7, v2
	v_and_b32_e32 v7, 32, v7
	s_ashr_i32 s11, s10, 31
	s_lshl_b32 s8, s2, 8
	v_ashrrev_i32_e32 v1, 6, v142
	v_and_or_b32 v6, v4, s0, v5
	v_and_or_b32 v2, v9, s0, v5
	v_or_b32_e32 v3, v8, v7
	s_lshl_b64 s[0:1], s[10:11], 12
	v_lshl_or_b32 v166, v6, 11, v3
	s_add_u32 s54, s84, s0
	v_lshlrev_b32_e32 v143, 10, v1
	s_nop 0
	v_readfirstlane_b32 s100, v143
	s_nop 3
	s_addc_u32 s55, s85, s1
	v_lshlrev_b64 v[128:129], 1, v[166:167]
	v_add_u32_e32 v157, 0x18000, v143
	v_lshl_or_b32 v132, v2, 11, v3
	v_lshl_add_u64 v[2:3], s[54:55], 0, v[128:129]
	v_mov_b32_e32 v133, v167
	v_lshl_add_u64 v[2:3], v[2:3], 0, s[62:63]
	s_add_i32 m0, s100, 0x18000
	v_lshlrev_b64 v[130:131], 1, v[132:133]
	s_ashr_i32 s9, s8, 31
	s_waitcnt vmcnt(4)
	s_barrier
	global_load_lds_dwordx4 v[2:3], off
	v_lshl_add_u64 v[2:3], s[54:55], 0, v[130:131]
	v_add_u32_e32 v158, 0x1a000, v143
	s_lshl_b64 s[54:55], s[8:9], 12
	v_readfirstlane_b32 s2, v158
	s_add_u32 s60, s28, s54
	v_lshl_add_u64 v[2:3], v[2:3], 0, s[62:63]
	s_mov_b32 m0, s2
	s_addc_u32 s61, s29, s55
	v_add_u32_e32 v159, 0x8000, v143
	global_load_lds_dwordx4 v[2:3], off
	v_lshl_add_u64 v[2:3], s[60:61], 0, v[128:129]
	v_lshl_add_u64 v[2:3], v[2:3], 0, s[62:63]
	s_add_i32 m0, s100, 0x8000
	v_add_u32_e32 v160, 0xa000, v143
	global_load_lds_dwordx4 v[2:3], off
	v_lshl_add_u64 v[2:3], s[60:61], 0, v[130:131]
	s_or_b32 s60, s10, 0x80
	s_ashr_i32 s61, s60, 31
	s_lshl_b64 s[60:61], s[60:61], 12
	v_readfirstlane_b32 s2, v160
	s_add_u32 s60, s84, s60
	v_lshl_add_u64 v[2:3], v[2:3], 0, s[62:63]
	s_mov_b32 m0, s2
	s_addc_u32 s61, s85, s61
	v_add_u32_e32 v161, 0x1c000, v143
	global_load_lds_dwordx4 v[2:3], off
	v_lshl_add_u64 v[2:3], s[60:61], 0, v[128:129]
	v_lshl_add_u64 v[2:3], v[2:3], 0, s[62:63]
	s_add_i32 m0, s100, 0x1c000
	v_add_u32_e32 v163, 0x1e000, v143
	global_load_lds_dwordx4 v[2:3], off
	v_lshl_add_u64 v[2:3], s[60:61], 0, v[130:131]
	v_lshl_add_u64 v[2:3], v[2:3], 0, s[62:63]
	s_add_i32 m0, s100, 0x1e000
	v_and_b32_e32 v10, 15, v142
	global_load_lds_dwordx4 v[2:3], off
	v_lshlrev_b32_e32 v1, 12, v1
	v_and_b32_e32 v11, 48, v142
	v_and_b32_e32 v6, 0x3000, v1
	v_lshlrev_b32_e32 v1, 6, v10
	v_lshlrev_b32_e32 v3, 2, v142
	v_or_b32_e32 v2, v1, v11
	v_and_b32_e32 v3, 32, v3
	s_mov_b32 s2, 0x14000
	v_bitop3_b32 v13, v2, s2, v3 bitop3:0xde
	s_mov_b32 s2, 0x18000
	v_lshlrev_b32_e32 v16, 13, v0
	v_lshlrev_b32_e32 v0, 6, v142
	v_bitop3_b32 v14, v2, s2, v3 bitop3:0xde
	s_mov_b32 s2, 0x1c000
	v_and_b32_e32 v0, 0x3c0, v0
	v_bitop3_b32 v10, v1, v3, v11 bitop3:0x36
	v_bitop3_b32 v12, v2, s3, v3 bitop3:0xde
	v_bitop3_b32 v15, v2, s2, v3 bitop3:0xde
	v_bitop3_b32 v11, v0, v3, v11 bitop3:0x36
	v_lshlrev_b32_e32 v0, 11, v9
	s_movk_i32 s2, 0x8000
	v_lshlrev_b32_e32 v3, 11, v4
	v_and_or_b32 v0, v0, s2, v8
	v_lshlrev_b32_e32 v2, 11, v5
	v_and_or_b32 v3, v3, s2, v8
	v_or3_b32 v0, v0, v2, v7
	v_mov_b32_e32 v1, v167
	v_or3_b32 v2, v3, v2, v7
	v_mov_b32_e32 v3, v167
	v_lshlrev_b64 v[0:1], 1, v[0:1]
	v_lshlrev_b64 v[2:3], 1, v[2:3]
	v_lshl_add_u64 v[134:135], s[0:1], 0, v[0:1]
	v_lshl_add_u64 v[136:137], s[0:1], 0, v[2:3]
	s_add_u32 s0, s4, s54
	s_waitcnt vmcnt(6)
	s_addc_u32 s1, s5, s55
	v_or_b32_e32 v17, 0x800, v16
	v_or_b32_e32 v18, 0x1000, v16
	v_or_b32_e32 v19, 0x1800, v16
	v_lshl_add_u64 v[138:139], s[0:1], 0, v[0:1]
	v_mov_b32_e32 v0, 0
	v_lshl_add_u64 v[140:141], s[0:1], 0, v[2:3]
	s_mov_b32 s0, -2
	v_add_u32_e32 v172, v12, v6
	v_add_u32_e32 v154, v10, v16
	v_add_u32_e32 v153, v11, v17
	v_add_u32_e32 v152, v11, v18
	v_add_u32_e32 v151, v11, v19
	v_add_u32_e32 v171, 0xc000, v143
	v_add_u32_e32 v170, 0xe000, v143
	v_add_u32_e32 v162, v13, v6
	v_add_u32_e32 v150, 0x10000, v143
	v_add_u32_e32 v149, 0x12000, v143
	v_add_u32_e32 v148, 0x2000, v143
	v_add_u32_e32 v147, 0x14000, v143
	v_add_u32_e32 v146, 0x16000, v143
	v_add_u32_e32 v156, v14, v6
	v_add_u32_e32 v145, 0x4000, v143
	v_add_u32_e32 v144, 0x6000, v143
	v_add_u32_e32 v155, v15, v6
	v_mov_b32_e32 v1, v0
	v_mov_b32_e32 v2, v0
	v_mov_b32_e32 v3, v0
	v_mov_b32_e32 v4, v0
	v_mov_b32_e32 v5, v0
	v_mov_b32_e32 v6, v0
	v_mov_b32_e32 v7, v0
	v_mov_b32_e32 v8, v0
	v_mov_b32_e32 v9, v0
	v_mov_b32_e32 v10, v0
	v_mov_b32_e32 v11, v0
	v_mov_b32_e32 v12, v0
	v_mov_b32_e32 v13, v0
	v_mov_b32_e32 v14, v0
	v_mov_b32_e32 v15, v0
	v_mov_b32_e32 v16, v0
	v_mov_b32_e32 v17, v0
	v_mov_b32_e32 v18, v0
	v_mov_b32_e32 v19, v0
	v_mov_b32_e32 v20, v0
	v_mov_b32_e32 v21, v0
	v_mov_b32_e32 v22, v0
	v_mov_b32_e32 v23, v0
	v_mov_b32_e32 v24, v0
	v_mov_b32_e32 v25, v0
	v_mov_b32_e32 v26, v0
	v_mov_b32_e32 v27, v0
	v_mov_b32_e32 v28, v0
	v_mov_b32_e32 v29, v0
	v_mov_b32_e32 v30, v0
	v_mov_b32_e32 v31, v0
	v_mov_b32_e32 v32, v0
	v_mov_b32_e32 v33, v0
	v_mov_b32_e32 v34, v0
	v_mov_b32_e32 v35, v0
	v_mov_b32_e32 v36, v0
	v_mov_b32_e32 v37, v0
	v_mov_b32_e32 v38, v0
	v_mov_b32_e32 v39, v0
	v_mov_b32_e32 v40, v0
	v_mov_b32_e32 v41, v0
	v_mov_b32_e32 v42, v0
	v_mov_b32_e32 v43, v0
	v_mov_b32_e32 v44, v0
	v_mov_b32_e32 v45, v0
	v_mov_b32_e32 v46, v0
	v_mov_b32_e32 v47, v0
	v_mov_b32_e32 v48, v0
	v_mov_b32_e32 v49, v0
	v_mov_b32_e32 v50, v0
	v_mov_b32_e32 v51, v0
	v_mov_b32_e32 v52, v0
	v_mov_b32_e32 v53, v0
	v_mov_b32_e32 v54, v0
	v_mov_b32_e32 v55, v0
	v_mov_b32_e32 v56, v0
	v_mov_b32_e32 v57, v0
	v_mov_b32_e32 v58, v0
	v_mov_b32_e32 v59, v0
	v_mov_b32_e32 v60, v0
; #define P8_STAGE(P,BASE,br,kt) do{const bfr* _ub=(BASE)+((long)(br)*K+(long)(kt)*BK); \
;     __builtin_amdgcn_global_load_lds((const unsigned*)(_ub+so0),(unsigned*)((char*)(P)+wid*1024),16,0,0); \
;     __builtin_amdgcn_global_load_lds((const unsigned*)(_ub+so1),(unsigned*)((char*)(P)+wid*1024+8192),16,0,0);}while(0)
; #define P8_LDA(dst,b,h) _Pragma("unroll") for(int m=0;m<4;++m) _Pragma("unroll") for(int k=0;k<2;++k) \
;     dst[m][k]=*reinterpret_cast<const bf16x8*>((char*)P8_SA(b,h)+lds_byte(wr*64+m*16+fr,k*32+fq*8))
; #define P8_LDB(dst,b,h) _Pragma("unroll") for(int n=0;n<2;++n) _Pragma("unroll") for(int k=0;k<2;++k) \
;     dst[n][k]=*reinterpret_cast<const bf16x8*>((char*)P8_SB(b,h)+lds_byte(wc*32+n*16+fr,k*32+fq*8))
; #define P8_MMA(ai,bj,At,Bt) do{__builtin_amdgcn_s_setprio(1); \
;     _Pragma("unroll") for(int m=0;m<4;++m) _Pragma("unroll") for(int n=0;n<2;++n) _Pragma("unroll") for(int k=0;k<2;++k) \
;       acc[ai][bj][m][n]=__builtin_amdgcn_mfma_f32_16x16x32_bf16(At[m][k],Bt[n][k],acc[ai][bj][m][n],0,0,0); \
;     __builtin_amdgcn_s_setprio(0);}while(0)
; #define P8_WAIT_V(n) asm volatile("s_waitcnt vmcnt(" #n ")":::"memory")
; #define P8_WAIT_L(n) asm volatile("s_waitcnt lgkmcnt(" #n ")":::"memory")
; #define P8_BAR __builtin_amdgcn_s_barrier()
; #define P8_SCHED __builtin_amdgcn_sched_barrier(0)
; template <class EPI>
; DEVI void gemm8_tile(const bfr* __restrict__ A, const bfr* __restrict__ Bt, int K, int brow, int bcol, int nbrow, int nbcol, char* shmc, EPI epi) {
;     ...
;   for(int t=0;t<nt-2;t+=2){
;     P8_LDB(B0,0,0); P8_SCHED; P8_LDA(At,0,0); P8_STAGE(P8_SA(1,1),A,brow+128,t+1);
;     P8_WAIT_L(8); P8_BAR; P8_WAIT_L(0); P8_MMA(0,0,At,B0); P8_BAR; P8_SCHED;
;     P8_LDB(B1,0,1); P8_STAGE(P8_SB(0,0),Bt,bcol,t+2);
;     P8_BAR; P8_WAIT_L(0); P8_MMA(0,1,At,B1); P8_BAR;
;     P8_LDA(At,0,1); P8_STAGE(P8_SA(0,0),A,brow,t+2);
;     P8_BAR; P8_WAIT_L(0); P8_MMA(1,0,At,B0); P8_BAR; P8_SCHED;
;     P8_STAGE(P8_SB(0,1),Bt,bcol+128,t+2);
;     P8_WAIT_V(6); P8_BAR; P8_MMA(1,1,At,B1); P8_BAR;
	v_mov_b32_e32 v61, v0
	v_mov_b32_e32 v62, v0
	v_mov_b32_e32 v63, v0
	v_mov_b32_e32 v64, v0
	v_mov_b32_e32 v65, v0
	v_mov_b32_e32 v66, v0
	v_mov_b32_e32 v67, v0
	v_mov_b32_e32 v68, v0
	v_mov_b32_e32 v69, v0
	v_mov_b32_e32 v70, v0
	v_mov_b32_e32 v71, v0
	v_mov_b32_e32 v72, v0
	v_mov_b32_e32 v73, v0
	v_mov_b32_e32 v74, v0
	v_mov_b32_e32 v75, v0
	v_mov_b32_e32 v76, v0
	v_mov_b32_e32 v77, v0
	v_mov_b32_e32 v78, v0
	v_mov_b32_e32 v79, v0
	v_mov_b32_e32 v80, v0
	v_mov_b32_e32 v81, v0
	v_mov_b32_e32 v82, v0
	v_mov_b32_e32 v83, v0
	v_mov_b32_e32 v84, v0
	v_mov_b32_e32 v85, v0
	v_mov_b32_e32 v86, v0
	v_mov_b32_e32 v87, v0
	v_mov_b32_e32 v88, v0
	v_mov_b32_e32 v89, v0
	v_mov_b32_e32 v90, v0
	v_mov_b32_e32 v91, v0
	v_mov_b32_e32 v92, v0
	v_mov_b32_e32 v93, v0
	v_mov_b32_e32 v94, v0
	v_mov_b32_e32 v95, v0
	v_mov_b32_e32 v96, v0
	v_mov_b32_e32 v97, v0
	v_mov_b32_e32 v98, v0
	v_mov_b32_e32 v99, v0
	v_mov_b32_e32 v100, v0
	v_mov_b32_e32 v101, v0
	v_mov_b32_e32 v102, v0
	v_mov_b32_e32 v103, v0
	v_mov_b32_e32 v104, v0
	v_mov_b32_e32 v105, v0
	v_mov_b32_e32 v106, v0
	v_mov_b32_e32 v107, v0
	v_mov_b32_e32 v108, v0
	v_mov_b32_e32 v109, v0
	v_mov_b32_e32 v110, v0
	v_mov_b32_e32 v111, v0
	v_mov_b32_e32 v112, v0
	v_mov_b32_e32 v113, v0
	v_mov_b32_e32 v114, v0
	v_mov_b32_e32 v115, v0
	v_mov_b32_e32 v116, v0
	v_mov_b32_e32 v117, v0
	v_mov_b32_e32 v118, v0
	v_mov_b32_e32 v119, v0
	v_mov_b32_e32 v120, v0
	v_mov_b32_e32 v121, v0
	v_mov_b32_e32 v122, v0
	v_mov_b32_e32 v123, v0
	v_mov_b32_e32 v124, v0
	v_mov_b32_e32 v125, v0
	v_mov_b32_e32 v126, v0
	v_mov_b32_e32 v127, v0
	s_mov_b64 s[54:55], 0x1a80080
	s_mov_b64 s[60:61], 0x1a00100
	s_mov_b64 s[72:73], 0x1a80100
	s_mov_b64 s[82:83], 0x1a00180
	s_barrier
.LBB0_66:
	ds_read_b128 v[174:177], v172
	ds_read_b128 v[178:181], v172 offset:1024
	ds_read_b128 v[182:185], v172 offset:2048
	ds_read_b128 v[186:189], v172 offset:3072
	v_add_u32_e32 v224, s54, v140
	s_add_i32 m0, s100, 0xc000
	ds_read_b128 v[190:193], v154
	ds_read_b128 v[196:199], v154 offset:1024
	ds_read_b128 v[200:203], v153
	ds_read_b128 v[204:207], v153 offset:1024
	ds_read_b128 v[208:211], v152
	ds_read_b128 v[212:215], v152 offset:1024
	ds_read_b128 v[216:219], v151
	ds_read_b128 v[220:223], v151 offset:1024
	global_load_lds_dwordx4 v224, s[86:87]
	v_add_u32_e32 v224, s54, v138
	s_add_i32 m0, s100, 0xe000
	s_nop 0
	global_load_lds_dwordx4 v224, s[86:87]
	s_waitcnt lgkmcnt(8)
	s_barrier
	s_waitcnt lgkmcnt(0)
	s_setprio 1
	s_waitcnt lgkmcnt(0)
	v_mfma_f32_16x16x32_bf16 v[124:127], v[190:193], v[174:177], v[124:127]
	v_mfma_f32_16x16x32_bf16 v[120:123], v[190:193], v[182:185], v[120:123]
	v_mfma_f32_16x16x32_bf16 v[116:119], v[200:203], v[174:177], v[116:119]
	v_mfma_f32_16x16x32_bf16 v[112:115], v[200:203], v[182:185], v[112:115]
	v_mfma_f32_16x16x32_bf16 v[108:111], v[208:211], v[174:177], v[108:111]
	v_mfma_f32_16x16x32_bf16 v[104:107], v[208:211], v[182:185], v[104:107]
	v_mfma_f32_16x16x32_bf16 v[100:103], v[216:219], v[174:177], v[100:103]
	v_mfma_f32_16x16x32_bf16 v[96:99], v[216:219], v[182:185], v[96:99]
	v_mfma_f32_16x16x32_bf16 v[124:127], v[196:199], v[178:181], v[124:127]
	v_mfma_f32_16x16x32_bf16 v[120:123], v[196:199], v[186:189], v[120:123]
	v_mfma_f32_16x16x32_bf16 v[116:119], v[204:207], v[178:181], v[116:119]
	v_mfma_f32_16x16x32_bf16 v[112:115], v[204:207], v[186:189], v[112:115]
	v_mfma_f32_16x16x32_bf16 v[108:111], v[212:215], v[178:181], v[108:111]
	v_mfma_f32_16x16x32_bf16 v[104:107], v[212:215], v[186:189], v[104:107]
	v_mfma_f32_16x16x32_bf16 v[100:103], v[220:223], v[178:181], v[100:103]
	v_mfma_f32_16x16x32_bf16 v[96:99], v[220:223], v[186:189], v[96:99]
	s_setprio 0
	s_barrier
	v_add_u32_e32 v246, s66, v136
	s_add_i32 m0, s100, 0x10000
	ds_read_b128 v[224:227], v162
	ds_read_b128 v[228:231], v162 offset:1024
	ds_read_b128 v[232:235], v162 offset:2048
	ds_read_b128 v[236:239], v162 offset:3072
	global_load_lds_dwordx4 v246, s[86:87]
	v_add_u32_e32 v248, s66, v134
	s_add_i32 m0, s100, 0x12000
	s_nop 0
	global_load_lds_dwordx4 v248, s[86:87]
	s_barrier
	s_waitcnt lgkmcnt(0)
	s_setprio 1
	s_waitcnt lgkmcnt(0)
	v_mfma_f32_16x16x32_bf16 v[92:95], v[190:193], v[224:227], v[92:95]
	v_mfma_f32_16x16x32_bf16 v[88:91], v[190:193], v[232:235], v[88:91]
	v_mfma_f32_16x16x32_bf16 v[84:87], v[200:203], v[224:227], v[84:87]
	v_mfma_f32_16x16x32_bf16 v[80:83], v[200:203], v[232:235], v[80:83]
	v_mfma_f32_16x16x32_bf16 v[76:79], v[208:211], v[224:227], v[76:79]
	v_mfma_f32_16x16x32_bf16 v[72:75], v[208:211], v[232:235], v[72:75]
	v_mfma_f32_16x16x32_bf16 v[68:71], v[216:219], v[224:227], v[68:71]
	v_mfma_f32_16x16x32_bf16 v[64:67], v[216:219], v[232:235], v[64:67]
	v_mfma_f32_16x16x32_bf16 v[92:95], v[196:199], v[228:231], v[92:95]
	v_mfma_f32_16x16x32_bf16 v[88:91], v[196:199], v[236:239], v[88:91]
	v_mfma_f32_16x16x32_bf16 v[84:87], v[204:207], v[228:231], v[84:87]
	v_mfma_f32_16x16x32_bf16 v[80:83], v[204:207], v[236:239], v[80:83]
	v_mfma_f32_16x16x32_bf16 v[76:79], v[212:215], v[228:231], v[76:79]
	v_mfma_f32_16x16x32_bf16 v[72:75], v[212:215], v[236:239], v[72:75]
	v_mfma_f32_16x16x32_bf16 v[68:71], v[220:223], v[228:231], v[68:71]
	v_mfma_f32_16x16x32_bf16 v[64:67], v[220:223], v[236:239], v[64:67]
	s_setprio 0
	v_add_u32_e32 v248, s60, v140
	s_mov_b32 m0, s100
	s_barrier
	ds_read_b128 v[190:193], v154 offset:16384
	ds_read_b128 v[196:199], v154 offset:17408
	ds_read_b128 v[200:203], v153 offset:16384
	ds_read_b128 v[204:207], v153 offset:17408
	ds_read_b128 v[208:211], v152 offset:16384
	ds_read_b128 v[212:215], v152 offset:17408
	ds_read_b128 v[216:219], v151 offset:16384
	ds_read_b128 v[220:223], v151 offset:17408
	global_load_lds_dwordx4 v248, s[86:87]
	v_add_u32_e32 v248, s60, v138
	s_add_i32 m0, s100, 0x2000
	s_nop 0
	global_load_lds_dwordx4 v248, s[86:87]
	s_barrier
; #define P8_STAGE(P,BASE,br,kt) do{const bfr* _ub=(BASE)+((long)(br)*K+(long)(kt)*BK); \
;     __builtin_amdgcn_global_load_lds((const unsigned*)(_ub+so0),(unsigned*)((char*)(P)+wid*1024),16,0,0); \
;     __builtin_amdgcn_global_load_lds((const unsigned*)(_ub+so1),(unsigned*)((char*)(P)+wid*1024+8192),16,0,0);}while(0)
; #define P8_LDA(dst,b,h) _Pragma("unroll") for(int m=0;m<4;++m) _Pragma("unroll") for(int k=0;k<2;++k) \
;     dst[m][k]=*reinterpret_cast<const bf16x8*>((char*)P8_SA(b,h)+lds_byte(wr*64+m*16+fr,k*32+fq*8))
; #define P8_LDB(dst,b,h) _Pragma("unroll") for(int n=0;n<2;++n) _Pragma("unroll") for(int k=0;k<2;++k) \
;     dst[n][k]=*reinterpret_cast<const bf16x8*>((char*)P8_SB(b,h)+lds_byte(wc*32+n*16+fr,k*32+fq*8))
; #define P8_MMA(ai,bj,At,Bt) do{__builtin_amdgcn_s_setprio(1); \
;     _Pragma("unroll") for(int m=0;m<4;++m) _Pragma("unroll") for(int n=0;n<2;++n) _Pragma("unroll") for(int k=0;k<2;++k) \
;       acc[ai][bj][m][n]=__builtin_amdgcn_mfma_f32_16x16x32_bf16(At[m][k],Bt[n][k],acc[ai][bj][m][n],0,0,0); \
;     __builtin_amdgcn_s_setprio(0);}while(0)
; #define P8_WAIT_V(n) asm volatile("s_waitcnt vmcnt(" #n ")":::"memory")
; #define P8_WAIT_L(n) asm volatile("s_waitcnt lgkmcnt(" #n ")":::"memory")
; #define P8_BAR __builtin_amdgcn_s_barrier()
; #define P8_SCHED __builtin_amdgcn_sched_barrier(0)
; template <class EPI>
; DEVI void gemm8_tile(const bfr* __restrict__ A, const bfr* __restrict__ Bt, int K, int brow, int bcol, int nbrow, int nbcol, char* shmc, EPI epi) {
;     ...
;     P8_BAR; P8_WAIT_L(0); P8_MMA(1,0,At,B0); P8_BAR; P8_SCHED;
;     P8_STAGE(P8_SB(0,1),Bt,bcol+128,t+2);
;     P8_WAIT_V(6); P8_BAR; P8_MMA(1,1,At,B1); P8_BAR;
;     P8_LDB(B0,1,0); P8_SCHED; P8_LDA(At,1,0); P8_STAGE(P8_SA(0,1),A,brow+128,t+2);
;     P8_WAIT_L(8); P8_BAR; P8_WAIT_L(0); P8_MMA(0,0,At,B0); P8_BAR; P8_SCHED;
;     P8_LDB(B1,1,1); P8_STAGE(P8_SB(1,0),Bt,bcol,t+3);
;     P8_BAR; P8_WAIT_L(0); P8_MMA(0,1,At,B1); P8_BAR;
	s_waitcnt lgkmcnt(0)
	s_setprio 1
	s_waitcnt lgkmcnt(0)
	v_mfma_f32_16x16x32_bf16 v[60:63], v[190:193], v[174:177], v[60:63]
	v_mfma_f32_16x16x32_bf16 v[56:59], v[190:193], v[182:185], v[56:59]
	v_mfma_f32_16x16x32_bf16 v[52:55], v[200:203], v[174:177], v[52:55]
	v_mfma_f32_16x16x32_bf16 v[48:51], v[200:203], v[182:185], v[48:51]
	v_mfma_f32_16x16x32_bf16 v[44:47], v[208:211], v[174:177], v[44:47]
	v_mfma_f32_16x16x32_bf16 v[40:43], v[208:211], v[182:185], v[40:43]
	v_mfma_f32_16x16x32_bf16 v[36:39], v[216:219], v[174:177], v[36:39]
	v_mfma_f32_16x16x32_bf16 v[32:35], v[216:219], v[182:185], v[32:35]
	v_mfma_f32_16x16x32_bf16 v[60:63], v[196:199], v[178:181], v[60:63]
	v_mfma_f32_16x16x32_bf16 v[56:59], v[196:199], v[186:189], v[56:59]
	v_mfma_f32_16x16x32_bf16 v[52:55], v[204:207], v[178:181], v[52:55]
	v_mfma_f32_16x16x32_bf16 v[48:51], v[204:207], v[186:189], v[48:51]
	v_mfma_f32_16x16x32_bf16 v[44:47], v[212:215], v[178:181], v[44:47]
	v_mfma_f32_16x16x32_bf16 v[40:43], v[212:215], v[186:189], v[40:43]
	v_mfma_f32_16x16x32_bf16 v[36:39], v[220:223], v[178:181], v[36:39]
	v_mfma_f32_16x16x32_bf16 v[32:35], v[220:223], v[186:189], v[32:35]
	s_setprio 0
	s_barrier
	v_add_u32_e32 v174, s70, v136
	s_add_i32 m0, s100, 0x14000
	s_nop 0
	global_load_lds_dwordx4 v174, s[86:87]
	v_add_u32_e32 v174, s70, v134
	s_add_i32 m0, s100, 0x16000
	s_nop 0
	global_load_lds_dwordx4 v174, s[86:87]
	s_waitcnt vmcnt(6)
	s_barrier
	s_setprio 1
	v_mfma_f32_16x16x32_bf16 v[28:31], v[190:193], v[224:227], v[28:31]
	v_mfma_f32_16x16x32_bf16 v[24:27], v[190:193], v[232:235], v[24:27]
	v_mfma_f32_16x16x32_bf16 v[20:23], v[200:203], v[224:227], v[20:23]
	v_mfma_f32_16x16x32_bf16 v[16:19], v[200:203], v[232:235], v[16:19]
	v_mfma_f32_16x16x32_bf16 v[12:15], v[208:211], v[224:227], v[12:15]
	v_mfma_f32_16x16x32_bf16 v[8:11], v[208:211], v[232:235], v[8:11]
	v_mfma_f32_16x16x32_bf16 v[4:7], v[216:219], v[224:227], v[4:7]
	v_mfma_f32_16x16x32_bf16 v[0:3], v[216:219], v[232:235], v[0:3]
	v_mfma_f32_16x16x32_bf16 v[28:31], v[196:199], v[228:231], v[28:31]
	v_mfma_f32_16x16x32_bf16 v[24:27], v[196:199], v[236:239], v[24:27]
	v_mfma_f32_16x16x32_bf16 v[20:23], v[204:207], v[228:231], v[20:23]
	v_mfma_f32_16x16x32_bf16 v[16:19], v[204:207], v[236:239], v[16:19]
	v_mfma_f32_16x16x32_bf16 v[12:15], v[212:215], v[228:231], v[12:15]
	v_mfma_f32_16x16x32_bf16 v[8:11], v[212:215], v[236:239], v[8:11]
	v_mfma_f32_16x16x32_bf16 v[4:7], v[220:223], v[228:231], v[4:7]
	v_mfma_f32_16x16x32_bf16 v[0:3], v[220:223], v[236:239], v[0:3]
	s_setprio 0
	s_barrier
	ds_read_b128 v[174:177], v156
	ds_read_b128 v[178:181], v156 offset:1024
	ds_read_b128 v[182:185], v156 offset:2048
	ds_read_b128 v[186:189], v156 offset:3072
	v_add_u32_e32 v224, s72, v140
	s_add_i32 m0, s100, 0x4000
	ds_read_b128 v[190:193], v154 offset:32768
	ds_read_b128 v[196:199], v154 offset:33792
	ds_read_b128 v[200:203], v153 offset:32768
	ds_read_b128 v[204:207], v153 offset:33792
	ds_read_b128 v[208:211], v152 offset:32768
	ds_read_b128 v[212:215], v152 offset:33792
	ds_read_b128 v[216:219], v151 offset:32768
	ds_read_b128 v[220:223], v151 offset:33792
	global_load_lds_dwordx4 v224, s[86:87]
	v_add_u32_e32 v224, s72, v138
	s_add_i32 m0, s100, 0x6000
	s_nop 0
	global_load_lds_dwordx4 v224, s[86:87]
	s_waitcnt lgkmcnt(8)
	s_barrier
	s_waitcnt lgkmcnt(0)
	s_setprio 1
	s_waitcnt lgkmcnt(0)
	v_mfma_f32_16x16x32_bf16 v[124:127], v[190:193], v[174:177], v[124:127]
	v_mfma_f32_16x16x32_bf16 v[120:123], v[190:193], v[182:185], v[120:123]
	v_mfma_f32_16x16x32_bf16 v[116:119], v[200:203], v[174:177], v[116:119]
	v_mfma_f32_16x16x32_bf16 v[112:115], v[200:203], v[182:185], v[112:115]
	v_mfma_f32_16x16x32_bf16 v[108:111], v[208:211], v[174:177], v[108:111]
	v_mfma_f32_16x16x32_bf16 v[104:107], v[208:211], v[182:185], v[104:107]
	v_mfma_f32_16x16x32_bf16 v[100:103], v[216:219], v[174:177], v[100:103]
	v_mfma_f32_16x16x32_bf16 v[96:99], v[216:219], v[182:185], v[96:99]
	v_mfma_f32_16x16x32_bf16 v[124:127], v[196:199], v[178:181], v[124:127]
	v_mfma_f32_16x16x32_bf16 v[120:123], v[196:199], v[186:189], v[120:123]
	v_mfma_f32_16x16x32_bf16 v[116:119], v[204:207], v[178:181], v[116:119]
	v_mfma_f32_16x16x32_bf16 v[112:115], v[204:207], v[186:189], v[112:115]
	v_mfma_f32_16x16x32_bf16 v[108:111], v[212:215], v[178:181], v[108:111]
	v_mfma_f32_16x16x32_bf16 v[104:107], v[212:215], v[186:189], v[104:107]
	v_mfma_f32_16x16x32_bf16 v[100:103], v[220:223], v[178:181], v[100:103]
	v_mfma_f32_16x16x32_bf16 v[96:99], v[220:223], v[186:189], v[96:99]
	s_setprio 0
	s_barrier
	v_add_u32_e32 v248, s74, v136
	s_add_i32 m0, s100, 0x18000
	ds_read_b128 v[224:227], v155
	ds_read_b128 v[228:231], v155 offset:1024
	ds_read_b128 v[232:235], v155 offset:2048
	ds_read_b128 v[236:239], v155 offset:3072
	global_load_lds_dwordx4 v248, s[86:87]
	v_add_u32_e32 v248, s74, v134
	s_add_i32 m0, s100, 0x1a000
	s_nop 0
	global_load_lds_dwordx4 v248, s[86:87]
	s_barrier
	s_waitcnt lgkmcnt(0)
	s_setprio 1
	s_waitcnt lgkmcnt(0)
	v_mfma_f32_16x16x32_bf16 v[92:95], v[190:193], v[224:227], v[92:95]
	v_mfma_f32_16x16x32_bf16 v[88:91], v[190:193], v[232:235], v[88:91]
	v_mfma_f32_16x16x32_bf16 v[84:87], v[200:203], v[224:227], v[84:87]
	v_mfma_f32_16x16x32_bf16 v[80:83], v[200:203], v[232:235], v[80:83]
	v_mfma_f32_16x16x32_bf16 v[76:79], v[208:211], v[224:227], v[76:79]
	v_mfma_f32_16x16x32_bf16 v[72:75], v[208:211], v[232:235], v[72:75]
	v_mfma_f32_16x16x32_bf16 v[68:71], v[216:219], v[224:227], v[68:71]
	v_mfma_f32_16x16x32_bf16 v[64:67], v[216:219], v[232:235], v[64:67]
	v_mfma_f32_16x16x32_bf16 v[92:95], v[196:199], v[228:231], v[92:95]
	v_mfma_f32_16x16x32_bf16 v[88:91], v[196:199], v[236:239], v[88:91]
	v_mfma_f32_16x16x32_bf16 v[84:87], v[204:207], v[228:231], v[84:87]
	v_mfma_f32_16x16x32_bf16 v[80:83], v[204:207], v[236:239], v[80:83]
	v_mfma_f32_16x16x32_bf16 v[76:79], v[212:215], v[228:231], v[76:79]
	v_mfma_f32_16x16x32_bf16 v[72:75], v[212:215], v[236:239], v[72:75]
	v_mfma_f32_16x16x32_bf16 v[68:71], v[220:223], v[228:231], v[68:71]
	v_mfma_f32_16x16x32_bf16 v[64:67], v[220:223], v[236:239], v[64:67]
	s_setprio 0
	v_add_u32_e32 v240, s82, v140
	s_add_i32 m0, s100, 0x8000
	s_barrier
; #define P8_STAGE(P,BASE,br,kt) do{const bfr* _ub=(BASE)+((long)(br)*K+(long)(kt)*BK); \
;     __builtin_amdgcn_global_load_lds((const unsigned*)(_ub+so0),(unsigned*)((char*)(P)+wid*1024),16,0,0); \
;     __builtin_amdgcn_global_load_lds((const unsigned*)(_ub+so1),(unsigned*)((char*)(P)+wid*1024+8192),16,0,0);}while(0)
; #define P8_LDA(dst,b,h) _Pragma("unroll") for(int m=0;m<4;++m) _Pragma("unroll") for(int k=0;k<2;++k) \
;     dst[m][k]=*reinterpret_cast<const bf16x8*>((char*)P8_SA(b,h)+lds_byte(wr*64+m*16+fr,k*32+fq*8))
; #define P8_LDB(dst,b,h) _Pragma("unroll") for(int n=0;n<2;++n) _Pragma("unroll") for(int k=0;k<2;++k) \
;     dst[n][k]=*reinterpret_cast<const bf16x8*>((char*)P8_SB(b,h)+lds_byte(wc*32+n*16+fr,k*32+fq*8))
; #define P8_MMA(ai,bj,At,Bt) do{__builtin_amdgcn_s_setprio(1); \
;     _Pragma("unroll") for(int m=0;m<4;++m) _Pragma("unroll") for(int n=0;n<2;++n) _Pragma("unroll") for(int k=0;k<2;++k) \
;       acc[ai][bj][m][n]=__builtin_amdgcn_mfma_f32_16x16x32_bf16(At[m][k],Bt[n][k],acc[ai][bj][m][n],0,0,0); \
;     __builtin_amdgcn_s_setprio(0);}while(0)
; #define P8_WAIT_V(n) asm volatile("s_waitcnt vmcnt(" #n ")":::"memory")
; #define P8_WAIT_L(n) asm volatile("s_waitcnt lgkmcnt(" #n ")":::"memory")
; #define P8_BAR __builtin_amdgcn_s_barrier()
; #define P8_SCHED __builtin_amdgcn_sched_barrier(0)
; template <class EPI>
; DEVI void gemm8_tile(const bfr* __restrict__ A, const bfr* __restrict__ Bt, int K, int brow, int bcol, int nbrow, int nbcol, char* shmc, EPI epi) {
;     ...
;     P8_LDA(At,1,1); P8_STAGE(P8_SA(1,0),A,brow,t+3);
;     P8_BAR; P8_WAIT_L(0); P8_MMA(1,0,At,B0); P8_BAR; P8_SCHED;
;     P8_STAGE(P8_SB(1,1),Bt,bcol+128,t+3);
;     P8_WAIT_V(6); P8_BAR; P8_MMA(1,1,At,B1); P8_BAR;
;   }
;   { P8_LDB(B0,0,0); P8_LDA(At,0,0); P8_STAGE(P8_SA(1,1),A,brow+128,nt-1);
;     P8_BAR; P8_WAIT_L(0); P8_MMA(0,0,At,B0); P8_BAR;
;     P8_LDB(B1,0,1); P8_BAR; P8_WAIT_L(0); P8_MMA(0,1,At,B1); P8_BAR;
;     P8_LDA(At,0,1); P8_WAIT_V(4); P8_BAR; P8_WAIT_L(0); P8_MMA(1,0,At,B0); P8_MMA(1,1,At,B1); P8_BAR; }
	ds_read_b128 v[190:193], v154 offset:49152
	ds_read_b128 v[196:199], v154 offset:50176
	ds_read_b128 v[200:203], v153 offset:49152
	ds_read_b128 v[204:207], v153 offset:50176
	ds_read_b128 v[208:211], v152 offset:49152
	ds_read_b128 v[212:215], v152 offset:50176
	ds_read_b128 v[216:219], v151 offset:49152
	ds_read_b128 v[220:223], v151 offset:50176
	global_load_lds_dwordx4 v240, s[86:87]
	v_add_u32_e32 v240, s82, v138
	s_add_i32 m0, s100, 0xa000
	s_nop 0
	global_load_lds_dwordx4 v240, s[86:87]
	s_barrier
	s_waitcnt lgkmcnt(0)
	s_setprio 1
	s_waitcnt lgkmcnt(0)
	v_mfma_f32_16x16x32_bf16 v[60:63], v[190:193], v[174:177], v[60:63]
	v_mfma_f32_16x16x32_bf16 v[56:59], v[190:193], v[182:185], v[56:59]
	v_mfma_f32_16x16x32_bf16 v[52:55], v[200:203], v[174:177], v[52:55]
	v_mfma_f32_16x16x32_bf16 v[48:51], v[200:203], v[182:185], v[48:51]
	v_mfma_f32_16x16x32_bf16 v[44:47], v[208:211], v[174:177], v[44:47]
	v_mfma_f32_16x16x32_bf16 v[40:43], v[208:211], v[182:185], v[40:43]
	v_mfma_f32_16x16x32_bf16 v[36:39], v[216:219], v[174:177], v[36:39]
	v_mfma_f32_16x16x32_bf16 v[32:35], v[216:219], v[182:185], v[32:35]
	v_mfma_f32_16x16x32_bf16 v[60:63], v[196:199], v[178:181], v[60:63]
	v_mfma_f32_16x16x32_bf16 v[56:59], v[196:199], v[186:189], v[56:59]
	v_mfma_f32_16x16x32_bf16 v[52:55], v[204:207], v[178:181], v[52:55]
	v_mfma_f32_16x16x32_bf16 v[48:51], v[204:207], v[186:189], v[48:51]
	v_mfma_f32_16x16x32_bf16 v[44:47], v[212:215], v[178:181], v[44:47]
	v_mfma_f32_16x16x32_bf16 v[40:43], v[212:215], v[186:189], v[40:43]
	v_mfma_f32_16x16x32_bf16 v[36:39], v[220:223], v[178:181], v[36:39]
	v_mfma_f32_16x16x32_bf16 v[32:35], v[220:223], v[186:189], v[32:35]
	s_setprio 0
	s_barrier
	v_add_u32_e32 v174, s78, v136
	s_add_i32 m0, s100, 0x1c000
	s_nop 0
	global_load_lds_dwordx4 v174, s[86:87]
	v_add_u32_e32 v174, s78, v134
	s_add_i32 m0, s100, 0x1e000
	s_nop 0
	global_load_lds_dwordx4 v174, s[86:87]
	s_waitcnt vmcnt(6)
	s_barrier
	s_setprio 1
	v_mfma_f32_16x16x32_bf16 v[28:31], v[190:193], v[224:227], v[28:31]
	v_mfma_f32_16x16x32_bf16 v[24:27], v[190:193], v[232:235], v[24:27]
	v_mfma_f32_16x16x32_bf16 v[20:23], v[200:203], v[224:227], v[20:23]
	v_mfma_f32_16x16x32_bf16 v[16:19], v[200:203], v[232:235], v[16:19]
	v_mfma_f32_16x16x32_bf16 v[12:15], v[208:211], v[224:227], v[12:15]
	v_mfma_f32_16x16x32_bf16 v[8:11], v[208:211], v[232:235], v[8:11]
	v_mfma_f32_16x16x32_bf16 v[4:7], v[216:219], v[224:227], v[4:7]
	v_mfma_f32_16x16x32_bf16 v[0:3], v[216:219], v[232:235], v[0:3]
	v_mfma_f32_16x16x32_bf16 v[28:31], v[196:199], v[228:231], v[28:31]
	v_mfma_f32_16x16x32_bf16 v[24:27], v[196:199], v[236:239], v[24:27]
	v_mfma_f32_16x16x32_bf16 v[20:23], v[204:207], v[228:231], v[20:23]
	v_mfma_f32_16x16x32_bf16 v[16:19], v[204:207], v[236:239], v[16:19]
	v_mfma_f32_16x16x32_bf16 v[12:15], v[212:215], v[228:231], v[12:15]
	v_mfma_f32_16x16x32_bf16 v[8:11], v[212:215], v[236:239], v[8:11]
	v_mfma_f32_16x16x32_bf16 v[4:7], v[220:223], v[228:231], v[4:7]
	v_mfma_f32_16x16x32_bf16 v[0:3], v[220:223], v[236:239], v[0:3]
	s_setprio 0
	s_add_i32 s0, s0, 2
	v_lshl_add_u64 v[134:135], v[134:135], 0, s[80:81]
	v_lshl_add_u64 v[136:137], v[136:137], 0, s[80:81]
	v_lshl_add_u64 v[138:139], v[138:139], 0, s[80:81]
	s_cmp_lt_u32 s0, 28
	v_lshl_add_u64 v[140:141], v[140:141], 0, s[80:81]
	s_barrier
	s_cbranch_scc1 .LBB0_66
	s_or_b32 s0, s8, 0x80
	s_ashr_i32 s1, s0, 31
	s_lshl_b64 s[0:1], s[0:1], 12
	s_add_u32 s0, s28, s0
	s_addc_u32 s1, s29, s1
	v_lshl_add_u64 v[192:193], v[166:167], 1, s[0:1]
	s_mov_b64 s[54:55], 0xf80
	v_lshl_add_u64 v[192:193], v[192:193], 0, s[54:55]
	s_add_i32 m0, s100, 0xc000
	v_lshl_add_u64 v[132:133], v[132:133], 1, s[0:1]
	ds_read_b128 v[134:137], v172
	ds_read_b128 v[138:141], v172 offset:1024
	ds_read_b128 v[158:161], v172 offset:2048
	ds_read_b128 v[172:175], v172 offset:3072
	ds_read_b128 v[176:179], v154
	ds_read_b128 v[180:183], v154 offset:1024
	ds_read_b128 v[184:187], v153
	ds_read_b128 v[188:191], v153 offset:1024
	ds_read_b128 v[196:199], v152
	ds_read_b128 v[200:203], v152 offset:1024
	ds_read_b128 v[204:207], v151
	ds_read_b128 v[208:211], v151 offset:1024
	global_load_lds_dwordx4 v[192:193], off
	v_lshl_add_u64 v[132:133], v[132:133], 0, s[54:55]
	s_add_i32 m0, s100, 0xe000
	s_nop 0
	global_load_lds_dwordx4 v[132:133], off
	s_barrier
	s_waitcnt lgkmcnt(0)
	s_setprio 1
	s_waitcnt lgkmcnt(0)
	v_mfma_f32_16x16x32_bf16 v[124:127], v[176:179], v[134:137], v[124:127]
	v_mfma_f32_16x16x32_bf16 v[116:119], v[184:187], v[134:137], v[116:119]
	v_mfma_f32_16x16x32_bf16 v[112:115], v[184:187], v[158:161], v[112:115]
	v_mfma_f32_16x16x32_bf16 v[96:99], v[204:207], v[158:161], v[96:99]
	v_mfma_f32_16x16x32_bf16 v[124:127], v[180:183], v[138:141], v[124:127]
	v_mfma_f32_16x16x32_bf16 v[120:123], v[176:179], v[158:161], v[120:123]
	v_mfma_f32_16x16x32_bf16 v[116:119], v[188:191], v[138:141], v[116:119]
	v_mfma_f32_16x16x32_bf16 v[112:115], v[188:191], v[172:175], v[112:115]
	v_mfma_f32_16x16x32_bf16 v[108:111], v[196:199], v[134:137], v[108:111]
	v_mfma_f32_16x16x32_bf16 v[104:107], v[196:199], v[158:161], v[104:107]
	v_mfma_f32_16x16x32_bf16 v[100:103], v[204:207], v[134:137], v[100:103]
	v_mfma_f32_16x16x32_bf16 v[96:99], v[208:211], v[172:175], v[96:99]
	v_mfma_f32_16x16x32_bf16 v[212:215], v[180:183], v[172:175], v[120:123]
	v_mfma_f32_16x16x32_bf16 v[216:219], v[200:203], v[138:141], v[108:111]
	v_mfma_f32_16x16x32_bf16 v[220:223], v[200:203], v[172:175], v[104:107]
	v_mfma_f32_16x16x32_bf16 v[224:227], v[208:211], v[138:141], v[100:103]
	s_setprio 0
	s_barrier
; #define P8_LDA(dst,b,h) _Pragma("unroll") for(int m=0;m<4;++m) _Pragma("unroll") for(int k=0;k<2;++k) \
;     dst[m][k]=*reinterpret_cast<const bf16x8*>((char*)P8_SA(b,h)+lds_byte(wr*64+m*16+fr,k*32+fq*8))
; #define P8_LDB(dst,b,h) _Pragma("unroll") for(int n=0;n<2;++n) _Pragma("unroll") for(int k=0;k<2;++k) \
;     dst[n][k]=*reinterpret_cast<const bf16x8*>((char*)P8_SB(b,h)+lds_byte(wc*32+n*16+fr,k*32+fq*8))
; #define P8_MMA(ai,bj,At,Bt) do{__builtin_amdgcn_s_setprio(1); \
;     _Pragma("unroll") for(int m=0;m<4;++m) _Pragma("unroll") for(int n=0;n<2;++n) _Pragma("unroll") for(int k=0;k<2;++k) \
;       acc[ai][bj][m][n]=__builtin_amdgcn_mfma_f32_16x16x32_bf16(At[m][k],Bt[n][k],acc[ai][bj][m][n],0,0,0); \
;     __builtin_amdgcn_s_setprio(0);}while(0)
; #define P8_WAIT_V(n) asm volatile("s_waitcnt vmcnt(" #n ")":::"memory")
; #define P8_WAIT_L(n) asm volatile("s_waitcnt lgkmcnt(" #n ")":::"memory")
; #define P8_BAR __builtin_amdgcn_s_barrier()
; template <class EPI>
; DEVI void gemm8_tile(const bfr* __restrict__ A, const bfr* __restrict__ Bt, int K, int brow, int bcol, int nbrow, int nbcol, char* shmc, EPI epi) {
;     ...
;     P8_BAR; P8_WAIT_L(0); P8_MMA(0,0,At,B0); P8_BAR;
;     P8_LDB(B1,0,1); P8_BAR; P8_WAIT_L(0); P8_MMA(0,1,At,B1); P8_BAR;
;     P8_LDA(At,0,1); P8_WAIT_V(4); P8_BAR; P8_WAIT_L(0); P8_MMA(1,0,At,B0); P8_MMA(1,1,At,B1); P8_BAR; }
;   { P8_LDB(B0,1,0); P8_LDA(At,1,0); P8_WAIT_V(2); P8_BAR; P8_WAIT_L(0); P8_MMA(0,0,At,B0); P8_BAR;
;     P8_LDB(B1,1,1); P8_WAIT_V(0); P8_BAR; P8_WAIT_L(0); P8_MMA(0,1,At,B1); P8_BAR;
;     P8_LDA(At,1,1); P8_BAR; P8_WAIT_L(0); P8_MMA(1,0,At,B0); P8_MMA(1,1,At,B1); P8_BAR; }
	s_nop 0
	ds_read_b128 v[100:103], v162
	ds_read_b128 v[104:107], v162 offset:1024
	ds_read_b128 v[108:111], v162 offset:2048
	ds_read_b128 v[120:123], v162 offset:3072
	s_barrier
	s_waitcnt lgkmcnt(0)
	s_setprio 1
	s_waitcnt lgkmcnt(0)
	v_mfma_f32_16x16x32_bf16 v[92:95], v[176:179], v[100:103], v[92:95]
	v_mfma_f32_16x16x32_bf16 v[84:87], v[184:187], v[100:103], v[84:87]
	v_mfma_f32_16x16x32_bf16 v[80:83], v[184:187], v[108:111], v[80:83]
	v_mfma_f32_16x16x32_bf16 v[64:67], v[204:207], v[108:111], v[64:67]
	v_mfma_f32_16x16x32_bf16 v[92:95], v[180:183], v[104:107], v[92:95]
	v_mfma_f32_16x16x32_bf16 v[88:91], v[176:179], v[108:111], v[88:91]
	v_mfma_f32_16x16x32_bf16 v[84:87], v[188:191], v[104:107], v[84:87]
	v_mfma_f32_16x16x32_bf16 v[80:83], v[188:191], v[120:123], v[80:83]
	v_mfma_f32_16x16x32_bf16 v[76:79], v[196:199], v[100:103], v[76:79]
	v_mfma_f32_16x16x32_bf16 v[72:75], v[196:199], v[108:111], v[72:75]
	v_mfma_f32_16x16x32_bf16 v[68:71], v[204:207], v[100:103], v[68:71]
	v_mfma_f32_16x16x32_bf16 v[64:67], v[208:211], v[120:123], v[64:67]
	v_mfma_f32_16x16x32_bf16 v[176:179], v[180:183], v[120:123], v[88:91]
	v_mfma_f32_16x16x32_bf16 v[180:183], v[200:203], v[104:107], v[76:79]
	v_mfma_f32_16x16x32_bf16 v[184:187], v[200:203], v[120:123], v[72:75]
	v_mfma_f32_16x16x32_bf16 v[188:191], v[208:211], v[104:107], v[68:71]
	s_setprio 0
	s_barrier
	s_nop 0
	ds_read_b128 v[68:71], v154 offset:16384
	ds_read_b128 v[72:75], v154 offset:17408
	ds_read_b128 v[76:79], v153 offset:16384
	ds_read_b128 v[88:91], v153 offset:17408
	ds_read_b128 v[196:199], v152 offset:16384
	ds_read_b128 v[200:203], v152 offset:17408
	ds_read_b128 v[204:207], v151 offset:16384
	ds_read_b128 v[208:211], v151 offset:17408
	s_waitcnt vmcnt(4)
	s_barrier
	s_waitcnt lgkmcnt(0)
	s_setprio 1
	s_waitcnt lgkmcnt(0)
	v_mfma_f32_16x16x32_bf16 v[60:63], v[68:71], v[134:137], v[60:63]
	v_mfma_f32_16x16x32_bf16 v[52:55], v[76:79], v[134:137], v[52:55]
	v_mfma_f32_16x16x32_bf16 v[48:51], v[76:79], v[158:161], v[48:51]
	v_mfma_f32_16x16x32_bf16 v[32:35], v[204:207], v[158:161], v[32:35]
	v_mfma_f32_16x16x32_bf16 v[60:63], v[72:75], v[138:141], v[60:63]
	v_mfma_f32_16x16x32_bf16 v[56:59], v[68:71], v[158:161], v[56:59]
	v_mfma_f32_16x16x32_bf16 v[52:55], v[88:91], v[138:141], v[52:55]
	v_mfma_f32_16x16x32_bf16 v[48:51], v[88:91], v[172:175], v[48:51]
	v_mfma_f32_16x16x32_bf16 v[44:47], v[196:199], v[134:137], v[44:47]
	v_mfma_f32_16x16x32_bf16 v[40:43], v[196:199], v[158:161], v[40:43]
	v_mfma_f32_16x16x32_bf16 v[36:39], v[204:207], v[134:137], v[36:39]
	v_mfma_f32_16x16x32_bf16 v[32:35], v[208:211], v[172:175], v[32:35]
	v_mfma_f32_16x16x32_bf16 v[228:231], v[72:75], v[172:175], v[56:59]
	v_mfma_f32_16x16x32_bf16 v[232:235], v[200:203], v[138:141], v[44:47]
	v_mfma_f32_16x16x32_bf16 v[236:239], v[200:203], v[172:175], v[40:43]
	v_mfma_f32_16x16x32_bf16 v[132:135], v[208:211], v[138:141], v[36:39]
	s_setprio 0
	s_setprio 1
	v_mfma_f32_16x16x32_bf16 v[28:31], v[68:71], v[100:103], v[28:31]
	v_mfma_f32_16x16x32_bf16 v[20:23], v[76:79], v[100:103], v[20:23]
	v_mfma_f32_16x16x32_bf16 v[16:19], v[76:79], v[108:111], v[16:19]
	v_mfma_f32_16x16x32_bf16 v[0:3], v[204:207], v[108:111], v[0:3]
	v_mfma_f32_16x16x32_bf16 v[28:31], v[72:75], v[104:107], v[28:31]
	v_mfma_f32_16x16x32_bf16 v[24:27], v[68:71], v[108:111], v[24:27]
	v_mfma_f32_16x16x32_bf16 v[20:23], v[88:91], v[104:107], v[20:23]
	v_mfma_f32_16x16x32_bf16 v[16:19], v[88:91], v[120:123], v[16:19]
	v_mfma_f32_16x16x32_bf16 v[12:15], v[196:199], v[100:103], v[12:15]
	v_mfma_f32_16x16x32_bf16 v[8:11], v[196:199], v[108:111], v[8:11]
	v_mfma_f32_16x16x32_bf16 v[4:7], v[204:207], v[100:103], v[4:7]
	v_mfma_f32_16x16x32_bf16 v[0:3], v[208:211], v[120:123], v[0:3]
	v_mfma_f32_16x16x32_bf16 v[136:139], v[72:75], v[120:123], v[24:27]
	v_mfma_f32_16x16x32_bf16 v[158:161], v[200:203], v[104:107], v[12:15]
	v_mfma_f32_16x16x32_bf16 v[170:173], v[200:203], v[120:123], v[8:11]
	v_mfma_f32_16x16x32_bf16 v[196:199], v[208:211], v[104:107], v[4:7]
	s_setprio 0
	s_barrier
	s_nop 0
	ds_read_b128 v[4:7], v156
	ds_read_b128 v[8:11], v156 offset:1024
	ds_read_b128 v[12:15], v156 offset:2048
	ds_read_b128 v[24:27], v156 offset:3072
	ds_read_b128 v[36:39], v154 offset:32768
	ds_read_b128 v[40:43], v154 offset:33792
	ds_read_b128 v[44:47], v153 offset:32768
	ds_read_b128 v[56:59], v153 offset:33792
	ds_read_b128 v[68:71], v152 offset:32768
	ds_read_b128 v[200:203], v152 offset:33792
	ds_read_b128 v[204:207], v151 offset:32768
	ds_read_b128 v[208:211], v151 offset:33792
	s_waitcnt vmcnt(2)
	s_barrier
	s_waitcnt lgkmcnt(0)
	s_setprio 1
	s_waitcnt lgkmcnt(0)
	v_mfma_f32_16x16x32_bf16 v[72:75], v[36:39], v[4:7], v[124:127]
	v_mfma_f32_16x16x32_bf16 v[120:123], v[40:43], v[8:11], v[72:75]
	v_mfma_f32_16x16x32_bf16 v[72:75], v[36:39], v[12:15], v[212:215]
	v_mfma_f32_16x16x32_bf16 v[104:107], v[40:43], v[24:27], v[72:75]
	v_mfma_f32_16x16x32_bf16 v[72:75], v[44:47], v[4:7], v[116:119]
	v_mfma_f32_16x16x32_bf16 v[124:127], v[56:59], v[8:11], v[72:75]
	v_mfma_f32_16x16x32_bf16 v[72:75], v[44:47], v[12:15], v[112:115]
	v_mfma_f32_16x16x32_bf16 v[108:111], v[56:59], v[24:27], v[72:75]
	v_mfma_f32_16x16x32_bf16 v[72:75], v[68:71], v[4:7], v[216:219]
	v_mfma_f32_16x16x32_bf16 v[112:115], v[200:203], v[8:11], v[72:75]
	v_mfma_f32_16x16x32_bf16 v[72:75], v[68:71], v[12:15], v[220:223]
	v_mfma_f32_16x16x32_bf16 v[100:103], v[200:203], v[24:27], v[72:75]
	v_mfma_f32_16x16x32_bf16 v[72:75], v[204:207], v[4:7], v[224:227]
	v_mfma_f32_16x16x32_bf16 v[116:119], v[208:211], v[8:11], v[72:75]
	v_mfma_f32_16x16x32_bf16 v[72:75], v[204:207], v[12:15], v[96:99]
	v_mfma_f32_16x16x32_bf16 v[96:99], v[208:211], v[24:27], v[72:75]
	s_setprio 0
	s_barrier
; #define P8_STAGE(P,BASE,br,kt) do{const bfr* _ub=(BASE)+((long)(br)*K+(long)(kt)*BK); \
;     __builtin_amdgcn_global_load_lds((const unsigned*)(_ub+so0),(unsigned*)((char*)(P)+wid*1024),16,0,0); \
;     __builtin_amdgcn_global_load_lds((const unsigned*)(_ub+so1),(unsigned*)((char*)(P)+wid*1024+8192),16,0,0);}while(0)
; #define P8_LDA(dst,b,h) _Pragma("unroll") for(int m=0;m<4;++m) _Pragma("unroll") for(int k=0;k<2;++k) \
;     dst[m][k]=*reinterpret_cast<const bf16x8*>((char*)P8_SA(b,h)+lds_byte(wr*64+m*16+fr,k*32+fq*8))
; #define P8_LDB(dst,b,h) _Pragma("unroll") for(int n=0;n<2;++n) _Pragma("unroll") for(int k=0;k<2;++k) \
;     dst[n][k]=*reinterpret_cast<const bf16x8*>((char*)P8_SB(b,h)+lds_byte(wc*32+n*16+fr,k*32+fq*8))
; #define P8_MMA(ai,bj,At,Bt) do{__builtin_amdgcn_s_setprio(1); \
;     _Pragma("unroll") for(int m=0;m<4;++m) _Pragma("unroll") for(int n=0;n<2;++n) _Pragma("unroll") for(int k=0;k<2;++k) \
;       acc[ai][bj][m][n]=__builtin_amdgcn_mfma_f32_16x16x32_bf16(At[m][k],Bt[n][k],acc[ai][bj][m][n],0,0,0); \
;     __builtin_amdgcn_s_setprio(0);}while(0)
; #define P8_WAIT_V(n) asm volatile("s_waitcnt vmcnt(" #n ")":::"memory")
; #define P8_WAIT_L(n) asm volatile("s_waitcnt lgkmcnt(" #n ")":::"memory")
; #define P8_BAR __builtin_amdgcn_s_barrier()
; template <class EPI>
; DEVI void gemm8_tile(const bfr* __restrict__ A, const bfr* __restrict__ Bt, int K, int brow, int bcol, int nbrow, int nbcol, char* shmc, EPI epi) {
;     ...
;   { P8_LDB(B0,1,0); P8_LDA(At,1,0); P8_WAIT_V(2); P8_BAR; P8_WAIT_L(0); P8_MMA(0,0,At,B0); P8_BAR;
;     P8_LDB(B1,1,1); P8_WAIT_V(0); P8_BAR; P8_WAIT_L(0); P8_MMA(0,1,At,B1); P8_BAR;
;     P8_LDA(At,1,1); P8_BAR; P8_WAIT_L(0); P8_MMA(1,0,At,B0); P8_MMA(1,1,At,B1); P8_BAR; }
;   if(wr==0)P8_BAR;
;   if (nbrow >= 0) {
;     P8_STAGE(P8_SB(0,0),Bt,nbcol,0); P8_STAGE(P8_SA(0,0),A,nbrow,0);
;     P8_STAGE(P8_SB(0,1),Bt,nbcol+128,0); P8_STAGE(P8_SA(0,1),A,nbrow+128,0);
;   }
	ds_read_b128 v[212:215], v155
	ds_read_b128 v[216:219], v155 offset:1024
	ds_read_b128 v[220:223], v155 offset:2048
	ds_read_b128 v[224:227], v155 offset:3072
	s_waitcnt vmcnt(0)
	s_barrier
	s_waitcnt lgkmcnt(0)
	s_setprio 1
	s_waitcnt lgkmcnt(0)
	v_mfma_f32_16x16x32_bf16 v[72:75], v[36:39], v[212:215], v[92:95]
	v_mfma_f32_16x16x32_bf16 v[36:39], v[36:39], v[220:223], v[176:179]
	v_mfma_f32_16x16x32_bf16 v[88:91], v[40:43], v[216:219], v[72:75]
	v_mfma_f32_16x16x32_bf16 v[72:75], v[40:43], v[224:227], v[36:39]
	v_mfma_f32_16x16x32_bf16 v[36:39], v[44:47], v[212:215], v[84:87]
	v_mfma_f32_16x16x32_bf16 v[92:95], v[56:59], v[216:219], v[36:39]
	v_mfma_f32_16x16x32_bf16 v[36:39], v[44:47], v[220:223], v[80:83]
	v_mfma_f32_16x16x32_bf16 v[76:79], v[56:59], v[224:227], v[36:39]
	v_mfma_f32_16x16x32_bf16 v[36:39], v[68:71], v[212:215], v[180:183]
	v_mfma_f32_16x16x32_bf16 v[80:83], v[200:203], v[216:219], v[36:39]
	v_mfma_f32_16x16x32_bf16 v[36:39], v[68:71], v[220:223], v[184:187]
	v_mfma_f32_16x16x32_bf16 v[68:71], v[200:203], v[224:227], v[36:39]
	v_mfma_f32_16x16x32_bf16 v[36:39], v[204:207], v[212:215], v[188:191]
	v_mfma_f32_16x16x32_bf16 v[84:87], v[208:211], v[216:219], v[36:39]
	v_mfma_f32_16x16x32_bf16 v[36:39], v[204:207], v[220:223], v[64:67]
	v_mfma_f32_16x16x32_bf16 v[64:67], v[208:211], v[224:227], v[36:39]
	s_setprio 0
	s_barrier
	ds_read_b128 v[174:177], v154 offset:49152
	ds_read_b128 v[154:157], v154 offset:50176
	ds_read_b128 v[178:181], v153 offset:49152
	ds_read_b128 v[182:185], v153 offset:50176
	ds_read_b128 v[186:189], v152 offset:49152
	ds_read_b128 v[190:193], v152 offset:50176
	ds_read_b128 v[200:203], v151 offset:49152
	ds_read_b128 v[204:207], v151 offset:50176
	s_barrier
	s_waitcnt lgkmcnt(0)
	s_setprio 1
	s_waitcnt lgkmcnt(0)
	v_mfma_f32_16x16x32_bf16 v[36:39], v[174:177], v[4:7], v[60:63]
	v_mfma_f32_16x16x32_bf16 v[56:59], v[154:157], v[8:11], v[36:39]
	v_mfma_f32_16x16x32_bf16 v[36:39], v[174:177], v[12:15], v[228:231]
	v_mfma_f32_16x16x32_bf16 v[40:43], v[154:157], v[24:27], v[36:39]
	v_mfma_f32_16x16x32_bf16 v[36:39], v[178:181], v[4:7], v[52:55]
	v_mfma_f32_16x16x32_bf16 v[60:63], v[182:185], v[8:11], v[36:39]
	v_mfma_f32_16x16x32_bf16 v[36:39], v[178:181], v[12:15], v[48:51]
	v_mfma_f32_16x16x32_bf16 v[44:47], v[182:185], v[24:27], v[36:39]
	v_mfma_f32_16x16x32_bf16 v[36:39], v[186:189], v[4:7], v[232:235]
	v_mfma_f32_16x16x32_bf16 v[4:7], v[200:203], v[4:7], v[132:135]
	v_mfma_f32_16x16x32_bf16 v[48:51], v[190:193], v[8:11], v[36:39]
	v_mfma_f32_16x16x32_bf16 v[36:39], v[186:189], v[12:15], v[236:239]
	v_mfma_f32_16x16x32_bf16 v[52:55], v[204:207], v[8:11], v[4:7]
	v_mfma_f32_16x16x32_bf16 v[4:7], v[200:203], v[12:15], v[32:35]
	v_mfma_f32_16x16x32_bf16 v[36:39], v[190:193], v[24:27], v[36:39]
	v_mfma_f32_16x16x32_bf16 v[32:35], v[204:207], v[24:27], v[4:7]
	s_setprio 0
	s_setprio 1
	v_mfma_f32_16x16x32_bf16 v[4:7], v[174:177], v[212:215], v[28:31]
	v_mfma_f32_16x16x32_bf16 v[24:27], v[154:157], v[216:219], v[4:7]
	v_mfma_f32_16x16x32_bf16 v[4:7], v[174:177], v[220:223], v[136:139]
	v_mfma_f32_16x16x32_bf16 v[8:11], v[154:157], v[224:227], v[4:7]
	v_mfma_f32_16x16x32_bf16 v[4:7], v[178:181], v[212:215], v[20:23]
	v_mfma_f32_16x16x32_bf16 v[28:31], v[182:185], v[216:219], v[4:7]
	v_mfma_f32_16x16x32_bf16 v[4:7], v[178:181], v[220:223], v[16:19]
	v_mfma_f32_16x16x32_bf16 v[12:15], v[182:185], v[224:227], v[4:7]
	v_mfma_f32_16x16x32_bf16 v[4:7], v[186:189], v[212:215], v[158:161]
	v_mfma_f32_16x16x32_bf16 v[16:19], v[190:193], v[216:219], v[4:7]
	v_mfma_f32_16x16x32_bf16 v[4:7], v[186:189], v[220:223], v[170:173]
	v_mfma_f32_16x16x32_bf16 v[20:23], v[200:203], v[212:215], v[196:199]
	v_mfma_f32_16x16x32_bf16 v[0:3], v[200:203], v[220:223], v[0:3]
	v_mfma_f32_16x16x32_bf16 v[4:7], v[190:193], v[224:227], v[4:7]
	v_mfma_f32_16x16x32_bf16 v[20:23], v[204:207], v[216:219], v[20:23]
	v_mfma_f32_16x16x32_bf16 v[0:3], v[204:207], v[224:227], v[0:3]
	s_setprio 0
	v_cmp_gt_u32_e32 vcc, s57, v142
	s_barrier
	s_and_saveexec_b64 s[0:1], vcc
	s_cbranch_execz .LBB0_69
	s_barrier
.LBB0_69:
	s_or_b64 exec, exec, s[0:1]
	s_lshl_b32 s2, s65, 8
	s_and_b64 s[0:1], s[34:35], exec
	s_cselect_b32 s58, s2, -1
	s_cmp_lt_i32 s58, 0
	s_cbranch_scc1 .LBB0_58
	s_lshl_b32 s0, s68, 8
	s_ashr_i32 s1, s0, 31
	s_lshl_b64 s[34:35], s[0:1], 12
	s_add_u32 s34, s84, s34
	s_addc_u32 s35, s85, s35
	v_lshl_add_u64 v[132:133], s[34:35], 0, v[128:129]
	s_add_i32 m0, s100, 0x10000
	v_readfirstlane_b32 s1, v149
	global_load_lds_dwordx4 v[132:133], off
	v_lshl_add_u64 v[132:133], s[34:35], 0, v[130:131]
	s_lshl_b64 s[34:35], s[58:59], 12
	s_add_u32 s34, s28, s34
	s_mov_b32 m0, s1
	s_addc_u32 s35, s29, s35
	global_load_lds_dwordx4 v[132:133], off
	v_lshl_add_u64 v[132:133], s[34:35], 0, v[128:129]
	s_mov_b32 m0, s100
	s_bitset1_b32 s0, 7
	global_load_lds_dwordx4 v[132:133], off
	s_add_i32 m0, s100, 0x2000
	s_ashr_i32 s1, s0, 31
	s_lshl_b64 s[0:1], s[0:1], 12
	s_add_u32 s0, s84, s0
	v_lshl_add_u64 v[132:133], s[34:35], 0, v[130:131]
	s_addc_u32 s1, s85, s1
	global_load_lds_dwordx4 v[132:133], off
	v_lshl_add_u64 v[132:133], s[0:1], 0, v[128:129]
	s_add_i32 m0, s100, 0x14000
	s_addk_i32 s58, 0x80
	global_load_lds_dwordx4 v[132:133], off
	v_lshl_add_u64 v[132:133], s[0:1], 0, v[130:131]
	s_add_i32 m0, s100, 0x16000
	s_lshl_b64 s[0:1], s[58:59], 12
	s_add_u32 s0, s28, s0
	s_addc_u32 s1, s29, s1
	v_readfirstlane_b32 s2, v145
	global_load_lds_dwordx4 v[132:133], off
	v_lshl_add_u64 v[128:129], s[0:1], 0, v[128:129]
	s_mov_b32 m0, s2
	s_nop 0
	global_load_lds_dwordx4 v[128:129], off
	v_lshl_add_u64 v[128:129], s[0:1], 0, v[130:131]
	v_readfirstlane_b32 s0, v144
	s_mov_b32 m0, s0
	s_nop 0
	global_load_lds_dwordx4 v[128:129], off
	s_branch .LBB0_58

; #define P8_STAGE(P,BASE,br,kt) do{const bfr* _ub=(BASE)+((long)(br)*K+(long)(kt)*BK); \
;     __builtin_amdgcn_global_load_lds((const unsigned*)(_ub+so0),(unsigned*)((char*)(P)+wid*1024),16,0,0); \
;     __builtin_amdgcn_global_load_lds((const unsigned*)(_ub+so1),(unsigned*)((char*)(P)+wid*1024+8192),16,0,0);}while(0)
; #define P8_WAIT_V(n) asm volatile("s_waitcnt vmcnt(" #n ")":::"memory")
; #define P8_BAR __builtin_amdgcn_s_barrier()
; template <class EPI>
; DEVI void gemm8_tile(const bfr* __restrict__ A, const bfr* __restrict__ Bt, int K, int brow, int bcol, int nbrow, int nbcol, char* shmc, EPI epi) {
;     ...
;   unsigned so0, so1;
;   { int _r, _c; stage_rc(tid * 16, _r, _c); so0 = (unsigned)(_r * K + _c); stage_rc(tid * 16 + 8192, _r, _c); so1 = (unsigned)(_r * K + _c); }
;   f32x4 acc[2][2][4][2];
; #pragma unroll
;   for (int a = 0; a < 2; ++a)
; #pragma unroll
;     for (int b = 0; b < 2; ++b)
; #pragma unroll
;       for (int m = 0; m < 4; ++m)
; #pragma unroll
;         for (int n = 0; n < 2; ++n) acc[a][b][m][n] = f32x4{0.f, 0.f, 0.f, 0.f};
;   bf16x8 At[4][2], B0[2][2], B1[2][2];
;   const int nt = K / BK;
;   if(wr==1)P8_BAR;
;   P8_WAIT_V(4); P8_BAR;
;   P8_STAGE(P8_SB(1,0),Bt,bcol,1); P8_STAGE(P8_SA(1,0),A,brow,1); P8_STAGE(P8_SB(1,1),Bt,bcol+128,1);
;   P8_WAIT_V(6); P8_BAR;
.LBB0_84:
	s_or_b64 exec, exec, s[0:1]
	v_lshlrev_b32_e32 v2, 4, v142
	v_and_b32_e32 v3, 32, v142
	s_lshl_b32 s10, s9, 8
	v_lshrrev_b32_e32 v7, 1, v142
	v_bitop3_b32 v3, v2, v3, 48 bitop3:0x6c
	v_add_u32_e32 v2, 0x2000, v2
	v_ashrrev_i32_e32 v4, 3, v142
	v_bfe_u32 v5, v142, 2, 4
	s_mov_b32 s0, 0x1ffff0
	v_lshrrev_b32_e32 v8, 1, v3
	v_ashrrev_i32_e32 v9, 7, v2
	v_and_b32_e32 v7, 32, v7
	s_ashr_i32 s11, s10, 31
	s_lshl_b32 s8, s2, 8
	v_ashrrev_i32_e32 v1, 6, v142
	v_and_or_b32 v6, v4, s0, v5
	v_and_or_b32 v2, v9, s0, v5
	v_or_b32_e32 v3, v8, v7
	s_lshl_b64 s[0:1], s[10:11], 12
	v_lshl_or_b32 v166, v6, 11, v3
	s_add_u32 s54, s84, s0
	v_lshlrev_b32_e32 v143, 10, v1
	s_nop 0
	v_readfirstlane_b32 s100, v143
	s_nop 3
	s_addc_u32 s55, s85, s1
	v_lshlrev_b64 v[128:129], 1, v[166:167]
	v_add_u32_e32 v150, 0x18000, v143
	v_lshl_or_b32 v132, v2, 11, v3
	v_lshl_add_u64 v[2:3], s[54:55], 0, v[128:129]
	v_mov_b32_e32 v133, v167
	v_lshl_add_u64 v[2:3], v[2:3], 0, s[62:63]
	s_add_i32 m0, s100, 0x18000
	v_lshlrev_b64 v[130:131], 1, v[132:133]
	s_ashr_i32 s9, s8, 31
	s_waitcnt vmcnt(4)
	s_barrier
	global_load_lds_dwordx4 v[2:3], off
	v_lshl_add_u64 v[2:3], s[54:55], 0, v[130:131]
	v_add_u32_e32 v151, 0x1a000, v143
	s_lshl_b64 s[54:55], s[8:9], 12
	v_readfirstlane_b32 s2, v151
	s_add_u32 s60, s28, s54
	v_lshl_add_u64 v[2:3], v[2:3], 0, s[62:63]
	s_mov_b32 m0, s2
	s_addc_u32 s61, s29, s55
	v_add_u32_e32 v152, 0x8000, v143
	global_load_lds_dwordx4 v[2:3], off
	v_lshl_add_u64 v[2:3], s[60:61], 0, v[128:129]
	v_lshl_add_u64 v[2:3], v[2:3], 0, s[62:63]
	s_add_i32 m0, s100, 0x8000
	v_add_u32_e32 v153, 0xa000, v143
	global_load_lds_dwordx4 v[2:3], off
	v_lshl_add_u64 v[2:3], s[60:61], 0, v[130:131]
	s_or_b32 s60, s10, 0x80
	s_ashr_i32 s61, s60, 31
	s_lshl_b64 s[60:61], s[60:61], 12
	v_readfirstlane_b32 s2, v153
	s_add_u32 s60, s84, s60
	v_lshl_add_u64 v[2:3], v[2:3], 0, s[62:63]
	s_mov_b32 m0, s2
	s_addc_u32 s61, s85, s61
	v_add_u32_e32 v154, 0x1c000, v143
	global_load_lds_dwordx4 v[2:3], off
	v_lshl_add_u64 v[2:3], s[60:61], 0, v[128:129]
	v_lshl_add_u64 v[2:3], v[2:3], 0, s[62:63]
	s_add_i32 m0, s100, 0x1c000
	v_add_u32_e32 v156, 0x1e000, v143
	global_load_lds_dwordx4 v[2:3], off
	v_lshl_add_u64 v[2:3], s[60:61], 0, v[130:131]
	v_lshl_add_u64 v[2:3], v[2:3], 0, s[62:63]
	s_add_i32 m0, s100, 0x1e000
	v_and_b32_e32 v10, 15, v142
	global_load_lds_dwordx4 v[2:3], off
	v_lshlrev_b32_e32 v1, 12, v1
	v_and_b32_e32 v11, 48, v142
	v_and_b32_e32 v6, 0x3000, v1
	v_lshlrev_b32_e32 v1, 6, v10
	v_lshlrev_b32_e32 v3, 2, v142
	v_or_b32_e32 v2, v1, v11
	v_and_b32_e32 v3, 32, v3
	s_mov_b32 s2, 0x14000
	v_bitop3_b32 v13, v2, s2, v3 bitop3:0xde
	s_mov_b32 s2, 0x18000
	v_lshlrev_b32_e32 v16, 13, v0
	v_lshlrev_b32_e32 v0, 6, v142
	v_bitop3_b32 v14, v2, s2, v3 bitop3:0xde
	s_mov_b32 s2, 0x1c000
	v_and_b32_e32 v0, 0x3c0, v0
	v_bitop3_b32 v10, v1, v3, v11 bitop3:0x36
	v_bitop3_b32 v12, v2, s3, v3 bitop3:0xde
	v_bitop3_b32 v15, v2, s2, v3 bitop3:0xde
	v_bitop3_b32 v11, v0, v3, v11 bitop3:0x36
	v_lshlrev_b32_e32 v0, 11, v9
	s_movk_i32 s2, 0x8000
	v_lshlrev_b32_e32 v3, 11, v4
	v_and_or_b32 v0, v0, s2, v8
	v_lshlrev_b32_e32 v2, 11, v5
	v_and_or_b32 v3, v3, s2, v8
	v_or3_b32 v0, v0, v2, v7
	v_mov_b32_e32 v1, v167
	v_or3_b32 v2, v3, v2, v7
	v_mov_b32_e32 v3, v167
	v_lshlrev_b64 v[0:1], 1, v[0:1]
	v_lshlrev_b64 v[2:3], 1, v[2:3]
	v_lshl_add_u64 v[134:135], s[0:1], 0, v[0:1]
	v_lshl_add_u64 v[136:137], s[0:1], 0, v[2:3]
	s_add_u32 s0, s4, s54
	s_waitcnt vmcnt(6)
	s_addc_u32 s1, s5, s55
	v_or_b32_e32 v17, 0x800, v16
	v_or_b32_e32 v18, 0x1000, v16
	v_or_b32_e32 v19, 0x1800, v16
	v_lshl_add_u64 v[138:139], s[0:1], 0, v[0:1]
	v_mov_b32_e32 v0, 0
	v_lshl_add_u64 v[140:141], s[0:1], 0, v[2:3]
	s_mov_b32 s0, -2
	v_add_u32_e32 v157, v12, v6
	v_add_u32_e32 v147, v10, v16
	v_add_u32_e32 v146, v11, v17
	v_add_u32_e32 v145, v11, v18
	v_add_u32_e32 v144, v11, v19
	v_add_u32_e32 v155, v13, v6
	v_add_u32_e32 v149, v14, v6
	v_add_u32_e32 v148, v15, v6
	v_mov_b32_e32 v1, v0
	v_mov_b32_e32 v2, v0
	v_mov_b32_e32 v3, v0
	v_mov_b32_e32 v4, v0
	v_mov_b32_e32 v5, v0
	v_mov_b32_e32 v6, v0
	v_mov_b32_e32 v7, v0
	v_mov_b32_e32 v8, v0
	v_mov_b32_e32 v9, v0
	v_mov_b32_e32 v10, v0
	v_mov_b32_e32 v11, v0
	v_mov_b32_e32 v12, v0
	v_mov_b32_e32 v13, v0
	v_mov_b32_e32 v14, v0
	v_mov_b32_e32 v15, v0
	v_mov_b32_e32 v16, v0
	v_mov_b32_e32 v17, v0
	v_mov_b32_e32 v18, v0
	v_mov_b32_e32 v19, v0
	v_mov_b32_e32 v20, v0
	v_mov_b32_e32 v21, v0
	v_mov_b32_e32 v22, v0
	v_mov_b32_e32 v23, v0
	v_mov_b32_e32 v24, v0
	v_mov_b32_e32 v25, v0
	v_mov_b32_e32 v26, v0
	v_mov_b32_e32 v27, v0
	v_mov_b32_e32 v28, v0
	v_mov_b32_e32 v29, v0
	v_mov_b32_e32 v30, v0
	v_mov_b32_e32 v31, v0
	v_mov_b32_e32 v32, v0
	v_mov_b32_e32 v33, v0
	v_mov_b32_e32 v34, v0
	v_mov_b32_e32 v35, v0
	v_mov_b32_e32 v36, v0
	v_mov_b32_e32 v37, v0
	v_mov_b32_e32 v38, v0
	v_mov_b32_e32 v39, v0
	v_mov_b32_e32 v40, v0
	v_mov_b32_e32 v41, v0
	v_mov_b32_e32 v42, v0
	v_mov_b32_e32 v43, v0
	v_mov_b32_e32 v44, v0
	v_mov_b32_e32 v45, v0
	v_mov_b32_e32 v46, v0
	v_mov_b32_e32 v47, v0
	v_mov_b32_e32 v48, v0
	v_mov_b32_e32 v49, v0
	v_mov_b32_e32 v50, v0
	v_mov_b32_e32 v51, v0
	v_mov_b32_e32 v52, v0
	v_mov_b32_e32 v53, v0
	v_mov_b32_e32 v54, v0
	v_mov_b32_e32 v55, v0
	v_mov_b32_e32 v56, v0
	v_mov_b32_e32 v57, v0
	v_mov_b32_e32 v58, v0
	v_mov_b32_e32 v59, v0
	v_mov_b32_e32 v60, v0
	v_mov_b32_e32 v61, v0
	v_mov_b32_e32 v62, v0
	v_mov_b32_e32 v63, v0
	v_mov_b32_e32 v64, v0
	v_mov_b32_e32 v65, v0
	v_mov_b32_e32 v66, v0
	v_mov_b32_e32 v67, v0
	v_mov_b32_e32 v68, v0
	v_mov_b32_e32 v69, v0
	v_mov_b32_e32 v70, v0
	v_mov_b32_e32 v71, v0
	v_mov_b32_e32 v72, v0
	v_mov_b32_e32 v73, v0
	v_mov_b32_e32 v74, v0
	v_mov_b32_e32 v75, v0
	v_mov_b32_e32 v76, v0
	v_mov_b32_e32 v77, v0
	v_mov_b32_e32 v78, v0
	v_mov_b32_e32 v79, v0
	v_mov_b32_e32 v80, v0
	v_mov_b32_e32 v81, v0
	v_mov_b32_e32 v82, v0
	v_mov_b32_e32 v83, v0
	v_mov_b32_e32 v84, v0
	v_mov_b32_e32 v85, v0
	v_mov_b32_e32 v86, v0
	v_mov_b32_e32 v87, v0
	v_mov_b32_e32 v88, v0
	v_mov_b32_e32 v89, v0
	v_mov_b32_e32 v90, v0
	v_mov_b32_e32 v91, v0
	v_mov_b32_e32 v92, v0
	v_mov_b32_e32 v93, v0
	v_mov_b32_e32 v94, v0
	v_mov_b32_e32 v95, v0
	v_mov_b32_e32 v96, v0
	v_mov_b32_e32 v97, v0
	v_mov_b32_e32 v98, v0
	v_mov_b32_e32 v99, v0
	v_mov_b32_e32 v100, v0
	v_mov_b32_e32 v101, v0
	v_mov_b32_e32 v102, v0
	v_mov_b32_e32 v103, v0
	v_mov_b32_e32 v104, v0
	v_mov_b32_e32 v105, v0
	v_mov_b32_e32 v106, v0
	v_mov_b32_e32 v107, v0
	v_mov_b32_e32 v108, v0
	v_mov_b32_e32 v109, v0
	v_mov_b32_e32 v110, v0
	v_mov_b32_e32 v111, v0
	v_mov_b32_e32 v112, v0
	v_mov_b32_e32 v113, v0
	v_mov_b32_e32 v114, v0
	v_mov_b32_e32 v115, v0
	v_mov_b32_e32 v116, v0
	v_mov_b32_e32 v117, v0
	v_mov_b32_e32 v118, v0
	v_mov_b32_e32 v119, v0
	v_mov_b32_e32 v120, v0
	v_mov_b32_e32 v121, v0
	v_mov_b32_e32 v122, v0
	v_mov_b32_e32 v123, v0
	v_mov_b32_e32 v124, v0
	v_mov_b32_e32 v125, v0
	v_mov_b32_e32 v126, v0
	v_mov_b32_e32 v127, v0
	s_mov_b64 s[54:55], 0x1a80080
	s_mov_b64 s[60:61], 0x1a00100
	s_mov_b64 s[72:73], 0x1a80100
	s_mov_b64 s[82:83], 0x1a00180
	s_barrier
; #define P8_STAGE(P,BASE,br,kt) do{const bfr* _ub=(BASE)+((long)(br)*K+(long)(kt)*BK); \
;     __builtin_amdgcn_global_load_lds((const unsigned*)(_ub+so0),(unsigned*)((char*)(P)+wid*1024),16,0,0); \
;     __builtin_amdgcn_global_load_lds((const unsigned*)(_ub+so1),(unsigned*)((char*)(P)+wid*1024+8192),16,0,0);}while(0)
; #define P8_LDA(dst,b,h) _Pragma("unroll") for(int m=0;m<4;++m) _Pragma("unroll") for(int k=0;k<2;++k) \
;     dst[m][k]=*reinterpret_cast<const bf16x8*>((char*)P8_SA(b,h)+lds_byte(wr*64+m*16+fr,k*32+fq*8))
; #define P8_LDB(dst,b,h) _Pragma("unroll") for(int n=0;n<2;++n) _Pragma("unroll") for(int k=0;k<2;++k) \
;     dst[n][k]=*reinterpret_cast<const bf16x8*>((char*)P8_SB(b,h)+lds_byte(wc*32+n*16+fr,k*32+fq*8))
; #define P8_MMA(ai,bj,At,Bt) do{__builtin_amdgcn_s_setprio(1); \
;     _Pragma("unroll") for(int m=0;m<4;++m) _Pragma("unroll") for(int n=0;n<2;++n) _Pragma("unroll") for(int k=0;k<2;++k) \
;       acc[ai][bj][m][n]=__builtin_amdgcn_mfma_f32_16x16x32_bf16(At[m][k],Bt[n][k],acc[ai][bj][m][n],0,0,0); \
;     __builtin_amdgcn_s_setprio(0);}while(0)
; #define P8_WAIT_V(n) asm volatile("s_waitcnt vmcnt(" #n ")":::"memory")
; #define P8_WAIT_L(n) asm volatile("s_waitcnt lgkmcnt(" #n ")":::"memory")
; #define P8_BAR __builtin_amdgcn_s_barrier()
; #define P8_SCHED __builtin_amdgcn_sched_barrier(0)
; template <class EPI>
; DEVI void gemm8_tile(const bfr* __restrict__ A, const bfr* __restrict__ Bt, int K, int brow, int bcol, int nbrow, int nbcol, char* shmc, EPI epi) {
;     ...
;   for(int t=0;t<nt-2;t+=2){
;     P8_LDB(B0,0,0); P8_SCHED; P8_LDA(At,0,0); P8_STAGE(P8_SA(1,1),A,brow+128,t+1);
;     P8_WAIT_L(8); P8_BAR; P8_WAIT_L(0); P8_MMA(0,0,At,B0); P8_BAR; P8_SCHED;
;     P8_LDB(B1,0,1); P8_STAGE(P8_SB(0,0),Bt,bcol,t+2);
;     P8_BAR; P8_WAIT_L(0); P8_MMA(0,1,At,B1); P8_BAR;
;     P8_LDA(At,0,1); P8_STAGE(P8_SA(0,0),A,brow,t+2);
;     P8_BAR; P8_WAIT_L(0); P8_MMA(1,0,At,B0); P8_BAR; P8_SCHED;
;     P8_STAGE(P8_SB(0,1),Bt,bcol+128,t+2);
;     P8_WAIT_V(6); P8_BAR; P8_MMA(1,1,At,B1); P8_BAR;
;     P8_LDB(B0,1,0); P8_SCHED; P8_LDA(At,1,0); P8_STAGE(P8_SA(0,1),A,brow+128,t+2);
;     P8_WAIT_L(8); P8_BAR; P8_WAIT_L(0); P8_MMA(0,0,At,B0); P8_BAR; P8_SCHED;
.LBB0_85:
	ds_read_b128 v[174:177], v157
	ds_read_b128 v[178:181], v157 offset:1024
	ds_read_b128 v[182:185], v157 offset:2048
	ds_read_b128 v[186:189], v157 offset:3072
	v_add_u32_e32 v171, 0xc000, v143
	v_add_u32_e32 v172, 0xe000, v143
	v_add_u32_e32 v158, s54, v140
	s_add_i32 m0, s100, 0xc000
	ds_read_b128 v[160:163], v147
	ds_read_b128 v[190:193], v147 offset:1024
	ds_read_b128 v[196:199], v146
	ds_read_b128 v[200:203], v146 offset:1024
	ds_read_b128 v[204:207], v145
	ds_read_b128 v[208:211], v145 offset:1024
	ds_read_b128 v[212:215], v144
	ds_read_b128 v[216:219], v144 offset:1024
	global_load_lds_dwordx4 v158, s[86:87]
	v_add_u32_e32 v158, s54, v138
	s_add_i32 m0, s100, 0xe000
	s_nop 0
	global_load_lds_dwordx4 v158, s[86:87]
	s_waitcnt lgkmcnt(8)
	s_barrier
	s_waitcnt lgkmcnt(0)
	s_setprio 1
	s_waitcnt lgkmcnt(0)
	v_mfma_f32_16x16x32_bf16 v[124:127], v[160:163], v[174:177], v[124:127]
	v_mfma_f32_16x16x32_bf16 v[120:123], v[160:163], v[182:185], v[120:123]
	v_mfma_f32_16x16x32_bf16 v[116:119], v[196:199], v[174:177], v[116:119]
	v_mfma_f32_16x16x32_bf16 v[112:115], v[196:199], v[182:185], v[112:115]
	v_mfma_f32_16x16x32_bf16 v[108:111], v[204:207], v[174:177], v[108:111]
	v_mfma_f32_16x16x32_bf16 v[104:107], v[204:207], v[182:185], v[104:107]
	v_mfma_f32_16x16x32_bf16 v[100:103], v[212:215], v[174:177], v[100:103]
	v_mfma_f32_16x16x32_bf16 v[96:99], v[212:215], v[182:185], v[96:99]
	v_mfma_f32_16x16x32_bf16 v[124:127], v[190:193], v[178:181], v[124:127]
	v_mfma_f32_16x16x32_bf16 v[120:123], v[190:193], v[186:189], v[120:123]
	v_mfma_f32_16x16x32_bf16 v[116:119], v[200:203], v[178:181], v[116:119]
	v_mfma_f32_16x16x32_bf16 v[112:115], v[200:203], v[186:189], v[112:115]
	v_mfma_f32_16x16x32_bf16 v[108:111], v[208:211], v[178:181], v[108:111]
	v_mfma_f32_16x16x32_bf16 v[104:107], v[208:211], v[186:189], v[104:107]
	v_mfma_f32_16x16x32_bf16 v[100:103], v[216:219], v[178:181], v[100:103]
	v_mfma_f32_16x16x32_bf16 v[96:99], v[216:219], v[186:189], v[96:99]
	s_setprio 0
	s_barrier
	v_add_u32_e32 v158, 0x10000, v143
	v_add_u32_e32 v159, 0x12000, v143
	v_add_u32_e32 v236, s66, v136
	s_add_i32 m0, s100, 0x10000
	ds_read_b128 v[220:223], v155
	ds_read_b128 v[224:227], v155 offset:1024
	ds_read_b128 v[228:231], v155 offset:2048
	ds_read_b128 v[232:235], v155 offset:3072
	global_load_lds_dwordx4 v236, s[86:87]
	v_add_u32_e32 v236, s66, v134
	s_add_i32 m0, s100, 0x12000
	s_nop 0
	global_load_lds_dwordx4 v236, s[86:87]
	s_barrier
	s_waitcnt lgkmcnt(0)
	s_setprio 1
	s_waitcnt lgkmcnt(0)
	v_mfma_f32_16x16x32_bf16 v[92:95], v[160:163], v[220:223], v[92:95]
	v_mfma_f32_16x16x32_bf16 v[88:91], v[160:163], v[228:231], v[88:91]
	v_mfma_f32_16x16x32_bf16 v[84:87], v[196:199], v[220:223], v[84:87]
	v_mfma_f32_16x16x32_bf16 v[80:83], v[196:199], v[228:231], v[80:83]
	v_mfma_f32_16x16x32_bf16 v[76:79], v[204:207], v[220:223], v[76:79]
	v_mfma_f32_16x16x32_bf16 v[72:75], v[204:207], v[228:231], v[72:75]
	v_mfma_f32_16x16x32_bf16 v[68:71], v[212:215], v[220:223], v[68:71]
	v_mfma_f32_16x16x32_bf16 v[64:67], v[212:215], v[228:231], v[64:67]
	v_mfma_f32_16x16x32_bf16 v[92:95], v[190:193], v[224:227], v[92:95]
	v_mfma_f32_16x16x32_bf16 v[88:91], v[190:193], v[232:235], v[88:91]
	v_mfma_f32_16x16x32_bf16 v[84:87], v[200:203], v[224:227], v[84:87]
	v_mfma_f32_16x16x32_bf16 v[80:83], v[200:203], v[232:235], v[80:83]
	v_mfma_f32_16x16x32_bf16 v[76:79], v[208:211], v[224:227], v[76:79]
	v_mfma_f32_16x16x32_bf16 v[72:75], v[208:211], v[232:235], v[72:75]
	v_mfma_f32_16x16x32_bf16 v[68:71], v[216:219], v[224:227], v[68:71]
	v_mfma_f32_16x16x32_bf16 v[64:67], v[216:219], v[232:235], v[64:67]
	s_setprio 0
	v_add_u32_e32 v160, s60, v140
	s_mov_b32 m0, s100
	s_barrier
	ds_read_b128 v[190:193], v147 offset:16384
	ds_read_b128 v[196:199], v147 offset:17408
	ds_read_b128 v[200:203], v146 offset:16384
	ds_read_b128 v[204:207], v146 offset:17408
	ds_read_b128 v[208:211], v145 offset:16384
	ds_read_b128 v[212:215], v145 offset:17408
	ds_read_b128 v[216:219], v144 offset:16384
	ds_read_b128 v[236:239], v144 offset:17408
	global_load_lds_dwordx4 v160, s[86:87]
	v_add_u32_e32 v160, 0x2000, v143
	v_add_u32_e32 v162, s60, v138
	s_add_i32 m0, s100, 0x2000
	s_nop 0
	global_load_lds_dwordx4 v162, s[86:87]
	s_barrier
	s_waitcnt lgkmcnt(0)
	s_setprio 1
	s_waitcnt lgkmcnt(0)
	v_mfma_f32_16x16x32_bf16 v[60:63], v[190:193], v[174:177], v[60:63]
	v_mfma_f32_16x16x32_bf16 v[56:59], v[190:193], v[182:185], v[56:59]
	v_mfma_f32_16x16x32_bf16 v[52:55], v[200:203], v[174:177], v[52:55]
	v_mfma_f32_16x16x32_bf16 v[48:51], v[200:203], v[182:185], v[48:51]
	v_mfma_f32_16x16x32_bf16 v[44:47], v[208:211], v[174:177], v[44:47]
	v_mfma_f32_16x16x32_bf16 v[40:43], v[208:211], v[182:185], v[40:43]
	v_mfma_f32_16x16x32_bf16 v[36:39], v[216:219], v[174:177], v[36:39]
	v_mfma_f32_16x16x32_bf16 v[32:35], v[216:219], v[182:185], v[32:35]
	v_mfma_f32_16x16x32_bf16 v[60:63], v[196:199], v[178:181], v[60:63]
	v_mfma_f32_16x16x32_bf16 v[56:59], v[196:199], v[186:189], v[56:59]
	v_mfma_f32_16x16x32_bf16 v[52:55], v[204:207], v[178:181], v[52:55]
	v_mfma_f32_16x16x32_bf16 v[48:51], v[204:207], v[186:189], v[48:51]
	v_mfma_f32_16x16x32_bf16 v[44:47], v[212:215], v[178:181], v[44:47]
	v_mfma_f32_16x16x32_bf16 v[40:43], v[212:215], v[186:189], v[40:43]
	v_mfma_f32_16x16x32_bf16 v[36:39], v[236:239], v[178:181], v[36:39]
	v_mfma_f32_16x16x32_bf16 v[32:35], v[236:239], v[186:189], v[32:35]
	s_setprio 0
	s_barrier
	v_add_u32_e32 v161, 0x14000, v143
	v_add_u32_e32 v162, s70, v136
	s_add_i32 m0, s100, 0x14000
	v_add_u32_e32 v174, s70, v134
	global_load_lds_dwordx4 v162, s[86:87]
	v_add_u32_e32 v162, 0x16000, v143
	s_nop 0
	s_add_i32 m0, s100, 0x16000
	s_nop 0
	global_load_lds_dwordx4 v174, s[86:87]
	s_waitcnt vmcnt(6)
	s_barrier
; #define P8_STAGE(P,BASE,br,kt) do{const bfr* _ub=(BASE)+((long)(br)*K+(long)(kt)*BK); \
;     __builtin_amdgcn_global_load_lds((const unsigned*)(_ub+so0),(unsigned*)((char*)(P)+wid*1024),16,0,0); \
;     __builtin_amdgcn_global_load_lds((const unsigned*)(_ub+so1),(unsigned*)((char*)(P)+wid*1024+8192),16,0,0);}while(0)
; #define P8_LDA(dst,b,h) _Pragma("unroll") for(int m=0;m<4;++m) _Pragma("unroll") for(int k=0;k<2;++k) \
;     dst[m][k]=*reinterpret_cast<const bf16x8*>((char*)P8_SA(b,h)+lds_byte(wr*64+m*16+fr,k*32+fq*8))
; #define P8_LDB(dst,b,h) _Pragma("unroll") for(int n=0;n<2;++n) _Pragma("unroll") for(int k=0;k<2;++k) \
;     dst[n][k]=*reinterpret_cast<const bf16x8*>((char*)P8_SB(b,h)+lds_byte(wc*32+n*16+fr,k*32+fq*8))
; #define P8_MMA(ai,bj,At,Bt) do{__builtin_amdgcn_s_setprio(1); \
;     _Pragma("unroll") for(int m=0;m<4;++m) _Pragma("unroll") for(int n=0;n<2;++n) _Pragma("unroll") for(int k=0;k<2;++k) \
;       acc[ai][bj][m][n]=__builtin_amdgcn_mfma_f32_16x16x32_bf16(At[m][k],Bt[n][k],acc[ai][bj][m][n],0,0,0); \
;     __builtin_amdgcn_s_setprio(0);}while(0)
; #define P8_WAIT_V(n) asm volatile("s_waitcnt vmcnt(" #n ")":::"memory")
; #define P8_WAIT_L(n) asm volatile("s_waitcnt lgkmcnt(" #n ")":::"memory")
; #define P8_BAR __builtin_amdgcn_s_barrier()
; #define P8_SCHED __builtin_amdgcn_sched_barrier(0)
; template <class EPI>
; DEVI void gemm8_tile(const bfr* __restrict__ A, const bfr* __restrict__ Bt, int K, int brow, int bcol, int nbrow, int nbcol, char* shmc, EPI epi) {
;     ...
;     P8_WAIT_V(6); P8_BAR; P8_MMA(1,1,At,B1); P8_BAR;
;     P8_LDB(B0,1,0); P8_SCHED; P8_LDA(At,1,0); P8_STAGE(P8_SA(0,1),A,brow+128,t+2);
;     P8_WAIT_L(8); P8_BAR; P8_WAIT_L(0); P8_MMA(0,0,At,B0); P8_BAR; P8_SCHED;
;     P8_LDB(B1,1,1); P8_STAGE(P8_SB(1,0),Bt,bcol,t+3);
;     P8_BAR; P8_WAIT_L(0); P8_MMA(0,1,At,B1); P8_BAR;
;     P8_LDA(At,1,1); P8_STAGE(P8_SA(1,0),A,brow,t+3);
;     P8_BAR; P8_WAIT_L(0); P8_MMA(1,0,At,B0); P8_BAR; P8_SCHED;
	s_setprio 1
	v_mfma_f32_16x16x32_bf16 v[28:31], v[190:193], v[220:223], v[28:31]
	v_mfma_f32_16x16x32_bf16 v[24:27], v[190:193], v[228:231], v[24:27]
	v_mfma_f32_16x16x32_bf16 v[20:23], v[200:203], v[220:223], v[20:23]
	v_mfma_f32_16x16x32_bf16 v[16:19], v[200:203], v[228:231], v[16:19]
	v_mfma_f32_16x16x32_bf16 v[12:15], v[208:211], v[220:223], v[12:15]
	v_mfma_f32_16x16x32_bf16 v[8:11], v[208:211], v[228:231], v[8:11]
	v_mfma_f32_16x16x32_bf16 v[4:7], v[216:219], v[220:223], v[4:7]
	v_mfma_f32_16x16x32_bf16 v[0:3], v[216:219], v[228:231], v[0:3]
	v_mfma_f32_16x16x32_bf16 v[28:31], v[196:199], v[224:227], v[28:31]
	v_mfma_f32_16x16x32_bf16 v[24:27], v[196:199], v[232:235], v[24:27]
	v_mfma_f32_16x16x32_bf16 v[20:23], v[204:207], v[224:227], v[20:23]
	v_mfma_f32_16x16x32_bf16 v[16:19], v[204:207], v[232:235], v[16:19]
	v_mfma_f32_16x16x32_bf16 v[12:15], v[212:215], v[224:227], v[12:15]
	v_mfma_f32_16x16x32_bf16 v[8:11], v[212:215], v[232:235], v[8:11]
	v_mfma_f32_16x16x32_bf16 v[4:7], v[236:239], v[224:227], v[4:7]
	v_mfma_f32_16x16x32_bf16 v[0:3], v[236:239], v[232:235], v[0:3]
	s_setprio 0
	s_barrier
	ds_read_b128 v[174:177], v149
	ds_read_b128 v[178:181], v149 offset:1024
	ds_read_b128 v[182:185], v149 offset:2048
	ds_read_b128 v[186:189], v149 offset:3072
	v_add_u32_e32 v163, 0x4000, v143
	v_add_u32_e32 v170, 0x6000, v143
	v_add_u32_e32 v224, s72, v140
	s_add_i32 m0, s100, 0x4000
	ds_read_b128 v[190:193], v147 offset:32768
	ds_read_b128 v[196:199], v147 offset:33792
	ds_read_b128 v[200:203], v146 offset:32768
	ds_read_b128 v[204:207], v146 offset:33792
	ds_read_b128 v[208:211], v145 offset:32768
	ds_read_b128 v[212:215], v145 offset:33792
	ds_read_b128 v[216:219], v144 offset:32768
	ds_read_b128 v[220:223], v144 offset:33792
	global_load_lds_dwordx4 v224, s[86:87]
	v_add_u32_e32 v224, s72, v138
	s_add_i32 m0, s100, 0x6000
	s_nop 0
	global_load_lds_dwordx4 v224, s[86:87]
	s_waitcnt lgkmcnt(8)
	s_barrier
	s_waitcnt lgkmcnt(0)
	s_setprio 1
	s_waitcnt lgkmcnt(0)
	v_mfma_f32_16x16x32_bf16 v[124:127], v[190:193], v[174:177], v[124:127]
	v_mfma_f32_16x16x32_bf16 v[120:123], v[190:193], v[182:185], v[120:123]
	v_mfma_f32_16x16x32_bf16 v[116:119], v[200:203], v[174:177], v[116:119]
	v_mfma_f32_16x16x32_bf16 v[112:115], v[200:203], v[182:185], v[112:115]
	v_mfma_f32_16x16x32_bf16 v[108:111], v[208:211], v[174:177], v[108:111]
	v_mfma_f32_16x16x32_bf16 v[104:107], v[208:211], v[182:185], v[104:107]
	v_mfma_f32_16x16x32_bf16 v[100:103], v[216:219], v[174:177], v[100:103]
	v_mfma_f32_16x16x32_bf16 v[96:99], v[216:219], v[182:185], v[96:99]
	v_mfma_f32_16x16x32_bf16 v[124:127], v[196:199], v[178:181], v[124:127]
	v_mfma_f32_16x16x32_bf16 v[120:123], v[196:199], v[186:189], v[120:123]
	v_mfma_f32_16x16x32_bf16 v[116:119], v[204:207], v[178:181], v[116:119]
	v_mfma_f32_16x16x32_bf16 v[112:115], v[204:207], v[186:189], v[112:115]
	v_mfma_f32_16x16x32_bf16 v[108:111], v[212:215], v[178:181], v[108:111]
	v_mfma_f32_16x16x32_bf16 v[104:107], v[212:215], v[186:189], v[104:107]
	v_mfma_f32_16x16x32_bf16 v[100:103], v[220:223], v[178:181], v[100:103]
	v_mfma_f32_16x16x32_bf16 v[96:99], v[220:223], v[186:189], v[96:99]
	s_setprio 0
	s_barrier
	v_add_u32_e32 v248, s74, v136
	s_add_i32 m0, s100, 0x18000
	ds_read_b128 v[224:227], v148
	ds_read_b128 v[228:231], v148 offset:1024
	ds_read_b128 v[232:235], v148 offset:2048
	ds_read_b128 v[236:239], v148 offset:3072
	global_load_lds_dwordx4 v248, s[86:87]
	v_add_u32_e32 v248, s74, v134
	s_add_i32 m0, s100, 0x1a000
	s_nop 0
	global_load_lds_dwordx4 v248, s[86:87]
	s_barrier
	s_waitcnt lgkmcnt(0)
	s_setprio 1
	s_waitcnt lgkmcnt(0)
	v_mfma_f32_16x16x32_bf16 v[92:95], v[190:193], v[224:227], v[92:95]
	v_mfma_f32_16x16x32_bf16 v[88:91], v[190:193], v[232:235], v[88:91]
	v_mfma_f32_16x16x32_bf16 v[84:87], v[200:203], v[224:227], v[84:87]
	v_mfma_f32_16x16x32_bf16 v[80:83], v[200:203], v[232:235], v[80:83]
	v_mfma_f32_16x16x32_bf16 v[76:79], v[208:211], v[224:227], v[76:79]
	v_mfma_f32_16x16x32_bf16 v[72:75], v[208:211], v[232:235], v[72:75]
	v_mfma_f32_16x16x32_bf16 v[68:71], v[216:219], v[224:227], v[68:71]
	v_mfma_f32_16x16x32_bf16 v[64:67], v[216:219], v[232:235], v[64:67]
	v_mfma_f32_16x16x32_bf16 v[92:95], v[196:199], v[228:231], v[92:95]
	v_mfma_f32_16x16x32_bf16 v[88:91], v[196:199], v[236:239], v[88:91]
	v_mfma_f32_16x16x32_bf16 v[84:87], v[204:207], v[228:231], v[84:87]
	v_mfma_f32_16x16x32_bf16 v[80:83], v[204:207], v[236:239], v[80:83]
	v_mfma_f32_16x16x32_bf16 v[76:79], v[212:215], v[228:231], v[76:79]
	v_mfma_f32_16x16x32_bf16 v[72:75], v[212:215], v[236:239], v[72:75]
	v_mfma_f32_16x16x32_bf16 v[68:71], v[220:223], v[228:231], v[68:71]
	v_mfma_f32_16x16x32_bf16 v[64:67], v[220:223], v[236:239], v[64:67]
	s_setprio 0
	v_add_u32_e32 v240, s82, v140
	s_add_i32 m0, s100, 0x8000
	s_barrier
	ds_read_b128 v[190:193], v147 offset:49152
	ds_read_b128 v[196:199], v147 offset:50176
	ds_read_b128 v[200:203], v146 offset:49152
	ds_read_b128 v[204:207], v146 offset:50176
	ds_read_b128 v[208:211], v145 offset:49152
	ds_read_b128 v[212:215], v145 offset:50176
	ds_read_b128 v[216:219], v144 offset:49152
	ds_read_b128 v[220:223], v144 offset:50176
	global_load_lds_dwordx4 v240, s[86:87]
	v_add_u32_e32 v240, s82, v138
	s_add_i32 m0, s100, 0xa000
	s_nop 0
	global_load_lds_dwordx4 v240, s[86:87]
	s_barrier
; #define P8_STAGE(P,BASE,br,kt) do{const bfr* _ub=(BASE)+((long)(br)*K+(long)(kt)*BK); \
;     __builtin_amdgcn_global_load_lds((const unsigned*)(_ub+so0),(unsigned*)((char*)(P)+wid*1024),16,0,0); \
;     __builtin_amdgcn_global_load_lds((const unsigned*)(_ub+so1),(unsigned*)((char*)(P)+wid*1024+8192),16,0,0);}while(0)
; #define P8_LDA(dst,b,h) _Pragma("unroll") for(int m=0;m<4;++m) _Pragma("unroll") for(int k=0;k<2;++k) \
;     dst[m][k]=*reinterpret_cast<const bf16x8*>((char*)P8_SA(b,h)+lds_byte(wr*64+m*16+fr,k*32+fq*8))
; #define P8_LDB(dst,b,h) _Pragma("unroll") for(int n=0;n<2;++n) _Pragma("unroll") for(int k=0;k<2;++k) \
;     dst[n][k]=*reinterpret_cast<const bf16x8*>((char*)P8_SB(b,h)+lds_byte(wc*32+n*16+fr,k*32+fq*8))
; #define P8_MMA(ai,bj,At,Bt) do{__builtin_amdgcn_s_setprio(1); \
;     _Pragma("unroll") for(int m=0;m<4;++m) _Pragma("unroll") for(int n=0;n<2;++n) _Pragma("unroll") for(int k=0;k<2;++k) \
;       acc[ai][bj][m][n]=__builtin_amdgcn_mfma_f32_16x16x32_bf16(At[m][k],Bt[n][k],acc[ai][bj][m][n],0,0,0); \
;     __builtin_amdgcn_s_setprio(0);}while(0)
; #define P8_WAIT_V(n) asm volatile("s_waitcnt vmcnt(" #n ")":::"memory")
; #define P8_WAIT_L(n) asm volatile("s_waitcnt lgkmcnt(" #n ")":::"memory")
; #define P8_BAR __builtin_amdgcn_s_barrier()
; #define P8_SCHED __builtin_amdgcn_sched_barrier(0)
; template <class EPI>
; DEVI void gemm8_tile(const bfr* __restrict__ A, const bfr* __restrict__ Bt, int K, int brow, int bcol, int nbrow, int nbcol, char* shmc, EPI epi) {
;     ...
;     P8_BAR; P8_WAIT_L(0); P8_MMA(1,0,At,B0); P8_BAR; P8_SCHED;
;     P8_STAGE(P8_SB(1,1),Bt,bcol+128,t+3);
;     P8_WAIT_V(6); P8_BAR; P8_MMA(1,1,At,B1); P8_BAR;
;   }
;   { P8_LDB(B0,0,0); P8_LDA(At,0,0); P8_STAGE(P8_SA(1,1),A,brow+128,nt-1);
;     P8_BAR; P8_WAIT_L(0); P8_MMA(0,0,At,B0); P8_BAR;
;     P8_LDB(B1,0,1); P8_BAR; P8_WAIT_L(0); P8_MMA(0,1,At,B1); P8_BAR;
;     P8_LDA(At,0,1); P8_WAIT_V(4); P8_BAR; P8_WAIT_L(0); P8_MMA(1,0,At,B0); P8_MMA(1,1,At,B1); P8_BAR; }
	s_waitcnt lgkmcnt(0)
	s_setprio 1
	s_waitcnt lgkmcnt(0)
	v_mfma_f32_16x16x32_bf16 v[60:63], v[190:193], v[174:177], v[60:63]
	v_mfma_f32_16x16x32_bf16 v[56:59], v[190:193], v[182:185], v[56:59]
	v_mfma_f32_16x16x32_bf16 v[52:55], v[200:203], v[174:177], v[52:55]
	v_mfma_f32_16x16x32_bf16 v[48:51], v[200:203], v[182:185], v[48:51]
	v_mfma_f32_16x16x32_bf16 v[44:47], v[208:211], v[174:177], v[44:47]
	v_mfma_f32_16x16x32_bf16 v[40:43], v[208:211], v[182:185], v[40:43]
	v_mfma_f32_16x16x32_bf16 v[36:39], v[216:219], v[174:177], v[36:39]
	v_mfma_f32_16x16x32_bf16 v[32:35], v[216:219], v[182:185], v[32:35]
	v_mfma_f32_16x16x32_bf16 v[60:63], v[196:199], v[178:181], v[60:63]
	v_mfma_f32_16x16x32_bf16 v[56:59], v[196:199], v[186:189], v[56:59]
	v_mfma_f32_16x16x32_bf16 v[52:55], v[204:207], v[178:181], v[52:55]
	v_mfma_f32_16x16x32_bf16 v[48:51], v[204:207], v[186:189], v[48:51]
	v_mfma_f32_16x16x32_bf16 v[44:47], v[212:215], v[178:181], v[44:47]
	v_mfma_f32_16x16x32_bf16 v[40:43], v[212:215], v[186:189], v[40:43]
	v_mfma_f32_16x16x32_bf16 v[36:39], v[220:223], v[178:181], v[36:39]
	v_mfma_f32_16x16x32_bf16 v[32:35], v[220:223], v[186:189], v[32:35]
	s_setprio 0
	s_barrier
	v_add_u32_e32 v174, s78, v136
	s_add_i32 m0, s100, 0x1c000
	s_nop 0
	global_load_lds_dwordx4 v174, s[86:87]
	v_add_u32_e32 v174, s78, v134
	s_add_i32 m0, s100, 0x1e000
	s_nop 0
	global_load_lds_dwordx4 v174, s[86:87]
	s_waitcnt vmcnt(6)
	s_barrier
	s_setprio 1
	v_mfma_f32_16x16x32_bf16 v[28:31], v[190:193], v[224:227], v[28:31]
	v_mfma_f32_16x16x32_bf16 v[24:27], v[190:193], v[232:235], v[24:27]
	v_mfma_f32_16x16x32_bf16 v[20:23], v[200:203], v[224:227], v[20:23]
	v_mfma_f32_16x16x32_bf16 v[16:19], v[200:203], v[232:235], v[16:19]
	v_mfma_f32_16x16x32_bf16 v[12:15], v[208:211], v[224:227], v[12:15]
	v_mfma_f32_16x16x32_bf16 v[8:11], v[208:211], v[232:235], v[8:11]
	v_mfma_f32_16x16x32_bf16 v[4:7], v[216:219], v[224:227], v[4:7]
	v_mfma_f32_16x16x32_bf16 v[0:3], v[216:219], v[232:235], v[0:3]
	v_mfma_f32_16x16x32_bf16 v[28:31], v[196:199], v[228:231], v[28:31]
	v_mfma_f32_16x16x32_bf16 v[24:27], v[196:199], v[236:239], v[24:27]
	v_mfma_f32_16x16x32_bf16 v[20:23], v[204:207], v[228:231], v[20:23]
	v_mfma_f32_16x16x32_bf16 v[16:19], v[204:207], v[236:239], v[16:19]
	v_mfma_f32_16x16x32_bf16 v[12:15], v[212:215], v[228:231], v[12:15]
	v_mfma_f32_16x16x32_bf16 v[8:11], v[212:215], v[236:239], v[8:11]
	v_mfma_f32_16x16x32_bf16 v[4:7], v[220:223], v[228:231], v[4:7]
	v_mfma_f32_16x16x32_bf16 v[0:3], v[220:223], v[236:239], v[0:3]
	s_setprio 0
	s_add_i32 s0, s0, 2
	v_lshl_add_u64 v[134:135], v[134:135], 0, s[80:81]
	v_lshl_add_u64 v[136:137], v[136:137], 0, s[80:81]
	v_lshl_add_u64 v[138:139], v[138:139], 0, s[80:81]
	s_cmp_lt_u32 s0, 28
	v_lshl_add_u64 v[140:141], v[140:141], 0, s[80:81]
	s_barrier
	s_cbranch_scc1 .LBB0_85
	s_or_b32 s0, s8, 0x80
	s_ashr_i32 s1, s0, 31
	s_lshl_b64 s[0:1], s[0:1], 12
	s_add_u32 s0, s28, s0
	s_addc_u32 s1, s29, s1
	ds_read_b128 v[134:137], v157
	ds_read_b128 v[138:141], v157 offset:1024
	ds_read_b128 v[150:153], v157 offset:2048
	ds_read_b128 v[174:177], v157 offset:3072
	ds_read_b128 v[178:181], v147
	ds_read_b128 v[182:185], v147 offset:1024
	ds_read_b128 v[186:189], v146
	ds_read_b128 v[190:193], v146 offset:1024
	ds_read_b128 v[196:199], v145
	ds_read_b128 v[200:203], v145 offset:1024
	ds_read_b128 v[204:207], v144
	ds_read_b128 v[208:211], v144 offset:1024
	v_lshl_add_u64 v[156:157], v[166:167], 1, s[0:1]
	s_mov_b64 s[54:55], 0xf80
	v_lshl_add_u64 v[156:157], v[156:157], 0, s[54:55]
	s_add_i32 m0, s100, 0xc000
	v_lshl_add_u64 v[132:133], v[132:133], 1, s[0:1]
	global_load_lds_dwordx4 v[156:157], off
	v_lshl_add_u64 v[132:133], v[132:133], 0, s[54:55]
	s_add_i32 m0, s100, 0xe000
	s_nop 0
	global_load_lds_dwordx4 v[132:133], off
	s_barrier
	s_waitcnt lgkmcnt(0)
	s_setprio 1
	s_waitcnt lgkmcnt(0)
	v_mfma_f32_16x16x32_bf16 v[124:127], v[178:181], v[134:137], v[124:127]
	v_mfma_f32_16x16x32_bf16 v[116:119], v[186:189], v[134:137], v[116:119]
	v_mfma_f32_16x16x32_bf16 v[112:115], v[186:189], v[150:153], v[112:115]
	v_mfma_f32_16x16x32_bf16 v[96:99], v[204:207], v[150:153], v[96:99]
	v_mfma_f32_16x16x32_bf16 v[124:127], v[182:185], v[138:141], v[124:127]
	v_mfma_f32_16x16x32_bf16 v[120:123], v[178:181], v[150:153], v[120:123]
	v_mfma_f32_16x16x32_bf16 v[116:119], v[190:193], v[138:141], v[116:119]
	v_mfma_f32_16x16x32_bf16 v[112:115], v[190:193], v[174:177], v[112:115]
	v_mfma_f32_16x16x32_bf16 v[108:111], v[196:199], v[134:137], v[108:111]
	v_mfma_f32_16x16x32_bf16 v[104:107], v[196:199], v[150:153], v[104:107]
	v_mfma_f32_16x16x32_bf16 v[100:103], v[204:207], v[134:137], v[100:103]
	v_mfma_f32_16x16x32_bf16 v[96:99], v[208:211], v[174:177], v[96:99]
	v_mfma_f32_16x16x32_bf16 v[212:215], v[182:185], v[174:177], v[120:123]
	v_mfma_f32_16x16x32_bf16 v[216:219], v[200:203], v[138:141], v[108:111]
	v_mfma_f32_16x16x32_bf16 v[220:223], v[200:203], v[174:177], v[104:107]
	v_mfma_f32_16x16x32_bf16 v[224:227], v[208:211], v[138:141], v[100:103]
	s_setprio 0
	s_barrier
	s_nop 0
	ds_read_b128 v[100:103], v155
	ds_read_b128 v[104:107], v155 offset:1024
	ds_read_b128 v[108:111], v155 offset:2048
	ds_read_b128 v[120:123], v155 offset:3072
	s_barrier
; #define P8_LDA(dst,b,h) _Pragma("unroll") for(int m=0;m<4;++m) _Pragma("unroll") for(int k=0;k<2;++k) \
;     dst[m][k]=*reinterpret_cast<const bf16x8*>((char*)P8_SA(b,h)+lds_byte(wr*64+m*16+fr,k*32+fq*8))
; #define P8_LDB(dst,b,h) _Pragma("unroll") for(int n=0;n<2;++n) _Pragma("unroll") for(int k=0;k<2;++k) \
;     dst[n][k]=*reinterpret_cast<const bf16x8*>((char*)P8_SB(b,h)+lds_byte(wc*32+n*16+fr,k*32+fq*8))
; #define P8_MMA(ai,bj,At,Bt) do{__builtin_amdgcn_s_setprio(1); \
;     _Pragma("unroll") for(int m=0;m<4;++m) _Pragma("unroll") for(int n=0;n<2;++n) _Pragma("unroll") for(int k=0;k<2;++k) \
;       acc[ai][bj][m][n]=__builtin_amdgcn_mfma_f32_16x16x32_bf16(At[m][k],Bt[n][k],acc[ai][bj][m][n],0,0,0); \
;     __builtin_amdgcn_s_setprio(0);}while(0)
; #define P8_WAIT_V(n) asm volatile("s_waitcnt vmcnt(" #n ")":::"memory")
; #define P8_WAIT_L(n) asm volatile("s_waitcnt lgkmcnt(" #n ")":::"memory")
; #define P8_BAR __builtin_amdgcn_s_barrier()
; template <class EPI>
; DEVI void gemm8_tile(const bfr* __restrict__ A, const bfr* __restrict__ Bt, int K, int brow, int bcol, int nbrow, int nbcol, char* shmc, EPI epi) {
;     ...
;     P8_LDA(At,0,1); P8_WAIT_V(4); P8_BAR; P8_WAIT_L(0); P8_MMA(1,0,At,B0); P8_MMA(1,1,At,B1); P8_BAR; }
;   { P8_LDB(B0,1,0); P8_LDA(At,1,0); P8_WAIT_V(2); P8_BAR; P8_WAIT_L(0); P8_MMA(0,0,At,B0); P8_BAR;
;     P8_LDB(B1,1,1); P8_WAIT_V(0); P8_BAR; P8_WAIT_L(0); P8_MMA(0,1,At,B1); P8_BAR;
;     P8_LDA(At,1,1); P8_BAR; P8_WAIT_L(0); P8_MMA(1,0,At,B0); P8_MMA(1,1,At,B1); P8_BAR; }
	s_waitcnt lgkmcnt(0)
	s_setprio 1
	s_waitcnt lgkmcnt(0)
	v_mfma_f32_16x16x32_bf16 v[92:95], v[178:181], v[100:103], v[92:95]
	v_mfma_f32_16x16x32_bf16 v[84:87], v[186:189], v[100:103], v[84:87]
	v_mfma_f32_16x16x32_bf16 v[80:83], v[186:189], v[108:111], v[80:83]
	v_mfma_f32_16x16x32_bf16 v[64:67], v[204:207], v[108:111], v[64:67]
	v_mfma_f32_16x16x32_bf16 v[92:95], v[182:185], v[104:107], v[92:95]
	v_mfma_f32_16x16x32_bf16 v[88:91], v[178:181], v[108:111], v[88:91]
	v_mfma_f32_16x16x32_bf16 v[84:87], v[190:193], v[104:107], v[84:87]
	v_mfma_f32_16x16x32_bf16 v[80:83], v[190:193], v[120:123], v[80:83]
	v_mfma_f32_16x16x32_bf16 v[76:79], v[196:199], v[100:103], v[76:79]
	v_mfma_f32_16x16x32_bf16 v[72:75], v[196:199], v[108:111], v[72:75]
	v_mfma_f32_16x16x32_bf16 v[68:71], v[204:207], v[100:103], v[68:71]
	v_mfma_f32_16x16x32_bf16 v[64:67], v[208:211], v[120:123], v[64:67]
	v_mfma_f32_16x16x32_bf16 v[154:157], v[182:185], v[120:123], v[88:91]
	v_mfma_f32_16x16x32_bf16 v[178:181], v[200:203], v[104:107], v[76:79]
	v_mfma_f32_16x16x32_bf16 v[182:185], v[200:203], v[120:123], v[72:75]
	v_mfma_f32_16x16x32_bf16 v[186:189], v[208:211], v[104:107], v[68:71]
	s_setprio 0
	s_barrier
	s_nop 0
	ds_read_b128 v[68:71], v147 offset:16384
	ds_read_b128 v[72:75], v147 offset:17408
	ds_read_b128 v[76:79], v146 offset:16384
	ds_read_b128 v[88:91], v146 offset:17408
	ds_read_b128 v[190:193], v145 offset:16384
	ds_read_b128 v[196:199], v145 offset:17408
	ds_read_b128 v[200:203], v144 offset:16384
	ds_read_b128 v[204:207], v144 offset:17408
	s_waitcnt vmcnt(4)
	s_barrier
	s_waitcnt lgkmcnt(0)
	s_setprio 1
	s_waitcnt lgkmcnt(0)
	v_mfma_f32_16x16x32_bf16 v[60:63], v[68:71], v[134:137], v[60:63]
	v_mfma_f32_16x16x32_bf16 v[52:55], v[76:79], v[134:137], v[52:55]
	v_mfma_f32_16x16x32_bf16 v[48:51], v[76:79], v[150:153], v[48:51]
	v_mfma_f32_16x16x32_bf16 v[32:35], v[200:203], v[150:153], v[32:35]
	v_mfma_f32_16x16x32_bf16 v[60:63], v[72:75], v[138:141], v[60:63]
	v_mfma_f32_16x16x32_bf16 v[56:59], v[68:71], v[150:153], v[56:59]
	v_mfma_f32_16x16x32_bf16 v[52:55], v[88:91], v[138:141], v[52:55]
	v_mfma_f32_16x16x32_bf16 v[48:51], v[88:91], v[174:177], v[48:51]
	v_mfma_f32_16x16x32_bf16 v[44:47], v[190:193], v[134:137], v[44:47]
	v_mfma_f32_16x16x32_bf16 v[40:43], v[190:193], v[150:153], v[40:43]
	v_mfma_f32_16x16x32_bf16 v[36:39], v[200:203], v[134:137], v[36:39]
	v_mfma_f32_16x16x32_bf16 v[32:35], v[204:207], v[174:177], v[32:35]
	v_mfma_f32_16x16x32_bf16 v[208:211], v[72:75], v[174:177], v[56:59]
	v_mfma_f32_16x16x32_bf16 v[228:231], v[196:199], v[138:141], v[44:47]
	v_mfma_f32_16x16x32_bf16 v[232:235], v[196:199], v[174:177], v[40:43]
	v_mfma_f32_16x16x32_bf16 v[132:135], v[204:207], v[138:141], v[36:39]
	s_setprio 0
	s_setprio 1
	v_mfma_f32_16x16x32_bf16 v[28:31], v[68:71], v[100:103], v[28:31]
	v_mfma_f32_16x16x32_bf16 v[20:23], v[76:79], v[100:103], v[20:23]
	v_mfma_f32_16x16x32_bf16 v[16:19], v[76:79], v[108:111], v[16:19]
	v_mfma_f32_16x16x32_bf16 v[0:3], v[200:203], v[108:111], v[0:3]
	v_mfma_f32_16x16x32_bf16 v[28:31], v[72:75], v[104:107], v[28:31]
	v_mfma_f32_16x16x32_bf16 v[24:27], v[68:71], v[108:111], v[24:27]
	v_mfma_f32_16x16x32_bf16 v[20:23], v[88:91], v[104:107], v[20:23]
	v_mfma_f32_16x16x32_bf16 v[16:19], v[88:91], v[120:123], v[16:19]
	v_mfma_f32_16x16x32_bf16 v[12:15], v[190:193], v[100:103], v[12:15]
	v_mfma_f32_16x16x32_bf16 v[8:11], v[190:193], v[108:111], v[8:11]
	v_mfma_f32_16x16x32_bf16 v[4:7], v[200:203], v[100:103], v[4:7]
	v_mfma_f32_16x16x32_bf16 v[0:3], v[204:207], v[120:123], v[0:3]
	v_mfma_f32_16x16x32_bf16 v[136:139], v[72:75], v[120:123], v[24:27]
	v_mfma_f32_16x16x32_bf16 v[150:153], v[196:199], v[104:107], v[12:15]
	v_mfma_f32_16x16x32_bf16 v[172:175], v[196:199], v[120:123], v[8:11]
	v_mfma_f32_16x16x32_bf16 v[190:193], v[204:207], v[104:107], v[4:7]
	s_setprio 0
	s_barrier
	s_nop 0
	ds_read_b128 v[4:7], v149
	ds_read_b128 v[8:11], v149 offset:1024
	ds_read_b128 v[12:15], v149 offset:2048
	ds_read_b128 v[24:27], v149 offset:3072
	ds_read_b128 v[36:39], v147 offset:32768
	ds_read_b128 v[40:43], v147 offset:33792
	ds_read_b128 v[44:47], v146 offset:32768
	ds_read_b128 v[56:59], v146 offset:33792
	ds_read_b128 v[68:71], v145 offset:32768
	ds_read_b128 v[196:199], v145 offset:33792
	ds_read_b128 v[200:203], v144 offset:32768
	ds_read_b128 v[204:207], v144 offset:33792
	s_waitcnt vmcnt(2)
	s_barrier
	s_waitcnt lgkmcnt(0)
	s_setprio 1
	s_waitcnt lgkmcnt(0)
	v_mfma_f32_16x16x32_bf16 v[72:75], v[36:39], v[4:7], v[124:127]
	v_mfma_f32_16x16x32_bf16 v[120:123], v[40:43], v[8:11], v[72:75]
	v_mfma_f32_16x16x32_bf16 v[72:75], v[36:39], v[12:15], v[212:215]
	v_mfma_f32_16x16x32_bf16 v[104:107], v[40:43], v[24:27], v[72:75]
	v_mfma_f32_16x16x32_bf16 v[72:75], v[44:47], v[4:7], v[116:119]
	v_mfma_f32_16x16x32_bf16 v[124:127], v[56:59], v[8:11], v[72:75]
	v_mfma_f32_16x16x32_bf16 v[72:75], v[44:47], v[12:15], v[112:115]
	v_mfma_f32_16x16x32_bf16 v[108:111], v[56:59], v[24:27], v[72:75]
	v_mfma_f32_16x16x32_bf16 v[72:75], v[68:71], v[4:7], v[216:219]
	v_mfma_f32_16x16x32_bf16 v[112:115], v[196:199], v[8:11], v[72:75]
	v_mfma_f32_16x16x32_bf16 v[72:75], v[68:71], v[12:15], v[220:223]
	v_mfma_f32_16x16x32_bf16 v[100:103], v[196:199], v[24:27], v[72:75]
	v_mfma_f32_16x16x32_bf16 v[72:75], v[200:203], v[4:7], v[224:227]
	v_mfma_f32_16x16x32_bf16 v[116:119], v[204:207], v[8:11], v[72:75]
	v_mfma_f32_16x16x32_bf16 v[72:75], v[200:203], v[12:15], v[96:99]
	v_mfma_f32_16x16x32_bf16 v[96:99], v[204:207], v[24:27], v[72:75]
	s_setprio 0
	s_barrier
	ds_read_b128 v[212:215], v148
	ds_read_b128 v[216:219], v148 offset:1024
	ds_read_b128 v[220:223], v148 offset:2048
	ds_read_b128 v[224:227], v148 offset:3072
	s_waitcnt vmcnt(0)
	s_barrier
; #define P8_STAGE(P,BASE,br,kt) do{const bfr* _ub=(BASE)+((long)(br)*K+(long)(kt)*BK); \
;     __builtin_amdgcn_global_load_lds((const unsigned*)(_ub+so0),(unsigned*)((char*)(P)+wid*1024),16,0,0); \
;     __builtin_amdgcn_global_load_lds((const unsigned*)(_ub+so1),(unsigned*)((char*)(P)+wid*1024+8192),16,0,0);}while(0)
; #define P8_LDA(dst,b,h) _Pragma("unroll") for(int m=0;m<4;++m) _Pragma("unroll") for(int k=0;k<2;++k) \
;     dst[m][k]=*reinterpret_cast<const bf16x8*>((char*)P8_SA(b,h)+lds_byte(wr*64+m*16+fr,k*32+fq*8))
; #define P8_LDB(dst,b,h) _Pragma("unroll") for(int n=0;n<2;++n) _Pragma("unroll") for(int k=0;k<2;++k) \
;     dst[n][k]=*reinterpret_cast<const bf16x8*>((char*)P8_SB(b,h)+lds_byte(wc*32+n*16+fr,k*32+fq*8))
; #define P8_MMA(ai,bj,At,Bt) do{__builtin_amdgcn_s_setprio(1); \
;     _Pragma("unroll") for(int m=0;m<4;++m) _Pragma("unroll") for(int n=0;n<2;++n) _Pragma("unroll") for(int k=0;k<2;++k) \
;       acc[ai][bj][m][n]=__builtin_amdgcn_mfma_f32_16x16x32_bf16(At[m][k],Bt[n][k],acc[ai][bj][m][n],0,0,0); \
;     __builtin_amdgcn_s_setprio(0);}while(0)
; #define P8_WAIT_V(n) asm volatile("s_waitcnt vmcnt(" #n ")":::"memory")
; #define P8_WAIT_L(n) asm volatile("s_waitcnt lgkmcnt(" #n ")":::"memory")
; #define P8_BAR __builtin_amdgcn_s_barrier()
; template <class EPI>
; DEVI void gemm8_tile(const bfr* __restrict__ A, const bfr* __restrict__ Bt, int K, int brow, int bcol, int nbrow, int nbcol, char* shmc, EPI epi) {
;     ...
;   { P8_LDB(B0,1,0); P8_LDA(At,1,0); P8_WAIT_V(2); P8_BAR; P8_WAIT_L(0); P8_MMA(0,0,At,B0); P8_BAR;
;     P8_LDB(B1,1,1); P8_WAIT_V(0); P8_BAR; P8_WAIT_L(0); P8_MMA(0,1,At,B1); P8_BAR;
;     P8_LDA(At,1,1); P8_BAR; P8_WAIT_L(0); P8_MMA(1,0,At,B0); P8_MMA(1,1,At,B1); P8_BAR; }
;   if(wr==0)P8_BAR;
;   if (nbrow >= 0) {
;     P8_STAGE(P8_SB(0,0),Bt,nbcol,0); P8_STAGE(P8_SA(0,0),A,nbrow,0);
;     P8_STAGE(P8_SB(0,1),Bt,nbcol+128,0); P8_STAGE(P8_SA(0,1),A,nbrow+128,0);
;   }
	s_waitcnt lgkmcnt(0)
	s_setprio 1
	s_waitcnt lgkmcnt(0)
	v_mfma_f32_16x16x32_bf16 v[72:75], v[36:39], v[212:215], v[92:95]
	v_mfma_f32_16x16x32_bf16 v[36:39], v[36:39], v[220:223], v[154:157]
	v_mfma_f32_16x16x32_bf16 v[88:91], v[40:43], v[216:219], v[72:75]
	v_mfma_f32_16x16x32_bf16 v[72:75], v[40:43], v[224:227], v[36:39]
	v_mfma_f32_16x16x32_bf16 v[36:39], v[44:47], v[212:215], v[84:87]
	v_mfma_f32_16x16x32_bf16 v[92:95], v[56:59], v[216:219], v[36:39]
	v_mfma_f32_16x16x32_bf16 v[36:39], v[44:47], v[220:223], v[80:83]
	v_mfma_f32_16x16x32_bf16 v[76:79], v[56:59], v[224:227], v[36:39]
	v_mfma_f32_16x16x32_bf16 v[36:39], v[68:71], v[212:215], v[178:181]
	v_mfma_f32_16x16x32_bf16 v[80:83], v[196:199], v[216:219], v[36:39]
	v_mfma_f32_16x16x32_bf16 v[36:39], v[68:71], v[220:223], v[182:185]
	v_mfma_f32_16x16x32_bf16 v[68:71], v[196:199], v[224:227], v[36:39]
	v_mfma_f32_16x16x32_bf16 v[36:39], v[200:203], v[212:215], v[186:189]
	v_mfma_f32_16x16x32_bf16 v[84:87], v[204:207], v[216:219], v[36:39]
	v_mfma_f32_16x16x32_bf16 v[36:39], v[200:203], v[220:223], v[64:67]
	v_mfma_f32_16x16x32_bf16 v[64:67], v[204:207], v[224:227], v[36:39]
	s_setprio 0
	s_barrier
	ds_read_b128 v[154:157], v147 offset:49152
	ds_read_b128 v[176:179], v147 offset:50176
	ds_read_b128 v[180:183], v146 offset:49152
	ds_read_b128 v[146:149], v146 offset:50176
	ds_read_b128 v[184:187], v145 offset:49152
	ds_read_b128 v[196:199], v145 offset:50176
	ds_read_b128 v[200:203], v144 offset:49152
	ds_read_b128 v[204:207], v144 offset:50176
	s_barrier
	s_waitcnt lgkmcnt(0)
	s_setprio 1
	s_waitcnt lgkmcnt(0)
	v_mfma_f32_16x16x32_bf16 v[36:39], v[154:157], v[4:7], v[60:63]
	v_mfma_f32_16x16x32_bf16 v[56:59], v[176:179], v[8:11], v[36:39]
	v_mfma_f32_16x16x32_bf16 v[36:39], v[154:157], v[12:15], v[208:211]
	v_mfma_f32_16x16x32_bf16 v[40:43], v[176:179], v[24:27], v[36:39]
	v_mfma_f32_16x16x32_bf16 v[36:39], v[180:183], v[4:7], v[52:55]
	v_mfma_f32_16x16x32_bf16 v[60:63], v[146:149], v[8:11], v[36:39]
	v_mfma_f32_16x16x32_bf16 v[36:39], v[180:183], v[12:15], v[48:51]
	v_mfma_f32_16x16x32_bf16 v[44:47], v[146:149], v[24:27], v[36:39]
	v_mfma_f32_16x16x32_bf16 v[36:39], v[184:187], v[4:7], v[228:231]
	v_mfma_f32_16x16x32_bf16 v[4:7], v[200:203], v[4:7], v[132:135]
	v_mfma_f32_16x16x32_bf16 v[48:51], v[196:199], v[8:11], v[36:39]
	v_mfma_f32_16x16x32_bf16 v[36:39], v[184:187], v[12:15], v[232:235]
	v_mfma_f32_16x16x32_bf16 v[52:55], v[204:207], v[8:11], v[4:7]
	v_mfma_f32_16x16x32_bf16 v[4:7], v[200:203], v[12:15], v[32:35]
	v_mfma_f32_16x16x32_bf16 v[36:39], v[196:199], v[24:27], v[36:39]
	v_mfma_f32_16x16x32_bf16 v[32:35], v[204:207], v[24:27], v[4:7]
	s_setprio 0
	s_setprio 1
	v_mfma_f32_16x16x32_bf16 v[4:7], v[154:157], v[212:215], v[28:31]
	v_mfma_f32_16x16x32_bf16 v[24:27], v[176:179], v[216:219], v[4:7]
	v_mfma_f32_16x16x32_bf16 v[4:7], v[154:157], v[220:223], v[136:139]
	v_mfma_f32_16x16x32_bf16 v[8:11], v[176:179], v[224:227], v[4:7]
	v_mfma_f32_16x16x32_bf16 v[4:7], v[180:183], v[212:215], v[20:23]
	v_mfma_f32_16x16x32_bf16 v[28:31], v[146:149], v[216:219], v[4:7]
	v_mfma_f32_16x16x32_bf16 v[4:7], v[180:183], v[220:223], v[16:19]
	v_mfma_f32_16x16x32_bf16 v[12:15], v[146:149], v[224:227], v[4:7]
	v_mfma_f32_16x16x32_bf16 v[4:7], v[184:187], v[212:215], v[150:153]
	v_mfma_f32_16x16x32_bf16 v[16:19], v[196:199], v[216:219], v[4:7]
	v_mfma_f32_16x16x32_bf16 v[4:7], v[184:187], v[220:223], v[172:175]
	v_mfma_f32_16x16x32_bf16 v[20:23], v[200:203], v[212:215], v[190:193]
	v_mfma_f32_16x16x32_bf16 v[0:3], v[200:203], v[220:223], v[0:3]
	v_mfma_f32_16x16x32_bf16 v[4:7], v[196:199], v[224:227], v[4:7]
	v_mfma_f32_16x16x32_bf16 v[20:23], v[204:207], v[216:219], v[20:23]
	v_mfma_f32_16x16x32_bf16 v[0:3], v[204:207], v[224:227], v[0:3]
	s_setprio 0
	v_cmp_gt_u32_e32 vcc, s57, v142
	s_barrier
	s_and_saveexec_b64 s[0:1], vcc
	s_cbranch_execz .LBB0_88
	s_barrier
.LBB0_88:
	s_or_b64 exec, exec, s[0:1]
	s_lshl_b32 s2, s65, 8
	s_and_b64 s[0:1], s[34:35], exec
	s_cselect_b32 s58, s2, -1
	s_cmp_lt_i32 s58, 0
	s_cbranch_scc1 .LBB0_77
	s_lshl_b32 s0, s68, 8
	s_ashr_i32 s1, s0, 31
	s_lshl_b64 s[34:35], s[0:1], 12
	s_add_u32 s34, s84, s34
	s_addc_u32 s35, s85, s35
	v_lshl_add_u64 v[132:133], s[34:35], 0, v[128:129]
	s_add_i32 m0, s100, 0x10000
	v_readfirstlane_b32 s1, v159
	global_load_lds_dwordx4 v[132:133], off
	v_lshl_add_u64 v[132:133], s[34:35], 0, v[130:131]
	s_lshl_b64 s[34:35], s[58:59], 12
	s_add_u32 s34, s28, s34
	s_mov_b32 m0, s1
	s_addc_u32 s35, s29, s35
	global_load_lds_dwordx4 v[132:133], off
	v_lshl_add_u64 v[132:133], s[34:35], 0, v[128:129]
	s_mov_b32 m0, s100
	s_bitset1_b32 s0, 7
	global_load_lds_dwordx4 v[132:133], off
	s_add_i32 m0, s100, 0x2000
	s_ashr_i32 s1, s0, 31
	s_lshl_b64 s[0:1], s[0:1], 12
	s_add_u32 s0, s84, s0
	v_lshl_add_u64 v[132:133], s[34:35], 0, v[130:131]
	s_addc_u32 s1, s85, s1
	global_load_lds_dwordx4 v[132:133], off
	v_lshl_add_u64 v[132:133], s[0:1], 0, v[128:129]
	s_add_i32 m0, s100, 0x14000
	s_addk_i32 s58, 0x80
	global_load_lds_dwordx4 v[132:133], off
	v_lshl_add_u64 v[132:133], s[0:1], 0, v[130:131]
	s_add_i32 m0, s100, 0x16000
	s_lshl_b64 s[0:1], s[58:59], 12
	s_add_u32 s0, s28, s0
	s_addc_u32 s1, s29, s1
	v_readfirstlane_b32 s2, v163
	global_load_lds_dwordx4 v[132:133], off
	v_lshl_add_u64 v[128:129], s[0:1], 0, v[128:129]
	s_mov_b32 m0, s2
	s_nop 0
	global_load_lds_dwordx4 v[128:129], off
	v_lshl_add_u64 v[128:129], s[0:1], 0, v[130:131]
	v_readfirstlane_b32 s0, v170
	s_mov_b32 m0, s0
	s_nop 0
	global_load_lds_dwordx4 v[128:129], off
	s_branch .LBB0_77

; DEVI int otid() { int t = threadIdx.x; asm volatile("" : "+v"(t)); return t; }
; DEVI int v_st(int k, int c) { const int kk = (k & ~0xC) | ((k & 4) << 1) | ((k & 8) >> 1); return ((kk >> 3) * 4 + (c >> 5)) * 512 + ((kk & 7) * 32 + (c & 31)) * 2; }
; DEVI int v_rd_base(int lane) { return ((lane & 3) << 3) | (((lane >> 2) & 3) << 6) | (((lane >> 4) & 1) << 5) | (((lane >> 5) & 1) << 8); }
; template <bool FIX>
; DEVI void attn_item(const bfr* __restrict__ Qb, const bfr* __restrict__ Kh, const bfr* __restrict__ Vh, bfr* __restrict__ Ob, int seq, char* lds, float negBC) {
;   const int tid = otid(), wid = tid >> 6, lane = tid & 63, r32 = lane & 31, hi = lane >> 5;
;   char* V_lds = lds; char* K_lds = lds + 2 * SHM_V;
;   float* ws = (float*)(lds + 2 * SHM_V + 2 * SHM_K) + wid * 64; float* li_l = ws; float* al_l = ws + 32;
;   float m_reg = -1e30f, l_reg = 0; f32x16 o[4] = {}; bf16x8 qr[12];
;   const bfr* Qw = Qb + (long)(wid * QBLK + r32) * LDQ + hi * 8;
; #pragma unroll
;   for (int d0 = 0; d0 < 12; ++d0) qr[d0] = *reinterpret_cast<const bf16x8*>(Qw + d0 * 16);
;   const int sr = tid >> 4, sc = (tid & 15) * 8, vst0 = v_st(sr, sc), vst1 = v_st(32 + sr, sc);
;   const int kr = tid >> 3, kc = 128 + (tid & 7) * 8;
;   const int vb0 = (int)(uintptr_t)V_lds + v_rd_base(lane);
;   struct { bf16x8 vs0, vs1, ks0, ks1, ks2; } sr_[1];
;     ...
;   f32x16 pA0, pA1; float mnA, alA; bf16x8 pa0, pa1, pa2, pa3; const int NT = seq / KVBLK;
;   SLOAD(0, 0); asm volatile("s_waitcnt vmcnt(0)" ::: "memory"); SWRITE(0, 0); SLOAD(0, KVBLK); __syncthreads();
.LBB0_118:
	s_and_b64 vcc, exec, s[0:1]
	s_cbranch_vccz .LBB0_95
	v_mov_b32_e32 v184, v164
	s_movk_i32 s0, 0xffe0
	v_ashrrev_i32_e32 v0, 1, v184
	v_bfe_u32 v183, v184, 5, 1
	v_and_b32_e32 v170, 0xffffffe0, v0
	v_bfi_b32 v2, s0, v0, v184
	v_mov_b64_e32 v[0:1], s[8:9]
	s_movk_i32 s2, 0x1800
	v_mad_i64_i32 v[0:1], s[0:1], v2, s2, v[0:1]
	v_lshlrev_b32_e32 v166, 4, v183
	v_lshl_add_u64 v[0:1], v[0:1], 0, v[166:167]
	global_load_dwordx4 v[140:143], v[0:1], off
	global_load_dwordx4 v[136:139], v[0:1], off offset:32
	global_load_dwordx4 v[132:135], v[0:1], off offset:64
	global_load_dwordx4 v[128:131], v[0:1], off offset:96
	global_load_dwordx4 v[124:127], v[0:1], off offset:128
	global_load_dwordx4 v[120:123], v[0:1], off offset:160
	global_load_dwordx4 v[116:119], v[0:1], off offset:192
	global_load_dwordx4 v[112:115], v[0:1], off offset:224
	global_load_dwordx4 v[108:111], v[0:1], off offset:256
	global_load_dwordx4 v[104:107], v[0:1], off offset:288
	global_load_dwordx4 v[100:103], v[0:1], off offset:320
	global_load_dwordx4 v[96:99], v[0:1], off offset:352
	v_ashrrev_i32_e32 v0, 4, v184
	v_and_b32_e32 v2, 0xfffff0, v0
	v_lshlrev_b32_e32 v3, 1, v0
	v_lshlrev_b32_e32 v28, 3, v184
	v_and_or_b32 v2, v3, 8, v2
	v_lshrrev_b32_e32 v2, 1, v2
	v_bfe_u32 v4, v28, 5, 2
	v_or_b32_e32 v2, v2, v4
	v_lshrrev_b32_e32 v3, 1, v0
	v_lshlrev_b32_e32 v5, 9, v2
	v_and_b32_e32 v2, 3, v0
	v_and_b32_e32 v1, 0x78, v28
	v_and_or_b32 v2, v3, 4, v2
	v_lshlrev_b32_e32 v3, 6, v2
	v_lshlrev_b32_e32 v2, 1, v1
	v_and_b32_e32 v1, 48, v2
	v_add_u32_e32 v20, 32, v0
	v_or3_b32 v185, v5, v3, v1
	v_and_b32_e32 v5, 0xfffff0, v20
	v_lshlrev_b32_e32 v6, 1, v20
	v_and_or_b32 v5, v6, 8, v5
	v_lshrrev_b32_e32 v5, 1, v5
	v_or_b32_e32 v4, v5, v4
	v_lshlrev_b32_e32 v4, 9, v4
	v_or3_b32 v186, v4, v3, v1
	v_ashrrev_i32_e32 v1, 31, v0
	v_lshlrev_b64 v[6:7], 12, v[0:1]
	v_lshl_add_u64 v[6:7], s[82:83], 0, v[6:7]
	v_mov_b32_e32 v3, v167
	v_lshl_add_u64 v[6:7], v[6:7], 0, v[2:3]
	v_ashrrev_i32_e32 v21, 31, v20
	global_load_dwordx4 v[8:11], v[6:7], off
	v_lshlrev_b64 v[6:7], 12, v[20:21]
	v_lshl_add_u64 v[6:7], s[82:83], 0, v[6:7]
	v_lshl_add_u64 v[6:7], v[6:7], 0, v[2:3]
	v_ashrrev_i32_e32 v29, 3, v184
	v_lshlrev_b32_e32 v30, 4, v184
	global_load_dwordx4 v[12:15], v[6:7], off
	v_mov_b64_e32 v[6:7], s[34:35]
	v_and_b32_e32 v4, 0x70, v30
	v_mad_i64_i32 v[16:17], s[0:1], v0, s2, v[6:7]
	v_mad_i64_i32 v[24:25], s[0:1], v29, s2, v[6:7]
	v_mov_b32_e32 v5, v167
	v_lshl_add_u64 v[16:17], v[16:17], 0, v[2:3]
	v_mad_i64_i32 v[20:21], s[0:1], v20, s2, v[6:7]
	v_lshl_add_u64 v[24:25], v[24:25], 0, v[4:5]
	global_load_dwordx4 v[16:19], v[16:17], off
	v_lshl_add_u64 v[20:21], v[20:21], 0, v[2:3]
	global_load_dwordx4 v[24:27], v[24:25], off offset:256
	s_movk_i32 s4, 0x190
	global_load_dwordx4 v[20:23], v[20:21], off
	s_waitcnt vmcnt(0)
	v_mad_u64_u32 v[172:173], s[0:1], v0, s4, v[2:3]
	v_add_u32_e32 v1, 64, v29
	v_and_b32_e32 v182, 31, v184
	v_mov_b32_e32 v173, 0
	v_and_b32_e32 v171, 63, v184
	v_lshl_add_u32 v174, v0, 12, v2
	v_add_u32_e32 v175, 0x20000, v174
	v_mad_u32_u24 v176, v0, s2, v2
	v_add_u32_e32 v177, 0x30000, v176
	v_mad_u32_u24 v178, v29, s2, v4
	v_mul_u32_u24_e32 v189, 0x190, v182
	v_mov_b32_e32 v31, v173
	v_mov_b32_e32 v32, 0
	v_mov_b32_e32 v33, v173
	v_mov_b32_e32 v34, v173
	v_mov_b32_e32 v35, v173
	v_mov_b32_e32 v36, v173
	v_mov_b32_e32 v37, v173
	v_mov_b32_e32 v38, v173
	v_mov_b32_e32 v39, v173
	v_mov_b32_e32 v40, v173
	v_mov_b32_e32 v41, v173
	v_mov_b32_e32 v42, v173
	v_mov_b32_e32 v43, v173
	v_mov_b32_e32 v44, v173
	v_mov_b32_e32 v45, v173
	v_mov_b32_e32 v46, v173
	v_mov_b32_e32 v47, v173
	v_mov_b32_e32 v48, 0
	v_mov_b32_e32 v49, v173
	v_mov_b32_e32 v50, v173
	v_mov_b32_e32 v51, v173
	v_mov_b32_e32 v52, v173
	v_mov_b32_e32 v53, v173
	v_mov_b32_e32 v54, v173
	s_waitcnt vmcnt(0) lgkmcnt(0)
	ds_write_b128 v185, v[8:11]
	ds_write_b128 v186, v[12:15]
	v_mad_u64_u32 v[8:9], s[0:1], v29, s4, v[4:5]
	ds_write_b128 v172, v[16:19] offset:32768
	ds_write_b128 v172, v[20:23] offset:45568
	v_add_u32_e32 v188, 0x100, v8
	ds_write_b128 v8, v[24:27] offset:33024
	v_add_u32_e32 v8, 64, v0
	v_ashrrev_i32_e32 v9, 31, v8
	v_lshlrev_b64 v[10:11], 12, v[8:9]
	v_lshl_add_u64 v[10:11], s[82:83], 0, v[10:11]
	v_mad_i64_i32 v[8:9], s[0:1], v8, s2, v[6:7]
	v_lshl_add_u64 v[10:11], v[10:11], 0, v[2:3]
	v_lshl_add_u64 v[8:9], v[8:9], 0, v[2:3]
	global_load_dwordx4 v[144:147], v[10:11], off
	global_load_dwordx4 v[152:155], v[8:9], off
	v_add_u32_e32 v10, 0x60, v0
	v_ashrrev_i32_e32 v11, 31, v10
	v_lshlrev_b64 v[12:13], 12, v[10:11]
	v_lshl_add_u64 v[12:13], s[82:83], 0, v[12:13]
	v_mad_i64_i32 v[8:9], s[0:1], v10, s2, v[6:7]
	v_mad_i64_i32 v[6:7], s[0:1], v1, s2, v[6:7]
	v_lshl_add_u64 v[12:13], v[12:13], 0, v[2:3]
	v_lshl_add_u64 v[8:9], v[8:9], 0, v[2:3]
	v_lshl_add_u64 v[6:7], v[6:7], 0, v[4:5]
	global_load_dwordx4 v[148:151], v[12:13], off
	global_load_dwordx4 v[156:159], v[8:9], off
	global_load_dwordx4 v[160:163], v[6:7], off offset:256
	v_lshlrev_b32_e32 v1, 1, v184
	v_and_b32_e32 v1, 32, v1
	s_movk_i32 s0, 0x118
	v_and_or_b32 v1, v28, s0, v1
	v_and_or_b32 v187, v30, s77, v1
	s_add_i32 s0, s64, -1
	s_mov_b32 s1, 0
	v_mov_b32_e32 v0, 0
	v_mov_b32_e32 v1, v173
	v_mov_b32_e32 v2, v173
	v_mov_b32_e32 v3, v173
	v_mov_b32_e32 v4, v173
	v_mov_b32_e32 v5, v173
	v_mov_b32_e32 v6, v173
	v_mov_b32_e32 v7, v173
	v_mov_b32_e32 v8, v173
	v_mov_b32_e32 v9, v173
	v_mov_b32_e32 v10, v173
	v_mov_b32_e32 v11, v173
	v_mov_b32_e32 v12, v173
	v_mov_b32_e32 v13, v173
	v_mov_b32_e32 v14, v173
	v_mov_b32_e32 v15, v173
	v_mov_b32_e32 v16, 0
	v_mov_b32_e32 v17, v173
	v_mov_b32_e32 v18, v173
	v_mov_b32_e32 v19, v173
	v_mov_b32_e32 v20, v173
	v_mov_b32_e32 v21, v173
	v_mov_b32_e32 v22, v173
	v_mov_b32_e32 v23, v173
	v_mov_b32_e32 v24, v173
	v_mov_b32_e32 v25, v173
	v_mov_b32_e32 v26, v173
	v_mov_b32_e32 v27, v173
	v_mov_b32_e32 v28, v173
	v_mov_b32_e32 v29, v173
	v_mov_b32_e32 v30, v173
	v_mov_b32_e32 v55, v173
	v_mov_b32_e32 v56, v173
	v_mov_b32_e32 v57, v173
	v_mov_b32_e32 v58, v173
	v_mov_b32_e32 v59, v173
	v_mov_b32_e32 v60, v173
	v_mov_b32_e32 v61, v173
	v_mov_b32_e32 v62, v173
	v_mov_b32_e32 v63, v173
	s_waitcnt lgkmcnt(0)
	s_barrier
	s_add_u32 s34, s34, 0xc0000
	s_addc_u32 s35, s35, 0
	s_add_u32 s82, s82, 0x80000
	s_addc_u32 s83, s83, 0
	s_mov_b32 s100, 0x4000
	s_branch .LBB0_121
; #define SCHEDB() __builtin_amdgcn_sched_barrier(0)
; DEVI void qkt(f32x16& p0, f32x16& p1, const char* Ks, const bf16x8* qr, int r32, int hi) {
;   p0 = f32x16{}; p1 = f32x16{};
; #pragma unroll
;   for (int d0 = 0; d0 < 12; ++d0) { int cb = (d0 * 16 + hi * 8) * 2;
;     bf16x8 b0 = *reinterpret_cast<const bf16x8*>(Ks + KSWZ(r32, cb));
;     bf16x8 b1 = *reinterpret_cast<const bf16x8*>(Ks + KSWZ(32 + r32, cb));
;     p0 = __builtin_amdgcn_mfma_f32_32x32x16_bf16(b0, qr[d0], p0, 0, 0, 0);
;     p1 = __builtin_amdgcn_mfma_f32_32x32x16_bf16(b1, qr[d0], p1, 0, 0, 0); }
; template <bool FIX>
; DEVI void attn_item(const bfr* __restrict__ Qb, const bfr* __restrict__ Kh, const bfr* __restrict__ Vh, bfr* __restrict__ Ob, int seq, char* lds, float negBC) {
;     ...
;   for (int j = 0; j < NT; ++j) {
;     const int buf = j & 1;
;     SCHEDB(); qkt(pA0, pA1, K_lds + buf * SHM_K, qr, r32, hi);
;     if (j + 1 < NT) { SWRITE(buf ^ 1, 0); if (j + 2 < NT) SLOAD(0, (j + 2) * KVBLK); }
.LBB0_121:
	s_and_b32 s2, s1, 1
	s_mul_i32 s4, s2, 0x6400
	v_add3_u32 v191, s4, v189, v166
	s_xor_b32 s4, s2, 1
	s_mulk_i32 s4, 0x6400
	s_cmp_eq_u32 s100, 0x4000
	s_cselect_b32 s101, 0x15000, 0
	s_cmp_eq_u32 s100, 0
	s_cselect_b32 s101, 0x4000, s101
	v_add_u32_e32 v194, s101, v187
	ds_read_b128 v[196:199], v191 offset:32768
	ds_read_b128 v[200:203], v191 offset:32800
	ds_read_b128 v[204:207], v191 offset:32832
	ds_read_b128 v[224:227], v191 offset:32864
	ds_read_b128 v[228:231], v191 offset:32896
	ds_read_b128 v[232:235], v191 offset:32928
	ds_read_b128 v[236:239], v191 offset:32960
	ds_read_b128 v[240:243], v191 offset:32992
	v_cvt_pk_bf16_f32 v208, v80, v81
	v_cvt_pk_bf16_f32 v209, v82, v83
	v_cvt_pk_bf16_f32 v210, v84, v85
	v_cvt_pk_bf16_f32 v211, v86, v87
	v_cvt_pk_bf16_f32 v212, v88, v89
	v_cvt_pk_bf16_f32 v213, v90, v91
	v_cvt_pk_bf16_f32 v214, v92, v93
	v_cvt_pk_bf16_f32 v215, v94, v95
	v_cvt_pk_bf16_f32 v216, v64, v65
	v_cvt_pk_bf16_f32 v217, v66, v67
	v_cvt_pk_bf16_f32 v218, v68, v69
	v_cvt_pk_bf16_f32 v219, v70, v71
	v_cvt_pk_bf16_f32 v220, v72, v73
	v_cvt_pk_bf16_f32 v221, v74, v75
	v_cvt_pk_bf16_f32 v222, v76, v77
	v_cvt_pk_bf16_f32 v223, v78, v79
	s_nop 1
	v_permlane32_swap_b32_e32 v208, v210
	v_permlane32_swap_b32_e32 v209, v211
	v_permlane32_swap_b32_e32 v212, v214
	v_permlane32_swap_b32_e32 v213, v215
	v_permlane32_swap_b32_e32 v216, v218
	v_permlane32_swap_b32_e32 v217, v219
	v_permlane32_swap_b32_e32 v220, v222
	v_permlane32_swap_b32_e32 v221, v223
	s_waitcnt lgkmcnt(7)
	v_mfma_f32_32x32x16_bf16 v[80:95], v[196:199], v[140:143], 0
	ds_read_b128 v[244:247], v191 offset:33024
	s_waitcnt lgkmcnt(7)
	v_mfma_f32_32x32x16_bf16 v[80:95], v[200:203], v[136:139], v[80:95]
	ds_read_b128 v[248:251], v191 offset:33056
	v_add_u32_e32 v181, s100, v185
	s_waitcnt vmcnt(0)
	ds_write_b128 v181, v[144:147]
	s_waitcnt lgkmcnt(8)
	v_mfma_f32_32x32x16_bf16 v[80:95], v[204:207], v[132:135], v[80:95]
	ds_read_b128 v[196:199], v191 offset:33088
	v_add_u32_e32 v181, s100, v186
	ds_write_b128 v181, v[148:151]
	s_waitcnt lgkmcnt(9)
	v_mfma_f32_32x32x16_bf16 v[80:95], v[224:227], v[128:131], v[80:95]
	ds_read_b128 v[200:203], v191 offset:33120
	v_add_u32_e32 v181, s4, v172
	ds_write_b128 v181, v[152:155] offset:32768
	s_waitcnt lgkmcnt(10)
	v_mfma_f32_32x32x16_bf16 v[80:95], v[228:231], v[124:127], v[80:95]
	ds_read_b128 v[204:207], v191 offset:45568
	ds_write_b128 v181, v[156:159] offset:45568
	s_waitcnt lgkmcnt(11)
	v_mfma_f32_32x32x16_bf16 v[80:95], v[232:235], v[120:123], v[80:95]
	ds_read_b128 v[224:227], v191 offset:45600
	v_add_u32_e32 v181, s4, v188
	ds_write_b128 v181, v[160:163] offset:32768
	s_waitcnt lgkmcnt(12)
	v_mfma_f32_32x32x16_bf16 v[80:95], v[236:239], v[116:119], v[80:95]
	ds_read_b128 v[228:231], v191 offset:45632
	s_add_i32 s5, s1, 2
	s_cmp_ge_u32 s5, s64
	s_cbranch_scc1 .Lfa_skipload
	global_load_dwordx4 v[144:147], v174, s[82:83]
	global_load_dwordx4 v[148:151], v175, s[82:83]
	global_load_dwordx4 v[152:155], v176, s[34:35]
	global_load_dwordx4 v[156:159], v177, s[34:35]
	global_load_dwordx4 v[160:163], v178, s[34:35] offset:256
	s_add_u32 s34, s34, 0x60000
	s_addc_u32 s35, s35, 0
	s_add_u32 s82, s82, 0x40000
	s_addc_u32 s83, s83, 0
; #define SCHEDB() __builtin_amdgcn_sched_barrier(0)
; DEVI void partialSM_fix(f32x16& p0, f32x16& p1) {
;     ...
;   for (int r = 0; r < 16; ++r) p0[r] = __builtin_amdgcn_exp2f(p0[r]);
; }
; DEVI void finishSM(f32x16& p0, f32x16& p1, float alpha, float& l_reg, bf16x8& pa0, bf16x8& pa1, bf16x8& pa2, bf16x8& pa3) {
; #pragma unroll
;   for (int r = 0; r < 16; ++r) p1[r] = __builtin_amdgcn_exp2f(p1[r]);
;   float ps = 0;
; #pragma unroll
;   for (int r = 0; r < 16; ++r) ps += p0[r];
; #pragma unroll
;   for (int r = 0; r < 16; ++r) ps += p1[r];
;   { auto rr = __builtin_amdgcn_permlane32_swap(__float_as_uint(ps), __float_as_uint(ps), false, false);
;     ps = __uint_as_float(rr[0]) + __uint_as_float(rr[1]); }
;   l_reg = l_reg * alpha + ps;
; template <int D0> DEVI void pv_one(f32x16& od, int vb, bf16x8 pa0, bf16x8 pa1, bf16x8 pa2, bf16x8 pa3) {
;   const s16x4 l0 = tr_read<v_rd_off(D0, 0, 0)>(vb), h0 = tr_read<v_rd_off(D0, 0, 1)>(vb), l1 = tr_read<v_rd_off(D0, 1, 0)>(vb), h1 = tr_read<v_rd_off(D0, 1, 1)>(vb);
;   const s16x4 l2 = tr_read<v_rd_off(D0, 2, 0)>(vb), h2 = tr_read<v_rd_off(D0, 2, 1)>(vb), l3 = tr_read<v_rd_off(D0, 3, 0)>(vb), h3 = tr_read<v_rd_off(D0, 3, 1)>(vb);
;   asm volatile("s_waitcnt lgkmcnt(0)" ::: "memory"); SCHEDB();
;     ...
;   od = __builtin_amdgcn_mfma_f32_32x32x16_bf16(pa0, PK(l0, h0), od, 0, 0, 0);
;   od = __builtin_amdgcn_mfma_f32_32x32x16_bf16(pa1, PK(l1, h1), od, 0, 0, 0);
;   od = __builtin_amdgcn_mfma_f32_32x32x16_bf16(pa2, PK(l2, h2), od, 0, 0, 0);
;   od = __builtin_amdgcn_mfma_f32_32x32x16_bf16(pa3, PK(l3, h3), od, 0, 0, 0);
;     ...
; }
; DEVI void pv_d0(f32x16* o, int vb, bf16x8 pa0, bf16x8 pa1, bf16x8 pa2, bf16x8 pa3) {
;   pv_one<0>(o[0], vb, pa0, pa1, pa2, pa3); pv_one<1>(o[1], vb, pa0, pa1, pa2, pa3); pv_one<2>(o[2], vb, pa0, pa1, pa2, pa3); pv_one<3>(o[3], vb, pa0, pa1, pa2, pa3);
.Lfa_skipload:
	s_waitcnt lgkmcnt(12)
	v_mfma_f32_32x32x16_bf16 v[80:95], v[240:243], v[112:115], v[80:95]
	ds_read_b128 v[232:235], v191 offset:45664
	s_waitcnt lgkmcnt(12)
	v_mfma_f32_32x32x16_bf16 v[80:95], v[244:247], v[108:111], v[80:95]
	ds_read_b128 v[236:239], v191 offset:45696
	s_waitcnt lgkmcnt(12)
	v_mfma_f32_32x32x16_bf16 v[80:95], v[248:251], v[104:107], v[80:95]
	ds_read_b128 v[240:243], v191 offset:45728
	s_waitcnt lgkmcnt(11)
	v_mfma_f32_32x32x16_bf16 v[80:95], v[196:199], v[100:103], v[80:95]
	ds_read_b128 v[244:247], v191 offset:45760
	s_waitcnt lgkmcnt(10)
	v_mfma_f32_32x32x16_bf16 v[80:95], v[200:203], v[96:99], v[80:95]
	ds_read_b128 v[248:251], v191 offset:45792
	s_waitcnt lgkmcnt(9)
	v_mfma_f32_32x32x16_bf16 v[64:79], v[204:207], v[140:143], 0
	ds_read_b128 v[196:199], v191 offset:45824
	s_waitcnt lgkmcnt(8)
	v_mfma_f32_32x32x16_bf16 v[64:79], v[224:227], v[136:139], v[64:79]
	ds_read_b128 v[200:203], v191 offset:45856
	s_waitcnt lgkmcnt(7)
	v_mfma_f32_32x32x16_bf16 v[64:79], v[228:231], v[132:135], v[64:79]
	ds_read_b128 v[204:207], v191 offset:45888
	s_waitcnt lgkmcnt(7)
	v_mfma_f32_32x32x16_bf16 v[64:79], v[232:235], v[128:131], v[64:79]
	ds_read_b128 v[224:227], v191 offset:45920
	v_exp_f32_e32 v80, v80
	v_exp_f32_e32 v81, v81
	v_add_f32_e32 v192, 0, v80
	v_add_f32_e32 v192, v81, v192
	s_waitcnt lgkmcnt(7)
	v_mfma_f32_32x32x16_bf16 v[64:79], v[236:239], v[124:127], v[64:79]
	ds_read_b64_tr_b16 v[228:229], v194 offset:0
	ds_read_b64_tr_b16 v[230:231], v194 offset:2048
	v_exp_f32_e32 v82, v82
	v_exp_f32_e32 v83, v83
	v_add_f32_e32 v192, v82, v192
	v_add_f32_e32 v192, v83, v192
	s_waitcnt lgkmcnt(8)
	v_mfma_f32_32x32x16_bf16 v[64:79], v[240:243], v[120:123], v[64:79]
	ds_read_b64_tr_b16 v[232:233], v194 offset:4096
	ds_read_b64_tr_b16 v[234:235], v194 offset:6144
	v_exp_f32_e32 v84, v84
	v_exp_f32_e32 v85, v85
	v_add_f32_e32 v192, v84, v192
	v_add_f32_e32 v192, v85, v192
	s_waitcnt lgkmcnt(9)
	v_mfma_f32_32x32x16_bf16 v[64:79], v[244:247], v[116:119], v[64:79]
	ds_read_b64_tr_b16 v[236:237], v194 offset:8192
	ds_read_b64_tr_b16 v[238:239], v194 offset:10240
	v_exp_f32_e32 v86, v86
	v_exp_f32_e32 v87, v87
	v_add_f32_e32 v192, v86, v192
	v_add_f32_e32 v192, v87, v192
	s_waitcnt lgkmcnt(10)
	v_mfma_f32_32x32x16_bf16 v[64:79], v[248:251], v[112:115], v[64:79]
	ds_read_b64_tr_b16 v[240:241], v194 offset:12288
	ds_read_b64_tr_b16 v[242:243], v194 offset:14336
	v_exp_f32_e32 v88, v88
	v_exp_f32_e32 v89, v89
	v_add_f32_e32 v192, v88, v192
	v_add_f32_e32 v192, v89, v192
	s_waitcnt lgkmcnt(11)
	v_mfma_f32_32x32x16_bf16 v[64:79], v[196:199], v[108:111], v[64:79]
	ds_read_b64_tr_b16 v[244:245], v194 offset:512
	ds_read_b64_tr_b16 v[246:247], v194 offset:2560
	v_exp_f32_e32 v90, v90
	v_exp_f32_e32 v91, v91
	v_add_f32_e32 v192, v90, v192
	v_add_f32_e32 v192, v91, v192
	s_waitcnt lgkmcnt(12)
	v_mfma_f32_32x32x16_bf16 v[64:79], v[200:203], v[104:107], v[64:79]
	ds_read_b64_tr_b16 v[248:249], v194 offset:4608
	ds_read_b64_tr_b16 v[250:251], v194 offset:6656
	v_exp_f32_e32 v92, v92
	v_exp_f32_e32 v93, v93
	v_add_f32_e32 v192, v92, v192
	v_add_f32_e32 v192, v93, v192
	s_waitcnt lgkmcnt(13)
	v_mfma_f32_32x32x16_bf16 v[64:79], v[204:207], v[100:103], v[64:79]
	ds_read_b64_tr_b16 v[196:197], v194 offset:8704
	ds_read_b64_tr_b16 v[198:199], v194 offset:10752
	v_exp_f32_e32 v94, v94
	v_exp_f32_e32 v95, v95
	v_add_f32_e32 v192, v94, v192
	v_add_f32_e32 v192, v95, v192
	s_waitcnt lgkmcnt(14)
	v_mfma_f32_32x32x16_bf16 v[64:79], v[224:227], v[96:99], v[64:79]
	s_cmp_eq_u32 s1, 0
	s_cbranch_scc1 .Lfa_first
	s_waitcnt lgkmcnt(12)
	v_mfma_f32_32x32x16_bf16 v[0:15], v[208:211], v[228:231], v[0:15]
	ds_read_b64_tr_b16 v[200:201], v194 offset:12800
	ds_read_b64_tr_b16 v[202:203], v194 offset:14848
	s_waitcnt lgkmcnt(12)
	v_mfma_f32_32x32x16_bf16 v[0:15], v[212:215], v[232:235], v[0:15]
	ds_read_b64_tr_b16 v[204:205], v194 offset:1024
	ds_read_b64_tr_b16 v[206:207], v194 offset:3072
	s_waitcnt lgkmcnt(12)
	v_mfma_f32_32x32x16_bf16 v[0:15], v[216:219], v[236:239], v[0:15]
	ds_read_b64_tr_b16 v[224:225], v194 offset:5120
	ds_read_b64_tr_b16 v[226:227], v194 offset:7168
	s_waitcnt lgkmcnt(12)
	v_mfma_f32_32x32x16_bf16 v[0:15], v[220:223], v[240:243], v[0:15]
	ds_read_b64_tr_b16 v[228:229], v194 offset:9216
	ds_read_b64_tr_b16 v[230:231], v194 offset:11264
	v_exp_f32_e32 v64, v64
	v_exp_f32_e32 v65, v65
	v_add_f32_e32 v192, v64, v192
	v_add_f32_e32 v192, v65, v192
	s_waitcnt lgkmcnt(12)
	v_mfma_f32_32x32x16_bf16 v[16:31], v[208:211], v[244:247], v[16:31]
	ds_read_b64_tr_b16 v[232:233], v194 offset:13312
	ds_read_b64_tr_b16 v[234:235], v194 offset:15360
	v_exp_f32_e32 v66, v66
	v_exp_f32_e32 v67, v67
	v_add_f32_e32 v192, v66, v192
	v_add_f32_e32 v192, v67, v192
	s_waitcnt lgkmcnt(12)
	v_mfma_f32_32x32x16_bf16 v[16:31], v[212:215], v[248:251], v[16:31]
	ds_read_b64_tr_b16 v[236:237], v194 offset:1536
	ds_read_b64_tr_b16 v[238:239], v194 offset:3584
	v_exp_f32_e32 v68, v68
	v_exp_f32_e32 v69, v69
	v_add_f32_e32 v192, v68, v192
	v_add_f32_e32 v192, v69, v192
	s_waitcnt lgkmcnt(12)
	v_mfma_f32_32x32x16_bf16 v[16:31], v[216:219], v[196:199], v[16:31]
	ds_read_b64_tr_b16 v[240:241], v194 offset:5632
	ds_read_b64_tr_b16 v[242:243], v194 offset:7680
	v_exp_f32_e32 v70, v70
	v_exp_f32_e32 v71, v71
	v_add_f32_e32 v192, v70, v192
	v_add_f32_e32 v192, v71, v192
	s_waitcnt lgkmcnt(12)
	v_mfma_f32_32x32x16_bf16 v[16:31], v[220:223], v[200:203], v[16:31]
	ds_read_b64_tr_b16 v[244:245], v194 offset:9728
	ds_read_b64_tr_b16 v[246:247], v194 offset:11776
	v_exp_f32_e32 v72, v72
	v_exp_f32_e32 v73, v73
	v_add_f32_e32 v192, v72, v192
	v_add_f32_e32 v192, v73, v192
	s_waitcnt lgkmcnt(12)
	v_mfma_f32_32x32x16_bf16 v[32:47], v[208:211], v[204:207], v[32:47]
	ds_read_b64_tr_b16 v[248:249], v194 offset:13824
	ds_read_b64_tr_b16 v[250:251], v194 offset:15872
	v_exp_f32_e32 v74, v74
	v_exp_f32_e32 v75, v75
	v_add_f32_e32 v192, v74, v192
	v_add_f32_e32 v192, v75, v192
	s_waitcnt lgkmcnt(12)
	v_mfma_f32_32x32x16_bf16 v[32:47], v[212:215], v[224:227], v[32:47]
	v_exp_f32_e32 v76, v76
	v_exp_f32_e32 v77, v77
	v_add_f32_e32 v192, v76, v192
	v_add_f32_e32 v192, v77, v192
	s_waitcnt lgkmcnt(10)
	v_mfma_f32_32x32x16_bf16 v[32:47], v[216:219], v[228:231], v[32:47]
	v_exp_f32_e32 v78, v78
	v_exp_f32_e32 v79, v79
	v_add_f32_e32 v192, v78, v192
	v_add_f32_e32 v192, v79, v192
	s_waitcnt lgkmcnt(8)
	v_mfma_f32_32x32x16_bf16 v[32:47], v[220:223], v[232:235], v[32:47]
	v_mov_b32_e32 v193, v192
	s_waitcnt lgkmcnt(6)
	v_mfma_f32_32x32x16_bf16 v[48:63], v[208:211], v[236:239], v[48:63]
	v_permlane32_swap_b32_e32 v192, v193
	v_add_f32_e32 v192, v192, v193
	v_add_f32_e32 v173, v173, v192
	s_waitcnt lgkmcnt(4)
	v_mfma_f32_32x32x16_bf16 v[48:63], v[212:215], v[240:243], v[48:63]
	s_add_i32 s1, s1, 1
	s_waitcnt lgkmcnt(2)
	v_mfma_f32_32x32x16_bf16 v[48:63], v[216:219], v[244:247], v[48:63]
	s_waitcnt lgkmcnt(0)
	v_mfma_f32_32x32x16_bf16 v[48:63], v[220:223], v[248:251], v[48:63]

; DEVI void partialSM_fix(f32x16& p0, f32x16& p1) {
; #pragma unroll
;   for (int r = 0; r < 16; ++r) p0[r] = __builtin_amdgcn_exp2f(p0[r]);
; }
; DEVI void finishSM(f32x16& p0, f32x16& p1, float alpha, float& l_reg, bf16x8& pa0, bf16x8& pa1, bf16x8& pa2, bf16x8& pa3) {
; #pragma unroll
;   for (int r = 0; r < 16; ++r) p1[r] = __builtin_amdgcn_exp2f(p1[r]);
;   float ps = 0;
; #pragma unroll
;   for (int r = 0; r < 16; ++r) ps += p0[r];
; #pragma unroll
;   for (int r = 0; r < 16; ++r) ps += p1[r];
;   { auto rr = __builtin_amdgcn_permlane32_swap(__float_as_uint(ps), __float_as_uint(ps), false, false);
;     ps = __uint_as_float(rr[0]) + __uint_as_float(rr[1]); }
;   l_reg = l_reg * alpha + ps;
.Lfa_first:
	s_nop 11
	v_exp_f32_e32 v64, v64
	v_exp_f32_e32 v65, v65
	v_add_f32_e32 v192, v64, v192
	v_add_f32_e32 v192, v65, v192
	v_exp_f32_e32 v66, v66
	v_exp_f32_e32 v67, v67
	v_add_f32_e32 v192, v66, v192
	v_add_f32_e32 v192, v67, v192
	v_exp_f32_e32 v68, v68
	v_exp_f32_e32 v69, v69
	v_add_f32_e32 v192, v68, v192
	v_add_f32_e32 v192, v69, v192
	v_exp_f32_e32 v70, v70
	v_exp_f32_e32 v71, v71
	v_add_f32_e32 v192, v70, v192
	v_add_f32_e32 v192, v71, v192
	v_exp_f32_e32 v72, v72
	v_exp_f32_e32 v73, v73
	v_add_f32_e32 v192, v72, v192
	v_add_f32_e32 v192, v73, v192
	v_exp_f32_e32 v74, v74
	v_exp_f32_e32 v75, v75
	v_add_f32_e32 v192, v74, v192
	v_add_f32_e32 v192, v75, v192
	v_exp_f32_e32 v76, v76
	v_exp_f32_e32 v77, v77
	v_add_f32_e32 v192, v76, v192
	v_add_f32_e32 v192, v77, v192
	v_exp_f32_e32 v78, v78
	v_exp_f32_e32 v79, v79
	v_add_f32_e32 v192, v78, v192
	v_add_f32_e32 v192, v79, v192
	v_mov_b32_e32 v193, v192
	s_nop 1
	v_permlane32_swap_b32_e32 v192, v193
	v_add_f32_e32 v192, v192, v193
	v_add_f32_e32 v173, v173, v192
	s_add_i32 s1, s1, 1
	s_branch .Lfa_end

; #define P8_STAGE(P,BASE,br,kt) do{const bfr* _ub=(BASE)+((long)(br)*K+(long)(kt)*BK); \
;     __builtin_amdgcn_global_load_lds((const unsigned*)(_ub+so0),(unsigned*)((char*)(P)+wid*1024),16,0,0); \
;     __builtin_amdgcn_global_load_lds((const unsigned*)(_ub+so1),(unsigned*)((char*)(P)+wid*1024+8192),16,0,0);}while(0)
; #define P8_WAIT_V(n) asm volatile("s_waitcnt vmcnt(" #n ")":::"memory")
; #define P8_BAR __builtin_amdgcn_s_barrier()
; template <class EPI>
; DEVI void gemm8_tile(const bfr* __restrict__ A, const bfr* __restrict__ Bt, int K, int brow, int bcol, int nbrow, int nbcol, char* shmc, EPI epi) {
;     ...
;   unsigned so0, so1;
;   { int _r, _c; stage_rc(tid * 16, _r, _c); so0 = (unsigned)(_r * K + _c); stage_rc(tid * 16 + 8192, _r, _c); so1 = (unsigned)(_r * K + _c); }
;   f32x4 acc[2][2][4][2];
; #pragma unroll
;   for (int a = 0; a < 2; ++a)
; #pragma unroll
;     for (int b = 0; b < 2; ++b)
; #pragma unroll
;       for (int m = 0; m < 4; ++m)
; #pragma unroll
;         for (int n = 0; n < 2; ++n) acc[a][b][m][n] = f32x4{0.f, 0.f, 0.f, 0.f};
;   bf16x8 At[4][2], B0[2][2], B1[2][2];
;   const int nt = K / BK;
;   if(wr==1)P8_BAR;
;   P8_WAIT_V(4); P8_BAR;
;   P8_STAGE(P8_SB(1,0),Bt,bcol,1); P8_STAGE(P8_SA(1,0),A,brow,1); P8_STAGE(P8_SB(1,1),Bt,bcol+128,1);
;   P8_WAIT_V(6); P8_BAR;
.LBB0_140:
	s_or_b64 exec, exec, s[0:1]
	v_lshlrev_b32_e32 v2, 4, v142
	v_and_b32_e32 v3, 32, v142
	s_lshl_b32 s10, s2, 8
	v_lshrrev_b32_e32 v7, 1, v142
	v_bitop3_b32 v3, v2, v3, 48 bitop3:0x6c
	v_add_u32_e32 v2, 0x2000, v2
	v_ashrrev_i32_e32 v4, 3, v142
	v_bfe_u32 v5, v142, 2, 4
	s_mov_b32 s0, 0x7ffff0
	v_lshrrev_b32_e32 v8, 1, v3
	v_ashrrev_i32_e32 v9, 7, v2
	v_and_b32_e32 v7, 32, v7
	s_ashr_i32 s11, s10, 31
	s_lshl_b32 s6, s34, 8
	v_ashrrev_i32_e32 v1, 6, v142
	v_and_or_b32 v6, v4, s0, v5
	v_and_or_b32 v2, v9, s0, v5
	v_or_b32_e32 v3, v8, v7
	s_lshl_b64 s[0:1], s[10:11], 10
	v_lshl_or_b32 v166, v6, 9, v3
	s_add_u32 s8, s84, s0
	v_lshlrev_b32_e32 v143, 10, v1
	s_nop 0
	v_readfirstlane_b32 s100, v143
	s_nop 3
	s_addc_u32 s9, s85, s1
	v_lshlrev_b64 v[128:129], 1, v[166:167]
	v_add_u32_e32 v150, 0x18000, v143
	v_lshl_or_b32 v132, v2, 9, v3
	v_lshl_add_u64 v[2:3], s[8:9], 0, v[128:129]
	v_mov_b32_e32 v133, v167
	v_lshl_add_u64 v[2:3], v[2:3], 0, s[62:63]
	s_add_i32 m0, s100, 0x18000
	v_lshlrev_b64 v[130:131], 1, v[132:133]
	s_ashr_i32 s7, s6, 31
	s_waitcnt vmcnt(4)
	s_barrier
	global_load_lds_dwordx4 v[2:3], off
	v_lshl_add_u64 v[2:3], s[8:9], 0, v[130:131]
	v_add_u32_e32 v151, 0x1a000, v143
	s_lshl_b64 s[8:9], s[6:7], 10
	v_readfirstlane_b32 s2, v151
	s_add_u32 s54, s28, s8
	v_lshl_add_u64 v[2:3], v[2:3], 0, s[62:63]
	s_mov_b32 m0, s2
	s_addc_u32 s55, s29, s9
	v_add_u32_e32 v152, 0x8000, v143
	global_load_lds_dwordx4 v[2:3], off
	v_lshl_add_u64 v[2:3], s[54:55], 0, v[128:129]
	v_lshl_add_u64 v[2:3], v[2:3], 0, s[62:63]
	s_add_i32 m0, s100, 0x8000
	v_add_u32_e32 v153, 0xa000, v143
	global_load_lds_dwordx4 v[2:3], off
	v_lshl_add_u64 v[2:3], s[54:55], 0, v[130:131]
	s_or_b32 s54, s10, 0x80
	s_ashr_i32 s55, s54, 31
	s_lshl_b64 s[54:55], s[54:55], 10
	v_readfirstlane_b32 s2, v153
	s_add_u32 s54, s84, s54
	v_lshl_add_u64 v[2:3], v[2:3], 0, s[62:63]
	s_mov_b32 m0, s2
	s_addc_u32 s55, s85, s55
	v_add_u32_e32 v155, 0x1c000, v143
	global_load_lds_dwordx4 v[2:3], off
	v_lshl_add_u64 v[2:3], s[54:55], 0, v[128:129]
	v_lshl_add_u64 v[2:3], v[2:3], 0, s[62:63]
	s_add_i32 m0, s100, 0x1c000
	v_add_u32_e32 v156, 0x1e000, v143
	global_load_lds_dwordx4 v[2:3], off
	v_lshl_add_u64 v[2:3], s[54:55], 0, v[130:131]
	v_lshl_add_u64 v[2:3], v[2:3], 0, s[62:63]
	s_add_i32 m0, s100, 0x1e000
	v_and_b32_e32 v10, 15, v142
	global_load_lds_dwordx4 v[2:3], off
	v_lshlrev_b32_e32 v1, 12, v1
	v_and_b32_e32 v11, 48, v142
	v_and_b32_e32 v6, 0x3000, v1
	v_lshlrev_b32_e32 v1, 6, v10
	v_lshlrev_b32_e32 v3, 2, v142
	v_or_b32_e32 v2, v1, v11
	v_and_b32_e32 v3, 32, v3
	s_mov_b32 s2, 0x14000
	v_bitop3_b32 v13, v2, s2, v3 bitop3:0xde
	s_mov_b32 s2, 0x18000
	v_lshlrev_b32_e32 v16, 13, v0
	v_lshlrev_b32_e32 v0, 6, v142
	v_bitop3_b32 v14, v2, s2, v3 bitop3:0xde
	s_mov_b32 s2, 0x1c000
	v_and_b32_e32 v0, 0x3c0, v0
	v_bitop3_b32 v10, v1, v3, v11 bitop3:0x36
	v_bitop3_b32 v15, v2, s2, v3 bitop3:0xde
	v_bitop3_b32 v11, v0, v3, v11 bitop3:0x36
	v_lshlrev_b32_e32 v0, 9, v9
	s_movk_i32 s2, 0xe000
	v_bitop3_b32 v12, v2, s3, v3 bitop3:0xde
	v_and_or_b32 v0, v0, s2, v8
	v_lshlrev_b32_e32 v2, 9, v5
	v_lshlrev_b32_e32 v3, 9, v4
	s_add_u32 s8, s96, s8
	v_or3_b32 v0, v0, v2, v7
	v_mov_b32_e32 v1, v167
	v_and_or_b32 v3, v3, s2, v8
	s_waitcnt vmcnt(6)
	s_addc_u32 s9, s97, s9
	v_lshlrev_b64 v[0:1], 1, v[0:1]
	v_or3_b32 v2, v3, v2, v7
	v_mov_b32_e32 v3, v167
	v_or_b32_e32 v17, 0x800, v16
	v_or_b32_e32 v18, 0x1000, v16
	v_or_b32_e32 v19, 0x1800, v16
	v_lshl_add_u64 v[134:135], s[8:9], 0, v[0:1]
	v_lshlrev_b64 v[2:3], 1, v[2:3]
	v_lshl_add_u64 v[138:139], s[0:1], 0, v[0:1]
	v_mov_b32_e32 v0, 0
	v_lshl_add_u64 v[136:137], s[8:9], 0, v[2:3]
	v_lshl_add_u64 v[140:141], s[0:1], 0, v[2:3]
	s_mov_b32 s0, -2
	v_add_u32_e32 v157, v12, v6
	v_add_u32_e32 v147, v10, v16
	v_add_u32_e32 v146, v11, v17
	v_add_u32_e32 v145, v11, v18
	v_add_u32_e32 v144, v11, v19
	v_add_u32_e32 v154, v13, v6
	v_add_u32_e32 v149, v14, v6
	v_add_u32_e32 v148, v15, v6
	v_mov_b32_e32 v1, v0
	v_mov_b32_e32 v2, v0
	v_mov_b32_e32 v3, v0
	v_mov_b32_e32 v4, v0
	v_mov_b32_e32 v5, v0
	v_mov_b32_e32 v6, v0
	v_mov_b32_e32 v7, v0
	v_mov_b32_e32 v8, v0
	v_mov_b32_e32 v9, v0
	v_mov_b32_e32 v10, v0
	v_mov_b32_e32 v11, v0
	v_mov_b32_e32 v12, v0
	v_mov_b32_e32 v13, v0
	v_mov_b32_e32 v14, v0
	v_mov_b32_e32 v15, v0
	v_mov_b32_e32 v16, v0
	v_mov_b32_e32 v17, v0
	v_mov_b32_e32 v18, v0
	v_mov_b32_e32 v19, v0
	v_mov_b32_e32 v20, v0
	v_mov_b32_e32 v21, v0
	v_mov_b32_e32 v22, v0
	v_mov_b32_e32 v23, v0
	v_mov_b32_e32 v24, v0
	v_mov_b32_e32 v25, v0
	v_mov_b32_e32 v26, v0
	v_mov_b32_e32 v27, v0
	v_mov_b32_e32 v28, v0
	v_mov_b32_e32 v29, v0
	v_mov_b32_e32 v30, v0
	v_mov_b32_e32 v31, v0
	v_mov_b32_e32 v32, v0
	v_mov_b32_e32 v33, v0
	v_mov_b32_e32 v34, v0
	v_mov_b32_e32 v35, v0
	v_mov_b32_e32 v36, v0
	v_mov_b32_e32 v37, v0
	v_mov_b32_e32 v38, v0
	v_mov_b32_e32 v39, v0
	v_mov_b32_e32 v40, v0
	v_mov_b32_e32 v41, v0
	v_mov_b32_e32 v42, v0
	v_mov_b32_e32 v43, v0
	v_mov_b32_e32 v44, v0
	v_mov_b32_e32 v45, v0
	v_mov_b32_e32 v46, v0
	v_mov_b32_e32 v47, v0
	v_mov_b32_e32 v48, v0
	v_mov_b32_e32 v49, v0
	v_mov_b32_e32 v50, v0
	v_mov_b32_e32 v51, v0
	v_mov_b32_e32 v52, v0
	v_mov_b32_e32 v53, v0
	v_mov_b32_e32 v54, v0
	v_mov_b32_e32 v55, v0
	v_mov_b32_e32 v56, v0
	v_mov_b32_e32 v57, v0
	v_mov_b32_e32 v58, v0
	v_mov_b32_e32 v59, v0
	v_mov_b32_e32 v60, v0
	v_mov_b32_e32 v61, v0
	v_mov_b32_e32 v62, v0
	v_mov_b32_e32 v63, v0
	v_mov_b32_e32 v64, v0
	v_mov_b32_e32 v65, v0
	v_mov_b32_e32 v66, v0
	v_mov_b32_e32 v67, v0
	v_mov_b32_e32 v68, v0
	v_mov_b32_e32 v69, v0
	v_mov_b32_e32 v70, v0
	v_mov_b32_e32 v71, v0
	v_mov_b32_e32 v72, v0
	v_mov_b32_e32 v73, v0
	v_mov_b32_e32 v74, v0
; #define P8_STAGE(P,BASE,br,kt) do{const bfr* _ub=(BASE)+((long)(br)*K+(long)(kt)*BK); \
;     __builtin_amdgcn_global_load_lds((const unsigned*)(_ub+so0),(unsigned*)((char*)(P)+wid*1024),16,0,0); \
;     __builtin_amdgcn_global_load_lds((const unsigned*)(_ub+so1),(unsigned*)((char*)(P)+wid*1024+8192),16,0,0);}while(0)
; #define P8_LDA(dst,b,h) _Pragma("unroll") for(int m=0;m<4;++m) _Pragma("unroll") for(int k=0;k<2;++k) \
;     dst[m][k]=*reinterpret_cast<const bf16x8*>((char*)P8_SA(b,h)+lds_byte(wr*64+m*16+fr,k*32+fq*8))
; #define P8_LDB(dst,b,h) _Pragma("unroll") for(int n=0;n<2;++n) _Pragma("unroll") for(int k=0;k<2;++k) \
;     dst[n][k]=*reinterpret_cast<const bf16x8*>((char*)P8_SB(b,h)+lds_byte(wc*32+n*16+fr,k*32+fq*8))
; #define P8_MMA(ai,bj,At,Bt) do{__builtin_amdgcn_s_setprio(1); \
;     _Pragma("unroll") for(int m=0;m<4;++m) _Pragma("unroll") for(int n=0;n<2;++n) _Pragma("unroll") for(int k=0;k<2;++k) \
;       acc[ai][bj][m][n]=__builtin_amdgcn_mfma_f32_16x16x32_bf16(At[m][k],Bt[n][k],acc[ai][bj][m][n],0,0,0); \
;     __builtin_amdgcn_s_setprio(0);}while(0)
; #define P8_WAIT_L(n) asm volatile("s_waitcnt lgkmcnt(" #n ")":::"memory")
; #define P8_BAR __builtin_amdgcn_s_barrier()
; #define P8_SCHED __builtin_amdgcn_sched_barrier(0)
; template <class EPI>
; DEVI void gemm8_tile(const bfr* __restrict__ A, const bfr* __restrict__ Bt, int K, int brow, int bcol, int nbrow, int nbcol, char* shmc, EPI epi) {
;     ...
;   for(int t=0;t<nt-2;t+=2){
;     P8_LDB(B0,0,0); P8_SCHED; P8_LDA(At,0,0); P8_STAGE(P8_SA(1,1),A,brow+128,t+1);
;     P8_WAIT_L(8); P8_BAR; P8_WAIT_L(0); P8_MMA(0,0,At,B0); P8_BAR; P8_SCHED;
;     P8_LDB(B1,0,1); P8_STAGE(P8_SB(0,0),Bt,bcol,t+2);
;     P8_BAR; P8_WAIT_L(0); P8_MMA(0,1,At,B1); P8_BAR;
;     P8_LDA(At,0,1); P8_STAGE(P8_SA(0,0),A,brow,t+2);
;     P8_BAR; P8_WAIT_L(0); P8_MMA(1,0,At,B0); P8_BAR; P8_SCHED;
	v_mov_b32_e32 v75, v0
	v_mov_b32_e32 v76, v0
	v_mov_b32_e32 v77, v0
	v_mov_b32_e32 v78, v0
	v_mov_b32_e32 v79, v0
	v_mov_b32_e32 v80, v0
	v_mov_b32_e32 v81, v0
	v_mov_b32_e32 v82, v0
	v_mov_b32_e32 v83, v0
	v_mov_b32_e32 v84, v0
	v_mov_b32_e32 v85, v0
	v_mov_b32_e32 v86, v0
	v_mov_b32_e32 v87, v0
	v_mov_b32_e32 v88, v0
	v_mov_b32_e32 v89, v0
	v_mov_b32_e32 v90, v0
	v_mov_b32_e32 v91, v0
	v_mov_b32_e32 v92, v0
	v_mov_b32_e32 v93, v0
	v_mov_b32_e32 v94, v0
	v_mov_b32_e32 v95, v0
	v_mov_b32_e32 v96, v0
	v_mov_b32_e32 v97, v0
	v_mov_b32_e32 v98, v0
	v_mov_b32_e32 v99, v0
	v_mov_b32_e32 v100, v0
	v_mov_b32_e32 v101, v0
	v_mov_b32_e32 v102, v0
	v_mov_b32_e32 v103, v0
	v_mov_b32_e32 v104, v0
	v_mov_b32_e32 v105, v0
	v_mov_b32_e32 v106, v0
	v_mov_b32_e32 v107, v0
	v_mov_b32_e32 v108, v0
	v_mov_b32_e32 v109, v0
	v_mov_b32_e32 v110, v0
	v_mov_b32_e32 v111, v0
	v_mov_b32_e32 v112, v0
	v_mov_b32_e32 v113, v0
	v_mov_b32_e32 v114, v0
	v_mov_b32_e32 v115, v0
	v_mov_b32_e32 v116, v0
	v_mov_b32_e32 v117, v0
	v_mov_b32_e32 v118, v0
	v_mov_b32_e32 v119, v0
	v_mov_b32_e32 v120, v0
	v_mov_b32_e32 v121, v0
	v_mov_b32_e32 v122, v0
	v_mov_b32_e32 v123, v0
	v_mov_b32_e32 v124, v0
	v_mov_b32_e32 v125, v0
	v_mov_b32_e32 v126, v0
	v_mov_b32_e32 v127, v0
	s_mov_b64 s[8:9], 0xa20080
	s_mov_b64 s[54:55], 0xa00100
	s_mov_b64 s[60:61], 0x13eb0100
	s_mov_b64 s[72:73], 0xa20100
	s_mov_b64 s[92:93], 0xa00180
	s_mov_b64 s[94:95], 0x13eb0180
	s_barrier
.LBB0_141:
	ds_read_b128 v[174:177], v157
	ds_read_b128 v[178:181], v157 offset:1024
	ds_read_b128 v[182:185], v157 offset:2048
	ds_read_b128 v[186:189], v157 offset:3072
	v_add_u32_e32 v171, 0xc000, v143
	v_add_u32_e32 v172, 0xe000, v143
	v_add_u32_e32 v158, s8, v136
	s_add_i32 m0, s100, 0xc000
	ds_read_b128 v[160:163], v147
	ds_read_b128 v[190:193], v147 offset:1024
	ds_read_b128 v[196:199], v146
	ds_read_b128 v[208:211], v146 offset:1024
	ds_read_b128 v[212:215], v145
	ds_read_b128 v[216:219], v145 offset:1024
	ds_read_b128 v[220:223], v144
	ds_read_b128 v[224:227], v144 offset:1024
	global_load_lds_dwordx4 v158, s[86:87]
	v_add_u32_e32 v158, s8, v134
	s_add_i32 m0, s100, 0xe000
	s_nop 0
	global_load_lds_dwordx4 v158, s[86:87]
	s_waitcnt lgkmcnt(8)
	s_barrier
	s_waitcnt lgkmcnt(0)
	s_setprio 1
	s_waitcnt lgkmcnt(0)
	v_mfma_f32_16x16x32_bf16 v[124:127], v[160:163], v[174:177], v[124:127]
	v_mfma_f32_16x16x32_bf16 v[120:123], v[160:163], v[182:185], v[120:123]
	v_mfma_f32_16x16x32_bf16 v[116:119], v[196:199], v[174:177], v[116:119]
	v_mfma_f32_16x16x32_bf16 v[112:115], v[196:199], v[182:185], v[112:115]
	v_mfma_f32_16x16x32_bf16 v[108:111], v[212:215], v[174:177], v[108:111]
	v_mfma_f32_16x16x32_bf16 v[104:107], v[212:215], v[182:185], v[104:107]
	v_mfma_f32_16x16x32_bf16 v[100:103], v[220:223], v[174:177], v[100:103]
	v_mfma_f32_16x16x32_bf16 v[96:99], v[220:223], v[182:185], v[96:99]
	v_mfma_f32_16x16x32_bf16 v[124:127], v[190:193], v[178:181], v[124:127]
	v_mfma_f32_16x16x32_bf16 v[120:123], v[190:193], v[186:189], v[120:123]
	v_mfma_f32_16x16x32_bf16 v[116:119], v[208:211], v[178:181], v[116:119]
	v_mfma_f32_16x16x32_bf16 v[112:115], v[208:211], v[186:189], v[112:115]
	v_mfma_f32_16x16x32_bf16 v[108:111], v[216:219], v[178:181], v[108:111]
	v_mfma_f32_16x16x32_bf16 v[104:107], v[216:219], v[186:189], v[104:107]
	v_mfma_f32_16x16x32_bf16 v[100:103], v[224:227], v[178:181], v[100:103]
	v_mfma_f32_16x16x32_bf16 v[96:99], v[224:227], v[186:189], v[96:99]
	s_setprio 0
	s_barrier
	v_add_u32_e32 v158, 0x10000, v143
	v_add_u32_e32 v206, s66, v140
	s_add_i32 m0, s100, 0x10000
	v_add_u32_e32 v159, 0x12000, v143
	ds_read_b128 v[228:231], v154
	ds_read_b128 v[232:235], v154 offset:1024
	ds_read_b128 v[236:239], v154 offset:2048
	ds_read_b128 v[240:243], v154 offset:3072
	global_load_lds_dwordx4 v206, s[86:87]
	v_add_u32_e32 v244, s66, v138
	s_add_i32 m0, s100, 0x12000
	s_nop 0
	global_load_lds_dwordx4 v244, s[86:87]
	s_barrier
	s_waitcnt lgkmcnt(0)
	s_setprio 1
	s_waitcnt lgkmcnt(0)
	v_mfma_f32_16x16x32_bf16 v[92:95], v[160:163], v[228:231], v[92:95]
	v_mfma_f32_16x16x32_bf16 v[88:91], v[160:163], v[236:239], v[88:91]
	v_mfma_f32_16x16x32_bf16 v[84:87], v[196:199], v[228:231], v[84:87]
	v_mfma_f32_16x16x32_bf16 v[80:83], v[196:199], v[236:239], v[80:83]
	v_mfma_f32_16x16x32_bf16 v[76:79], v[212:215], v[228:231], v[76:79]
	v_mfma_f32_16x16x32_bf16 v[72:75], v[212:215], v[236:239], v[72:75]
	v_mfma_f32_16x16x32_bf16 v[68:71], v[220:223], v[228:231], v[68:71]
	v_mfma_f32_16x16x32_bf16 v[64:67], v[220:223], v[236:239], v[64:67]
	v_mfma_f32_16x16x32_bf16 v[92:95], v[190:193], v[232:235], v[92:95]
	v_mfma_f32_16x16x32_bf16 v[88:91], v[190:193], v[240:243], v[88:91]
	v_mfma_f32_16x16x32_bf16 v[84:87], v[208:211], v[232:235], v[84:87]
	v_mfma_f32_16x16x32_bf16 v[80:83], v[208:211], v[240:243], v[80:83]
	v_mfma_f32_16x16x32_bf16 v[76:79], v[216:219], v[232:235], v[76:79]
	v_mfma_f32_16x16x32_bf16 v[72:75], v[216:219], v[240:243], v[72:75]
	v_mfma_f32_16x16x32_bf16 v[68:71], v[224:227], v[232:235], v[68:71]
	v_mfma_f32_16x16x32_bf16 v[64:67], v[224:227], v[240:243], v[64:67]
	s_setprio 0
	v_add_u32_e32 v160, s54, v136
	s_mov_b32 m0, s100
	s_barrier
	ds_read_b128 v[190:193], v147 offset:16384
	ds_read_b128 v[196:199], v147 offset:17408
	ds_read_b128 v[208:211], v146 offset:16384
	ds_read_b128 v[212:215], v146 offset:17408
	ds_read_b128 v[216:219], v145 offset:16384
	ds_read_b128 v[220:223], v145 offset:17408
	ds_read_b128 v[224:227], v144 offset:16384
	ds_read_b128 v[244:247], v144 offset:17408
	global_load_lds_dwordx4 v160, s[86:87]
	v_add_u32_e32 v160, 0x2000, v143
	v_add_u32_e32 v162, s54, v134
	s_add_i32 m0, s100, 0x2000
	s_nop 0
	global_load_lds_dwordx4 v162, s[86:87]
	s_barrier
; #define P8_STAGE(P,BASE,br,kt) do{const bfr* _ub=(BASE)+((long)(br)*K+(long)(kt)*BK); \
;     __builtin_amdgcn_global_load_lds((const unsigned*)(_ub+so0),(unsigned*)((char*)(P)+wid*1024),16,0,0); \
;     __builtin_amdgcn_global_load_lds((const unsigned*)(_ub+so1),(unsigned*)((char*)(P)+wid*1024+8192),16,0,0);}while(0)
; #define P8_LDA(dst,b,h) _Pragma("unroll") for(int m=0;m<4;++m) _Pragma("unroll") for(int k=0;k<2;++k) \
;     dst[m][k]=*reinterpret_cast<const bf16x8*>((char*)P8_SA(b,h)+lds_byte(wr*64+m*16+fr,k*32+fq*8))
; #define P8_LDB(dst,b,h) _Pragma("unroll") for(int n=0;n<2;++n) _Pragma("unroll") for(int k=0;k<2;++k) \
;     dst[n][k]=*reinterpret_cast<const bf16x8*>((char*)P8_SB(b,h)+lds_byte(wc*32+n*16+fr,k*32+fq*8))
; #define P8_MMA(ai,bj,At,Bt) do{__builtin_amdgcn_s_setprio(1); \
;     _Pragma("unroll") for(int m=0;m<4;++m) _Pragma("unroll") for(int n=0;n<2;++n) _Pragma("unroll") for(int k=0;k<2;++k) \
;       acc[ai][bj][m][n]=__builtin_amdgcn_mfma_f32_16x16x32_bf16(At[m][k],Bt[n][k],acc[ai][bj][m][n],0,0,0); \
;     __builtin_amdgcn_s_setprio(0);}while(0)
; #define P8_WAIT_V(n) asm volatile("s_waitcnt vmcnt(" #n ")":::"memory")
; #define P8_WAIT_L(n) asm volatile("s_waitcnt lgkmcnt(" #n ")":::"memory")
; #define P8_BAR __builtin_amdgcn_s_barrier()
; #define P8_SCHED __builtin_amdgcn_sched_barrier(0)
; template <class EPI>
; DEVI void gemm8_tile(const bfr* __restrict__ A, const bfr* __restrict__ Bt, int K, int brow, int bcol, int nbrow, int nbcol, char* shmc, EPI epi) {
;     ...
;     P8_BAR; P8_WAIT_L(0); P8_MMA(1,0,At,B0); P8_BAR; P8_SCHED;
;     P8_STAGE(P8_SB(0,1),Bt,bcol+128,t+2);
;     P8_WAIT_V(6); P8_BAR; P8_MMA(1,1,At,B1); P8_BAR;
;     P8_LDB(B0,1,0); P8_SCHED; P8_LDA(At,1,0); P8_STAGE(P8_SA(0,1),A,brow+128,t+2);
;     P8_WAIT_L(8); P8_BAR; P8_WAIT_L(0); P8_MMA(0,0,At,B0); P8_BAR; P8_SCHED;
;     P8_LDB(B1,1,1); P8_STAGE(P8_SB(1,0),Bt,bcol,t+3);
;     P8_BAR; P8_WAIT_L(0); P8_MMA(0,1,At,B1); P8_BAR;
	s_waitcnt lgkmcnt(0)
	s_setprio 1
	s_waitcnt lgkmcnt(0)
	v_mfma_f32_16x16x32_bf16 v[60:63], v[190:193], v[174:177], v[60:63]
	v_mfma_f32_16x16x32_bf16 v[56:59], v[190:193], v[182:185], v[56:59]
	v_mfma_f32_16x16x32_bf16 v[52:55], v[208:211], v[174:177], v[52:55]
	v_mfma_f32_16x16x32_bf16 v[48:51], v[208:211], v[182:185], v[48:51]
	v_mfma_f32_16x16x32_bf16 v[44:47], v[216:219], v[174:177], v[44:47]
	v_mfma_f32_16x16x32_bf16 v[40:43], v[216:219], v[182:185], v[40:43]
	v_mfma_f32_16x16x32_bf16 v[36:39], v[224:227], v[174:177], v[36:39]
	v_mfma_f32_16x16x32_bf16 v[32:35], v[224:227], v[182:185], v[32:35]
	v_mfma_f32_16x16x32_bf16 v[60:63], v[196:199], v[178:181], v[60:63]
	v_mfma_f32_16x16x32_bf16 v[56:59], v[196:199], v[186:189], v[56:59]
	v_mfma_f32_16x16x32_bf16 v[52:55], v[212:215], v[178:181], v[52:55]
	v_mfma_f32_16x16x32_bf16 v[48:51], v[212:215], v[186:189], v[48:51]
	v_mfma_f32_16x16x32_bf16 v[44:47], v[220:223], v[178:181], v[44:47]
	v_mfma_f32_16x16x32_bf16 v[40:43], v[220:223], v[186:189], v[40:43]
	v_mfma_f32_16x16x32_bf16 v[36:39], v[244:247], v[178:181], v[36:39]
	v_mfma_f32_16x16x32_bf16 v[32:35], v[244:247], v[186:189], v[32:35]
	s_setprio 0
	s_barrier
	v_add_u32_e32 v161, 0x14000, v143
	v_add_u32_e32 v162, s60, v140
	s_add_i32 m0, s100, 0x14000
	v_add_u32_e32 v174, s60, v138
	global_load_lds_dwordx4 v162, s[86:87]
	v_add_u32_e32 v162, 0x16000, v143
	s_nop 0
	s_add_i32 m0, s100, 0x16000
	s_nop 0
	global_load_lds_dwordx4 v174, s[86:87]
	s_waitcnt vmcnt(6)
	s_barrier
	s_setprio 1
	v_mfma_f32_16x16x32_bf16 v[28:31], v[190:193], v[228:231], v[28:31]
	v_mfma_f32_16x16x32_bf16 v[24:27], v[190:193], v[236:239], v[24:27]
	v_mfma_f32_16x16x32_bf16 v[20:23], v[208:211], v[228:231], v[20:23]
	v_mfma_f32_16x16x32_bf16 v[16:19], v[208:211], v[236:239], v[16:19]
	v_mfma_f32_16x16x32_bf16 v[12:15], v[216:219], v[228:231], v[12:15]
	v_mfma_f32_16x16x32_bf16 v[8:11], v[216:219], v[236:239], v[8:11]
	v_mfma_f32_16x16x32_bf16 v[4:7], v[224:227], v[228:231], v[4:7]
	v_mfma_f32_16x16x32_bf16 v[0:3], v[224:227], v[236:239], v[0:3]
	v_mfma_f32_16x16x32_bf16 v[28:31], v[196:199], v[232:235], v[28:31]
	v_mfma_f32_16x16x32_bf16 v[24:27], v[196:199], v[240:243], v[24:27]
	v_mfma_f32_16x16x32_bf16 v[20:23], v[212:215], v[232:235], v[20:23]
	v_mfma_f32_16x16x32_bf16 v[16:19], v[212:215], v[240:243], v[16:19]
	v_mfma_f32_16x16x32_bf16 v[12:15], v[220:223], v[232:235], v[12:15]
	v_mfma_f32_16x16x32_bf16 v[8:11], v[220:223], v[240:243], v[8:11]
	v_mfma_f32_16x16x32_bf16 v[4:7], v[244:247], v[232:235], v[4:7]
	v_mfma_f32_16x16x32_bf16 v[0:3], v[244:247], v[240:243], v[0:3]
	s_setprio 0
	s_barrier
	ds_read_b128 v[174:177], v149
	ds_read_b128 v[178:181], v149 offset:1024
	ds_read_b128 v[182:185], v149 offset:2048
	ds_read_b128 v[186:189], v149 offset:3072
	v_add_u32_e32 v163, 0x4000, v143
	v_add_u32_e32 v170, 0x6000, v143
	v_add_u32_e32 v232, s72, v136
	s_add_i32 m0, s100, 0x4000
	ds_read_b128 v[190:193], v147 offset:32768
	ds_read_b128 v[196:199], v147 offset:33792
	ds_read_b128 v[208:211], v146 offset:32768
	ds_read_b128 v[212:215], v146 offset:33792
	ds_read_b128 v[216:219], v145 offset:32768
	ds_read_b128 v[220:223], v145 offset:33792
	ds_read_b128 v[224:227], v144 offset:32768
	ds_read_b128 v[228:231], v144 offset:33792
	global_load_lds_dwordx4 v232, s[86:87]
	v_add_u32_e32 v232, s72, v134
	s_add_i32 m0, s100, 0x6000
	s_nop 0
	global_load_lds_dwordx4 v232, s[86:87]
	s_waitcnt lgkmcnt(8)
	s_barrier
	s_waitcnt lgkmcnt(0)
	s_setprio 1
	s_waitcnt lgkmcnt(0)
	v_mfma_f32_16x16x32_bf16 v[124:127], v[190:193], v[174:177], v[124:127]
	v_mfma_f32_16x16x32_bf16 v[120:123], v[190:193], v[182:185], v[120:123]
	v_mfma_f32_16x16x32_bf16 v[116:119], v[208:211], v[174:177], v[116:119]
	v_mfma_f32_16x16x32_bf16 v[112:115], v[208:211], v[182:185], v[112:115]
	v_mfma_f32_16x16x32_bf16 v[108:111], v[216:219], v[174:177], v[108:111]
	v_mfma_f32_16x16x32_bf16 v[104:107], v[216:219], v[182:185], v[104:107]
	v_mfma_f32_16x16x32_bf16 v[100:103], v[224:227], v[174:177], v[100:103]
	v_mfma_f32_16x16x32_bf16 v[96:99], v[224:227], v[182:185], v[96:99]
	v_mfma_f32_16x16x32_bf16 v[124:127], v[196:199], v[178:181], v[124:127]
	v_mfma_f32_16x16x32_bf16 v[120:123], v[196:199], v[186:189], v[120:123]
	v_mfma_f32_16x16x32_bf16 v[116:119], v[212:215], v[178:181], v[116:119]
	v_mfma_f32_16x16x32_bf16 v[112:115], v[212:215], v[186:189], v[112:115]
	v_mfma_f32_16x16x32_bf16 v[108:111], v[220:223], v[178:181], v[108:111]
	v_mfma_f32_16x16x32_bf16 v[104:107], v[220:223], v[186:189], v[104:107]
	v_mfma_f32_16x16x32_bf16 v[100:103], v[228:231], v[178:181], v[100:103]
	v_mfma_f32_16x16x32_bf16 v[96:99], v[228:231], v[186:189], v[96:99]
	s_setprio 0
	s_barrier
	v_add_u32_e32 v248, s74, v140
	s_add_i32 m0, s100, 0x18000
	ds_read_b128 v[232:235], v148
	ds_read_b128 v[236:239], v148 offset:1024
	ds_read_b128 v[240:243], v148 offset:2048
	ds_read_b128 v[244:247], v148 offset:3072
	global_load_lds_dwordx4 v248, s[86:87]
	v_add_u32_e32 v248, s74, v138
	s_add_i32 m0, s100, 0x1a000
	s_nop 0
	global_load_lds_dwordx4 v248, s[86:87]
	s_barrier
; #define P8_STAGE(P,BASE,br,kt) do{const bfr* _ub=(BASE)+((long)(br)*K+(long)(kt)*BK); \
;     __builtin_amdgcn_global_load_lds((const unsigned*)(_ub+so0),(unsigned*)((char*)(P)+wid*1024),16,0,0); \
;     __builtin_amdgcn_global_load_lds((const unsigned*)(_ub+so1),(unsigned*)((char*)(P)+wid*1024+8192),16,0,0);}while(0)
; #define P8_LDA(dst,b,h) _Pragma("unroll") for(int m=0;m<4;++m) _Pragma("unroll") for(int k=0;k<2;++k) \
;     dst[m][k]=*reinterpret_cast<const bf16x8*>((char*)P8_SA(b,h)+lds_byte(wr*64+m*16+fr,k*32+fq*8))
; #define P8_LDB(dst,b,h) _Pragma("unroll") for(int n=0;n<2;++n) _Pragma("unroll") for(int k=0;k<2;++k) \
;     dst[n][k]=*reinterpret_cast<const bf16x8*>((char*)P8_SB(b,h)+lds_byte(wc*32+n*16+fr,k*32+fq*8))
; #define P8_MMA(ai,bj,At,Bt) do{__builtin_amdgcn_s_setprio(1); \
;     _Pragma("unroll") for(int m=0;m<4;++m) _Pragma("unroll") for(int n=0;n<2;++n) _Pragma("unroll") for(int k=0;k<2;++k) \
;       acc[ai][bj][m][n]=__builtin_amdgcn_mfma_f32_16x16x32_bf16(At[m][k],Bt[n][k],acc[ai][bj][m][n],0,0,0); \
;     __builtin_amdgcn_s_setprio(0);}while(0)
; #define P8_WAIT_V(n) asm volatile("s_waitcnt vmcnt(" #n ")":::"memory")
; #define P8_WAIT_L(n) asm volatile("s_waitcnt lgkmcnt(" #n ")":::"memory")
; #define P8_BAR __builtin_amdgcn_s_barrier()
; #define P8_SCHED __builtin_amdgcn_sched_barrier(0)
; template <class EPI>
; DEVI void gemm8_tile(const bfr* __restrict__ A, const bfr* __restrict__ Bt, int K, int brow, int bcol, int nbrow, int nbcol, char* shmc, EPI epi) {
;     ...
;     P8_BAR; P8_WAIT_L(0); P8_MMA(0,1,At,B1); P8_BAR;
;     P8_LDA(At,1,1); P8_STAGE(P8_SA(1,0),A,brow,t+3);
;     P8_BAR; P8_WAIT_L(0); P8_MMA(1,0,At,B0); P8_BAR; P8_SCHED;
;     P8_STAGE(P8_SB(1,1),Bt,bcol+128,t+3);
;     P8_WAIT_V(6); P8_BAR; P8_MMA(1,1,At,B1); P8_BAR;
;   }
;   { P8_LDB(B0,0,0); P8_LDA(At,0,0); P8_STAGE(P8_SA(1,1),A,brow+128,nt-1);
;     P8_BAR; P8_WAIT_L(0); P8_MMA(0,0,At,B0); P8_BAR;
	s_waitcnt lgkmcnt(0)
	s_setprio 1
	s_waitcnt lgkmcnt(0)
	v_mfma_f32_16x16x32_bf16 v[92:95], v[190:193], v[232:235], v[92:95]
	v_mfma_f32_16x16x32_bf16 v[88:91], v[190:193], v[240:243], v[88:91]
	v_mfma_f32_16x16x32_bf16 v[84:87], v[208:211], v[232:235], v[84:87]
	v_mfma_f32_16x16x32_bf16 v[80:83], v[208:211], v[240:243], v[80:83]
	v_mfma_f32_16x16x32_bf16 v[76:79], v[216:219], v[232:235], v[76:79]
	v_mfma_f32_16x16x32_bf16 v[72:75], v[216:219], v[240:243], v[72:75]
	v_mfma_f32_16x16x32_bf16 v[68:71], v[224:227], v[232:235], v[68:71]
	v_mfma_f32_16x16x32_bf16 v[64:67], v[224:227], v[240:243], v[64:67]
	v_mfma_f32_16x16x32_bf16 v[92:95], v[196:199], v[236:239], v[92:95]
	v_mfma_f32_16x16x32_bf16 v[88:91], v[196:199], v[244:247], v[88:91]
	v_mfma_f32_16x16x32_bf16 v[84:87], v[212:215], v[236:239], v[84:87]
	v_mfma_f32_16x16x32_bf16 v[80:83], v[212:215], v[244:247], v[80:83]
	v_mfma_f32_16x16x32_bf16 v[76:79], v[220:223], v[236:239], v[76:79]
	v_mfma_f32_16x16x32_bf16 v[72:75], v[220:223], v[244:247], v[72:75]
	v_mfma_f32_16x16x32_bf16 v[68:71], v[228:231], v[236:239], v[68:71]
	v_mfma_f32_16x16x32_bf16 v[64:67], v[228:231], v[244:247], v[64:67]
	s_setprio 0
	v_add_u32_e32 v200, s92, v136
	s_add_i32 m0, s100, 0x8000
	s_barrier
	ds_read_b128 v[190:193], v147 offset:49152
	ds_read_b128 v[196:199], v147 offset:50176
	ds_read_b128 v[208:211], v146 offset:49152
	ds_read_b128 v[212:215], v146 offset:50176
	ds_read_b128 v[216:219], v145 offset:49152
	ds_read_b128 v[220:223], v145 offset:50176
	ds_read_b128 v[224:227], v144 offset:49152
	ds_read_b128 v[228:231], v144 offset:50176
	global_load_lds_dwordx4 v200, s[86:87]
	v_add_u32_e32 v200, s92, v134
	s_add_i32 m0, s100, 0xa000
	s_nop 0
	global_load_lds_dwordx4 v200, s[86:87]
	s_barrier
	s_waitcnt lgkmcnt(0)
	s_setprio 1
	s_waitcnt lgkmcnt(0)
	v_mfma_f32_16x16x32_bf16 v[60:63], v[190:193], v[174:177], v[60:63]
	v_mfma_f32_16x16x32_bf16 v[56:59], v[190:193], v[182:185], v[56:59]
	v_mfma_f32_16x16x32_bf16 v[52:55], v[208:211], v[174:177], v[52:55]
	v_mfma_f32_16x16x32_bf16 v[48:51], v[208:211], v[182:185], v[48:51]
	v_mfma_f32_16x16x32_bf16 v[44:47], v[216:219], v[174:177], v[44:47]
	v_mfma_f32_16x16x32_bf16 v[40:43], v[216:219], v[182:185], v[40:43]
	v_mfma_f32_16x16x32_bf16 v[36:39], v[224:227], v[174:177], v[36:39]
	v_mfma_f32_16x16x32_bf16 v[32:35], v[224:227], v[182:185], v[32:35]
	v_mfma_f32_16x16x32_bf16 v[60:63], v[196:199], v[178:181], v[60:63]
	v_mfma_f32_16x16x32_bf16 v[56:59], v[196:199], v[186:189], v[56:59]
	v_mfma_f32_16x16x32_bf16 v[52:55], v[212:215], v[178:181], v[52:55]
	v_mfma_f32_16x16x32_bf16 v[48:51], v[212:215], v[186:189], v[48:51]
	v_mfma_f32_16x16x32_bf16 v[44:47], v[220:223], v[178:181], v[44:47]
	v_mfma_f32_16x16x32_bf16 v[40:43], v[220:223], v[186:189], v[40:43]
	v_mfma_f32_16x16x32_bf16 v[36:39], v[228:231], v[178:181], v[36:39]
	v_mfma_f32_16x16x32_bf16 v[32:35], v[228:231], v[186:189], v[32:35]
	s_setprio 0
	s_barrier
	v_add_u32_e32 v174, s94, v140
	s_add_i32 m0, s100, 0x1c000
	s_nop 0
	global_load_lds_dwordx4 v174, s[86:87]
	v_add_u32_e32 v174, s94, v138
	s_add_i32 m0, s100, 0x1e000
	s_nop 0
	global_load_lds_dwordx4 v174, s[86:87]
	s_waitcnt vmcnt(6)
	s_barrier
	s_setprio 1
	v_mfma_f32_16x16x32_bf16 v[28:31], v[190:193], v[232:235], v[28:31]
	v_mfma_f32_16x16x32_bf16 v[24:27], v[190:193], v[240:243], v[24:27]
	v_mfma_f32_16x16x32_bf16 v[20:23], v[208:211], v[232:235], v[20:23]
	v_mfma_f32_16x16x32_bf16 v[16:19], v[208:211], v[240:243], v[16:19]
	v_mfma_f32_16x16x32_bf16 v[12:15], v[216:219], v[232:235], v[12:15]
	v_mfma_f32_16x16x32_bf16 v[8:11], v[216:219], v[240:243], v[8:11]
	v_mfma_f32_16x16x32_bf16 v[4:7], v[224:227], v[232:235], v[4:7]
	v_mfma_f32_16x16x32_bf16 v[0:3], v[224:227], v[240:243], v[0:3]
	v_mfma_f32_16x16x32_bf16 v[28:31], v[196:199], v[236:239], v[28:31]
	v_mfma_f32_16x16x32_bf16 v[24:27], v[196:199], v[244:247], v[24:27]
	v_mfma_f32_16x16x32_bf16 v[20:23], v[212:215], v[236:239], v[20:23]
	v_mfma_f32_16x16x32_bf16 v[16:19], v[212:215], v[244:247], v[16:19]
	v_mfma_f32_16x16x32_bf16 v[12:15], v[220:223], v[236:239], v[12:15]
	v_mfma_f32_16x16x32_bf16 v[8:11], v[220:223], v[244:247], v[8:11]
	v_mfma_f32_16x16x32_bf16 v[4:7], v[228:231], v[236:239], v[4:7]
	v_mfma_f32_16x16x32_bf16 v[0:3], v[228:231], v[244:247], v[0:3]
	s_setprio 0
	s_add_i32 s0, s0, 2
	v_lshl_add_u64 v[134:135], v[134:135], 0, s[80:81]
	v_lshl_add_u64 v[136:137], v[136:137], 0, s[80:81]
	v_lshl_add_u64 v[138:139], v[138:139], 0, s[80:81]
	s_cmp_lt_u32 s0, 4
	v_lshl_add_u64 v[140:141], v[140:141], 0, s[80:81]
	s_barrier
	s_cbranch_scc1 .LBB0_141
	s_or_b32 s0, s6, 0x80
	s_ashr_i32 s1, s0, 31
	s_lshl_b64 s[0:1], s[0:1], 10
	s_add_u32 s0, s28, s0
	s_addc_u32 s1, s29, s1
	ds_read_b128 v[134:137], v157
	ds_read_b128 v[138:141], v157 offset:1024
	ds_read_b128 v[150:153], v157 offset:2048
	ds_read_b128 v[174:177], v157 offset:3072
	ds_read_b128 v[178:181], v147
	ds_read_b128 v[182:185], v147 offset:1024
	ds_read_b128 v[186:189], v146
	ds_read_b128 v[190:193], v146 offset:1024
	ds_read_b128 v[196:199], v145
	ds_read_b128 v[208:211], v145 offset:1024
	ds_read_b128 v[212:215], v144
	ds_read_b128 v[216:219], v144 offset:1024
	v_lshl_add_u64 v[156:157], v[166:167], 1, s[0:1]
	s_mov_b64 s[6:7], 0x380
	v_lshl_add_u64 v[156:157], v[156:157], 0, s[6:7]
	s_add_i32 m0, s100, 0xc000
	v_lshl_add_u64 v[132:133], v[132:133], 1, s[0:1]
	global_load_lds_dwordx4 v[156:157], off
	v_lshl_add_u64 v[132:133], v[132:133], 0, s[6:7]
	s_add_i32 m0, s100, 0xe000
	s_nop 0
	global_load_lds_dwordx4 v[132:133], off
	s_barrier
; #define P8_LDA(dst,b,h) _Pragma("unroll") for(int m=0;m<4;++m) _Pragma("unroll") for(int k=0;k<2;++k) \
;     dst[m][k]=*reinterpret_cast<const bf16x8*>((char*)P8_SA(b,h)+lds_byte(wr*64+m*16+fr,k*32+fq*8))
; #define P8_LDB(dst,b,h) _Pragma("unroll") for(int n=0;n<2;++n) _Pragma("unroll") for(int k=0;k<2;++k) \
;     dst[n][k]=*reinterpret_cast<const bf16x8*>((char*)P8_SB(b,h)+lds_byte(wc*32+n*16+fr,k*32+fq*8))
; #define P8_MMA(ai,bj,At,Bt) do{__builtin_amdgcn_s_setprio(1); \
;     _Pragma("unroll") for(int m=0;m<4;++m) _Pragma("unroll") for(int n=0;n<2;++n) _Pragma("unroll") for(int k=0;k<2;++k) \
;       acc[ai][bj][m][n]=__builtin_amdgcn_mfma_f32_16x16x32_bf16(At[m][k],Bt[n][k],acc[ai][bj][m][n],0,0,0); \
;     __builtin_amdgcn_s_setprio(0);}while(0)
; #define P8_WAIT_V(n) asm volatile("s_waitcnt vmcnt(" #n ")":::"memory")
; #define P8_WAIT_L(n) asm volatile("s_waitcnt lgkmcnt(" #n ")":::"memory")
; #define P8_BAR __builtin_amdgcn_s_barrier()
; template <class EPI>
; DEVI void gemm8_tile(const bfr* __restrict__ A, const bfr* __restrict__ Bt, int K, int brow, int bcol, int nbrow, int nbcol, char* shmc, EPI epi) {
;     ...
;     P8_BAR; P8_WAIT_L(0); P8_MMA(0,0,At,B0); P8_BAR;
;     P8_LDB(B1,0,1); P8_BAR; P8_WAIT_L(0); P8_MMA(0,1,At,B1); P8_BAR;
;     P8_LDA(At,0,1); P8_WAIT_V(4); P8_BAR; P8_WAIT_L(0); P8_MMA(1,0,At,B0); P8_MMA(1,1,At,B1); P8_BAR; }
;   { P8_LDB(B0,1,0); P8_LDA(At,1,0); P8_WAIT_V(2); P8_BAR; P8_WAIT_L(0); P8_MMA(0,0,At,B0); P8_BAR;
	s_waitcnt lgkmcnt(0)
	s_setprio 1
	s_waitcnt lgkmcnt(0)
	v_mfma_f32_16x16x32_bf16 v[124:127], v[178:181], v[134:137], v[124:127]
	v_mfma_f32_16x16x32_bf16 v[120:123], v[178:181], v[150:153], v[120:123]
	v_mfma_f32_16x16x32_bf16 v[116:119], v[186:189], v[134:137], v[116:119]
	v_mfma_f32_16x16x32_bf16 v[112:115], v[186:189], v[150:153], v[112:115]
	v_mfma_f32_16x16x32_bf16 v[108:111], v[196:199], v[134:137], v[108:111]
	v_mfma_f32_16x16x32_bf16 v[104:107], v[196:199], v[150:153], v[104:107]
	v_mfma_f32_16x16x32_bf16 v[100:103], v[212:215], v[134:137], v[100:103]
	v_mfma_f32_16x16x32_bf16 v[96:99], v[212:215], v[150:153], v[96:99]
	v_mfma_f32_16x16x32_bf16 v[124:127], v[182:185], v[138:141], v[124:127]
	v_mfma_f32_16x16x32_bf16 v[120:123], v[182:185], v[174:177], v[120:123]
	v_mfma_f32_16x16x32_bf16 v[116:119], v[190:193], v[138:141], v[116:119]
	v_mfma_f32_16x16x32_bf16 v[112:115], v[190:193], v[174:177], v[112:115]
	v_mfma_f32_16x16x32_bf16 v[108:111], v[208:211], v[138:141], v[108:111]
	v_mfma_f32_16x16x32_bf16 v[104:107], v[208:211], v[174:177], v[104:107]
	v_mfma_f32_16x16x32_bf16 v[100:103], v[216:219], v[138:141], v[100:103]
	v_mfma_f32_16x16x32_bf16 v[96:99], v[216:219], v[174:177], v[96:99]
	s_setprio 0
	s_barrier
	ds_read_b128 v[220:223], v154
	ds_read_b128 v[224:227], v154 offset:1024
	ds_read_b128 v[228:231], v154 offset:2048
	ds_read_b128 v[154:157], v154 offset:3072
	s_barrier
	s_waitcnt lgkmcnt(0)
	s_setprio 1
	s_waitcnt lgkmcnt(0)
	v_mfma_f32_16x16x32_bf16 v[88:91], v[178:181], v[228:231], v[88:91]
	v_mfma_f32_16x16x32_bf16 v[76:79], v[196:199], v[220:223], v[76:79]
	v_mfma_f32_16x16x32_bf16 v[72:75], v[196:199], v[228:231], v[72:75]
	v_mfma_f32_16x16x32_bf16 v[68:71], v[212:215], v[220:223], v[68:71]
	v_mfma_f32_16x16x32_bf16 v[64:67], v[212:215], v[228:231], v[64:67]
	v_mfma_f32_16x16x32_bf16 v[92:95], v[178:181], v[220:223], v[92:95]
	v_mfma_f32_16x16x32_bf16 v[178:181], v[182:185], v[154:157], v[88:91]
	v_mfma_f32_16x16x32_bf16 v[84:87], v[186:189], v[220:223], v[84:87]
	v_mfma_f32_16x16x32_bf16 v[80:83], v[186:189], v[228:231], v[80:83]
	v_mfma_f32_16x16x32_bf16 v[76:79], v[208:211], v[224:227], v[76:79]
	v_mfma_f32_16x16x32_bf16 v[72:75], v[208:211], v[154:157], v[72:75]
	v_mfma_f32_16x16x32_bf16 v[68:71], v[216:219], v[224:227], v[68:71]
	v_mfma_f32_16x16x32_bf16 v[64:67], v[216:219], v[154:157], v[64:67]
	v_mfma_f32_16x16x32_bf16 v[232:235], v[182:185], v[224:227], v[92:95]
	v_mfma_f32_16x16x32_bf16 v[182:185], v[190:193], v[224:227], v[84:87]
	v_mfma_f32_16x16x32_bf16 v[186:189], v[190:193], v[154:157], v[80:83]
	s_setprio 0
	s_barrier
	s_nop 0
	ds_read_b128 v[80:83], v147 offset:16384
	ds_read_b128 v[84:87], v147 offset:17408
	ds_read_b128 v[88:91], v146 offset:16384
	ds_read_b128 v[92:95], v146 offset:17408
	ds_read_b128 v[190:193], v145 offset:16384
	ds_read_b128 v[196:199], v145 offset:17408
	ds_read_b128 v[208:211], v144 offset:16384
	ds_read_b128 v[212:215], v144 offset:17408
	s_waitcnt vmcnt(4)
	s_barrier
	s_waitcnt lgkmcnt(0)
	s_setprio 1
	s_waitcnt lgkmcnt(0)
	v_mfma_f32_16x16x32_bf16 v[44:47], v[190:193], v[134:137], v[44:47]
	v_mfma_f32_16x16x32_bf16 v[40:43], v[190:193], v[150:153], v[40:43]
	v_mfma_f32_16x16x32_bf16 v[36:39], v[208:211], v[134:137], v[36:39]
	v_mfma_f32_16x16x32_bf16 v[32:35], v[208:211], v[150:153], v[32:35]
	v_mfma_f32_16x16x32_bf16 v[60:63], v[80:83], v[134:137], v[60:63]
	v_mfma_f32_16x16x32_bf16 v[56:59], v[80:83], v[150:153], v[56:59]
	v_mfma_f32_16x16x32_bf16 v[52:55], v[88:91], v[134:137], v[52:55]
	v_mfma_f32_16x16x32_bf16 v[48:51], v[88:91], v[150:153], v[48:51]
	v_mfma_f32_16x16x32_bf16 v[44:47], v[196:199], v[138:141], v[44:47]
	v_mfma_f32_16x16x32_bf16 v[40:43], v[196:199], v[174:177], v[40:43]
	v_mfma_f32_16x16x32_bf16 v[36:39], v[212:215], v[138:141], v[36:39]
	v_mfma_f32_16x16x32_bf16 v[32:35], v[212:215], v[174:177], v[32:35]
	v_mfma_f32_16x16x32_bf16 v[216:219], v[84:87], v[138:141], v[60:63]
	v_mfma_f32_16x16x32_bf16 v[236:239], v[84:87], v[174:177], v[56:59]
	v_mfma_f32_16x16x32_bf16 v[240:243], v[92:95], v[138:141], v[52:55]
	v_mfma_f32_16x16x32_bf16 v[244:247], v[92:95], v[174:177], v[48:51]
	s_setprio 0
	s_setprio 1
	v_mfma_f32_16x16x32_bf16 v[12:15], v[190:193], v[220:223], v[12:15]
	v_mfma_f32_16x16x32_bf16 v[4:7], v[208:211], v[220:223], v[4:7]
	v_mfma_f32_16x16x32_bf16 v[28:31], v[80:83], v[220:223], v[28:31]
	v_mfma_f32_16x16x32_bf16 v[24:27], v[80:83], v[228:231], v[24:27]
	v_mfma_f32_16x16x32_bf16 v[20:23], v[88:91], v[220:223], v[20:23]
	v_mfma_f32_16x16x32_bf16 v[16:19], v[88:91], v[228:231], v[16:19]
	v_mfma_f32_16x16x32_bf16 v[12:15], v[196:199], v[224:227], v[12:15]
	v_mfma_f32_16x16x32_bf16 v[8:11], v[190:193], v[228:231], v[8:11]
	v_mfma_f32_16x16x32_bf16 v[4:7], v[212:215], v[224:227], v[4:7]
	v_mfma_f32_16x16x32_bf16 v[0:3], v[208:211], v[228:231], v[0:3]
	v_mfma_f32_16x16x32_bf16 v[132:135], v[84:87], v[224:227], v[28:31]
	v_mfma_f32_16x16x32_bf16 v[136:139], v[84:87], v[154:157], v[24:27]
	v_mfma_f32_16x16x32_bf16 v[150:153], v[92:95], v[224:227], v[20:23]
	v_mfma_f32_16x16x32_bf16 v[172:175], v[92:95], v[154:157], v[16:19]
	v_mfma_f32_16x16x32_bf16 v[190:193], v[196:199], v[154:157], v[8:11]
	v_mfma_f32_16x16x32_bf16 v[154:157], v[212:215], v[154:157], v[0:3]
	s_setprio 0
	s_barrier
	s_nop 0
	ds_read_b128 v[0:3], v149
	ds_read_b128 v[8:11], v149 offset:1024
	ds_read_b128 v[196:199], v149 offset:2048
	ds_read_b128 v[208:211], v149 offset:3072
	ds_read_b128 v[16:19], v147 offset:32768
	ds_read_b128 v[20:23], v147 offset:33792
	ds_read_b128 v[24:27], v146 offset:32768
	ds_read_b128 v[48:51], v146 offset:33792
	ds_read_b128 v[212:215], v145 offset:32768
	ds_read_b128 v[220:223], v145 offset:33792
	ds_read_b128 v[224:227], v144 offset:32768
	ds_read_b128 v[228:231], v144 offset:33792
	s_waitcnt vmcnt(2)
	s_barrier
; #define P8_STAGE(P,BASE,br,kt) do{const bfr* _ub=(BASE)+((long)(br)*K+(long)(kt)*BK); \
;     __builtin_amdgcn_global_load_lds((const unsigned*)(_ub+so0),(unsigned*)((char*)(P)+wid*1024),16,0,0); \
;     __builtin_amdgcn_global_load_lds((const unsigned*)(_ub+so1),(unsigned*)((char*)(P)+wid*1024+8192),16,0,0);}while(0)
; #define P8_LDA(dst,b,h) _Pragma("unroll") for(int m=0;m<4;++m) _Pragma("unroll") for(int k=0;k<2;++k) \
;     dst[m][k]=*reinterpret_cast<const bf16x8*>((char*)P8_SA(b,h)+lds_byte(wr*64+m*16+fr,k*32+fq*8))
; #define P8_LDB(dst,b,h) _Pragma("unroll") for(int n=0;n<2;++n) _Pragma("unroll") for(int k=0;k<2;++k) \
;     dst[n][k]=*reinterpret_cast<const bf16x8*>((char*)P8_SB(b,h)+lds_byte(wc*32+n*16+fr,k*32+fq*8))
; #define P8_MMA(ai,bj,At,Bt) do{__builtin_amdgcn_s_setprio(1); \
;     _Pragma("unroll") for(int m=0;m<4;++m) _Pragma("unroll") for(int n=0;n<2;++n) _Pragma("unroll") for(int k=0;k<2;++k) \
;       acc[ai][bj][m][n]=__builtin_amdgcn_mfma_f32_16x16x32_bf16(At[m][k],Bt[n][k],acc[ai][bj][m][n],0,0,0); \
;     __builtin_amdgcn_s_setprio(0);}while(0)
; #define P8_WAIT_V(n) asm volatile("s_waitcnt vmcnt(" #n ")":::"memory")
; #define P8_WAIT_L(n) asm volatile("s_waitcnt lgkmcnt(" #n ")":::"memory")
; #define P8_BAR __builtin_amdgcn_s_barrier()
; template <class EPI>
; DEVI void gemm8_tile(const bfr* __restrict__ A, const bfr* __restrict__ Bt, int K, int brow, int bcol, int nbrow, int nbcol, char* shmc, EPI epi) {
;     ...
;   { P8_LDB(B0,1,0); P8_LDA(At,1,0); P8_WAIT_V(2); P8_BAR; P8_WAIT_L(0); P8_MMA(0,0,At,B0); P8_BAR;
;     P8_LDB(B1,1,1); P8_WAIT_V(0); P8_BAR; P8_WAIT_L(0); P8_MMA(0,1,At,B1); P8_BAR;
;     P8_LDA(At,1,1); P8_BAR; P8_WAIT_L(0); P8_MMA(1,0,At,B0); P8_MMA(1,1,At,B1); P8_BAR; }
;   if(wr==0)P8_BAR;
;   if (nbrow >= 0) {
;     P8_STAGE(P8_SB(0,0),Bt,nbcol,0); P8_STAGE(P8_SA(0,0),A,nbrow,0);
;     P8_STAGE(P8_SB(0,1),Bt,nbcol+128,0); P8_STAGE(P8_SA(0,1),A,nbrow+128,0);
;   }
	s_waitcnt lgkmcnt(0)
	s_setprio 1
	s_waitcnt lgkmcnt(0)
	v_mfma_f32_16x16x32_bf16 v[28:31], v[16:19], v[0:3], v[124:127]
	v_mfma_f32_16x16x32_bf16 v[124:127], v[20:23], v[8:11], v[28:31]
	v_mfma_f32_16x16x32_bf16 v[28:31], v[16:19], v[196:199], v[120:123]
	v_mfma_f32_16x16x32_bf16 v[92:95], v[20:23], v[208:211], v[28:31]
	v_mfma_f32_16x16x32_bf16 v[28:31], v[24:27], v[0:3], v[116:119]
	v_mfma_f32_16x16x32_bf16 v[120:123], v[48:51], v[8:11], v[28:31]
	v_mfma_f32_16x16x32_bf16 v[28:31], v[24:27], v[196:199], v[112:115]
	v_mfma_f32_16x16x32_bf16 v[88:91], v[48:51], v[208:211], v[28:31]
	v_mfma_f32_16x16x32_bf16 v[28:31], v[212:215], v[0:3], v[108:111]
	v_mfma_f32_16x16x32_bf16 v[116:119], v[220:223], v[8:11], v[28:31]
	v_mfma_f32_16x16x32_bf16 v[28:31], v[212:215], v[196:199], v[104:107]
	v_mfma_f32_16x16x32_bf16 v[84:87], v[220:223], v[208:211], v[28:31]
	v_mfma_f32_16x16x32_bf16 v[28:31], v[224:227], v[0:3], v[100:103]
	v_mfma_f32_16x16x32_bf16 v[112:115], v[228:231], v[8:11], v[28:31]
	v_mfma_f32_16x16x32_bf16 v[28:31], v[224:227], v[196:199], v[96:99]
	v_mfma_f32_16x16x32_bf16 v[80:83], v[228:231], v[208:211], v[28:31]
	s_setprio 0
	s_barrier
	ds_read_b128 v[248:251], v148
	ds_read_b128 v[200:203], v148 offset:1024
	ds_read_b128 v[204:207], v148 offset:2048
	s_nop 1
	ds_read_b128 v[28:31], v148 offset:3072
	s_waitcnt vmcnt(0)
	s_barrier
	s_waitcnt lgkmcnt(0)
	s_setprio 1
	s_waitcnt lgkmcnt(0)
	v_mfma_f32_16x16x32_bf16 v[52:55], v[16:19], v[248:251], v[232:235]
	v_mfma_f32_16x16x32_bf16 v[16:19], v[16:19], v[204:207], v[178:181]
	v_mfma_f32_16x16x32_bf16 v[176:179], v[20:23], v[28:31], v[16:19]
	v_mfma_f32_16x16x32_bf16 v[16:19], v[24:27], v[248:251], v[182:185]
	v_mfma_f32_16x16x32_bf16 v[56:59], v[48:51], v[200:203], v[16:19]
	v_mfma_f32_16x16x32_bf16 v[16:19], v[24:27], v[204:207], v[186:189]
	v_mfma_f32_16x16x32_bf16 v[24:27], v[48:51], v[28:31], v[16:19]
	v_mfma_f32_16x16x32_bf16 v[16:19], v[212:215], v[248:251], v[76:79]
	v_mfma_f32_16x16x32_bf16 v[60:63], v[20:23], v[200:203], v[52:55]
	v_mfma_f32_16x16x32_bf16 v[52:55], v[220:223], v[200:203], v[16:19]
	v_mfma_f32_16x16x32_bf16 v[16:19], v[212:215], v[204:207], v[72:75]
	v_mfma_f32_16x16x32_bf16 v[20:23], v[220:223], v[28:31], v[16:19]
	v_mfma_f32_16x16x32_bf16 v[16:19], v[224:227], v[248:251], v[68:71]
	v_mfma_f32_16x16x32_bf16 v[48:51], v[228:231], v[200:203], v[16:19]
	v_mfma_f32_16x16x32_bf16 v[16:19], v[224:227], v[204:207], v[64:67]
	v_mfma_f32_16x16x32_bf16 v[16:19], v[228:231], v[28:31], v[16:19]
	s_setprio 0
	s_barrier
	ds_read_b128 v[180:183], v147 offset:49152
	ds_read_b128 v[184:187], v147 offset:50176
	ds_read_b128 v[212:215], v146 offset:49152
	ds_read_b128 v[146:149], v146 offset:50176
	ds_read_b128 v[220:223], v145 offset:49152
	ds_read_b128 v[224:227], v145 offset:50176
	ds_read_b128 v[228:231], v144 offset:49152
	ds_read_b128 v[232:235], v144 offset:50176
	s_barrier
	s_waitcnt lgkmcnt(0)
	s_setprio 1
	s_waitcnt lgkmcnt(0)
	v_mfma_f32_16x16x32_bf16 v[64:67], v[180:183], v[0:3], v[216:219]
	v_mfma_f32_16x16x32_bf16 v[104:107], v[184:187], v[8:11], v[64:67]
	v_mfma_f32_16x16x32_bf16 v[64:67], v[180:183], v[196:199], v[236:239]
	v_mfma_f32_16x16x32_bf16 v[72:75], v[184:187], v[208:211], v[64:67]
	v_mfma_f32_16x16x32_bf16 v[64:67], v[212:215], v[0:3], v[240:243]
	v_mfma_f32_16x16x32_bf16 v[44:47], v[220:223], v[0:3], v[44:47]
	v_mfma_f32_16x16x32_bf16 v[0:3], v[228:231], v[0:3], v[36:39]
	v_mfma_f32_16x16x32_bf16 v[96:99], v[146:149], v[8:11], v[64:67]
	v_mfma_f32_16x16x32_bf16 v[64:67], v[212:215], v[196:199], v[244:247]
	v_mfma_f32_16x16x32_bf16 v[40:43], v[220:223], v[196:199], v[40:43]
	v_mfma_f32_16x16x32_bf16 v[100:103], v[232:235], v[8:11], v[0:3]
	v_mfma_f32_16x16x32_bf16 v[0:3], v[228:231], v[196:199], v[32:35]
	v_mfma_f32_16x16x32_bf16 v[64:67], v[146:149], v[208:211], v[64:67]
	v_mfma_f32_16x16x32_bf16 v[108:111], v[224:227], v[8:11], v[44:47]
	v_mfma_f32_16x16x32_bf16 v[76:79], v[224:227], v[208:211], v[40:43]
	v_mfma_f32_16x16x32_bf16 v[68:71], v[232:235], v[208:211], v[0:3]
	s_setprio 0
	s_setprio 1
	v_mfma_f32_16x16x32_bf16 v[0:3], v[180:183], v[248:251], v[132:135]
	v_mfma_f32_16x16x32_bf16 v[40:43], v[184:187], v[200:203], v[0:3]
	v_mfma_f32_16x16x32_bf16 v[0:3], v[180:183], v[204:207], v[136:139]
	v_mfma_f32_16x16x32_bf16 v[8:11], v[184:187], v[28:31], v[0:3]
	v_mfma_f32_16x16x32_bf16 v[0:3], v[212:215], v[248:251], v[150:153]
	v_mfma_f32_16x16x32_bf16 v[12:15], v[220:223], v[248:251], v[12:15]
	v_mfma_f32_16x16x32_bf16 v[4:7], v[228:231], v[248:251], v[4:7]
	v_mfma_f32_16x16x32_bf16 v[32:35], v[146:149], v[200:203], v[0:3]
	v_mfma_f32_16x16x32_bf16 v[0:3], v[212:215], v[204:207], v[172:175]
	v_mfma_f32_16x16x32_bf16 v[44:47], v[224:227], v[200:203], v[12:15]
	v_mfma_f32_16x16x32_bf16 v[12:15], v[220:223], v[204:207], v[190:193]
	v_mfma_f32_16x16x32_bf16 v[36:39], v[232:235], v[200:203], v[4:7]
	v_mfma_f32_16x16x32_bf16 v[4:7], v[228:231], v[204:207], v[154:157]
	v_mfma_f32_16x16x32_bf16 v[0:3], v[146:149], v[28:31], v[0:3]
	v_mfma_f32_16x16x32_bf16 v[12:15], v[224:227], v[28:31], v[12:15]
	v_mfma_f32_16x16x32_bf16 v[4:7], v[232:235], v[28:31], v[4:7]
	s_setprio 0
	v_cmp_gt_u32_e32 vcc, s57, v142
	s_barrier
	s_and_saveexec_b64 s[0:1], vcc
	s_cbranch_execz .LBB0_144
	s_barrier
.LBB0_144:
	s_or_b64 exec, exec, s[0:1]
	s_lshl_b32 s2, s65, 8
	s_and_b64 s[0:1], s[4:5], exec
	s_cselect_b32 s58, s2, -1
	s_cmp_lt_i32 s58, 0
	s_cbranch_scc1 .LBB0_146
	s_lshl_b32 s0, s68, 8
	s_ashr_i32 s1, s0, 31
	s_lshl_b64 s[4:5], s[0:1], 10
	s_add_u32 s4, s84, s4
	s_addc_u32 s5, s85, s5
	v_lshl_add_u64 v[28:29], s[4:5], 0, v[128:129]
	s_add_i32 m0, s100, 0x10000
	v_readfirstlane_b32 s1, v159
	global_load_lds_dwordx4 v[28:29], off
	v_lshl_add_u64 v[28:29], s[4:5], 0, v[130:131]
	s_lshl_b64 s[4:5], s[58:59], 10
	s_add_u32 s4, s28, s4
	s_mov_b32 m0, s1
	s_addc_u32 s5, s29, s5
	global_load_lds_dwordx4 v[28:29], off
	v_lshl_add_u64 v[28:29], s[4:5], 0, v[128:129]
	s_mov_b32 m0, s100
	s_bitset1_b32 s0, 7
	global_load_lds_dwordx4 v[28:29], off
	s_add_i32 m0, s100, 0x2000
	s_ashr_i32 s1, s0, 31
	s_lshl_b64 s[0:1], s[0:1], 10
	s_add_u32 s0, s84, s0
	v_lshl_add_u64 v[28:29], s[4:5], 0, v[130:131]
	s_addc_u32 s1, s85, s1
	global_load_lds_dwordx4 v[28:29], off
	v_lshl_add_u64 v[28:29], s[0:1], 0, v[128:129]
	s_add_i32 m0, s100, 0x14000
	s_addk_i32 s58, 0x80
	global_load_lds_dwordx4 v[28:29], off
	v_lshl_add_u64 v[28:29], s[0:1], 0, v[130:131]
	s_add_i32 m0, s100, 0x16000
	s_lshl_b64 s[0:1], s[58:59], 10
	s_add_u32 s0, s28, s0
	s_addc_u32 s1, s29, s1
	v_readfirstlane_b32 s2, v163
	global_load_lds_dwordx4 v[28:29], off
	v_lshl_add_u64 v[28:29], s[0:1], 0, v[128:129]
	s_mov_b32 m0, s2
	s_nop 0
	global_load_lds_dwordx4 v[28:29], off
	v_lshl_add_u64 v[28:29], s[0:1], 0, v[130:131]
	v_readfirstlane_b32 s0, v170
	s_mov_b32 m0, s0
	s_nop 0
	global_load_lds_dwordx4 v[28:29], off

; #define P8_STAGE(P,BASE,br,kt) do{const bfr* _ub=(BASE)+((long)(br)*K+(long)(kt)*BK); \
;     __builtin_amdgcn_global_load_lds((const unsigned*)(_ub+so0),(unsigned*)((char*)(P)+wid*1024),16,0,0); \
;     __builtin_amdgcn_global_load_lds((const unsigned*)(_ub+so1),(unsigned*)((char*)(P)+wid*1024+8192),16,0,0);}while(0)
; #define P8_WAIT_V(n) asm volatile("s_waitcnt vmcnt(" #n ")":::"memory")
; #define P8_BAR __builtin_amdgcn_s_barrier()
; template <class EPI>
; DEVI void gemm8_tile(const bfr* __restrict__ A, const bfr* __restrict__ Bt, int K, int brow, int bcol, int nbrow, int nbcol, char* shmc, EPI epi) {
;     ...
;   unsigned so0, so1;
;   { int _r, _c; stage_rc(tid * 16, _r, _c); so0 = (unsigned)(_r * K + _c); stage_rc(tid * 16 + 8192, _r, _c); so1 = (unsigned)(_r * K + _c); }
;   f32x4 acc[2][2][4][2];
; #pragma unroll
;   for (int a = 0; a < 2; ++a)
; #pragma unroll
;     for (int b = 0; b < 2; ++b)
; #pragma unroll
;       for (int m = 0; m < 4; ++m)
; #pragma unroll
;         for (int n = 0; n < 2; ++n) acc[a][b][m][n] = f32x4{0.f, 0.f, 0.f, 0.f};
;   bf16x8 At[4][2], B0[2][2], B1[2][2];
;   const int nt = K / BK;
;   if(wr==1)P8_BAR;
;   P8_WAIT_V(4); P8_BAR;
;   P8_STAGE(P8_SB(1,0),Bt,bcol,1); P8_STAGE(P8_SA(1,0),A,brow,1); P8_STAGE(P8_SB(1,1),Bt,bcol+128,1);
;   P8_WAIT_V(6); P8_BAR;
.LBB0_174:
	s_or_b64 exec, exec, s[0:1]
	v_lshlrev_b32_e32 v2, 4, v142
	v_and_b32_e32 v3, 32, v142
	s_lshl_b32 s4, s2, 8
	v_lshrrev_b32_e32 v7, 1, v142
	v_bitop3_b32 v3, v2, v3, 48 bitop3:0x6c
	v_add_u32_e32 v2, 0x2000, v2
	v_ashrrev_i32_e32 v4, 3, v142
	v_bfe_u32 v5, v142, 2, 4
	s_mov_b32 s0, 0x7ffff0
	v_lshrrev_b32_e32 v8, 1, v3
	v_ashrrev_i32_e32 v9, 7, v2
	v_and_b32_e32 v7, 32, v7
	s_ashr_i32 s5, s4, 31
	s_lshl_b32 s34, s69, 8
	v_ashrrev_i32_e32 v1, 6, v142
	v_and_or_b32 v6, v4, s0, v5
	v_and_or_b32 v2, v9, s0, v5
	v_or_b32_e32 v3, v8, v7
	s_lshl_b64 s[0:1], s[4:5], 10
	v_readlane_b32 s72, v255, 28
	v_lshl_or_b32 v166, v6, 9, v3
	v_readlane_b32 s73, v255, 29
	s_add_u32 s54, s72, s0
	v_lshlrev_b32_e32 v143, 10, v1
	s_nop 0
	v_readfirstlane_b32 s100, v143
	s_nop 3
	s_addc_u32 s55, s73, s1
	v_lshlrev_b64 v[128:129], 1, v[166:167]
	v_add_u32_e32 v150, 0x18000, v143
	v_lshl_or_b32 v132, v2, 9, v3
	v_lshl_add_u64 v[2:3], s[54:55], 0, v[128:129]
	v_mov_b32_e32 v133, v167
	v_lshl_add_u64 v[2:3], v[2:3], 0, s[62:63]
	s_add_i32 m0, s100, 0x18000
	v_lshlrev_b64 v[130:131], 1, v[132:133]
	s_ashr_i32 s35, s34, 31
	s_waitcnt vmcnt(4)
	s_barrier
	global_load_lds_dwordx4 v[2:3], off
	v_lshl_add_u64 v[2:3], s[54:55], 0, v[130:131]
	v_add_u32_e32 v151, 0x1a000, v143
	s_lshl_b64 s[54:55], s[34:35], 10
	v_readfirstlane_b32 s2, v151
	s_add_u32 s60, s29, s54
	v_lshl_add_u64 v[2:3], v[2:3], 0, s[62:63]
	s_mov_b32 m0, s2
	s_addc_u32 s61, s64, s55
	v_add_u32_e32 v152, 0x8000, v143
	global_load_lds_dwordx4 v[2:3], off
	v_lshl_add_u64 v[2:3], s[60:61], 0, v[128:129]
	v_lshl_add_u64 v[2:3], v[2:3], 0, s[62:63]
	s_add_i32 m0, s100, 0x8000
	v_add_u32_e32 v153, 0xa000, v143
	global_load_lds_dwordx4 v[2:3], off
	v_lshl_add_u64 v[2:3], s[60:61], 0, v[130:131]
	s_or_b32 s60, s4, 0x80
	s_ashr_i32 s61, s60, 31
	s_lshl_b64 s[60:61], s[60:61], 10
	v_readfirstlane_b32 s2, v153
	s_add_u32 s60, s72, s60
	v_lshl_add_u64 v[2:3], v[2:3], 0, s[62:63]
	s_mov_b32 m0, s2
	s_addc_u32 s61, s73, s61
	v_add_u32_e32 v155, 0x1c000, v143
	global_load_lds_dwordx4 v[2:3], off
	v_lshl_add_u64 v[2:3], s[60:61], 0, v[128:129]
	v_lshl_add_u64 v[2:3], v[2:3], 0, s[62:63]
	s_add_i32 m0, s100, 0x1c000
	v_add_u32_e32 v156, 0x1e000, v143
	global_load_lds_dwordx4 v[2:3], off
	v_lshl_add_u64 v[2:3], s[60:61], 0, v[130:131]
	v_lshl_add_u64 v[2:3], v[2:3], 0, s[62:63]
	s_add_i32 m0, s100, 0x1e000
	v_and_b32_e32 v10, 15, v142
	global_load_lds_dwordx4 v[2:3], off
	v_lshlrev_b32_e32 v1, 12, v1
	v_and_b32_e32 v11, 48, v142
	v_and_b32_e32 v6, 0x3000, v1
	v_lshlrev_b32_e32 v1, 6, v10
	v_lshlrev_b32_e32 v3, 2, v142
	v_or_b32_e32 v2, v1, v11
	v_and_b32_e32 v3, 32, v3
	s_mov_b32 s2, 0x14000
	v_bitop3_b32 v13, v2, s2, v3 bitop3:0xde
	s_mov_b32 s2, 0x18000
	v_lshlrev_b32_e32 v16, 13, v0
	v_lshlrev_b32_e32 v0, 6, v142
	v_bitop3_b32 v14, v2, s2, v3 bitop3:0xde
	s_mov_b32 s2, 0x1c000
	v_and_b32_e32 v0, 0x3c0, v0
	v_bitop3_b32 v10, v1, v3, v11 bitop3:0x36
	v_bitop3_b32 v15, v2, s2, v3 bitop3:0xde
	v_bitop3_b32 v11, v0, v3, v11 bitop3:0x36
	v_lshlrev_b32_e32 v0, 9, v9
	s_movk_i32 s2, 0xe000
	v_bitop3_b32 v12, v2, s3, v3 bitop3:0xde
	v_and_or_b32 v0, v0, s2, v8
	v_lshlrev_b32_e32 v2, 9, v5
	v_lshlrev_b32_e32 v3, 9, v4
	s_add_u32 s54, s96, s54
	v_or3_b32 v0, v0, v2, v7
	v_mov_b32_e32 v1, v167
	v_and_or_b32 v3, v3, s2, v8
	s_waitcnt vmcnt(6)
	s_addc_u32 s55, s97, s55
	v_lshlrev_b64 v[0:1], 1, v[0:1]
	v_or3_b32 v2, v3, v2, v7
	v_mov_b32_e32 v3, v167
	v_or_b32_e32 v17, 0x800, v16
	v_or_b32_e32 v18, 0x1000, v16
	v_or_b32_e32 v19, 0x1800, v16
	v_lshl_add_u64 v[134:135], s[54:55], 0, v[0:1]
	v_lshlrev_b64 v[2:3], 1, v[2:3]
	v_lshl_add_u64 v[138:139], s[0:1], 0, v[0:1]
	v_mov_b32_e32 v0, 0
	s_mov_b64 s[6:7], s[96:97]
	v_lshl_add_u64 v[136:137], s[54:55], 0, v[2:3]
	v_lshl_add_u64 v[140:141], s[0:1], 0, v[2:3]
	s_mov_b32 s0, -2
	v_add_u32_e32 v157, v12, v6
	v_add_u32_e32 v147, v10, v16
	v_add_u32_e32 v146, v11, v17
	v_add_u32_e32 v145, v11, v18
	v_add_u32_e32 v144, v11, v19
	v_add_u32_e32 v154, v13, v6
	v_add_u32_e32 v149, v14, v6
	v_add_u32_e32 v148, v15, v6
	v_mov_b32_e32 v1, v0
	v_mov_b32_e32 v2, v0
	v_mov_b32_e32 v3, v0
	v_mov_b32_e32 v4, v0
	v_mov_b32_e32 v5, v0
	v_mov_b32_e32 v6, v0
	v_mov_b32_e32 v7, v0
	v_mov_b32_e32 v8, v0
	v_mov_b32_e32 v9, v0
	v_mov_b32_e32 v10, v0
	v_mov_b32_e32 v11, v0
	v_mov_b32_e32 v12, v0
	v_mov_b32_e32 v13, v0
	v_mov_b32_e32 v14, v0
	v_mov_b32_e32 v15, v0
	v_mov_b32_e32 v16, v0
	v_mov_b32_e32 v17, v0
	v_mov_b32_e32 v18, v0
	v_mov_b32_e32 v19, v0
	v_mov_b32_e32 v20, v0
	v_mov_b32_e32 v21, v0
	v_mov_b32_e32 v22, v0
	v_mov_b32_e32 v23, v0
	v_mov_b32_e32 v24, v0
	v_mov_b32_e32 v25, v0
	v_mov_b32_e32 v26, v0
	v_mov_b32_e32 v27, v0
	v_mov_b32_e32 v28, v0
	v_mov_b32_e32 v29, v0
	v_mov_b32_e32 v30, v0
	v_mov_b32_e32 v31, v0
	v_mov_b32_e32 v32, v0
	v_mov_b32_e32 v33, v0
	v_mov_b32_e32 v34, v0
	v_mov_b32_e32 v35, v0
	v_mov_b32_e32 v36, v0
	v_mov_b32_e32 v37, v0
	v_mov_b32_e32 v38, v0
	v_mov_b32_e32 v39, v0
	v_mov_b32_e32 v40, v0
	v_mov_b32_e32 v41, v0
	v_mov_b32_e32 v42, v0
	v_mov_b32_e32 v43, v0
	v_mov_b32_e32 v44, v0
	v_mov_b32_e32 v45, v0
	v_mov_b32_e32 v46, v0
	v_mov_b32_e32 v47, v0
	v_mov_b32_e32 v48, v0
	v_mov_b32_e32 v49, v0
	v_mov_b32_e32 v50, v0
	v_mov_b32_e32 v51, v0
	v_mov_b32_e32 v52, v0
	v_mov_b32_e32 v53, v0
	v_mov_b32_e32 v54, v0
	v_mov_b32_e32 v55, v0
	v_mov_b32_e32 v56, v0
	v_mov_b32_e32 v57, v0
	v_mov_b32_e32 v58, v0
	v_mov_b32_e32 v59, v0
	v_mov_b32_e32 v60, v0
	v_mov_b32_e32 v61, v0
	v_mov_b32_e32 v62, v0
	v_mov_b32_e32 v63, v0
	v_mov_b32_e32 v64, v0
	v_mov_b32_e32 v65, v0
	v_mov_b32_e32 v66, v0
	v_mov_b32_e32 v67, v0
	v_mov_b32_e32 v68, v0
	v_mov_b32_e32 v69, v0
	v_mov_b32_e32 v70, v0
; #define P8_STAGE(P,BASE,br,kt) do{const bfr* _ub=(BASE)+((long)(br)*K+(long)(kt)*BK); \
;     __builtin_amdgcn_global_load_lds((const unsigned*)(_ub+so0),(unsigned*)((char*)(P)+wid*1024),16,0,0); \
;     __builtin_amdgcn_global_load_lds((const unsigned*)(_ub+so1),(unsigned*)((char*)(P)+wid*1024+8192),16,0,0);}while(0)
; #define P8_LDA(dst,b,h) _Pragma("unroll") for(int m=0;m<4;++m) _Pragma("unroll") for(int k=0;k<2;++k) \
;     dst[m][k]=*reinterpret_cast<const bf16x8*>((char*)P8_SA(b,h)+lds_byte(wr*64+m*16+fr,k*32+fq*8))
; #define P8_LDB(dst,b,h) _Pragma("unroll") for(int n=0;n<2;++n) _Pragma("unroll") for(int k=0;k<2;++k) \
;     dst[n][k]=*reinterpret_cast<const bf16x8*>((char*)P8_SB(b,h)+lds_byte(wc*32+n*16+fr,k*32+fq*8))
; #define P8_MMA(ai,bj,At,Bt) do{__builtin_amdgcn_s_setprio(1); \
;     _Pragma("unroll") for(int m=0;m<4;++m) _Pragma("unroll") for(int n=0;n<2;++n) _Pragma("unroll") for(int k=0;k<2;++k) \
;       acc[ai][bj][m][n]=__builtin_amdgcn_mfma_f32_16x16x32_bf16(At[m][k],Bt[n][k],acc[ai][bj][m][n],0,0,0); \
;     __builtin_amdgcn_s_setprio(0);}while(0)
; #define P8_WAIT_L(n) asm volatile("s_waitcnt lgkmcnt(" #n ")":::"memory")
; #define P8_BAR __builtin_amdgcn_s_barrier()
; #define P8_SCHED __builtin_amdgcn_sched_barrier(0)
; template <class EPI>
; DEVI void gemm8_tile(const bfr* __restrict__ A, const bfr* __restrict__ Bt, int K, int brow, int bcol, int nbrow, int nbcol, char* shmc, EPI epi) {
;     ...
;   for(int t=0;t<nt-2;t+=2){
;     P8_LDB(B0,0,0); P8_SCHED; P8_LDA(At,0,0); P8_STAGE(P8_SA(1,1),A,brow+128,t+1);
;     P8_WAIT_L(8); P8_BAR; P8_WAIT_L(0); P8_MMA(0,0,At,B0); P8_BAR; P8_SCHED;
;     P8_LDB(B1,0,1); P8_STAGE(P8_SB(0,0),Bt,bcol,t+2);
;     P8_BAR; P8_WAIT_L(0); P8_MMA(0,1,At,B1); P8_BAR;
;     P8_LDA(At,0,1); P8_STAGE(P8_SA(0,0),A,brow,t+2);
;     P8_BAR; P8_WAIT_L(0); P8_MMA(1,0,At,B0); P8_BAR; P8_SCHED;
	v_mov_b32_e32 v71, v0
	v_mov_b32_e32 v72, v0
	v_mov_b32_e32 v73, v0
	v_mov_b32_e32 v74, v0
	v_mov_b32_e32 v75, v0
	v_mov_b32_e32 v76, v0
	v_mov_b32_e32 v77, v0
	v_mov_b32_e32 v78, v0
	v_mov_b32_e32 v79, v0
	v_mov_b32_e32 v80, v0
	v_mov_b32_e32 v81, v0
	v_mov_b32_e32 v82, v0
	v_mov_b32_e32 v83, v0
	v_mov_b32_e32 v84, v0
	v_mov_b32_e32 v85, v0
	v_mov_b32_e32 v86, v0
	v_mov_b32_e32 v87, v0
	v_mov_b32_e32 v88, v0
	v_mov_b32_e32 v89, v0
	v_mov_b32_e32 v90, v0
	v_mov_b32_e32 v91, v0
	v_mov_b32_e32 v92, v0
	v_mov_b32_e32 v93, v0
	v_mov_b32_e32 v94, v0
	v_mov_b32_e32 v95, v0
	v_mov_b32_e32 v96, v0
	v_mov_b32_e32 v97, v0
	v_mov_b32_e32 v98, v0
	v_mov_b32_e32 v99, v0
	v_mov_b32_e32 v100, v0
	v_mov_b32_e32 v101, v0
	v_mov_b32_e32 v102, v0
	v_mov_b32_e32 v103, v0
	v_mov_b32_e32 v104, v0
	v_mov_b32_e32 v105, v0
	v_mov_b32_e32 v106, v0
	v_mov_b32_e32 v107, v0
	v_mov_b32_e32 v108, v0
	v_mov_b32_e32 v109, v0
	v_mov_b32_e32 v110, v0
	v_mov_b32_e32 v111, v0
	v_mov_b32_e32 v112, v0
	v_mov_b32_e32 v113, v0
	v_mov_b32_e32 v114, v0
	v_mov_b32_e32 v115, v0
	v_mov_b32_e32 v116, v0
	v_mov_b32_e32 v117, v0
	v_mov_b32_e32 v118, v0
	v_mov_b32_e32 v119, v0
	v_mov_b32_e32 v120, v0
	v_mov_b32_e32 v121, v0
	v_mov_b32_e32 v122, v0
	v_mov_b32_e32 v123, v0
	v_mov_b32_e32 v124, v0
	v_mov_b32_e32 v125, v0
	v_mov_b32_e32 v126, v0
	v_mov_b32_e32 v127, v0
	s_mov_b64 s[54:55], 0x1220080
	s_mov_b64 s[60:61], 0x15e90100
	s_mov_b64 s[72:73], 0x1200100
	s_mov_b64 s[82:83], 0x15eb0100
	s_mov_b64 s[92:93], 0x1220100
	s_mov_b64 s[94:95], 0x15e90180
	s_mov_b64 vcc, 0x1200180
	s_mov_b64 s[96:97], 0x15eb0180
	s_barrier
.LBB0_175:
	ds_read_b128 v[174:177], v157
	ds_read_b128 v[178:181], v157 offset:1024
	ds_read_b128 v[182:185], v157 offset:2048
	ds_read_b128 v[186:189], v157 offset:3072
	v_add_u32_e32 v171, 0xc000, v143
	v_add_u32_e32 v172, 0xe000, v143
	v_add_u32_e32 v158, s54, v136
	s_add_i32 m0, s100, 0xc000
	ds_read_b128 v[160:163], v147
	ds_read_b128 v[190:193], v147 offset:1024
	ds_read_b128 v[196:199], v146
	ds_read_b128 v[200:203], v146 offset:1024
	ds_read_b128 v[204:207], v145
	ds_read_b128 v[208:211], v145 offset:1024
	ds_read_b128 v[212:215], v144
	ds_read_b128 v[216:219], v144 offset:1024
	global_load_lds_dwordx4 v158, s[86:87]
	v_add_u32_e32 v158, s54, v134
	s_add_i32 m0, s100, 0xe000
	s_nop 0
	global_load_lds_dwordx4 v158, s[86:87]
	s_waitcnt lgkmcnt(8)
	s_barrier
	s_waitcnt lgkmcnt(0)
	s_setprio 1
	s_waitcnt lgkmcnt(0)
	v_mfma_f32_16x16x32_bf16 v[124:127], v[160:163], v[174:177], v[124:127]
	v_mfma_f32_16x16x32_bf16 v[120:123], v[160:163], v[182:185], v[120:123]
	v_mfma_f32_16x16x32_bf16 v[116:119], v[196:199], v[174:177], v[116:119]
	v_mfma_f32_16x16x32_bf16 v[112:115], v[196:199], v[182:185], v[112:115]
	v_mfma_f32_16x16x32_bf16 v[108:111], v[204:207], v[174:177], v[108:111]
	v_mfma_f32_16x16x32_bf16 v[104:107], v[204:207], v[182:185], v[104:107]
	v_mfma_f32_16x16x32_bf16 v[100:103], v[212:215], v[174:177], v[100:103]
	v_mfma_f32_16x16x32_bf16 v[96:99], v[212:215], v[182:185], v[96:99]
	v_mfma_f32_16x16x32_bf16 v[124:127], v[190:193], v[178:181], v[124:127]
	v_mfma_f32_16x16x32_bf16 v[120:123], v[190:193], v[186:189], v[120:123]
	v_mfma_f32_16x16x32_bf16 v[116:119], v[200:203], v[178:181], v[116:119]
	v_mfma_f32_16x16x32_bf16 v[112:115], v[200:203], v[186:189], v[112:115]
	v_mfma_f32_16x16x32_bf16 v[108:111], v[208:211], v[178:181], v[108:111]
	v_mfma_f32_16x16x32_bf16 v[104:107], v[208:211], v[186:189], v[104:107]
	v_mfma_f32_16x16x32_bf16 v[100:103], v[216:219], v[178:181], v[100:103]
	v_mfma_f32_16x16x32_bf16 v[96:99], v[216:219], v[186:189], v[96:99]
	s_setprio 0
	s_barrier
	v_add_u32_e32 v158, 0x10000, v143
	v_add_u32_e32 v159, 0x12000, v143
	v_add_u32_e32 v236, s60, v140
	s_add_i32 m0, s100, 0x10000
	ds_read_b128 v[220:223], v154
	ds_read_b128 v[224:227], v154 offset:1024
	ds_read_b128 v[228:231], v154 offset:2048
	ds_read_b128 v[232:235], v154 offset:3072
	global_load_lds_dwordx4 v236, s[86:87]
	v_add_u32_e32 v236, s60, v138
	s_add_i32 m0, s100, 0x12000
	s_nop 0
	global_load_lds_dwordx4 v236, s[86:87]
	s_barrier
	s_waitcnt lgkmcnt(0)
	s_setprio 1
	s_waitcnt lgkmcnt(0)
	v_mfma_f32_16x16x32_bf16 v[92:95], v[160:163], v[220:223], v[92:95]
	v_mfma_f32_16x16x32_bf16 v[88:91], v[160:163], v[228:231], v[88:91]
	v_mfma_f32_16x16x32_bf16 v[84:87], v[196:199], v[220:223], v[84:87]
	v_mfma_f32_16x16x32_bf16 v[80:83], v[196:199], v[228:231], v[80:83]
	v_mfma_f32_16x16x32_bf16 v[76:79], v[204:207], v[220:223], v[76:79]
	v_mfma_f32_16x16x32_bf16 v[72:75], v[204:207], v[228:231], v[72:75]
	v_mfma_f32_16x16x32_bf16 v[68:71], v[212:215], v[220:223], v[68:71]
	v_mfma_f32_16x16x32_bf16 v[64:67], v[212:215], v[228:231], v[64:67]
	v_mfma_f32_16x16x32_bf16 v[92:95], v[190:193], v[224:227], v[92:95]
	v_mfma_f32_16x16x32_bf16 v[88:91], v[190:193], v[232:235], v[88:91]
	v_mfma_f32_16x16x32_bf16 v[84:87], v[200:203], v[224:227], v[84:87]
	v_mfma_f32_16x16x32_bf16 v[80:83], v[200:203], v[232:235], v[80:83]
	v_mfma_f32_16x16x32_bf16 v[76:79], v[208:211], v[224:227], v[76:79]
	v_mfma_f32_16x16x32_bf16 v[72:75], v[208:211], v[232:235], v[72:75]
	v_mfma_f32_16x16x32_bf16 v[68:71], v[216:219], v[224:227], v[68:71]
	v_mfma_f32_16x16x32_bf16 v[64:67], v[216:219], v[232:235], v[64:67]
	s_setprio 0
	v_add_u32_e32 v160, s72, v136
	s_mov_b32 m0, s100
	s_barrier
	ds_read_b128 v[190:193], v147 offset:16384
	ds_read_b128 v[196:199], v147 offset:17408
	ds_read_b128 v[200:203], v146 offset:16384
	ds_read_b128 v[204:207], v146 offset:17408
	ds_read_b128 v[208:211], v145 offset:16384
	ds_read_b128 v[212:215], v145 offset:17408
	ds_read_b128 v[216:219], v144 offset:16384
	ds_read_b128 v[236:239], v144 offset:17408
	global_load_lds_dwordx4 v160, s[86:87]
	v_add_u32_e32 v160, 0x2000, v143
	v_add_u32_e32 v162, s72, v134
	s_add_i32 m0, s100, 0x2000
	s_nop 0
	global_load_lds_dwordx4 v162, s[86:87]
	s_barrier
; #define P8_STAGE(P,BASE,br,kt) do{const bfr* _ub=(BASE)+((long)(br)*K+(long)(kt)*BK); \
;     __builtin_amdgcn_global_load_lds((const unsigned*)(_ub+so0),(unsigned*)((char*)(P)+wid*1024),16,0,0); \
;     __builtin_amdgcn_global_load_lds((const unsigned*)(_ub+so1),(unsigned*)((char*)(P)+wid*1024+8192),16,0,0);}while(0)
; #define P8_LDA(dst,b,h) _Pragma("unroll") for(int m=0;m<4;++m) _Pragma("unroll") for(int k=0;k<2;++k) \
;     dst[m][k]=*reinterpret_cast<const bf16x8*>((char*)P8_SA(b,h)+lds_byte(wr*64+m*16+fr,k*32+fq*8))
; #define P8_LDB(dst,b,h) _Pragma("unroll") for(int n=0;n<2;++n) _Pragma("unroll") for(int k=0;k<2;++k) \
;     dst[n][k]=*reinterpret_cast<const bf16x8*>((char*)P8_SB(b,h)+lds_byte(wc*32+n*16+fr,k*32+fq*8))
; #define P8_MMA(ai,bj,At,Bt) do{__builtin_amdgcn_s_setprio(1); \
;     _Pragma("unroll") for(int m=0;m<4;++m) _Pragma("unroll") for(int n=0;n<2;++n) _Pragma("unroll") for(int k=0;k<2;++k) \
;       acc[ai][bj][m][n]=__builtin_amdgcn_mfma_f32_16x16x32_bf16(At[m][k],Bt[n][k],acc[ai][bj][m][n],0,0,0); \
;     __builtin_amdgcn_s_setprio(0);}while(0)
; #define P8_WAIT_V(n) asm volatile("s_waitcnt vmcnt(" #n ")":::"memory")
; #define P8_WAIT_L(n) asm volatile("s_waitcnt lgkmcnt(" #n ")":::"memory")
; #define P8_BAR __builtin_amdgcn_s_barrier()
; #define P8_SCHED __builtin_amdgcn_sched_barrier(0)
; template <class EPI>
; DEVI void gemm8_tile(const bfr* __restrict__ A, const bfr* __restrict__ Bt, int K, int brow, int bcol, int nbrow, int nbcol, char* shmc, EPI epi) {
;     ...
;     P8_BAR; P8_WAIT_L(0); P8_MMA(1,0,At,B0); P8_BAR; P8_SCHED;
;     P8_STAGE(P8_SB(0,1),Bt,bcol+128,t+2);
;     P8_WAIT_V(6); P8_BAR; P8_MMA(1,1,At,B1); P8_BAR;
;     P8_LDB(B0,1,0); P8_SCHED; P8_LDA(At,1,0); P8_STAGE(P8_SA(0,1),A,brow+128,t+2);
;     P8_WAIT_L(8); P8_BAR; P8_WAIT_L(0); P8_MMA(0,0,At,B0); P8_BAR; P8_SCHED;
;     P8_LDB(B1,1,1); P8_STAGE(P8_SB(1,0),Bt,bcol,t+3);
;     P8_BAR; P8_WAIT_L(0); P8_MMA(0,1,At,B1); P8_BAR;
	s_waitcnt lgkmcnt(0)
	s_setprio 1
	s_waitcnt lgkmcnt(0)
	v_mfma_f32_16x16x32_bf16 v[60:63], v[190:193], v[174:177], v[60:63]
	v_mfma_f32_16x16x32_bf16 v[56:59], v[190:193], v[182:185], v[56:59]
	v_mfma_f32_16x16x32_bf16 v[52:55], v[200:203], v[174:177], v[52:55]
	v_mfma_f32_16x16x32_bf16 v[48:51], v[200:203], v[182:185], v[48:51]
	v_mfma_f32_16x16x32_bf16 v[44:47], v[208:211], v[174:177], v[44:47]
	v_mfma_f32_16x16x32_bf16 v[40:43], v[208:211], v[182:185], v[40:43]
	v_mfma_f32_16x16x32_bf16 v[36:39], v[216:219], v[174:177], v[36:39]
	v_mfma_f32_16x16x32_bf16 v[32:35], v[216:219], v[182:185], v[32:35]
	v_mfma_f32_16x16x32_bf16 v[60:63], v[196:199], v[178:181], v[60:63]
	v_mfma_f32_16x16x32_bf16 v[56:59], v[196:199], v[186:189], v[56:59]
	v_mfma_f32_16x16x32_bf16 v[52:55], v[204:207], v[178:181], v[52:55]
	v_mfma_f32_16x16x32_bf16 v[48:51], v[204:207], v[186:189], v[48:51]
	v_mfma_f32_16x16x32_bf16 v[44:47], v[212:215], v[178:181], v[44:47]
	v_mfma_f32_16x16x32_bf16 v[40:43], v[212:215], v[186:189], v[40:43]
	v_mfma_f32_16x16x32_bf16 v[36:39], v[236:239], v[178:181], v[36:39]
	v_mfma_f32_16x16x32_bf16 v[32:35], v[236:239], v[186:189], v[32:35]
	s_setprio 0
	s_barrier
	v_add_u32_e32 v161, 0x14000, v143
	v_add_u32_e32 v162, s82, v140
	s_add_i32 m0, s100, 0x14000
	v_add_u32_e32 v174, s82, v138
	global_load_lds_dwordx4 v162, s[86:87]
	v_add_u32_e32 v162, 0x16000, v143
	s_nop 0
	s_add_i32 m0, s100, 0x16000
	s_nop 0
	global_load_lds_dwordx4 v174, s[86:87]
	s_waitcnt vmcnt(6)
	s_barrier
	s_setprio 1
	v_mfma_f32_16x16x32_bf16 v[28:31], v[190:193], v[220:223], v[28:31]
	v_mfma_f32_16x16x32_bf16 v[24:27], v[190:193], v[228:231], v[24:27]
	v_mfma_f32_16x16x32_bf16 v[20:23], v[200:203], v[220:223], v[20:23]
	v_mfma_f32_16x16x32_bf16 v[16:19], v[200:203], v[228:231], v[16:19]
	v_mfma_f32_16x16x32_bf16 v[12:15], v[208:211], v[220:223], v[12:15]
	v_mfma_f32_16x16x32_bf16 v[8:11], v[208:211], v[228:231], v[8:11]
	v_mfma_f32_16x16x32_bf16 v[4:7], v[216:219], v[220:223], v[4:7]
	v_mfma_f32_16x16x32_bf16 v[0:3], v[216:219], v[228:231], v[0:3]
	v_mfma_f32_16x16x32_bf16 v[28:31], v[196:199], v[224:227], v[28:31]
	v_mfma_f32_16x16x32_bf16 v[24:27], v[196:199], v[232:235], v[24:27]
	v_mfma_f32_16x16x32_bf16 v[20:23], v[204:207], v[224:227], v[20:23]
	v_mfma_f32_16x16x32_bf16 v[16:19], v[204:207], v[232:235], v[16:19]
	v_mfma_f32_16x16x32_bf16 v[12:15], v[212:215], v[224:227], v[12:15]
	v_mfma_f32_16x16x32_bf16 v[8:11], v[212:215], v[232:235], v[8:11]
	v_mfma_f32_16x16x32_bf16 v[4:7], v[236:239], v[224:227], v[4:7]
	v_mfma_f32_16x16x32_bf16 v[0:3], v[236:239], v[232:235], v[0:3]
	s_setprio 0
	s_barrier
	ds_read_b128 v[174:177], v149
	ds_read_b128 v[178:181], v149 offset:1024
	ds_read_b128 v[182:185], v149 offset:2048
	ds_read_b128 v[186:189], v149 offset:3072
	v_add_u32_e32 v163, 0x4000, v143
	v_add_u32_e32 v170, 0x6000, v143
	v_add_u32_e32 v224, s92, v136
	s_add_i32 m0, s100, 0x4000
	ds_read_b128 v[190:193], v147 offset:32768
	ds_read_b128 v[196:199], v147 offset:33792
	ds_read_b128 v[200:203], v146 offset:32768
	ds_read_b128 v[204:207], v146 offset:33792
	ds_read_b128 v[208:211], v145 offset:32768
	ds_read_b128 v[212:215], v145 offset:33792
	ds_read_b128 v[216:219], v144 offset:32768
	ds_read_b128 v[220:223], v144 offset:33792
	global_load_lds_dwordx4 v224, s[86:87]
	v_add_u32_e32 v224, s92, v134
	s_add_i32 m0, s100, 0x6000
	s_nop 0
	global_load_lds_dwordx4 v224, s[86:87]
	s_waitcnt lgkmcnt(8)
	s_barrier
	s_waitcnt lgkmcnt(0)
	s_setprio 1
	s_waitcnt lgkmcnt(0)
	v_mfma_f32_16x16x32_bf16 v[124:127], v[190:193], v[174:177], v[124:127]
	v_mfma_f32_16x16x32_bf16 v[120:123], v[190:193], v[182:185], v[120:123]
	v_mfma_f32_16x16x32_bf16 v[116:119], v[200:203], v[174:177], v[116:119]
	v_mfma_f32_16x16x32_bf16 v[112:115], v[200:203], v[182:185], v[112:115]
	v_mfma_f32_16x16x32_bf16 v[108:111], v[208:211], v[174:177], v[108:111]
	v_mfma_f32_16x16x32_bf16 v[104:107], v[208:211], v[182:185], v[104:107]
	v_mfma_f32_16x16x32_bf16 v[100:103], v[216:219], v[174:177], v[100:103]
	v_mfma_f32_16x16x32_bf16 v[96:99], v[216:219], v[182:185], v[96:99]
	v_mfma_f32_16x16x32_bf16 v[124:127], v[196:199], v[178:181], v[124:127]
	v_mfma_f32_16x16x32_bf16 v[120:123], v[196:199], v[186:189], v[120:123]
	v_mfma_f32_16x16x32_bf16 v[116:119], v[204:207], v[178:181], v[116:119]
	v_mfma_f32_16x16x32_bf16 v[112:115], v[204:207], v[186:189], v[112:115]
	v_mfma_f32_16x16x32_bf16 v[108:111], v[212:215], v[178:181], v[108:111]
	v_mfma_f32_16x16x32_bf16 v[104:107], v[212:215], v[186:189], v[104:107]
	v_mfma_f32_16x16x32_bf16 v[100:103], v[220:223], v[178:181], v[100:103]
	v_mfma_f32_16x16x32_bf16 v[96:99], v[220:223], v[186:189], v[96:99]
	s_setprio 0
	s_barrier
	v_add_u32_e32 v248, s94, v140
	s_add_i32 m0, s100, 0x18000
	ds_read_b128 v[224:227], v148
	ds_read_b128 v[228:231], v148 offset:1024
	ds_read_b128 v[232:235], v148 offset:2048
	ds_read_b128 v[236:239], v148 offset:3072
	global_load_lds_dwordx4 v248, s[86:87]
	v_add_u32_e32 v248, s94, v138
	s_add_i32 m0, s100, 0x1a000
	s_nop 0
	global_load_lds_dwordx4 v248, s[86:87]
	s_barrier
; #define P8_STAGE(P,BASE,br,kt) do{const bfr* _ub=(BASE)+((long)(br)*K+(long)(kt)*BK); \
;     __builtin_amdgcn_global_load_lds((const unsigned*)(_ub+so0),(unsigned*)((char*)(P)+wid*1024),16,0,0); \
;     __builtin_amdgcn_global_load_lds((const unsigned*)(_ub+so1),(unsigned*)((char*)(P)+wid*1024+8192),16,0,0);}while(0)
; #define P8_LDA(dst,b,h) _Pragma("unroll") for(int m=0;m<4;++m) _Pragma("unroll") for(int k=0;k<2;++k) \
;     dst[m][k]=*reinterpret_cast<const bf16x8*>((char*)P8_SA(b,h)+lds_byte(wr*64+m*16+fr,k*32+fq*8))
; #define P8_LDB(dst,b,h) _Pragma("unroll") for(int n=0;n<2;++n) _Pragma("unroll") for(int k=0;k<2;++k) \
;     dst[n][k]=*reinterpret_cast<const bf16x8*>((char*)P8_SB(b,h)+lds_byte(wc*32+n*16+fr,k*32+fq*8))
; #define P8_MMA(ai,bj,At,Bt) do{__builtin_amdgcn_s_setprio(1); \
;     _Pragma("unroll") for(int m=0;m<4;++m) _Pragma("unroll") for(int n=0;n<2;++n) _Pragma("unroll") for(int k=0;k<2;++k) \
;       acc[ai][bj][m][n]=__builtin_amdgcn_mfma_f32_16x16x32_bf16(At[m][k],Bt[n][k],acc[ai][bj][m][n],0,0,0); \
;     __builtin_amdgcn_s_setprio(0);}while(0)
; #define P8_WAIT_V(n) asm volatile("s_waitcnt vmcnt(" #n ")":::"memory")
; #define P8_WAIT_L(n) asm volatile("s_waitcnt lgkmcnt(" #n ")":::"memory")
; #define P8_BAR __builtin_amdgcn_s_barrier()
; #define P8_SCHED __builtin_amdgcn_sched_barrier(0)
; template <class EPI>
; DEVI void gemm8_tile(const bfr* __restrict__ A, const bfr* __restrict__ Bt, int K, int brow, int bcol, int nbrow, int nbcol, char* shmc, EPI epi) {
;     ...
;     P8_BAR; P8_WAIT_L(0); P8_MMA(0,1,At,B1); P8_BAR;
;     P8_LDA(At,1,1); P8_STAGE(P8_SA(1,0),A,brow,t+3);
;     P8_BAR; P8_WAIT_L(0); P8_MMA(1,0,At,B0); P8_BAR; P8_SCHED;
;     P8_STAGE(P8_SB(1,1),Bt,bcol+128,t+3);
;     P8_WAIT_V(6); P8_BAR; P8_MMA(1,1,At,B1); P8_BAR;
;   }
;   { P8_LDB(B0,0,0); P8_LDA(At,0,0); P8_STAGE(P8_SA(1,1),A,brow+128,nt-1);
;     P8_BAR; P8_WAIT_L(0); P8_MMA(0,0,At,B0); P8_BAR;
	s_waitcnt lgkmcnt(0)
	s_setprio 1
	s_waitcnt lgkmcnt(0)
	v_mfma_f32_16x16x32_bf16 v[92:95], v[190:193], v[224:227], v[92:95]
	v_mfma_f32_16x16x32_bf16 v[88:91], v[190:193], v[232:235], v[88:91]
	v_mfma_f32_16x16x32_bf16 v[84:87], v[200:203], v[224:227], v[84:87]
	v_mfma_f32_16x16x32_bf16 v[80:83], v[200:203], v[232:235], v[80:83]
	v_mfma_f32_16x16x32_bf16 v[76:79], v[208:211], v[224:227], v[76:79]
	v_mfma_f32_16x16x32_bf16 v[72:75], v[208:211], v[232:235], v[72:75]
	v_mfma_f32_16x16x32_bf16 v[68:71], v[216:219], v[224:227], v[68:71]
	v_mfma_f32_16x16x32_bf16 v[64:67], v[216:219], v[232:235], v[64:67]
	v_mfma_f32_16x16x32_bf16 v[92:95], v[196:199], v[228:231], v[92:95]
	v_mfma_f32_16x16x32_bf16 v[88:91], v[196:199], v[236:239], v[88:91]
	v_mfma_f32_16x16x32_bf16 v[84:87], v[204:207], v[228:231], v[84:87]
	v_mfma_f32_16x16x32_bf16 v[80:83], v[204:207], v[236:239], v[80:83]
	v_mfma_f32_16x16x32_bf16 v[76:79], v[212:215], v[228:231], v[76:79]
	v_mfma_f32_16x16x32_bf16 v[72:75], v[212:215], v[236:239], v[72:75]
	v_mfma_f32_16x16x32_bf16 v[68:71], v[220:223], v[228:231], v[68:71]
	v_mfma_f32_16x16x32_bf16 v[64:67], v[220:223], v[236:239], v[64:67]
	s_setprio 0
	v_add_u32_e32 v240, vcc_lo, v136
	s_add_i32 m0, s100, 0x8000
	s_barrier
	ds_read_b128 v[190:193], v147 offset:49152
	ds_read_b128 v[196:199], v147 offset:50176
	ds_read_b128 v[200:203], v146 offset:49152
	ds_read_b128 v[204:207], v146 offset:50176
	ds_read_b128 v[208:211], v145 offset:49152
	ds_read_b128 v[212:215], v145 offset:50176
	ds_read_b128 v[216:219], v144 offset:49152
	ds_read_b128 v[220:223], v144 offset:50176
	global_load_lds_dwordx4 v240, s[86:87]
	v_add_u32_e32 v240, vcc_lo, v134
	s_add_i32 m0, s100, 0xa000
	s_nop 0
	global_load_lds_dwordx4 v240, s[86:87]
	s_barrier
	s_waitcnt lgkmcnt(0)
	s_setprio 1
	s_waitcnt lgkmcnt(0)
	v_mfma_f32_16x16x32_bf16 v[60:63], v[190:193], v[174:177], v[60:63]
	v_mfma_f32_16x16x32_bf16 v[56:59], v[190:193], v[182:185], v[56:59]
	v_mfma_f32_16x16x32_bf16 v[52:55], v[200:203], v[174:177], v[52:55]
	v_mfma_f32_16x16x32_bf16 v[48:51], v[200:203], v[182:185], v[48:51]
	v_mfma_f32_16x16x32_bf16 v[44:47], v[208:211], v[174:177], v[44:47]
	v_mfma_f32_16x16x32_bf16 v[40:43], v[208:211], v[182:185], v[40:43]
	v_mfma_f32_16x16x32_bf16 v[36:39], v[216:219], v[174:177], v[36:39]
	v_mfma_f32_16x16x32_bf16 v[32:35], v[216:219], v[182:185], v[32:35]
	v_mfma_f32_16x16x32_bf16 v[60:63], v[196:199], v[178:181], v[60:63]
	v_mfma_f32_16x16x32_bf16 v[56:59], v[196:199], v[186:189], v[56:59]
	v_mfma_f32_16x16x32_bf16 v[52:55], v[204:207], v[178:181], v[52:55]
	v_mfma_f32_16x16x32_bf16 v[48:51], v[204:207], v[186:189], v[48:51]
	v_mfma_f32_16x16x32_bf16 v[44:47], v[212:215], v[178:181], v[44:47]
	v_mfma_f32_16x16x32_bf16 v[40:43], v[212:215], v[186:189], v[40:43]
	v_mfma_f32_16x16x32_bf16 v[36:39], v[220:223], v[178:181], v[36:39]
	v_mfma_f32_16x16x32_bf16 v[32:35], v[220:223], v[186:189], v[32:35]
	s_setprio 0
	s_barrier
	v_add_u32_e32 v174, s96, v140
	s_add_i32 m0, s100, 0x1c000
	s_nop 0
	global_load_lds_dwordx4 v174, s[86:87]
	v_add_u32_e32 v174, s96, v138
	s_add_i32 m0, s100, 0x1e000
	s_nop 0
	global_load_lds_dwordx4 v174, s[86:87]
	s_waitcnt vmcnt(6)
	s_barrier
	s_setprio 1
	v_mfma_f32_16x16x32_bf16 v[28:31], v[190:193], v[224:227], v[28:31]
	v_mfma_f32_16x16x32_bf16 v[24:27], v[190:193], v[232:235], v[24:27]
	v_mfma_f32_16x16x32_bf16 v[20:23], v[200:203], v[224:227], v[20:23]
	v_mfma_f32_16x16x32_bf16 v[16:19], v[200:203], v[232:235], v[16:19]
	v_mfma_f32_16x16x32_bf16 v[12:15], v[208:211], v[224:227], v[12:15]
	v_mfma_f32_16x16x32_bf16 v[8:11], v[208:211], v[232:235], v[8:11]
	v_mfma_f32_16x16x32_bf16 v[4:7], v[216:219], v[224:227], v[4:7]
	v_mfma_f32_16x16x32_bf16 v[0:3], v[216:219], v[232:235], v[0:3]
	v_mfma_f32_16x16x32_bf16 v[28:31], v[196:199], v[228:231], v[28:31]
	v_mfma_f32_16x16x32_bf16 v[24:27], v[196:199], v[236:239], v[24:27]
	v_mfma_f32_16x16x32_bf16 v[20:23], v[204:207], v[228:231], v[20:23]
	v_mfma_f32_16x16x32_bf16 v[16:19], v[204:207], v[236:239], v[16:19]
	v_mfma_f32_16x16x32_bf16 v[12:15], v[212:215], v[228:231], v[12:15]
	v_mfma_f32_16x16x32_bf16 v[8:11], v[212:215], v[236:239], v[8:11]
	v_mfma_f32_16x16x32_bf16 v[4:7], v[220:223], v[228:231], v[4:7]
	v_mfma_f32_16x16x32_bf16 v[0:3], v[220:223], v[236:239], v[0:3]
	s_setprio 0
	s_add_i32 s0, s0, 2
	v_lshl_add_u64 v[134:135], v[134:135], 0, s[80:81]
	v_lshl_add_u64 v[136:137], v[136:137], 0, s[80:81]
	v_lshl_add_u64 v[138:139], v[138:139], 0, s[80:81]
	s_cmp_lt_u32 s0, 4
	v_lshl_add_u64 v[140:141], v[140:141], 0, s[80:81]
	s_barrier
	s_cbranch_scc1 .LBB0_175
	s_or_b32 s0, s34, 0x80
	s_ashr_i32 s1, s0, 31
	s_lshl_b64 s[0:1], s[0:1], 10
	s_add_u32 s0, s29, s0
	s_addc_u32 s1, s64, s1
	ds_read_b128 v[134:137], v157
	ds_read_b128 v[138:141], v157 offset:1024
	ds_read_b128 v[150:153], v157 offset:2048
	ds_read_b128 v[174:177], v157 offset:3072
	ds_read_b128 v[178:181], v147
	ds_read_b128 v[182:185], v147 offset:1024
	ds_read_b128 v[186:189], v146
	ds_read_b128 v[190:193], v146 offset:1024
	ds_read_b128 v[196:199], v145
	ds_read_b128 v[200:203], v145 offset:1024
	ds_read_b128 v[204:207], v144
	ds_read_b128 v[208:211], v144 offset:1024
	v_lshl_add_u64 v[156:157], v[166:167], 1, s[0:1]
	s_mov_b64 s[34:35], 0x380
	v_lshl_add_u64 v[156:157], v[156:157], 0, s[34:35]
	s_add_i32 m0, s100, 0xc000
	v_lshl_add_u64 v[132:133], v[132:133], 1, s[0:1]
	global_load_lds_dwordx4 v[156:157], off
	v_lshl_add_u64 v[132:133], v[132:133], 0, s[34:35]
	s_add_i32 m0, s100, 0xe000
	s_nop 0
	global_load_lds_dwordx4 v[132:133], off
	s_barrier
; #define P8_LDA(dst,b,h) _Pragma("unroll") for(int m=0;m<4;++m) _Pragma("unroll") for(int k=0;k<2;++k) \
;     dst[m][k]=*reinterpret_cast<const bf16x8*>((char*)P8_SA(b,h)+lds_byte(wr*64+m*16+fr,k*32+fq*8))
; #define P8_LDB(dst,b,h) _Pragma("unroll") for(int n=0;n<2;++n) _Pragma("unroll") for(int k=0;k<2;++k) \
;     dst[n][k]=*reinterpret_cast<const bf16x8*>((char*)P8_SB(b,h)+lds_byte(wc*32+n*16+fr,k*32+fq*8))
; #define P8_MMA(ai,bj,At,Bt) do{__builtin_amdgcn_s_setprio(1); \
;     _Pragma("unroll") for(int m=0;m<4;++m) _Pragma("unroll") for(int n=0;n<2;++n) _Pragma("unroll") for(int k=0;k<2;++k) \
;       acc[ai][bj][m][n]=__builtin_amdgcn_mfma_f32_16x16x32_bf16(At[m][k],Bt[n][k],acc[ai][bj][m][n],0,0,0); \
;     __builtin_amdgcn_s_setprio(0);}while(0)
; #define P8_WAIT_V(n) asm volatile("s_waitcnt vmcnt(" #n ")":::"memory")
; #define P8_WAIT_L(n) asm volatile("s_waitcnt lgkmcnt(" #n ")":::"memory")
; #define P8_BAR __builtin_amdgcn_s_barrier()
; template <class EPI>
; DEVI void gemm8_tile(const bfr* __restrict__ A, const bfr* __restrict__ Bt, int K, int brow, int bcol, int nbrow, int nbcol, char* shmc, EPI epi) {
;     ...
;     P8_BAR; P8_WAIT_L(0); P8_MMA(0,0,At,B0); P8_BAR;
;     P8_LDB(B1,0,1); P8_BAR; P8_WAIT_L(0); P8_MMA(0,1,At,B1); P8_BAR;
;     P8_LDA(At,0,1); P8_WAIT_V(4); P8_BAR; P8_WAIT_L(0); P8_MMA(1,0,At,B0); P8_MMA(1,1,At,B1); P8_BAR; }
;   { P8_LDB(B0,1,0); P8_LDA(At,1,0); P8_WAIT_V(2); P8_BAR; P8_WAIT_L(0); P8_MMA(0,0,At,B0); P8_BAR;
	s_waitcnt lgkmcnt(0)
	s_setprio 1
	s_waitcnt lgkmcnt(0)
	v_mfma_f32_16x16x32_bf16 v[124:127], v[178:181], v[134:137], v[124:127]
	v_mfma_f32_16x16x32_bf16 v[120:123], v[178:181], v[150:153], v[120:123]
	v_mfma_f32_16x16x32_bf16 v[116:119], v[186:189], v[134:137], v[116:119]
	v_mfma_f32_16x16x32_bf16 v[108:111], v[196:199], v[134:137], v[108:111]
	v_mfma_f32_16x16x32_bf16 v[124:127], v[182:185], v[138:141], v[124:127]
	v_mfma_f32_16x16x32_bf16 v[120:123], v[182:185], v[174:177], v[120:123]
	v_mfma_f32_16x16x32_bf16 v[116:119], v[190:193], v[138:141], v[116:119]
	v_mfma_f32_16x16x32_bf16 v[112:115], v[186:189], v[150:153], v[112:115]
	v_mfma_f32_16x16x32_bf16 v[108:111], v[200:203], v[138:141], v[108:111]
	v_mfma_f32_16x16x32_bf16 v[104:107], v[196:199], v[150:153], v[104:107]
	v_mfma_f32_16x16x32_bf16 v[100:103], v[204:207], v[134:137], v[100:103]
	v_mfma_f32_16x16x32_bf16 v[96:99], v[204:207], v[150:153], v[96:99]
	v_mfma_f32_16x16x32_bf16 v[212:215], v[190:193], v[174:177], v[112:115]
	v_mfma_f32_16x16x32_bf16 v[104:107], v[200:203], v[174:177], v[104:107]
	v_mfma_f32_16x16x32_bf16 v[216:219], v[208:211], v[138:141], v[100:103]
	v_mfma_f32_16x16x32_bf16 v[220:223], v[208:211], v[174:177], v[96:99]
	s_setprio 0
	s_barrier
	s_nop 1
	ds_read_b128 v[96:99], v154
	ds_read_b128 v[100:103], v154 offset:1024
	ds_read_b128 v[112:115], v154 offset:2048
	ds_read_b128 v[154:157], v154 offset:3072
	s_barrier
	s_waitcnt lgkmcnt(0)
	s_setprio 1
	s_waitcnt lgkmcnt(0)
	v_mfma_f32_16x16x32_bf16 v[88:91], v[178:181], v[112:115], v[88:91]
	v_mfma_f32_16x16x32_bf16 v[84:87], v[186:189], v[96:99], v[84:87]
	v_mfma_f32_16x16x32_bf16 v[76:79], v[196:199], v[96:99], v[76:79]
	v_mfma_f32_16x16x32_bf16 v[72:75], v[196:199], v[112:115], v[72:75]
	v_mfma_f32_16x16x32_bf16 v[92:95], v[178:181], v[96:99], v[92:95]
	v_mfma_f32_16x16x32_bf16 v[88:91], v[182:185], v[154:157], v[88:91]
	v_mfma_f32_16x16x32_bf16 v[84:87], v[190:193], v[100:103], v[84:87]
	v_mfma_f32_16x16x32_bf16 v[80:83], v[186:189], v[112:115], v[80:83]
	v_mfma_f32_16x16x32_bf16 v[76:79], v[200:203], v[100:103], v[76:79]
	v_mfma_f32_16x16x32_bf16 v[72:75], v[200:203], v[154:157], v[72:75]
	v_mfma_f32_16x16x32_bf16 v[68:71], v[204:207], v[96:99], v[68:71]
	v_mfma_f32_16x16x32_bf16 v[64:67], v[204:207], v[112:115], v[64:67]
	v_mfma_f32_16x16x32_bf16 v[224:227], v[182:185], v[100:103], v[92:95]
	v_mfma_f32_16x16x32_bf16 v[178:181], v[190:193], v[154:157], v[80:83]
	v_mfma_f32_16x16x32_bf16 v[182:185], v[208:211], v[100:103], v[68:71]
	v_mfma_f32_16x16x32_bf16 v[186:189], v[208:211], v[154:157], v[64:67]
	s_setprio 0
	s_barrier
	s_nop 1
	ds_read_b128 v[64:67], v147 offset:16384
	ds_read_b128 v[68:71], v147 offset:17408
	ds_read_b128 v[80:83], v146 offset:16384
	ds_read_b128 v[92:95], v146 offset:17408
	ds_read_b128 v[190:193], v145 offset:16384
	ds_read_b128 v[196:199], v145 offset:17408
	ds_read_b128 v[200:203], v144 offset:16384
	ds_read_b128 v[204:207], v144 offset:17408
	s_waitcnt vmcnt(4)
	s_barrier
	s_waitcnt lgkmcnt(0)
	s_setprio 1
	s_waitcnt lgkmcnt(0)
	v_mfma_f32_16x16x32_bf16 v[60:63], v[64:67], v[134:137], v[60:63]
	v_mfma_f32_16x16x32_bf16 v[56:59], v[64:67], v[150:153], v[56:59]
	v_mfma_f32_16x16x32_bf16 v[52:55], v[80:83], v[134:137], v[52:55]
	v_mfma_f32_16x16x32_bf16 v[40:43], v[190:193], v[150:153], v[40:43]
	v_mfma_f32_16x16x32_bf16 v[36:39], v[200:203], v[134:137], v[36:39]
	v_mfma_f32_16x16x32_bf16 v[208:211], v[68:71], v[138:141], v[60:63]
	v_mfma_f32_16x16x32_bf16 v[56:59], v[68:71], v[174:177], v[56:59]
	v_mfma_f32_16x16x32_bf16 v[52:55], v[92:95], v[138:141], v[52:55]
	v_mfma_f32_16x16x32_bf16 v[48:51], v[80:83], v[150:153], v[48:51]
	v_mfma_f32_16x16x32_bf16 v[44:47], v[190:193], v[134:137], v[44:47]
	v_mfma_f32_16x16x32_bf16 v[40:43], v[196:199], v[174:177], v[40:43]
	v_mfma_f32_16x16x32_bf16 v[36:39], v[204:207], v[138:141], v[36:39]
	v_mfma_f32_16x16x32_bf16 v[32:35], v[200:203], v[150:153], v[32:35]
	v_mfma_f32_16x16x32_bf16 v[228:231], v[92:95], v[174:177], v[48:51]
	v_mfma_f32_16x16x32_bf16 v[232:235], v[196:199], v[138:141], v[44:47]
	v_mfma_f32_16x16x32_bf16 v[132:135], v[204:207], v[174:177], v[32:35]
	s_setprio 0
	s_setprio 1
	v_mfma_f32_16x16x32_bf16 v[24:27], v[64:67], v[112:115], v[24:27]
	v_mfma_f32_16x16x32_bf16 v[20:23], v[80:83], v[96:99], v[20:23]
	v_mfma_f32_16x16x32_bf16 v[8:11], v[190:193], v[112:115], v[8:11]
	v_mfma_f32_16x16x32_bf16 v[28:31], v[64:67], v[96:99], v[28:31]
	v_mfma_f32_16x16x32_bf16 v[24:27], v[68:71], v[154:157], v[24:27]
	v_mfma_f32_16x16x32_bf16 v[20:23], v[92:95], v[100:103], v[20:23]
	v_mfma_f32_16x16x32_bf16 v[16:19], v[80:83], v[112:115], v[16:19]
	v_mfma_f32_16x16x32_bf16 v[12:15], v[190:193], v[96:99], v[12:15]
	v_mfma_f32_16x16x32_bf16 v[8:11], v[196:199], v[154:157], v[8:11]
	v_mfma_f32_16x16x32_bf16 v[4:7], v[200:203], v[96:99], v[4:7]
	v_mfma_f32_16x16x32_bf16 v[0:3], v[200:203], v[112:115], v[0:3]
	v_mfma_f32_16x16x32_bf16 v[136:139], v[68:71], v[100:103], v[28:31]
	v_mfma_f32_16x16x32_bf16 v[150:153], v[92:95], v[154:157], v[16:19]
	v_mfma_f32_16x16x32_bf16 v[172:175], v[196:199], v[100:103], v[12:15]
	v_mfma_f32_16x16x32_bf16 v[190:193], v[204:207], v[100:103], v[4:7]
	v_mfma_f32_16x16x32_bf16 v[154:157], v[204:207], v[154:157], v[0:3]
	s_setprio 0
	s_barrier
	ds_read_b128 v[4:7], v149
	ds_read_b128 v[196:199], v149 offset:1024
	ds_read_b128 v[200:203], v149 offset:2048
	ds_read_b128 v[204:207], v149 offset:3072
	ds_read_b128 v[0:3], v147 offset:32768
	ds_read_b128 v[12:15], v147 offset:33792
	ds_read_b128 v[16:19], v146 offset:32768
	ds_read_b128 v[32:35], v146 offset:33792
	ds_read_b128 v[236:239], v145 offset:32768
	ds_read_b128 v[240:243], v145 offset:33792
	ds_read_b128 v[244:247], v144 offset:32768
	ds_read_b128 v[248:251], v144 offset:33792
	s_waitcnt vmcnt(2)
	s_barrier
; #define P8_STAGE(P,BASE,br,kt) do{const bfr* _ub=(BASE)+((long)(br)*K+(long)(kt)*BK); \
;     __builtin_amdgcn_global_load_lds((const unsigned*)(_ub+so0),(unsigned*)((char*)(P)+wid*1024),16,0,0); \
;     __builtin_amdgcn_global_load_lds((const unsigned*)(_ub+so1),(unsigned*)((char*)(P)+wid*1024+8192),16,0,0);}while(0)
; #define P8_LDA(dst,b,h) _Pragma("unroll") for(int m=0;m<4;++m) _Pragma("unroll") for(int k=0;k<2;++k) \
;     dst[m][k]=*reinterpret_cast<const bf16x8*>((char*)P8_SA(b,h)+lds_byte(wr*64+m*16+fr,k*32+fq*8))
; #define P8_LDB(dst,b,h) _Pragma("unroll") for(int n=0;n<2;++n) _Pragma("unroll") for(int k=0;k<2;++k) \
;     dst[n][k]=*reinterpret_cast<const bf16x8*>((char*)P8_SB(b,h)+lds_byte(wc*32+n*16+fr,k*32+fq*8))
; #define P8_MMA(ai,bj,At,Bt) do{__builtin_amdgcn_s_setprio(1); \
;     _Pragma("unroll") for(int m=0;m<4;++m) _Pragma("unroll") for(int n=0;n<2;++n) _Pragma("unroll") for(int k=0;k<2;++k) \
;       acc[ai][bj][m][n]=__builtin_amdgcn_mfma_f32_16x16x32_bf16(At[m][k],Bt[n][k],acc[ai][bj][m][n],0,0,0); \
;     __builtin_amdgcn_s_setprio(0);}while(0)
; #define P8_WAIT_V(n) asm volatile("s_waitcnt vmcnt(" #n ")":::"memory")
; #define P8_WAIT_L(n) asm volatile("s_waitcnt lgkmcnt(" #n ")":::"memory")
; #define P8_BAR __builtin_amdgcn_s_barrier()
; template <class EPI>
; DEVI void gemm8_tile(const bfr* __restrict__ A, const bfr* __restrict__ Bt, int K, int brow, int bcol, int nbrow, int nbcol, char* shmc, EPI epi) {
;     ...
;   { P8_LDB(B0,1,0); P8_LDA(At,1,0); P8_WAIT_V(2); P8_BAR; P8_WAIT_L(0); P8_MMA(0,0,At,B0); P8_BAR;
;     P8_LDB(B1,1,1); P8_WAIT_V(0); P8_BAR; P8_WAIT_L(0); P8_MMA(0,1,At,B1); P8_BAR;
;     P8_LDA(At,1,1); P8_BAR; P8_WAIT_L(0); P8_MMA(1,0,At,B0); P8_MMA(1,1,At,B1); P8_BAR; }
;   if(wr==0)P8_BAR;
;   if (nbrow >= 0) {
;     P8_STAGE(P8_SB(0,0),Bt,nbcol,0); P8_STAGE(P8_SA(0,0),A,nbrow,0);
;     P8_STAGE(P8_SB(0,1),Bt,nbcol+128,0); P8_STAGE(P8_SA(0,1),A,nbrow+128,0);
;   }
	s_waitcnt lgkmcnt(0)
	s_setprio 1
	s_waitcnt lgkmcnt(0)
	v_mfma_f32_16x16x32_bf16 v[28:31], v[0:3], v[4:7], v[124:127]
	v_mfma_f32_16x16x32_bf16 v[124:127], v[12:15], v[196:199], v[28:31]
	v_mfma_f32_16x16x32_bf16 v[28:31], v[0:3], v[200:203], v[120:123]
	v_mfma_f32_16x16x32_bf16 v[92:95], v[12:15], v[204:207], v[28:31]
	v_mfma_f32_16x16x32_bf16 v[28:31], v[16:19], v[4:7], v[116:119]
	v_mfma_f32_16x16x32_bf16 v[112:115], v[32:35], v[196:199], v[28:31]
	v_mfma_f32_16x16x32_bf16 v[28:31], v[16:19], v[200:203], v[212:215]
	v_mfma_f32_16x16x32_bf16 v[80:83], v[32:35], v[204:207], v[28:31]
	v_mfma_f32_16x16x32_bf16 v[28:31], v[236:239], v[4:7], v[108:111]
	v_mfma_f32_16x16x32_bf16 v[100:103], v[240:243], v[196:199], v[28:31]
	v_mfma_f32_16x16x32_bf16 v[28:31], v[236:239], v[200:203], v[104:107]
	v_mfma_f32_16x16x32_bf16 v[68:71], v[240:243], v[204:207], v[28:31]
	v_mfma_f32_16x16x32_bf16 v[28:31], v[244:247], v[4:7], v[216:219]
	v_mfma_f32_16x16x32_bf16 v[96:99], v[248:251], v[196:199], v[28:31]
	v_mfma_f32_16x16x32_bf16 v[28:31], v[244:247], v[200:203], v[220:223]
	v_mfma_f32_16x16x32_bf16 v[64:67], v[248:251], v[204:207], v[28:31]
	s_setprio 0
	s_barrier
	ds_read_b128 v[212:215], v148
	ds_read_b128 v[216:219], v148 offset:1024
	ds_read_b128 v[220:223], v148 offset:2048
	ds_read_b128 v[104:107], v148 offset:3072
	s_waitcnt vmcnt(0)
	s_barrier
	s_waitcnt lgkmcnt(0)
	s_setprio 1
	s_waitcnt lgkmcnt(0)
	v_mfma_f32_16x16x32_bf16 v[28:31], v[0:3], v[212:215], v[224:227]
	v_mfma_f32_16x16x32_bf16 v[0:3], v[0:3], v[220:223], v[88:91]
	v_mfma_f32_16x16x32_bf16 v[60:63], v[12:15], v[216:219], v[28:31]
	v_mfma_f32_16x16x32_bf16 v[28:31], v[12:15], v[104:107], v[0:3]
	v_mfma_f32_16x16x32_bf16 v[0:3], v[16:19], v[212:215], v[84:87]
	v_mfma_f32_16x16x32_bf16 v[48:51], v[32:35], v[216:219], v[0:3]
	v_mfma_f32_16x16x32_bf16 v[0:3], v[16:19], v[220:223], v[178:181]
	v_mfma_f32_16x16x32_bf16 v[16:19], v[32:35], v[104:107], v[0:3]
	v_mfma_f32_16x16x32_bf16 v[0:3], v[236:239], v[212:215], v[76:79]
	v_mfma_f32_16x16x32_bf16 v[44:47], v[240:243], v[216:219], v[0:3]
	v_mfma_f32_16x16x32_bf16 v[0:3], v[236:239], v[220:223], v[72:75]
	v_mfma_f32_16x16x32_bf16 v[12:15], v[240:243], v[104:107], v[0:3]
	v_mfma_f32_16x16x32_bf16 v[0:3], v[244:247], v[212:215], v[182:185]
	v_mfma_f32_16x16x32_bf16 v[32:35], v[248:251], v[216:219], v[0:3]
	v_mfma_f32_16x16x32_bf16 v[0:3], v[244:247], v[220:223], v[186:189]
	v_mfma_f32_16x16x32_bf16 v[0:3], v[248:251], v[104:107], v[0:3]
	s_setprio 0
	s_barrier
	ds_read_b128 v[176:179], v147 offset:49152
	ds_read_b128 v[180:183], v147 offset:50176
	ds_read_b128 v[184:187], v146 offset:49152
	ds_read_b128 v[146:149], v146 offset:50176
	ds_read_b128 v[224:227], v145 offset:49152
	ds_read_b128 v[236:239], v145 offset:50176
	ds_read_b128 v[240:243], v144 offset:49152
	ds_read_b128 v[244:247], v144 offset:50176
	s_barrier
	s_waitcnt lgkmcnt(0)
	s_setprio 1
	s_waitcnt lgkmcnt(0)
	v_mfma_f32_16x16x32_bf16 v[52:55], v[184:187], v[4:7], v[52:55]
	v_mfma_f32_16x16x32_bf16 v[116:119], v[146:149], v[196:199], v[52:55]
	v_mfma_f32_16x16x32_bf16 v[52:55], v[184:187], v[200:203], v[228:231]
	v_mfma_f32_16x16x32_bf16 v[72:75], v[176:179], v[4:7], v[208:211]
	v_mfma_f32_16x16x32_bf16 v[84:87], v[146:149], v[204:207], v[52:55]
	v_mfma_f32_16x16x32_bf16 v[52:55], v[224:227], v[4:7], v[232:235]
	v_mfma_f32_16x16x32_bf16 v[4:7], v[240:243], v[4:7], v[36:39]
	v_mfma_f32_16x16x32_bf16 v[56:59], v[176:179], v[200:203], v[56:59]
	v_mfma_f32_16x16x32_bf16 v[40:43], v[224:227], v[200:203], v[40:43]
	v_mfma_f32_16x16x32_bf16 v[108:111], v[244:247], v[196:199], v[4:7]
	v_mfma_f32_16x16x32_bf16 v[4:7], v[240:243], v[200:203], v[132:135]
	v_mfma_f32_16x16x32_bf16 v[120:123], v[180:183], v[196:199], v[72:75]
	v_mfma_f32_16x16x32_bf16 v[88:91], v[180:183], v[204:207], v[56:59]
	v_mfma_f32_16x16x32_bf16 v[208:211], v[236:239], v[196:199], v[52:55]
	v_mfma_f32_16x16x32_bf16 v[72:75], v[236:239], v[204:207], v[40:43]
	v_mfma_f32_16x16x32_bf16 v[76:79], v[244:247], v[204:207], v[4:7]
	s_setprio 0
	s_setprio 1
	v_mfma_f32_16x16x32_bf16 v[4:7], v[176:179], v[212:215], v[136:139]
	v_mfma_f32_16x16x32_bf16 v[56:59], v[180:183], v[216:219], v[4:7]
	v_mfma_f32_16x16x32_bf16 v[4:7], v[176:179], v[220:223], v[24:27]
	v_mfma_f32_16x16x32_bf16 v[24:27], v[180:183], v[104:107], v[4:7]
	v_mfma_f32_16x16x32_bf16 v[4:7], v[184:187], v[212:215], v[20:23]
	v_mfma_f32_16x16x32_bf16 v[52:55], v[146:149], v[216:219], v[4:7]
	v_mfma_f32_16x16x32_bf16 v[4:7], v[184:187], v[220:223], v[150:153]
	v_mfma_f32_16x16x32_bf16 v[20:23], v[146:149], v[104:107], v[4:7]
	v_mfma_f32_16x16x32_bf16 v[4:7], v[224:227], v[212:215], v[172:175]
	v_mfma_f32_16x16x32_bf16 v[36:39], v[236:239], v[216:219], v[4:7]
	v_mfma_f32_16x16x32_bf16 v[4:7], v[224:227], v[220:223], v[8:11]
	v_mfma_f32_16x16x32_bf16 v[8:11], v[240:243], v[212:215], v[190:193]
	v_mfma_f32_16x16x32_bf16 v[40:43], v[244:247], v[216:219], v[8:11]
	v_mfma_f32_16x16x32_bf16 v[8:11], v[240:243], v[220:223], v[154:157]
	v_mfma_f32_16x16x32_bf16 v[4:7], v[236:239], v[104:107], v[4:7]
	v_mfma_f32_16x16x32_bf16 v[8:11], v[244:247], v[104:107], v[8:11]
	s_setprio 0
	v_cmp_gt_u32_e32 vcc, s57, v142
	s_barrier
	s_and_saveexec_b64 s[0:1], vcc
	s_cbranch_execz .LBB0_178
	s_barrier
.LBB0_178:
	s_or_b64 exec, exec, s[0:1]
	s_lshl_b32 s2, s65, 8
	s_and_b64 s[0:1], s[10:11], exec
	s_cselect_b32 s58, s2, -1
	s_cmp_lt_i32 s58, 0
	s_mov_b64 s[96:97], s[6:7]
	s_cbranch_scc1 .LBB0_180
	s_lshl_b32 s0, s68, 8
	s_ashr_i32 s1, s0, 31
	s_lshl_b64 s[10:11], s[0:1], 10
	v_readlane_b32 s34, v255, 28
	v_readlane_b32 s35, v255, 29
	s_add_u32 s10, s34, s10
	s_addc_u32 s11, s35, s11
	v_lshl_add_u64 v[104:105], s[10:11], 0, v[128:129]
	s_add_i32 m0, s100, 0x10000
	v_readfirstlane_b32 s1, v159
	global_load_lds_dwordx4 v[104:105], off
	v_lshl_add_u64 v[104:105], s[10:11], 0, v[130:131]
	s_lshl_b64 s[10:11], s[58:59], 10
	s_add_u32 s10, s29, s10
	s_mov_b32 m0, s1
	s_addc_u32 s11, s64, s11
	global_load_lds_dwordx4 v[104:105], off
	v_lshl_add_u64 v[104:105], s[10:11], 0, v[128:129]
	s_mov_b32 m0, s100
	s_bitset1_b32 s0, 7
	global_load_lds_dwordx4 v[104:105], off
	s_add_i32 m0, s100, 0x2000
	s_ashr_i32 s1, s0, 31
	s_lshl_b64 s[0:1], s[0:1], 10
	s_add_u32 s0, s34, s0
	v_lshl_add_u64 v[104:105], s[10:11], 0, v[130:131]
	s_addc_u32 s1, s35, s1
	global_load_lds_dwordx4 v[104:105], off
	v_lshl_add_u64 v[104:105], s[0:1], 0, v[128:129]
	s_add_i32 m0, s100, 0x14000
	s_addk_i32 s58, 0x80
	global_load_lds_dwordx4 v[104:105], off
	v_lshl_add_u64 v[104:105], s[0:1], 0, v[130:131]
	s_add_i32 m0, s100, 0x16000
	s_lshl_b64 s[0:1], s[58:59], 10
	s_add_u32 s0, s29, s0
	s_addc_u32 s1, s64, s1
	v_readfirstlane_b32 s2, v163
	global_load_lds_dwordx4 v[104:105], off
	v_lshl_add_u64 v[104:105], s[0:1], 0, v[128:129]
	s_mov_b32 m0, s2
	s_nop 0
	global_load_lds_dwordx4 v[104:105], off
	v_lshl_add_u64 v[104:105], s[0:1], 0, v[130:131]
	v_readfirstlane_b32 s0, v170
	s_mov_b32 m0, s0
	s_nop 0
	global_load_lds_dwordx4 v[104:105], off

; #define P8_STAGE(P,BASE,br,kt) do{const bfr* _ub=(BASE)+((long)(br)*K+(long)(kt)*BK); \
;     __builtin_amdgcn_global_load_lds((const unsigned*)(_ub+so0),(unsigned*)((char*)(P)+wid*1024),16,0,0); \
;     __builtin_amdgcn_global_load_lds((const unsigned*)(_ub+so1),(unsigned*)((char*)(P)+wid*1024+8192),16,0,0);}while(0)
; #define P8_WAIT_V(n) asm volatile("s_waitcnt vmcnt(" #n ")":::"memory")
; #define P8_BAR __builtin_amdgcn_s_barrier()
; template <class EPI>
; DEVI void gemm8_tile(const bfr* __restrict__ A, const bfr* __restrict__ Bt, int K, int brow, int bcol, int nbrow, int nbcol, char* shmc, EPI epi) {
;     ...
;   unsigned so0, so1;
;   { int _r, _c; stage_rc(tid * 16, _r, _c); so0 = (unsigned)(_r * K + _c); stage_rc(tid * 16 + 8192, _r, _c); so1 = (unsigned)(_r * K + _c); }
;   f32x4 acc[2][2][4][2];
; #pragma unroll
;   for (int a = 0; a < 2; ++a)
; #pragma unroll
;     for (int b = 0; b < 2; ++b)
; #pragma unroll
;       for (int m = 0; m < 4; ++m)
; #pragma unroll
;         for (int n = 0; n < 2; ++n) acc[a][b][m][n] = f32x4{0.f, 0.f, 0.f, 0.f};
;   bf16x8 At[4][2], B0[2][2], B1[2][2];
;   const int nt = K / BK;
;   if(wr==1)P8_BAR;
;   P8_WAIT_V(4); P8_BAR;
;   P8_STAGE(P8_SB(1,0),Bt,bcol,1); P8_STAGE(P8_SA(1,0),A,brow,1); P8_STAGE(P8_SB(1,1),Bt,bcol+128,1);
;   P8_WAIT_V(6); P8_BAR;
.LBB0_220:
	s_or_b64 exec, exec, s[0:1]
	v_lshlrev_b32_e32 v2, 4, v142
	v_and_b32_e32 v3, 32, v142
	s_lshl_b32 s8, s4, 8
	s_lshl_b32 s4, s2, 8
	v_lshrrev_b32_e32 v7, 1, v142
	v_bitop3_b32 v3, v2, v3, 48 bitop3:0x6c
	v_add_u32_e32 v2, 0x2000, v2
	v_ashrrev_i32_e32 v4, 3, v142
	v_bfe_u32 v5, v142, 2, 4
	s_mov_b32 s0, 0x1ffff0
	v_lshrrev_b32_e32 v8, 1, v3
	v_ashrrev_i32_e32 v9, 7, v2
	v_and_b32_e32 v7, 32, v7
	s_ashr_i32 s5, s4, 31
	v_ashrrev_i32_e32 v1, 6, v142
	v_and_or_b32 v6, v4, s0, v5
	v_and_or_b32 v2, v9, s0, v5
	v_or_b32_e32 v3, v8, v7
	s_lshl_b64 s[0:1], s[4:5], 12
	v_lshl_or_b32 v166, v6, 11, v3
	s_add_u32 s54, s84, s0
	v_lshlrev_b32_e32 v143, 10, v1
	s_nop 0
	v_readfirstlane_b32 s100, v143
	s_nop 3
	s_addc_u32 s55, s85, s1
	v_lshlrev_b64 v[128:129], 1, v[166:167]
	v_add_u32_e32 v150, 0x18000, v143
	v_lshl_or_b32 v132, v2, 11, v3
	v_lshl_add_u64 v[2:3], s[54:55], 0, v[128:129]
	v_mov_b32_e32 v133, v167
	v_lshl_add_u64 v[2:3], v[2:3], 0, s[62:63]
	s_add_i32 m0, s100, 0x18000
	v_lshlrev_b64 v[130:131], 1, v[132:133]
	s_ashr_i32 s9, s8, 31
	s_waitcnt vmcnt(4)
	s_barrier
	global_load_lds_dwordx4 v[2:3], off
	v_lshl_add_u64 v[2:3], s[54:55], 0, v[130:131]
	v_add_u32_e32 v151, 0x1a000, v143
	s_lshl_b64 s[54:55], s[8:9], 12
	v_readfirstlane_b32 s2, v151
	s_add_u32 s60, s34, s54
	v_lshl_add_u64 v[2:3], v[2:3], 0, s[62:63]
	s_mov_b32 m0, s2
	s_addc_u32 s61, s35, s55
	v_add_u32_e32 v152, 0x8000, v143
	global_load_lds_dwordx4 v[2:3], off
	v_lshl_add_u64 v[2:3], s[60:61], 0, v[128:129]
	v_lshl_add_u64 v[2:3], v[2:3], 0, s[62:63]
	s_add_i32 m0, s100, 0x8000
	v_add_u32_e32 v153, 0xa000, v143
	global_load_lds_dwordx4 v[2:3], off
	v_lshl_add_u64 v[2:3], s[60:61], 0, v[130:131]
	s_or_b32 s60, s4, 0x80
	s_ashr_i32 s61, s60, 31
	s_lshl_b64 s[60:61], s[60:61], 12
	v_readfirstlane_b32 s2, v153
	s_add_u32 s60, s84, s60
	v_lshl_add_u64 v[2:3], v[2:3], 0, s[62:63]
	s_mov_b32 m0, s2
	s_addc_u32 s61, s85, s61
	v_add_u32_e32 v154, 0x1c000, v143
	global_load_lds_dwordx4 v[2:3], off
	v_lshl_add_u64 v[2:3], s[60:61], 0, v[128:129]
	v_lshl_add_u64 v[2:3], v[2:3], 0, s[62:63]
	s_add_i32 m0, s100, 0x1c000
	v_add_u32_e32 v156, 0x1e000, v143
	global_load_lds_dwordx4 v[2:3], off
	v_lshl_add_u64 v[2:3], s[60:61], 0, v[130:131]
	v_lshl_add_u64 v[2:3], v[2:3], 0, s[62:63]
	s_add_i32 m0, s100, 0x1e000
	v_and_b32_e32 v10, 15, v142
	global_load_lds_dwordx4 v[2:3], off
	v_lshlrev_b32_e32 v1, 12, v1
	v_and_b32_e32 v11, 48, v142
	v_and_b32_e32 v6, 0x3000, v1
	v_lshlrev_b32_e32 v1, 6, v10
	v_lshlrev_b32_e32 v3, 2, v142
	v_or_b32_e32 v2, v1, v11
	v_and_b32_e32 v3, 32, v3
	s_mov_b32 s2, 0x14000
	v_bitop3_b32 v13, v2, s2, v3 bitop3:0xde
	s_mov_b32 s2, 0x18000
	v_lshlrev_b32_e32 v16, 13, v0
	v_lshlrev_b32_e32 v0, 6, v142
	v_bitop3_b32 v14, v2, s2, v3 bitop3:0xde
	s_mov_b32 s2, 0x1c000
	v_and_b32_e32 v0, 0x3c0, v0
	v_bitop3_b32 v10, v1, v3, v11 bitop3:0x36
	v_bitop3_b32 v15, v2, s2, v3 bitop3:0xde
	v_bitop3_b32 v11, v0, v3, v11 bitop3:0x36
	v_lshlrev_b32_e32 v0, 11, v9
	s_movk_i32 s2, 0x8000
	v_bitop3_b32 v12, v2, s3, v3 bitop3:0xde
	v_and_or_b32 v0, v0, s2, v8
	v_lshlrev_b32_e32 v2, 11, v5
	v_lshlrev_b32_e32 v3, 11, v4
	s_add_u32 s54, s29, s54
	v_or3_b32 v0, v0, v2, v7
	v_mov_b32_e32 v1, v167
	v_and_or_b32 v3, v3, s2, v8
	s_waitcnt vmcnt(6)
	s_addc_u32 s55, s28, s55
	v_lshlrev_b64 v[0:1], 1, v[0:1]
	v_or3_b32 v2, v3, v2, v7
	v_mov_b32_e32 v3, v167
	v_or_b32_e32 v17, 0x800, v16
	v_or_b32_e32 v18, 0x1000, v16
	v_or_b32_e32 v19, 0x1800, v16
	v_lshl_add_u64 v[134:135], s[54:55], 0, v[0:1]
	v_lshlrev_b64 v[2:3], 1, v[2:3]
	v_lshl_add_u64 v[138:139], s[0:1], 0, v[0:1]
	v_mov_b32_e32 v0, 0
	v_lshl_add_u64 v[136:137], s[54:55], 0, v[2:3]
	v_lshl_add_u64 v[140:141], s[0:1], 0, v[2:3]
	s_mov_b32 s0, -2
	v_add_u32_e32 v157, v12, v6
	v_add_u32_e32 v147, v10, v16
	v_add_u32_e32 v146, v11, v17
	v_add_u32_e32 v145, v11, v18
	v_add_u32_e32 v144, v11, v19
	v_add_u32_e32 v155, v13, v6
	v_add_u32_e32 v149, v14, v6
	v_add_u32_e32 v148, v15, v6
	v_mov_b32_e32 v1, v0
	v_mov_b32_e32 v2, v0
	v_mov_b32_e32 v3, v0
	v_mov_b32_e32 v4, v0
	v_mov_b32_e32 v5, v0
	v_mov_b32_e32 v6, v0
	v_mov_b32_e32 v7, v0
	v_mov_b32_e32 v8, v0
	v_mov_b32_e32 v9, v0
	v_mov_b32_e32 v10, v0
	v_mov_b32_e32 v11, v0
	v_mov_b32_e32 v12, v0
	v_mov_b32_e32 v13, v0
	v_mov_b32_e32 v14, v0
	v_mov_b32_e32 v15, v0
	v_mov_b32_e32 v16, v0
	v_mov_b32_e32 v17, v0
	v_mov_b32_e32 v18, v0
	v_mov_b32_e32 v19, v0
	v_mov_b32_e32 v20, v0
	v_mov_b32_e32 v21, v0
	v_mov_b32_e32 v22, v0
	v_mov_b32_e32 v23, v0
	v_mov_b32_e32 v24, v0
	v_mov_b32_e32 v25, v0
	v_mov_b32_e32 v26, v0
	v_mov_b32_e32 v27, v0
	v_mov_b32_e32 v28, v0
	v_mov_b32_e32 v29, v0
	v_mov_b32_e32 v30, v0
	v_mov_b32_e32 v31, v0
	v_mov_b32_e32 v32, v0
	v_mov_b32_e32 v33, v0
	v_mov_b32_e32 v34, v0
	v_mov_b32_e32 v35, v0
	v_mov_b32_e32 v36, v0
	v_mov_b32_e32 v37, v0
	v_mov_b32_e32 v38, v0
	v_mov_b32_e32 v39, v0
	v_mov_b32_e32 v40, v0
	v_mov_b32_e32 v41, v0
	v_mov_b32_e32 v42, v0
	v_mov_b32_e32 v43, v0
	v_mov_b32_e32 v44, v0
	v_mov_b32_e32 v45, v0
	v_mov_b32_e32 v46, v0
	v_mov_b32_e32 v47, v0
	v_mov_b32_e32 v48, v0
	v_mov_b32_e32 v49, v0
	v_mov_b32_e32 v50, v0
	v_mov_b32_e32 v51, v0
	v_mov_b32_e32 v52, v0
	v_mov_b32_e32 v53, v0
	v_mov_b32_e32 v54, v0
	v_mov_b32_e32 v55, v0
	v_mov_b32_e32 v56, v0
	v_mov_b32_e32 v57, v0
	v_mov_b32_e32 v58, v0
	v_mov_b32_e32 v59, v0
	v_mov_b32_e32 v60, v0
	v_mov_b32_e32 v61, v0
	v_mov_b32_e32 v62, v0
	v_mov_b32_e32 v63, v0
	v_mov_b32_e32 v64, v0
	v_mov_b32_e32 v65, v0
	v_mov_b32_e32 v66, v0
	v_mov_b32_e32 v67, v0
	v_mov_b32_e32 v68, v0
	v_mov_b32_e32 v69, v0
	v_mov_b32_e32 v70, v0
	v_mov_b32_e32 v71, v0
	v_mov_b32_e32 v72, v0
	v_mov_b32_e32 v73, v0
	v_mov_b32_e32 v74, v0
	v_mov_b32_e32 v75, v0
	v_mov_b32_e32 v76, v0
	v_mov_b32_e32 v77, v0
	v_mov_b32_e32 v78, v0
	v_mov_b32_e32 v79, v0
	v_mov_b32_e32 v80, v0
	v_mov_b32_e32 v81, v0
	v_mov_b32_e32 v82, v0
	v_mov_b32_e32 v83, v0
	v_mov_b32_e32 v84, v0
	v_mov_b32_e32 v85, v0
	v_mov_b32_e32 v86, v0
	v_mov_b32_e32 v87, v0
	v_mov_b32_e32 v88, v0
	v_mov_b32_e32 v89, v0
	v_mov_b32_e32 v90, v0
	v_mov_b32_e32 v91, v0
	v_mov_b32_e32 v92, v0
	v_mov_b32_e32 v93, v0
	v_mov_b32_e32 v94, v0
	v_mov_b32_e32 v95, v0
	v_mov_b32_e32 v96, v0
	v_mov_b32_e32 v97, v0
	v_mov_b32_e32 v98, v0
	v_mov_b32_e32 v99, v0
	v_mov_b32_e32 v100, v0
	v_mov_b32_e32 v101, v0
	v_mov_b32_e32 v102, v0
	v_mov_b32_e32 v103, v0
	v_mov_b32_e32 v104, v0
	v_mov_b32_e32 v105, v0
	v_mov_b32_e32 v106, v0
	v_mov_b32_e32 v107, v0
	v_mov_b32_e32 v108, v0
	v_mov_b32_e32 v109, v0
	v_mov_b32_e32 v110, v0
	v_mov_b32_e32 v111, v0
	v_mov_b32_e32 v112, v0
	v_mov_b32_e32 v113, v0
	v_mov_b32_e32 v114, v0
	v_mov_b32_e32 v115, v0
	v_mov_b32_e32 v116, v0
	v_mov_b32_e32 v117, v0
	v_mov_b32_e32 v118, v0
	v_mov_b32_e32 v119, v0
	v_mov_b32_e32 v120, v0
	v_mov_b32_e32 v121, v0
	v_mov_b32_e32 v122, v0
	v_mov_b32_e32 v123, v0
	v_mov_b32_e32 v124, v0
	v_mov_b32_e32 v125, v0
	v_mov_b32_e32 v126, v0
	v_mov_b32_e32 v127, v0
	s_mov_b64 s[54:55], 0x80080
	s_mov_b64 s[60:61], 0x80100
	s_mov_b64 s[72:73], 0x180
	s_barrier
; #define P8_STAGE(P,BASE,br,kt) do{const bfr* _ub=(BASE)+((long)(br)*K+(long)(kt)*BK); \
;     __builtin_amdgcn_global_load_lds((const unsigned*)(_ub+so0),(unsigned*)((char*)(P)+wid*1024),16,0,0); \
;     __builtin_amdgcn_global_load_lds((const unsigned*)(_ub+so1),(unsigned*)((char*)(P)+wid*1024+8192),16,0,0);}while(0)
; #define P8_LDA(dst,b,h) _Pragma("unroll") for(int m=0;m<4;++m) _Pragma("unroll") for(int k=0;k<2;++k) \
;     dst[m][k]=*reinterpret_cast<const bf16x8*>((char*)P8_SA(b,h)+lds_byte(wr*64+m*16+fr,k*32+fq*8))
; #define P8_LDB(dst,b,h) _Pragma("unroll") for(int n=0;n<2;++n) _Pragma("unroll") for(int k=0;k<2;++k) \
;     dst[n][k]=*reinterpret_cast<const bf16x8*>((char*)P8_SB(b,h)+lds_byte(wc*32+n*16+fr,k*32+fq*8))
; #define P8_MMA(ai,bj,At,Bt) do{__builtin_amdgcn_s_setprio(1); \
;     _Pragma("unroll") for(int m=0;m<4;++m) _Pragma("unroll") for(int n=0;n<2;++n) _Pragma("unroll") for(int k=0;k<2;++k) \
;       acc[ai][bj][m][n]=__builtin_amdgcn_mfma_f32_16x16x32_bf16(At[m][k],Bt[n][k],acc[ai][bj][m][n],0,0,0); \
;     __builtin_amdgcn_s_setprio(0);}while(0)
; #define P8_WAIT_V(n) asm volatile("s_waitcnt vmcnt(" #n ")":::"memory")
; #define P8_WAIT_L(n) asm volatile("s_waitcnt lgkmcnt(" #n ")":::"memory")
; #define P8_BAR __builtin_amdgcn_s_barrier()
; #define P8_SCHED __builtin_amdgcn_sched_barrier(0)
; template <class EPI>
; DEVI void gemm8_tile(const bfr* __restrict__ A, const bfr* __restrict__ Bt, int K, int brow, int bcol, int nbrow, int nbcol, char* shmc, EPI epi) {
;     ...
;   for(int t=0;t<nt-2;t+=2){
;     P8_LDB(B0,0,0); P8_SCHED; P8_LDA(At,0,0); P8_STAGE(P8_SA(1,1),A,brow+128,t+1);
;     P8_WAIT_L(8); P8_BAR; P8_WAIT_L(0); P8_MMA(0,0,At,B0); P8_BAR; P8_SCHED;
;     P8_LDB(B1,0,1); P8_STAGE(P8_SB(0,0),Bt,bcol,t+2);
;     P8_BAR; P8_WAIT_L(0); P8_MMA(0,1,At,B1); P8_BAR;
;     P8_LDA(At,0,1); P8_STAGE(P8_SA(0,0),A,brow,t+2);
;     P8_BAR; P8_WAIT_L(0); P8_MMA(1,0,At,B0); P8_BAR; P8_SCHED;
;     P8_STAGE(P8_SB(0,1),Bt,bcol+128,t+2);
;     P8_WAIT_V(6); P8_BAR; P8_MMA(1,1,At,B1); P8_BAR;
.LBB0_221:
	ds_read_b128 v[174:177], v157
	ds_read_b128 v[178:181], v157 offset:1024
	ds_read_b128 v[182:185], v157 offset:2048
	ds_read_b128 v[186:189], v157 offset:3072
	v_add_u32_e32 v171, 0xc000, v143
	v_add_u32_e32 v172, 0xe000, v143
	v_add_u32_e32 v158, s54, v136
	s_add_i32 m0, s100, 0xc000
	ds_read_b128 v[160:163], v147
	ds_read_b128 v[190:193], v147 offset:1024
	ds_read_b128 v[196:199], v146
	ds_read_b128 v[208:211], v146 offset:1024
	ds_read_b128 v[212:215], v145
	ds_read_b128 v[216:219], v145 offset:1024
	ds_read_b128 v[220:223], v144
	ds_read_b128 v[224:227], v144 offset:1024
	global_load_lds_dwordx4 v158, s[86:87]
	v_add_u32_e32 v158, s54, v134
	s_add_i32 m0, s100, 0xe000
	s_nop 0
	global_load_lds_dwordx4 v158, s[86:87]
	s_waitcnt lgkmcnt(8)
	s_barrier
	s_waitcnt lgkmcnt(0)
	s_setprio 1
	s_waitcnt lgkmcnt(0)
	v_mfma_f32_16x16x32_bf16 v[124:127], v[160:163], v[174:177], v[124:127]
	v_mfma_f32_16x16x32_bf16 v[120:123], v[160:163], v[182:185], v[120:123]
	v_mfma_f32_16x16x32_bf16 v[116:119], v[196:199], v[174:177], v[116:119]
	v_mfma_f32_16x16x32_bf16 v[112:115], v[196:199], v[182:185], v[112:115]
	v_mfma_f32_16x16x32_bf16 v[108:111], v[212:215], v[174:177], v[108:111]
	v_mfma_f32_16x16x32_bf16 v[104:107], v[212:215], v[182:185], v[104:107]
	v_mfma_f32_16x16x32_bf16 v[100:103], v[220:223], v[174:177], v[100:103]
	v_mfma_f32_16x16x32_bf16 v[96:99], v[220:223], v[182:185], v[96:99]
	v_mfma_f32_16x16x32_bf16 v[124:127], v[190:193], v[178:181], v[124:127]
	v_mfma_f32_16x16x32_bf16 v[120:123], v[190:193], v[186:189], v[120:123]
	v_mfma_f32_16x16x32_bf16 v[116:119], v[208:211], v[178:181], v[116:119]
	v_mfma_f32_16x16x32_bf16 v[112:115], v[208:211], v[186:189], v[112:115]
	v_mfma_f32_16x16x32_bf16 v[108:111], v[216:219], v[178:181], v[108:111]
	v_mfma_f32_16x16x32_bf16 v[104:107], v[216:219], v[186:189], v[104:107]
	v_mfma_f32_16x16x32_bf16 v[100:103], v[224:227], v[178:181], v[100:103]
	v_mfma_f32_16x16x32_bf16 v[96:99], v[224:227], v[186:189], v[96:99]
	s_setprio 0
	s_barrier
	v_add_u32_e32 v158, 0x10000, v143
	v_add_u32_e32 v206, s66, v140
	s_add_i32 m0, s100, 0x10000
	v_add_u32_e32 v159, 0x12000, v143
	ds_read_b128 v[228:231], v155
	ds_read_b128 v[232:235], v155 offset:1024
	ds_read_b128 v[236:239], v155 offset:2048
	ds_read_b128 v[240:243], v155 offset:3072
	global_load_lds_dwordx4 v206, s[86:87]
	v_add_u32_e32 v244, s66, v138
	s_add_i32 m0, s100, 0x12000
	s_nop 0
	global_load_lds_dwordx4 v244, s[86:87]
	s_barrier
	s_waitcnt lgkmcnt(0)
	s_setprio 1
	s_waitcnt lgkmcnt(0)
	v_mfma_f32_16x16x32_bf16 v[92:95], v[160:163], v[228:231], v[92:95]
	v_mfma_f32_16x16x32_bf16 v[88:91], v[160:163], v[236:239], v[88:91]
	v_mfma_f32_16x16x32_bf16 v[84:87], v[196:199], v[228:231], v[84:87]
	v_mfma_f32_16x16x32_bf16 v[80:83], v[196:199], v[236:239], v[80:83]
	v_mfma_f32_16x16x32_bf16 v[76:79], v[212:215], v[228:231], v[76:79]
	v_mfma_f32_16x16x32_bf16 v[72:75], v[212:215], v[236:239], v[72:75]
	v_mfma_f32_16x16x32_bf16 v[68:71], v[220:223], v[228:231], v[68:71]
	v_mfma_f32_16x16x32_bf16 v[64:67], v[220:223], v[236:239], v[64:67]
	v_mfma_f32_16x16x32_bf16 v[92:95], v[190:193], v[232:235], v[92:95]
	v_mfma_f32_16x16x32_bf16 v[88:91], v[190:193], v[240:243], v[88:91]
	v_mfma_f32_16x16x32_bf16 v[84:87], v[208:211], v[232:235], v[84:87]
	v_mfma_f32_16x16x32_bf16 v[80:83], v[208:211], v[240:243], v[80:83]
	v_mfma_f32_16x16x32_bf16 v[76:79], v[216:219], v[232:235], v[76:79]
	v_mfma_f32_16x16x32_bf16 v[72:75], v[216:219], v[240:243], v[72:75]
	v_mfma_f32_16x16x32_bf16 v[68:71], v[224:227], v[232:235], v[68:71]
	v_mfma_f32_16x16x32_bf16 v[64:67], v[224:227], v[240:243], v[64:67]
	s_setprio 0
	v_add_u32_e32 v160, s80, v136
	s_mov_b32 m0, s100
	s_barrier
	ds_read_b128 v[190:193], v147 offset:16384
	ds_read_b128 v[196:199], v147 offset:17408
	ds_read_b128 v[208:211], v146 offset:16384
	ds_read_b128 v[212:215], v146 offset:17408
	ds_read_b128 v[216:219], v145 offset:16384
	ds_read_b128 v[220:223], v145 offset:17408
	ds_read_b128 v[224:227], v144 offset:16384
	ds_read_b128 v[244:247], v144 offset:17408
	global_load_lds_dwordx4 v160, s[86:87]
	v_add_u32_e32 v160, 0x2000, v143
	v_add_u32_e32 v162, s80, v134
	s_add_i32 m0, s100, 0x2000
	s_nop 0
	global_load_lds_dwordx4 v162, s[86:87]
	s_barrier
	s_waitcnt lgkmcnt(0)
	s_setprio 1
	s_waitcnt lgkmcnt(0)
	v_mfma_f32_16x16x32_bf16 v[60:63], v[190:193], v[174:177], v[60:63]
	v_mfma_f32_16x16x32_bf16 v[56:59], v[190:193], v[182:185], v[56:59]
	v_mfma_f32_16x16x32_bf16 v[52:55], v[208:211], v[174:177], v[52:55]
	v_mfma_f32_16x16x32_bf16 v[48:51], v[208:211], v[182:185], v[48:51]
	v_mfma_f32_16x16x32_bf16 v[44:47], v[216:219], v[174:177], v[44:47]
	v_mfma_f32_16x16x32_bf16 v[40:43], v[216:219], v[182:185], v[40:43]
	v_mfma_f32_16x16x32_bf16 v[36:39], v[224:227], v[174:177], v[36:39]
	v_mfma_f32_16x16x32_bf16 v[32:35], v[224:227], v[182:185], v[32:35]
	v_mfma_f32_16x16x32_bf16 v[60:63], v[196:199], v[178:181], v[60:63]
	v_mfma_f32_16x16x32_bf16 v[56:59], v[196:199], v[186:189], v[56:59]
	v_mfma_f32_16x16x32_bf16 v[52:55], v[212:215], v[178:181], v[52:55]
	v_mfma_f32_16x16x32_bf16 v[48:51], v[212:215], v[186:189], v[48:51]
	v_mfma_f32_16x16x32_bf16 v[44:47], v[220:223], v[178:181], v[44:47]
	v_mfma_f32_16x16x32_bf16 v[40:43], v[220:223], v[186:189], v[40:43]
	v_mfma_f32_16x16x32_bf16 v[36:39], v[244:247], v[178:181], v[36:39]
	v_mfma_f32_16x16x32_bf16 v[32:35], v[244:247], v[186:189], v[32:35]
	s_setprio 0
	s_barrier
	v_add_u32_e32 v161, 0x14000, v143
	v_add_u32_e32 v162, s70, v140
	s_add_i32 m0, s100, 0x14000
	v_add_u32_e32 v174, s70, v138
	global_load_lds_dwordx4 v162, s[86:87]
	v_add_u32_e32 v162, 0x16000, v143
	s_nop 0
	s_add_i32 m0, s100, 0x16000
	s_nop 0
	global_load_lds_dwordx4 v174, s[86:87]
	s_waitcnt vmcnt(6)
	s_barrier
; #define P8_STAGE(P,BASE,br,kt) do{const bfr* _ub=(BASE)+((long)(br)*K+(long)(kt)*BK); \
;     __builtin_amdgcn_global_load_lds((const unsigned*)(_ub+so0),(unsigned*)((char*)(P)+wid*1024),16,0,0); \
;     __builtin_amdgcn_global_load_lds((const unsigned*)(_ub+so1),(unsigned*)((char*)(P)+wid*1024+8192),16,0,0);}while(0)
; #define P8_LDA(dst,b,h) _Pragma("unroll") for(int m=0;m<4;++m) _Pragma("unroll") for(int k=0;k<2;++k) \
;     dst[m][k]=*reinterpret_cast<const bf16x8*>((char*)P8_SA(b,h)+lds_byte(wr*64+m*16+fr,k*32+fq*8))
; #define P8_LDB(dst,b,h) _Pragma("unroll") for(int n=0;n<2;++n) _Pragma("unroll") for(int k=0;k<2;++k) \
;     dst[n][k]=*reinterpret_cast<const bf16x8*>((char*)P8_SB(b,h)+lds_byte(wc*32+n*16+fr,k*32+fq*8))
; #define P8_MMA(ai,bj,At,Bt) do{__builtin_amdgcn_s_setprio(1); \
;     _Pragma("unroll") for(int m=0;m<4;++m) _Pragma("unroll") for(int n=0;n<2;++n) _Pragma("unroll") for(int k=0;k<2;++k) \
;       acc[ai][bj][m][n]=__builtin_amdgcn_mfma_f32_16x16x32_bf16(At[m][k],Bt[n][k],acc[ai][bj][m][n],0,0,0); \
;     __builtin_amdgcn_s_setprio(0);}while(0)
; #define P8_WAIT_V(n) asm volatile("s_waitcnt vmcnt(" #n ")":::"memory")
; #define P8_WAIT_L(n) asm volatile("s_waitcnt lgkmcnt(" #n ")":::"memory")
; #define P8_BAR __builtin_amdgcn_s_barrier()
; #define P8_SCHED __builtin_amdgcn_sched_barrier(0)
; template <class EPI>
; DEVI void gemm8_tile(const bfr* __restrict__ A, const bfr* __restrict__ Bt, int K, int brow, int bcol, int nbrow, int nbcol, char* shmc, EPI epi) {
;     ...
;     P8_WAIT_V(6); P8_BAR; P8_MMA(1,1,At,B1); P8_BAR;
;     P8_LDB(B0,1,0); P8_SCHED; P8_LDA(At,1,0); P8_STAGE(P8_SA(0,1),A,brow+128,t+2);
;     P8_WAIT_L(8); P8_BAR; P8_WAIT_L(0); P8_MMA(0,0,At,B0); P8_BAR; P8_SCHED;
;     P8_LDB(B1,1,1); P8_STAGE(P8_SB(1,0),Bt,bcol,t+3);
;     P8_BAR; P8_WAIT_L(0); P8_MMA(0,1,At,B1); P8_BAR;
;     P8_LDA(At,1,1); P8_STAGE(P8_SA(1,0),A,brow,t+3);
;     P8_BAR; P8_WAIT_L(0); P8_MMA(1,0,At,B0); P8_BAR; P8_SCHED;
	s_setprio 1
	v_mfma_f32_16x16x32_bf16 v[28:31], v[190:193], v[228:231], v[28:31]
	v_mfma_f32_16x16x32_bf16 v[24:27], v[190:193], v[236:239], v[24:27]
	v_mfma_f32_16x16x32_bf16 v[20:23], v[208:211], v[228:231], v[20:23]
	v_mfma_f32_16x16x32_bf16 v[16:19], v[208:211], v[236:239], v[16:19]
	v_mfma_f32_16x16x32_bf16 v[12:15], v[216:219], v[228:231], v[12:15]
	v_mfma_f32_16x16x32_bf16 v[8:11], v[216:219], v[236:239], v[8:11]
	v_mfma_f32_16x16x32_bf16 v[4:7], v[224:227], v[228:231], v[4:7]
	v_mfma_f32_16x16x32_bf16 v[0:3], v[224:227], v[236:239], v[0:3]
	v_mfma_f32_16x16x32_bf16 v[28:31], v[196:199], v[232:235], v[28:31]
	v_mfma_f32_16x16x32_bf16 v[24:27], v[196:199], v[240:243], v[24:27]
	v_mfma_f32_16x16x32_bf16 v[20:23], v[212:215], v[232:235], v[20:23]
	v_mfma_f32_16x16x32_bf16 v[16:19], v[212:215], v[240:243], v[16:19]
	v_mfma_f32_16x16x32_bf16 v[12:15], v[220:223], v[232:235], v[12:15]
	v_mfma_f32_16x16x32_bf16 v[8:11], v[220:223], v[240:243], v[8:11]
	v_mfma_f32_16x16x32_bf16 v[4:7], v[244:247], v[232:235], v[4:7]
	v_mfma_f32_16x16x32_bf16 v[0:3], v[244:247], v[240:243], v[0:3]
	s_setprio 0
	s_barrier
	ds_read_b128 v[174:177], v149
	ds_read_b128 v[178:181], v149 offset:1024
	ds_read_b128 v[182:185], v149 offset:2048
	ds_read_b128 v[186:189], v149 offset:3072
	v_add_u32_e32 v163, 0x4000, v143
	v_add_u32_e32 v170, 0x6000, v143
	v_add_u32_e32 v232, s60, v136
	s_add_i32 m0, s100, 0x4000
	ds_read_b128 v[190:193], v147 offset:32768
	ds_read_b128 v[196:199], v147 offset:33792
	ds_read_b128 v[208:211], v146 offset:32768
	ds_read_b128 v[212:215], v146 offset:33792
	ds_read_b128 v[216:219], v145 offset:32768
	ds_read_b128 v[220:223], v145 offset:33792
	ds_read_b128 v[224:227], v144 offset:32768
	ds_read_b128 v[228:231], v144 offset:33792
	global_load_lds_dwordx4 v232, s[86:87]
	v_add_u32_e32 v232, s60, v134
	s_add_i32 m0, s100, 0x6000
	s_nop 0
	global_load_lds_dwordx4 v232, s[86:87]
	s_waitcnt lgkmcnt(8)
	s_barrier
	s_waitcnt lgkmcnt(0)
	s_setprio 1
	s_waitcnt lgkmcnt(0)
	v_mfma_f32_16x16x32_bf16 v[124:127], v[190:193], v[174:177], v[124:127]
	v_mfma_f32_16x16x32_bf16 v[120:123], v[190:193], v[182:185], v[120:123]
	v_mfma_f32_16x16x32_bf16 v[116:119], v[208:211], v[174:177], v[116:119]
	v_mfma_f32_16x16x32_bf16 v[112:115], v[208:211], v[182:185], v[112:115]
	v_mfma_f32_16x16x32_bf16 v[108:111], v[216:219], v[174:177], v[108:111]
	v_mfma_f32_16x16x32_bf16 v[104:107], v[216:219], v[182:185], v[104:107]
	v_mfma_f32_16x16x32_bf16 v[100:103], v[224:227], v[174:177], v[100:103]
	v_mfma_f32_16x16x32_bf16 v[96:99], v[224:227], v[182:185], v[96:99]
	v_mfma_f32_16x16x32_bf16 v[124:127], v[196:199], v[178:181], v[124:127]
	v_mfma_f32_16x16x32_bf16 v[120:123], v[196:199], v[186:189], v[120:123]
	v_mfma_f32_16x16x32_bf16 v[116:119], v[212:215], v[178:181], v[116:119]
	v_mfma_f32_16x16x32_bf16 v[112:115], v[212:215], v[186:189], v[112:115]
	v_mfma_f32_16x16x32_bf16 v[108:111], v[220:223], v[178:181], v[108:111]
	v_mfma_f32_16x16x32_bf16 v[104:107], v[220:223], v[186:189], v[104:107]
	v_mfma_f32_16x16x32_bf16 v[100:103], v[228:231], v[178:181], v[100:103]
	v_mfma_f32_16x16x32_bf16 v[96:99], v[228:231], v[186:189], v[96:99]
	s_setprio 0
	s_barrier
	v_add_u32_e32 v248, s74, v140
	s_add_i32 m0, s100, 0x18000
	ds_read_b128 v[232:235], v148
	ds_read_b128 v[236:239], v148 offset:1024
	ds_read_b128 v[240:243], v148 offset:2048
	ds_read_b128 v[244:247], v148 offset:3072
	global_load_lds_dwordx4 v248, s[86:87]
	v_add_u32_e32 v248, s74, v138
	s_add_i32 m0, s100, 0x1a000
	s_nop 0
	global_load_lds_dwordx4 v248, s[86:87]
	s_barrier
	s_waitcnt lgkmcnt(0)
	s_setprio 1
	s_waitcnt lgkmcnt(0)
	v_mfma_f32_16x16x32_bf16 v[92:95], v[190:193], v[232:235], v[92:95]
	v_mfma_f32_16x16x32_bf16 v[88:91], v[190:193], v[240:243], v[88:91]
	v_mfma_f32_16x16x32_bf16 v[84:87], v[208:211], v[232:235], v[84:87]
	v_mfma_f32_16x16x32_bf16 v[80:83], v[208:211], v[240:243], v[80:83]
	v_mfma_f32_16x16x32_bf16 v[76:79], v[216:219], v[232:235], v[76:79]
	v_mfma_f32_16x16x32_bf16 v[72:75], v[216:219], v[240:243], v[72:75]
	v_mfma_f32_16x16x32_bf16 v[68:71], v[224:227], v[232:235], v[68:71]
	v_mfma_f32_16x16x32_bf16 v[64:67], v[224:227], v[240:243], v[64:67]
	v_mfma_f32_16x16x32_bf16 v[92:95], v[196:199], v[236:239], v[92:95]
	v_mfma_f32_16x16x32_bf16 v[88:91], v[196:199], v[244:247], v[88:91]
	v_mfma_f32_16x16x32_bf16 v[84:87], v[212:215], v[236:239], v[84:87]
	v_mfma_f32_16x16x32_bf16 v[80:83], v[212:215], v[244:247], v[80:83]
	v_mfma_f32_16x16x32_bf16 v[76:79], v[220:223], v[236:239], v[76:79]
	v_mfma_f32_16x16x32_bf16 v[72:75], v[220:223], v[244:247], v[72:75]
	v_mfma_f32_16x16x32_bf16 v[68:71], v[228:231], v[236:239], v[68:71]
	v_mfma_f32_16x16x32_bf16 v[64:67], v[228:231], v[244:247], v[64:67]
	s_setprio 0
	v_add_u32_e32 v200, s72, v136
	s_add_i32 m0, s100, 0x8000
	s_barrier
	ds_read_b128 v[190:193], v147 offset:49152
	ds_read_b128 v[196:199], v147 offset:50176
	ds_read_b128 v[208:211], v146 offset:49152
	ds_read_b128 v[212:215], v146 offset:50176
	ds_read_b128 v[216:219], v145 offset:49152
	ds_read_b128 v[220:223], v145 offset:50176
	ds_read_b128 v[224:227], v144 offset:49152
	ds_read_b128 v[228:231], v144 offset:50176
	global_load_lds_dwordx4 v200, s[86:87]
	v_add_u32_e32 v200, s72, v134
	s_add_i32 m0, s100, 0xa000
	s_nop 0
	global_load_lds_dwordx4 v200, s[86:87]
	s_barrier
; #define P8_STAGE(P,BASE,br,kt) do{const bfr* _ub=(BASE)+((long)(br)*K+(long)(kt)*BK); \
;     __builtin_amdgcn_global_load_lds((const unsigned*)(_ub+so0),(unsigned*)((char*)(P)+wid*1024),16,0,0); \
;     __builtin_amdgcn_global_load_lds((const unsigned*)(_ub+so1),(unsigned*)((char*)(P)+wid*1024+8192),16,0,0);}while(0)
; #define P8_LDA(dst,b,h) _Pragma("unroll") for(int m=0;m<4;++m) _Pragma("unroll") for(int k=0;k<2;++k) \
;     dst[m][k]=*reinterpret_cast<const bf16x8*>((char*)P8_SA(b,h)+lds_byte(wr*64+m*16+fr,k*32+fq*8))
; #define P8_LDB(dst,b,h) _Pragma("unroll") for(int n=0;n<2;++n) _Pragma("unroll") for(int k=0;k<2;++k) \
;     dst[n][k]=*reinterpret_cast<const bf16x8*>((char*)P8_SB(b,h)+lds_byte(wc*32+n*16+fr,k*32+fq*8))
; #define P8_MMA(ai,bj,At,Bt) do{__builtin_amdgcn_s_setprio(1); \
;     _Pragma("unroll") for(int m=0;m<4;++m) _Pragma("unroll") for(int n=0;n<2;++n) _Pragma("unroll") for(int k=0;k<2;++k) \
;       acc[ai][bj][m][n]=__builtin_amdgcn_mfma_f32_16x16x32_bf16(At[m][k],Bt[n][k],acc[ai][bj][m][n],0,0,0); \
;     __builtin_amdgcn_s_setprio(0);}while(0)
; #define P8_WAIT_V(n) asm volatile("s_waitcnt vmcnt(" #n ")":::"memory")
; #define P8_WAIT_L(n) asm volatile("s_waitcnt lgkmcnt(" #n ")":::"memory")
; #define P8_BAR __builtin_amdgcn_s_barrier()
; #define P8_SCHED __builtin_amdgcn_sched_barrier(0)
; template <class EPI>
; DEVI void gemm8_tile(const bfr* __restrict__ A, const bfr* __restrict__ Bt, int K, int brow, int bcol, int nbrow, int nbcol, char* shmc, EPI epi) {
;     ...
;     P8_BAR; P8_WAIT_L(0); P8_MMA(1,0,At,B0); P8_BAR; P8_SCHED;
;     P8_STAGE(P8_SB(1,1),Bt,bcol+128,t+3);
;     P8_WAIT_V(6); P8_BAR; P8_MMA(1,1,At,B1); P8_BAR;
;   }
;   { P8_LDB(B0,0,0); P8_LDA(At,0,0); P8_STAGE(P8_SA(1,1),A,brow+128,nt-1);
;     P8_BAR; P8_WAIT_L(0); P8_MMA(0,0,At,B0); P8_BAR;
;     P8_LDB(B1,0,1); P8_BAR; P8_WAIT_L(0); P8_MMA(0,1,At,B1); P8_BAR;
;     P8_LDA(At,0,1); P8_WAIT_V(4); P8_BAR; P8_WAIT_L(0); P8_MMA(1,0,At,B0); P8_MMA(1,1,At,B1); P8_BAR; }
	s_waitcnt lgkmcnt(0)
	s_setprio 1
	s_waitcnt lgkmcnt(0)
	v_mfma_f32_16x16x32_bf16 v[60:63], v[190:193], v[174:177], v[60:63]
	v_mfma_f32_16x16x32_bf16 v[56:59], v[190:193], v[182:185], v[56:59]
	v_mfma_f32_16x16x32_bf16 v[52:55], v[208:211], v[174:177], v[52:55]
	v_mfma_f32_16x16x32_bf16 v[48:51], v[208:211], v[182:185], v[48:51]
	v_mfma_f32_16x16x32_bf16 v[44:47], v[216:219], v[174:177], v[44:47]
	v_mfma_f32_16x16x32_bf16 v[40:43], v[216:219], v[182:185], v[40:43]
	v_mfma_f32_16x16x32_bf16 v[36:39], v[224:227], v[174:177], v[36:39]
	v_mfma_f32_16x16x32_bf16 v[32:35], v[224:227], v[182:185], v[32:35]
	v_mfma_f32_16x16x32_bf16 v[60:63], v[196:199], v[178:181], v[60:63]
	v_mfma_f32_16x16x32_bf16 v[56:59], v[196:199], v[186:189], v[56:59]
	v_mfma_f32_16x16x32_bf16 v[52:55], v[212:215], v[178:181], v[52:55]
	v_mfma_f32_16x16x32_bf16 v[48:51], v[212:215], v[186:189], v[48:51]
	v_mfma_f32_16x16x32_bf16 v[44:47], v[220:223], v[178:181], v[44:47]
	v_mfma_f32_16x16x32_bf16 v[40:43], v[220:223], v[186:189], v[40:43]
	v_mfma_f32_16x16x32_bf16 v[36:39], v[228:231], v[178:181], v[36:39]
	v_mfma_f32_16x16x32_bf16 v[32:35], v[228:231], v[186:189], v[32:35]
	s_setprio 0
	s_barrier
	v_add_u32_e32 v174, s78, v140
	s_add_i32 m0, s100, 0x1c000
	s_nop 0
	global_load_lds_dwordx4 v174, s[86:87]
	v_add_u32_e32 v174, s78, v138
	s_add_i32 m0, s100, 0x1e000
	s_nop 0
	global_load_lds_dwordx4 v174, s[86:87]
	s_waitcnt vmcnt(6)
	s_barrier
	s_setprio 1
	v_mfma_f32_16x16x32_bf16 v[28:31], v[190:193], v[232:235], v[28:31]
	v_mfma_f32_16x16x32_bf16 v[24:27], v[190:193], v[240:243], v[24:27]
	v_mfma_f32_16x16x32_bf16 v[20:23], v[208:211], v[232:235], v[20:23]
	v_mfma_f32_16x16x32_bf16 v[16:19], v[208:211], v[240:243], v[16:19]
	v_mfma_f32_16x16x32_bf16 v[12:15], v[216:219], v[232:235], v[12:15]
	v_mfma_f32_16x16x32_bf16 v[8:11], v[216:219], v[240:243], v[8:11]
	v_mfma_f32_16x16x32_bf16 v[4:7], v[224:227], v[232:235], v[4:7]
	v_mfma_f32_16x16x32_bf16 v[0:3], v[224:227], v[240:243], v[0:3]
	v_mfma_f32_16x16x32_bf16 v[28:31], v[196:199], v[236:239], v[28:31]
	v_mfma_f32_16x16x32_bf16 v[24:27], v[196:199], v[244:247], v[24:27]
	v_mfma_f32_16x16x32_bf16 v[20:23], v[212:215], v[236:239], v[20:23]
	v_mfma_f32_16x16x32_bf16 v[16:19], v[212:215], v[244:247], v[16:19]
	v_mfma_f32_16x16x32_bf16 v[12:15], v[220:223], v[236:239], v[12:15]
	v_mfma_f32_16x16x32_bf16 v[8:11], v[220:223], v[244:247], v[8:11]
	v_mfma_f32_16x16x32_bf16 v[4:7], v[228:231], v[236:239], v[4:7]
	v_mfma_f32_16x16x32_bf16 v[0:3], v[228:231], v[244:247], v[0:3]
	s_setprio 0
	s_add_i32 s0, s0, 2
	v_lshl_add_u64 v[134:135], v[134:135], 0, s[80:81]
	v_lshl_add_u64 v[136:137], v[136:137], 0, s[80:81]
	v_lshl_add_u64 v[138:139], v[138:139], 0, s[80:81]
	s_cmp_lt_u32 s0, 28
	v_lshl_add_u64 v[140:141], v[140:141], 0, s[80:81]
	s_barrier
	s_cbranch_scc1 .LBB0_221
	s_or_b32 s0, s8, 0x80
	s_ashr_i32 s1, s0, 31
	s_lshl_b64 s[0:1], s[0:1], 12
	s_add_u32 s0, s34, s0
	s_addc_u32 s1, s35, s1
	ds_read_b128 v[134:137], v157
	ds_read_b128 v[138:141], v157 offset:1024
	ds_read_b128 v[150:153], v157 offset:2048
	ds_read_b128 v[174:177], v157 offset:3072
	ds_read_b128 v[178:181], v147
	ds_read_b128 v[182:185], v147 offset:1024
	ds_read_b128 v[186:189], v146
	ds_read_b128 v[190:193], v146 offset:1024
	ds_read_b128 v[196:199], v145
	ds_read_b128 v[208:211], v145 offset:1024
	ds_read_b128 v[212:215], v144
	ds_read_b128 v[216:219], v144 offset:1024
	v_lshl_add_u64 v[156:157], v[166:167], 1, s[0:1]
	s_mov_b64 s[54:55], 0xf80
	v_lshl_add_u64 v[156:157], v[156:157], 0, s[54:55]
	s_add_i32 m0, s100, 0xc000
	v_lshl_add_u64 v[132:133], v[132:133], 1, s[0:1]
	global_load_lds_dwordx4 v[156:157], off
	v_lshl_add_u64 v[132:133], v[132:133], 0, s[54:55]
	s_add_i32 m0, s100, 0xe000
	s_nop 0
	global_load_lds_dwordx4 v[132:133], off
	s_barrier
	s_waitcnt lgkmcnt(0)
	s_setprio 1
	s_waitcnt lgkmcnt(0)
	v_mfma_f32_16x16x32_bf16 v[124:127], v[178:181], v[134:137], v[124:127]
	v_mfma_f32_16x16x32_bf16 v[120:123], v[178:181], v[150:153], v[120:123]
	v_mfma_f32_16x16x32_bf16 v[116:119], v[186:189], v[134:137], v[116:119]
	v_mfma_f32_16x16x32_bf16 v[112:115], v[186:189], v[150:153], v[112:115]
	v_mfma_f32_16x16x32_bf16 v[96:99], v[212:215], v[150:153], v[96:99]
	v_mfma_f32_16x16x32_bf16 v[124:127], v[182:185], v[138:141], v[124:127]
	v_mfma_f32_16x16x32_bf16 v[120:123], v[182:185], v[174:177], v[120:123]
	v_mfma_f32_16x16x32_bf16 v[116:119], v[190:193], v[138:141], v[116:119]
	v_mfma_f32_16x16x32_bf16 v[112:115], v[190:193], v[174:177], v[112:115]
	v_mfma_f32_16x16x32_bf16 v[108:111], v[196:199], v[134:137], v[108:111]
	v_mfma_f32_16x16x32_bf16 v[104:107], v[196:199], v[150:153], v[104:107]
	v_mfma_f32_16x16x32_bf16 v[100:103], v[212:215], v[134:137], v[100:103]
	v_mfma_f32_16x16x32_bf16 v[96:99], v[216:219], v[174:177], v[96:99]
	v_mfma_f32_16x16x32_bf16 v[220:223], v[208:211], v[138:141], v[108:111]
	v_mfma_f32_16x16x32_bf16 v[224:227], v[208:211], v[174:177], v[104:107]
	v_mfma_f32_16x16x32_bf16 v[228:231], v[216:219], v[138:141], v[100:103]
	s_setprio 0
	s_barrier
	s_nop 1
	ds_read_b128 v[100:103], v155
	ds_read_b128 v[104:107], v155 offset:1024
	ds_read_b128 v[108:111], v155 offset:2048
	ds_read_b128 v[154:157], v155 offset:3072
	s_barrier
; #define P8_LDA(dst,b,h) _Pragma("unroll") for(int m=0;m<4;++m) _Pragma("unroll") for(int k=0;k<2;++k) \
;     dst[m][k]=*reinterpret_cast<const bf16x8*>((char*)P8_SA(b,h)+lds_byte(wr*64+m*16+fr,k*32+fq*8))
; #define P8_LDB(dst,b,h) _Pragma("unroll") for(int n=0;n<2;++n) _Pragma("unroll") for(int k=0;k<2;++k) \
;     dst[n][k]=*reinterpret_cast<const bf16x8*>((char*)P8_SB(b,h)+lds_byte(wc*32+n*16+fr,k*32+fq*8))
; #define P8_MMA(ai,bj,At,Bt) do{__builtin_amdgcn_s_setprio(1); \
;     _Pragma("unroll") for(int m=0;m<4;++m) _Pragma("unroll") for(int n=0;n<2;++n) _Pragma("unroll") for(int k=0;k<2;++k) \
;       acc[ai][bj][m][n]=__builtin_amdgcn_mfma_f32_16x16x32_bf16(At[m][k],Bt[n][k],acc[ai][bj][m][n],0,0,0); \
;     __builtin_amdgcn_s_setprio(0);}while(0)
; #define P8_WAIT_V(n) asm volatile("s_waitcnt vmcnt(" #n ")":::"memory")
; #define P8_WAIT_L(n) asm volatile("s_waitcnt lgkmcnt(" #n ")":::"memory")
; #define P8_BAR __builtin_amdgcn_s_barrier()
; template <class EPI>
; DEVI void gemm8_tile(const bfr* __restrict__ A, const bfr* __restrict__ Bt, int K, int brow, int bcol, int nbrow, int nbcol, char* shmc, EPI epi) {
;     ...
;     P8_BAR; P8_WAIT_L(0); P8_MMA(0,0,At,B0); P8_BAR;
;     P8_LDB(B1,0,1); P8_BAR; P8_WAIT_L(0); P8_MMA(0,1,At,B1); P8_BAR;
;     P8_LDA(At,0,1); P8_WAIT_V(4); P8_BAR; P8_WAIT_L(0); P8_MMA(1,0,At,B0); P8_MMA(1,1,At,B1); P8_BAR; }
;   { P8_LDB(B0,1,0); P8_LDA(At,1,0); P8_WAIT_V(2); P8_BAR; P8_WAIT_L(0); P8_MMA(0,0,At,B0); P8_BAR;
;     P8_LDB(B1,1,1); P8_WAIT_V(0); P8_BAR; P8_WAIT_L(0); P8_MMA(0,1,At,B1); P8_BAR;
	s_waitcnt lgkmcnt(0)
	s_setprio 1
	s_waitcnt lgkmcnt(0)
	v_mfma_f32_16x16x32_bf16 v[92:95], v[178:181], v[100:103], v[92:95]
	v_mfma_f32_16x16x32_bf16 v[88:91], v[178:181], v[108:111], v[88:91]
	v_mfma_f32_16x16x32_bf16 v[84:87], v[186:189], v[100:103], v[84:87]
	v_mfma_f32_16x16x32_bf16 v[80:83], v[186:189], v[108:111], v[80:83]
	v_mfma_f32_16x16x32_bf16 v[64:67], v[212:215], v[108:111], v[64:67]
	v_mfma_f32_16x16x32_bf16 v[92:95], v[182:185], v[104:107], v[92:95]
	v_mfma_f32_16x16x32_bf16 v[88:91], v[182:185], v[154:157], v[88:91]
	v_mfma_f32_16x16x32_bf16 v[84:87], v[190:193], v[104:107], v[84:87]
	v_mfma_f32_16x16x32_bf16 v[80:83], v[190:193], v[154:157], v[80:83]
	v_mfma_f32_16x16x32_bf16 v[76:79], v[196:199], v[100:103], v[76:79]
	v_mfma_f32_16x16x32_bf16 v[72:75], v[196:199], v[108:111], v[72:75]
	v_mfma_f32_16x16x32_bf16 v[68:71], v[212:215], v[100:103], v[68:71]
	v_mfma_f32_16x16x32_bf16 v[64:67], v[216:219], v[154:157], v[64:67]
	v_mfma_f32_16x16x32_bf16 v[178:181], v[208:211], v[104:107], v[76:79]
	v_mfma_f32_16x16x32_bf16 v[182:185], v[208:211], v[154:157], v[72:75]
	v_mfma_f32_16x16x32_bf16 v[186:189], v[216:219], v[104:107], v[68:71]
	s_setprio 0
	s_barrier
	s_nop 1
	ds_read_b128 v[68:71], v147 offset:16384
	ds_read_b128 v[72:75], v147 offset:17408
	ds_read_b128 v[76:79], v146 offset:16384
	ds_read_b128 v[190:193], v146 offset:17408
	ds_read_b128 v[196:199], v145 offset:16384
	ds_read_b128 v[208:211], v145 offset:17408
	ds_read_b128 v[212:215], v144 offset:16384
	ds_read_b128 v[216:219], v144 offset:17408
	s_waitcnt vmcnt(4)
	s_barrier
	s_waitcnt lgkmcnt(0)
	s_setprio 1
	s_waitcnt lgkmcnt(0)
	v_mfma_f32_16x16x32_bf16 v[60:63], v[68:71], v[134:137], v[60:63]
	v_mfma_f32_16x16x32_bf16 v[56:59], v[68:71], v[150:153], v[56:59]
	v_mfma_f32_16x16x32_bf16 v[52:55], v[76:79], v[134:137], v[52:55]
	v_mfma_f32_16x16x32_bf16 v[48:51], v[76:79], v[150:153], v[48:51]
	v_mfma_f32_16x16x32_bf16 v[32:35], v[212:215], v[150:153], v[32:35]
	v_mfma_f32_16x16x32_bf16 v[60:63], v[72:75], v[138:141], v[60:63]
	v_mfma_f32_16x16x32_bf16 v[56:59], v[72:75], v[174:177], v[56:59]
	v_mfma_f32_16x16x32_bf16 v[52:55], v[190:193], v[138:141], v[52:55]
	v_mfma_f32_16x16x32_bf16 v[48:51], v[190:193], v[174:177], v[48:51]
	v_mfma_f32_16x16x32_bf16 v[44:47], v[196:199], v[134:137], v[44:47]
	v_mfma_f32_16x16x32_bf16 v[40:43], v[196:199], v[150:153], v[40:43]
	v_mfma_f32_16x16x32_bf16 v[36:39], v[212:215], v[134:137], v[36:39]
	v_mfma_f32_16x16x32_bf16 v[32:35], v[216:219], v[174:177], v[32:35]
	v_mfma_f32_16x16x32_bf16 v[232:235], v[208:211], v[138:141], v[44:47]
	v_mfma_f32_16x16x32_bf16 v[236:239], v[208:211], v[174:177], v[40:43]
	v_mfma_f32_16x16x32_bf16 v[132:135], v[216:219], v[138:141], v[36:39]
	s_setprio 0
	s_setprio 1
	v_mfma_f32_16x16x32_bf16 v[28:31], v[68:71], v[100:103], v[28:31]
	v_mfma_f32_16x16x32_bf16 v[24:27], v[68:71], v[108:111], v[24:27]
	v_mfma_f32_16x16x32_bf16 v[20:23], v[76:79], v[100:103], v[20:23]
	v_mfma_f32_16x16x32_bf16 v[16:19], v[76:79], v[108:111], v[16:19]
	v_mfma_f32_16x16x32_bf16 v[0:3], v[212:215], v[108:111], v[0:3]
	v_mfma_f32_16x16x32_bf16 v[28:31], v[72:75], v[104:107], v[28:31]
	v_mfma_f32_16x16x32_bf16 v[24:27], v[72:75], v[154:157], v[24:27]
	v_mfma_f32_16x16x32_bf16 v[20:23], v[190:193], v[104:107], v[20:23]
	v_mfma_f32_16x16x32_bf16 v[16:19], v[190:193], v[154:157], v[16:19]
	v_mfma_f32_16x16x32_bf16 v[12:15], v[196:199], v[100:103], v[12:15]
	v_mfma_f32_16x16x32_bf16 v[8:11], v[196:199], v[108:111], v[8:11]
	v_mfma_f32_16x16x32_bf16 v[4:7], v[212:215], v[100:103], v[4:7]
	v_mfma_f32_16x16x32_bf16 v[0:3], v[216:219], v[154:157], v[0:3]
	v_mfma_f32_16x16x32_bf16 v[136:139], v[208:211], v[104:107], v[12:15]
	v_mfma_f32_16x16x32_bf16 v[150:153], v[208:211], v[154:157], v[8:11]
	v_mfma_f32_16x16x32_bf16 v[172:175], v[216:219], v[104:107], v[4:7]
	s_setprio 0
	s_barrier
	s_nop 1
	ds_read_b128 v[4:7], v149
	ds_read_b128 v[8:11], v149 offset:1024
	ds_read_b128 v[12:15], v149 offset:2048
	ds_read_b128 v[154:157], v149 offset:3072
	ds_read_b128 v[36:39], v147 offset:32768
	ds_read_b128 v[40:43], v147 offset:33792
	ds_read_b128 v[44:47], v146 offset:32768
	ds_read_b128 v[68:71], v146 offset:33792
	ds_read_b128 v[190:193], v145 offset:32768
	ds_read_b128 v[196:199], v145 offset:33792
	ds_read_b128 v[208:211], v144 offset:32768
	ds_read_b128 v[212:215], v144 offset:33792
	s_waitcnt vmcnt(2)
	s_barrier
	s_waitcnt lgkmcnt(0)
	s_setprio 1
	s_waitcnt lgkmcnt(0)
	v_mfma_f32_16x16x32_bf16 v[72:75], v[36:39], v[4:7], v[124:127]
	v_mfma_f32_16x16x32_bf16 v[124:127], v[40:43], v[8:11], v[72:75]
	v_mfma_f32_16x16x32_bf16 v[72:75], v[36:39], v[12:15], v[120:123]
	v_mfma_f32_16x16x32_bf16 v[108:111], v[40:43], v[154:157], v[72:75]
	v_mfma_f32_16x16x32_bf16 v[72:75], v[44:47], v[4:7], v[116:119]
	v_mfma_f32_16x16x32_bf16 v[120:123], v[68:71], v[8:11], v[72:75]
	v_mfma_f32_16x16x32_bf16 v[72:75], v[44:47], v[12:15], v[112:115]
	v_mfma_f32_16x16x32_bf16 v[104:107], v[68:71], v[154:157], v[72:75]
	v_mfma_f32_16x16x32_bf16 v[72:75], v[190:193], v[4:7], v[220:223]
	v_mfma_f32_16x16x32_bf16 v[116:119], v[196:199], v[8:11], v[72:75]
	v_mfma_f32_16x16x32_bf16 v[72:75], v[190:193], v[12:15], v[224:227]
	v_mfma_f32_16x16x32_bf16 v[100:103], v[196:199], v[154:157], v[72:75]
	v_mfma_f32_16x16x32_bf16 v[72:75], v[208:211], v[4:7], v[228:231]
	v_mfma_f32_16x16x32_bf16 v[112:115], v[212:215], v[8:11], v[72:75]
	v_mfma_f32_16x16x32_bf16 v[72:75], v[208:211], v[12:15], v[96:99]
	v_mfma_f32_16x16x32_bf16 v[96:99], v[212:215], v[154:157], v[72:75]
	s_setprio 0
	s_barrier
; #define P8_STAGE(P,BASE,br,kt) do{const bfr* _ub=(BASE)+((long)(br)*K+(long)(kt)*BK); \
;     __builtin_amdgcn_global_load_lds((const unsigned*)(_ub+so0),(unsigned*)((char*)(P)+wid*1024),16,0,0); \
;     __builtin_amdgcn_global_load_lds((const unsigned*)(_ub+so1),(unsigned*)((char*)(P)+wid*1024+8192),16,0,0);}while(0)
; #define P8_LDA(dst,b,h) _Pragma("unroll") for(int m=0;m<4;++m) _Pragma("unroll") for(int k=0;k<2;++k) \
;     dst[m][k]=*reinterpret_cast<const bf16x8*>((char*)P8_SA(b,h)+lds_byte(wr*64+m*16+fr,k*32+fq*8))
; #define P8_LDB(dst,b,h) _Pragma("unroll") for(int n=0;n<2;++n) _Pragma("unroll") for(int k=0;k<2;++k) \
;     dst[n][k]=*reinterpret_cast<const bf16x8*>((char*)P8_SB(b,h)+lds_byte(wc*32+n*16+fr,k*32+fq*8))
; #define P8_MMA(ai,bj,At,Bt) do{__builtin_amdgcn_s_setprio(1); \
;     _Pragma("unroll") for(int m=0;m<4;++m) _Pragma("unroll") for(int n=0;n<2;++n) _Pragma("unroll") for(int k=0;k<2;++k) \
;       acc[ai][bj][m][n]=__builtin_amdgcn_mfma_f32_16x16x32_bf16(At[m][k],Bt[n][k],acc[ai][bj][m][n],0,0,0); \
;     __builtin_amdgcn_s_setprio(0);}while(0)
; #define P8_WAIT_V(n) asm volatile("s_waitcnt vmcnt(" #n ")":::"memory")
; #define P8_WAIT_L(n) asm volatile("s_waitcnt lgkmcnt(" #n ")":::"memory")
; #define P8_BAR __builtin_amdgcn_s_barrier()
; template <class EPI>
; DEVI void gemm8_tile(const bfr* __restrict__ A, const bfr* __restrict__ Bt, int K, int brow, int bcol, int nbrow, int nbcol, char* shmc, EPI epi) {
;     ...
;     P8_LDB(B1,1,1); P8_WAIT_V(0); P8_BAR; P8_WAIT_L(0); P8_MMA(0,1,At,B1); P8_BAR;
;     P8_LDA(At,1,1); P8_BAR; P8_WAIT_L(0); P8_MMA(1,0,At,B0); P8_MMA(1,1,At,B1); P8_BAR; }
;   if(wr==0)P8_BAR;
;   if (nbrow >= 0) {
;     P8_STAGE(P8_SB(0,0),Bt,nbcol,0); P8_STAGE(P8_SA(0,0),A,nbrow,0);
;     P8_STAGE(P8_SB(0,1),Bt,nbcol+128,0); P8_STAGE(P8_SA(0,1),A,nbrow+128,0);
;   }
	ds_read_b128 v[216:219], v148
	ds_read_b128 v[220:223], v148 offset:1024
	ds_read_b128 v[224:227], v148 offset:2048
	ds_read_b128 v[228:231], v148 offset:3072
	s_waitcnt vmcnt(0)
	s_barrier
	s_waitcnt lgkmcnt(0)
	s_setprio 1
	s_waitcnt lgkmcnt(0)
	v_mfma_f32_16x16x32_bf16 v[72:75], v[36:39], v[216:219], v[92:95]
	v_mfma_f32_16x16x32_bf16 v[36:39], v[36:39], v[224:227], v[88:91]
	v_mfma_f32_16x16x32_bf16 v[76:79], v[40:43], v[228:231], v[36:39]
	v_mfma_f32_16x16x32_bf16 v[36:39], v[44:47], v[216:219], v[84:87]
	v_mfma_f32_16x16x32_bf16 v[88:91], v[68:71], v[220:223], v[36:39]
	v_mfma_f32_16x16x32_bf16 v[36:39], v[44:47], v[224:227], v[80:83]
	v_mfma_f32_16x16x32_bf16 v[92:95], v[40:43], v[220:223], v[72:75]
	v_mfma_f32_16x16x32_bf16 v[72:75], v[68:71], v[228:231], v[36:39]
	v_mfma_f32_16x16x32_bf16 v[36:39], v[190:193], v[216:219], v[178:181]
	v_mfma_f32_16x16x32_bf16 v[84:87], v[196:199], v[220:223], v[36:39]
	v_mfma_f32_16x16x32_bf16 v[36:39], v[190:193], v[224:227], v[182:185]
	v_mfma_f32_16x16x32_bf16 v[68:71], v[196:199], v[228:231], v[36:39]
	v_mfma_f32_16x16x32_bf16 v[36:39], v[208:211], v[216:219], v[186:189]
	v_mfma_f32_16x16x32_bf16 v[80:83], v[212:215], v[220:223], v[36:39]
	v_mfma_f32_16x16x32_bf16 v[36:39], v[208:211], v[224:227], v[64:67]
	v_mfma_f32_16x16x32_bf16 v[64:67], v[212:215], v[228:231], v[36:39]
	s_setprio 0
	s_barrier
	ds_read_b128 v[176:179], v147 offset:49152
	ds_read_b128 v[180:183], v147 offset:50176
	ds_read_b128 v[184:187], v146 offset:49152
	ds_read_b128 v[146:149], v146 offset:50176
	ds_read_b128 v[188:191], v145 offset:49152
	ds_read_b128 v[196:199], v145 offset:50176
	ds_read_b128 v[208:211], v144 offset:49152
	ds_read_b128 v[212:215], v144 offset:50176
	s_barrier
	s_waitcnt lgkmcnt(0)
	s_setprio 1
	s_waitcnt lgkmcnt(0)
	v_mfma_f32_16x16x32_bf16 v[36:39], v[176:179], v[4:7], v[60:63]
	v_mfma_f32_16x16x32_bf16 v[60:63], v[180:183], v[8:11], v[36:39]
	v_mfma_f32_16x16x32_bf16 v[36:39], v[176:179], v[12:15], v[56:59]
	v_mfma_f32_16x16x32_bf16 v[44:47], v[180:183], v[154:157], v[36:39]
	v_mfma_f32_16x16x32_bf16 v[36:39], v[184:187], v[4:7], v[52:55]
	v_mfma_f32_16x16x32_bf16 v[56:59], v[146:149], v[8:11], v[36:39]
	v_mfma_f32_16x16x32_bf16 v[36:39], v[184:187], v[12:15], v[48:51]
	v_mfma_f32_16x16x32_bf16 v[40:43], v[146:149], v[154:157], v[36:39]
	v_mfma_f32_16x16x32_bf16 v[36:39], v[188:191], v[4:7], v[232:235]
	v_mfma_f32_16x16x32_bf16 v[4:7], v[208:211], v[4:7], v[132:135]
	v_mfma_f32_16x16x32_bf16 v[52:55], v[196:199], v[8:11], v[36:39]
	v_mfma_f32_16x16x32_bf16 v[36:39], v[188:191], v[12:15], v[236:239]
	v_mfma_f32_16x16x32_bf16 v[48:51], v[212:215], v[8:11], v[4:7]
	v_mfma_f32_16x16x32_bf16 v[4:7], v[208:211], v[12:15], v[32:35]
	v_mfma_f32_16x16x32_bf16 v[36:39], v[196:199], v[154:157], v[36:39]
	v_mfma_f32_16x16x32_bf16 v[32:35], v[212:215], v[154:157], v[4:7]
	s_setprio 0
	s_setprio 1
	v_mfma_f32_16x16x32_bf16 v[4:7], v[176:179], v[216:219], v[28:31]
	v_mfma_f32_16x16x32_bf16 v[28:31], v[180:183], v[220:223], v[4:7]
	v_mfma_f32_16x16x32_bf16 v[4:7], v[176:179], v[224:227], v[24:27]
	v_mfma_f32_16x16x32_bf16 v[12:15], v[180:183], v[228:231], v[4:7]
	v_mfma_f32_16x16x32_bf16 v[4:7], v[184:187], v[216:219], v[20:23]
	v_mfma_f32_16x16x32_bf16 v[24:27], v[146:149], v[220:223], v[4:7]
	v_mfma_f32_16x16x32_bf16 v[4:7], v[184:187], v[224:227], v[16:19]
	v_mfma_f32_16x16x32_bf16 v[8:11], v[146:149], v[228:231], v[4:7]
	v_mfma_f32_16x16x32_bf16 v[4:7], v[188:191], v[216:219], v[136:139]
	v_mfma_f32_16x16x32_bf16 v[20:23], v[196:199], v[220:223], v[4:7]
	v_mfma_f32_16x16x32_bf16 v[4:7], v[188:191], v[224:227], v[150:153]
	v_mfma_f32_16x16x32_bf16 v[16:19], v[208:211], v[216:219], v[172:175]
	v_mfma_f32_16x16x32_bf16 v[0:3], v[208:211], v[224:227], v[0:3]
	v_mfma_f32_16x16x32_bf16 v[4:7], v[196:199], v[228:231], v[4:7]
	v_mfma_f32_16x16x32_bf16 v[16:19], v[212:215], v[220:223], v[16:19]
	v_mfma_f32_16x16x32_bf16 v[0:3], v[212:215], v[228:231], v[0:3]
	s_setprio 0
	v_cmp_gt_u32_e32 vcc, s57, v142
	s_barrier
	s_and_saveexec_b64 s[0:1], vcc
	s_cbranch_execz .LBB0_224
	s_barrier
.LBB0_224:
	s_or_b64 exec, exec, s[0:1]
	s_lshl_b32 s2, s65, 8
	s_and_b64 s[0:1], s[10:11], exec
	s_cselect_b32 s58, s2, -1
	s_cmp_lt_i32 s58, 0
	s_movk_i32 s5, 0x880
	s_cbranch_scc1 .LBB0_226
	s_lshl_b32 s0, s68, 8
	s_ashr_i32 s1, s0, 31
	s_lshl_b64 s[10:11], s[0:1], 12
	s_add_u32 s10, s84, s10
	s_addc_u32 s11, s85, s11
	v_lshl_add_u64 v[132:133], s[10:11], 0, v[128:129]
	s_add_i32 m0, s100, 0x10000
	v_readfirstlane_b32 s1, v159
	global_load_lds_dwordx4 v[132:133], off
	v_lshl_add_u64 v[132:133], s[10:11], 0, v[130:131]
	s_lshl_b64 s[10:11], s[58:59], 12
	s_add_u32 s10, s34, s10
	s_mov_b32 m0, s1
	s_addc_u32 s11, s35, s11
	global_load_lds_dwordx4 v[132:133], off
	v_lshl_add_u64 v[132:133], s[10:11], 0, v[128:129]
	s_mov_b32 m0, s100
	s_bitset1_b32 s0, 7
	global_load_lds_dwordx4 v[132:133], off
	s_add_i32 m0, s100, 0x2000
	s_ashr_i32 s1, s0, 31
	s_lshl_b64 s[0:1], s[0:1], 12
	s_add_u32 s0, s84, s0
	v_lshl_add_u64 v[132:133], s[10:11], 0, v[130:131]
	s_addc_u32 s1, s85, s1
	global_load_lds_dwordx4 v[132:133], off
	v_lshl_add_u64 v[132:133], s[0:1], 0, v[128:129]
	s_add_i32 m0, s100, 0x14000
	s_addk_i32 s58, 0x80
	global_load_lds_dwordx4 v[132:133], off
	v_lshl_add_u64 v[132:133], s[0:1], 0, v[130:131]
	s_add_i32 m0, s100, 0x16000
	s_lshl_b64 s[0:1], s[58:59], 12
	s_add_u32 s0, s34, s0
	s_addc_u32 s1, s35, s1
	v_readfirstlane_b32 s2, v163
	global_load_lds_dwordx4 v[132:133], off
	v_lshl_add_u64 v[128:129], s[0:1], 0, v[128:129]
	s_mov_b32 m0, s2
	s_nop 0
	global_load_lds_dwordx4 v[128:129], off
	v_lshl_add_u64 v[128:129], s[0:1], 0, v[130:131]
	v_readfirstlane_b32 s0, v170
	s_mov_b32 m0, s0
	s_nop 0
	global_load_lds_dwordx4 v[128:129], off

; #define P8_STAGE(P,BASE,br,kt) do{const bfr* _ub=(BASE)+((long)(br)*K+(long)(kt)*BK); \
;     __builtin_amdgcn_global_load_lds((const unsigned*)(_ub+so0),(unsigned*)((char*)(P)+wid*1024),16,0,0); \
;     __builtin_amdgcn_global_load_lds((const unsigned*)(_ub+so1),(unsigned*)((char*)(P)+wid*1024+8192),16,0,0);}while(0)
; #define P8_WAIT_V(n) asm volatile("s_waitcnt vmcnt(" #n ")":::"memory")
; #define P8_BAR __builtin_amdgcn_s_barrier()
; template <class EPI>
; DEVI void gemm8_tile(const bfr* __restrict__ A, const bfr* __restrict__ Bt, int K, int brow, int bcol, int nbrow, int nbcol, char* shmc, EPI epi) {
;     ...
;   unsigned so0, so1;
;   { int _r, _c; stage_rc(tid * 16, _r, _c); so0 = (unsigned)(_r * K + _c); stage_rc(tid * 16 + 8192, _r, _c); so1 = (unsigned)(_r * K + _c); }
;   f32x4 acc[2][2][4][2];
; #pragma unroll
;   for (int a = 0; a < 2; ++a)
; #pragma unroll
;     for (int b = 0; b < 2; ++b)
; #pragma unroll
;       for (int m = 0; m < 4; ++m)
; #pragma unroll
;         for (int n = 0; n < 2; ++n) acc[a][b][m][n] = f32x4{0.f, 0.f, 0.f, 0.f};
;   bf16x8 At[4][2], B0[2][2], B1[2][2];
;   const int nt = K / BK;
;   if(wr==1)P8_BAR;
;   P8_WAIT_V(4); P8_BAR;
;   P8_STAGE(P8_SB(1,0),Bt,bcol,1); P8_STAGE(P8_SA(1,0),A,brow,1); P8_STAGE(P8_SB(1,1),Bt,bcol+128,1);
;   P8_WAIT_V(6); P8_BAR;
.LBB0_285:
	s_or_b64 exec, exec, s[0:1]
	v_lshlrev_b32_e32 v2, 4, v142
	v_and_b32_e32 v3, 32, v142
	s_lshl_b32 s10, s9, 8
	v_lshrrev_b32_e32 v7, 1, v142
	v_bitop3_b32 v3, v2, v3, 48 bitop3:0x6c
	v_add_u32_e32 v2, 0x2000, v2
	v_ashrrev_i32_e32 v4, 3, v142
	v_bfe_u32 v5, v142, 2, 4
	s_mov_b32 s0, 0x1ffff0
	v_lshrrev_b32_e32 v8, 1, v3
	v_ashrrev_i32_e32 v9, 7, v2
	v_and_b32_e32 v7, 32, v7
	s_ashr_i32 s11, s10, 31
	s_lshl_b32 s8, s2, 8
	v_ashrrev_i32_e32 v1, 6, v142
	v_and_or_b32 v6, v4, s0, v5
	v_and_or_b32 v2, v9, s0, v5
	v_or_b32_e32 v3, v8, v7
	s_lshl_b64 s[0:1], s[10:11], 12
	v_lshl_or_b32 v166, v6, 11, v3
	s_add_u32 s54, s84, s0
	v_lshlrev_b32_e32 v143, 10, v1
	s_nop 0
	v_readfirstlane_b32 s100, v143
	s_nop 3
	s_addc_u32 s55, s85, s1
	v_lshlrev_b64 v[128:129], 1, v[166:167]
	v_add_u32_e32 v150, 0x18000, v143
	v_lshl_or_b32 v132, v2, 11, v3
	v_lshl_add_u64 v[2:3], s[54:55], 0, v[128:129]
	v_mov_b32_e32 v133, v167
	v_lshl_add_u64 v[2:3], v[2:3], 0, s[62:63]
	s_add_i32 m0, s100, 0x18000
	v_lshlrev_b64 v[130:131], 1, v[132:133]
	s_ashr_i32 s9, s8, 31
	s_waitcnt vmcnt(4)
	s_barrier
	global_load_lds_dwordx4 v[2:3], off
	v_lshl_add_u64 v[2:3], s[54:55], 0, v[130:131]
	v_add_u32_e32 v151, 0x1a000, v143
	s_lshl_b64 s[54:55], s[8:9], 12
	v_readfirstlane_b32 s2, v151
	s_add_u32 s60, s29, s54
	v_lshl_add_u64 v[2:3], v[2:3], 0, s[62:63]
	s_mov_b32 m0, s2
	s_addc_u32 s61, s68, s55
	v_add_u32_e32 v152, 0x8000, v143
	global_load_lds_dwordx4 v[2:3], off
	v_lshl_add_u64 v[2:3], s[60:61], 0, v[128:129]
	v_lshl_add_u64 v[2:3], v[2:3], 0, s[62:63]
	s_add_i32 m0, s100, 0x8000
	v_add_u32_e32 v153, 0xa000, v143
	global_load_lds_dwordx4 v[2:3], off
	v_lshl_add_u64 v[2:3], s[60:61], 0, v[130:131]
	s_or_b32 s60, s10, 0x80
	s_ashr_i32 s61, s60, 31
	s_lshl_b64 s[60:61], s[60:61], 12
	v_readfirstlane_b32 s2, v153
	s_add_u32 s60, s84, s60
	v_lshl_add_u64 v[2:3], v[2:3], 0, s[62:63]
	s_mov_b32 m0, s2
	s_addc_u32 s61, s85, s61
	v_add_u32_e32 v154, 0x1c000, v143
	global_load_lds_dwordx4 v[2:3], off
	v_lshl_add_u64 v[2:3], s[60:61], 0, v[128:129]
	v_lshl_add_u64 v[2:3], v[2:3], 0, s[62:63]
	s_add_i32 m0, s100, 0x1c000
	v_add_u32_e32 v156, 0x1e000, v143
	global_load_lds_dwordx4 v[2:3], off
	v_lshl_add_u64 v[2:3], s[60:61], 0, v[130:131]
	v_lshl_add_u64 v[2:3], v[2:3], 0, s[62:63]
	s_add_i32 m0, s100, 0x1e000
	v_and_b32_e32 v10, 15, v142
	global_load_lds_dwordx4 v[2:3], off
	v_lshlrev_b32_e32 v1, 12, v1
	v_and_b32_e32 v11, 48, v142
	v_and_b32_e32 v6, 0x3000, v1
	v_lshlrev_b32_e32 v1, 6, v10
	v_lshlrev_b32_e32 v3, 2, v142
	v_or_b32_e32 v2, v1, v11
	v_and_b32_e32 v3, 32, v3
	s_mov_b32 s2, 0x14000
	v_bitop3_b32 v13, v2, s2, v3 bitop3:0xde
	s_mov_b32 s2, 0x18000
	v_lshlrev_b32_e32 v16, 13, v0
	v_lshlrev_b32_e32 v0, 6, v142
	v_bitop3_b32 v14, v2, s2, v3 bitop3:0xde
	s_mov_b32 s2, 0x1c000
	v_and_b32_e32 v0, 0x3c0, v0
	v_bitop3_b32 v10, v1, v3, v11 bitop3:0x36
	v_bitop3_b32 v12, v2, s3, v3 bitop3:0xde
	v_bitop3_b32 v15, v2, s2, v3 bitop3:0xde
	v_bitop3_b32 v11, v0, v3, v11 bitop3:0x36
	v_lshlrev_b32_e32 v0, 11, v9
	s_movk_i32 s2, 0x8000
	v_lshlrev_b32_e32 v3, 11, v4
	v_and_or_b32 v0, v0, s2, v8
	v_lshlrev_b32_e32 v2, 11, v5
	v_and_or_b32 v3, v3, s2, v8
	v_or3_b32 v0, v0, v2, v7
	v_mov_b32_e32 v1, v167
	v_or3_b32 v2, v3, v2, v7
	v_mov_b32_e32 v3, v167
	v_lshlrev_b64 v[0:1], 1, v[0:1]
	v_lshlrev_b64 v[2:3], 1, v[2:3]
	v_lshl_add_u64 v[134:135], s[0:1], 0, v[0:1]
	v_lshl_add_u64 v[136:137], s[0:1], 0, v[2:3]
	s_add_u32 s0, s4, s54
	s_waitcnt vmcnt(6)
	s_addc_u32 s1, s5, s55
	v_or_b32_e32 v17, 0x800, v16
	v_or_b32_e32 v18, 0x1000, v16
	v_or_b32_e32 v19, 0x1800, v16
	v_lshl_add_u64 v[138:139], s[0:1], 0, v[0:1]
	v_mov_b32_e32 v0, 0
	v_lshl_add_u64 v[140:141], s[0:1], 0, v[2:3]
	s_mov_b32 s0, -2
	v_add_u32_e32 v157, v12, v6
	v_add_u32_e32 v147, v10, v16
	v_add_u32_e32 v146, v11, v17
	v_add_u32_e32 v145, v11, v18
	v_add_u32_e32 v144, v11, v19
	v_add_u32_e32 v155, v13, v6
	v_add_u32_e32 v149, v14, v6
	v_add_u32_e32 v148, v15, v6
	v_mov_b32_e32 v1, v0
	v_mov_b32_e32 v2, v0
	v_mov_b32_e32 v3, v0
	v_mov_b32_e32 v4, v0
	v_mov_b32_e32 v5, v0
	v_mov_b32_e32 v6, v0
	v_mov_b32_e32 v7, v0
	v_mov_b32_e32 v8, v0
	v_mov_b32_e32 v9, v0
	v_mov_b32_e32 v10, v0
	v_mov_b32_e32 v11, v0
	v_mov_b32_e32 v12, v0
	v_mov_b32_e32 v13, v0
	v_mov_b32_e32 v14, v0
	v_mov_b32_e32 v15, v0
	v_mov_b32_e32 v16, v0
	v_mov_b32_e32 v17, v0
	v_mov_b32_e32 v18, v0
	v_mov_b32_e32 v19, v0
	v_mov_b32_e32 v20, v0
	v_mov_b32_e32 v21, v0
	v_mov_b32_e32 v22, v0
	v_mov_b32_e32 v23, v0
	v_mov_b32_e32 v24, v0
	v_mov_b32_e32 v25, v0
	v_mov_b32_e32 v26, v0
	v_mov_b32_e32 v27, v0
	v_mov_b32_e32 v28, v0
	v_mov_b32_e32 v29, v0
	v_mov_b32_e32 v30, v0
	v_mov_b32_e32 v31, v0
	v_mov_b32_e32 v32, v0
	v_mov_b32_e32 v33, v0
	v_mov_b32_e32 v34, v0
	v_mov_b32_e32 v35, v0
	v_mov_b32_e32 v36, v0
	v_mov_b32_e32 v37, v0
	v_mov_b32_e32 v38, v0
	v_mov_b32_e32 v39, v0
	v_mov_b32_e32 v40, v0
	v_mov_b32_e32 v41, v0
	v_mov_b32_e32 v42, v0
	v_mov_b32_e32 v43, v0
	v_mov_b32_e32 v44, v0
	v_mov_b32_e32 v45, v0
	v_mov_b32_e32 v46, v0
	v_mov_b32_e32 v47, v0
	v_mov_b32_e32 v48, v0
	v_mov_b32_e32 v49, v0
	v_mov_b32_e32 v50, v0
	v_mov_b32_e32 v51, v0
	v_mov_b32_e32 v52, v0
	v_mov_b32_e32 v53, v0
	v_mov_b32_e32 v54, v0
	v_mov_b32_e32 v55, v0
	v_mov_b32_e32 v56, v0
	v_mov_b32_e32 v57, v0
	v_mov_b32_e32 v58, v0
	v_mov_b32_e32 v59, v0
	v_mov_b32_e32 v60, v0
	v_mov_b32_e32 v61, v0
	v_mov_b32_e32 v62, v0
	v_mov_b32_e32 v63, v0
	v_mov_b32_e32 v64, v0
	v_mov_b32_e32 v65, v0
	v_mov_b32_e32 v66, v0
	v_mov_b32_e32 v67, v0
	v_mov_b32_e32 v68, v0
	v_mov_b32_e32 v69, v0
	v_mov_b32_e32 v70, v0
	v_mov_b32_e32 v71, v0
	v_mov_b32_e32 v72, v0
	v_mov_b32_e32 v73, v0
	v_mov_b32_e32 v74, v0
	v_mov_b32_e32 v75, v0
	v_mov_b32_e32 v76, v0
	v_mov_b32_e32 v77, v0
	v_mov_b32_e32 v78, v0
	v_mov_b32_e32 v79, v0
	v_mov_b32_e32 v80, v0
	v_mov_b32_e32 v81, v0
	v_mov_b32_e32 v82, v0
	v_mov_b32_e32 v83, v0
	v_mov_b32_e32 v84, v0
	v_mov_b32_e32 v85, v0
	v_mov_b32_e32 v86, v0
	v_mov_b32_e32 v87, v0
	v_mov_b32_e32 v88, v0
	v_mov_b32_e32 v89, v0
	v_mov_b32_e32 v90, v0
	v_mov_b32_e32 v91, v0
	v_mov_b32_e32 v92, v0
	v_mov_b32_e32 v93, v0
	v_mov_b32_e32 v94, v0
	v_mov_b32_e32 v95, v0
	v_mov_b32_e32 v96, v0
	v_mov_b32_e32 v97, v0
	v_mov_b32_e32 v98, v0
	v_mov_b32_e32 v99, v0
	v_mov_b32_e32 v100, v0
	v_mov_b32_e32 v101, v0
	v_mov_b32_e32 v102, v0
	v_mov_b32_e32 v103, v0
	v_mov_b32_e32 v104, v0
	v_mov_b32_e32 v105, v0
	v_mov_b32_e32 v106, v0
	v_mov_b32_e32 v107, v0
	v_mov_b32_e32 v108, v0
	v_mov_b32_e32 v109, v0
	v_mov_b32_e32 v110, v0
	v_mov_b32_e32 v111, v0
	v_mov_b32_e32 v112, v0
	v_mov_b32_e32 v113, v0
	v_mov_b32_e32 v114, v0
	v_mov_b32_e32 v115, v0
	v_mov_b32_e32 v116, v0
	v_mov_b32_e32 v117, v0
	v_mov_b32_e32 v118, v0
	v_mov_b32_e32 v119, v0
	v_mov_b32_e32 v120, v0
	v_mov_b32_e32 v121, v0
	v_mov_b32_e32 v122, v0
	v_mov_b32_e32 v123, v0
	v_mov_b32_e32 v124, v0
	v_mov_b32_e32 v125, v0
	v_mov_b32_e32 v126, v0
	v_mov_b32_e32 v127, v0
	s_mov_b64 s[54:55], 0x2a80080
	s_mov_b64 s[60:61], 0x2a00100
	s_mov_b64 s[82:83], 0x2a80100
	s_mov_b64 s[92:93], 0x2a00180
	s_barrier
; #define P8_STAGE(P,BASE,br,kt) do{const bfr* _ub=(BASE)+((long)(br)*K+(long)(kt)*BK); \
;     __builtin_amdgcn_global_load_lds((const unsigned*)(_ub+so0),(unsigned*)((char*)(P)+wid*1024),16,0,0); \
;     __builtin_amdgcn_global_load_lds((const unsigned*)(_ub+so1),(unsigned*)((char*)(P)+wid*1024+8192),16,0,0);}while(0)
; #define P8_LDA(dst,b,h) _Pragma("unroll") for(int m=0;m<4;++m) _Pragma("unroll") for(int k=0;k<2;++k) \
;     dst[m][k]=*reinterpret_cast<const bf16x8*>((char*)P8_SA(b,h)+lds_byte(wr*64+m*16+fr,k*32+fq*8))
; #define P8_LDB(dst,b,h) _Pragma("unroll") for(int n=0;n<2;++n) _Pragma("unroll") for(int k=0;k<2;++k) \
;     dst[n][k]=*reinterpret_cast<const bf16x8*>((char*)P8_SB(b,h)+lds_byte(wc*32+n*16+fr,k*32+fq*8))
; #define P8_MMA(ai,bj,At,Bt) do{__builtin_amdgcn_s_setprio(1); \
;     _Pragma("unroll") for(int m=0;m<4;++m) _Pragma("unroll") for(int n=0;n<2;++n) _Pragma("unroll") for(int k=0;k<2;++k) \
;       acc[ai][bj][m][n]=__builtin_amdgcn_mfma_f32_16x16x32_bf16(At[m][k],Bt[n][k],acc[ai][bj][m][n],0,0,0); \
;     __builtin_amdgcn_s_setprio(0);}while(0)
; #define P8_WAIT_V(n) asm volatile("s_waitcnt vmcnt(" #n ")":::"memory")
; #define P8_WAIT_L(n) asm volatile("s_waitcnt lgkmcnt(" #n ")":::"memory")
; #define P8_BAR __builtin_amdgcn_s_barrier()
; #define P8_SCHED __builtin_amdgcn_sched_barrier(0)
; template <class EPI>
; DEVI void gemm8_tile(const bfr* __restrict__ A, const bfr* __restrict__ Bt, int K, int brow, int bcol, int nbrow, int nbcol, char* shmc, EPI epi) {
;     ...
;     P8_LDB(B0,0,0); P8_SCHED; P8_LDA(At,0,0); P8_STAGE(P8_SA(1,1),A,brow+128,t+1);
;     P8_WAIT_L(8); P8_BAR; P8_WAIT_L(0); P8_MMA(0,0,At,B0); P8_BAR; P8_SCHED;
;     P8_LDB(B1,0,1); P8_STAGE(P8_SB(0,0),Bt,bcol,t+2);
;     P8_BAR; P8_WAIT_L(0); P8_MMA(0,1,At,B1); P8_BAR;
;     P8_LDA(At,0,1); P8_STAGE(P8_SA(0,0),A,brow,t+2);
;     P8_BAR; P8_WAIT_L(0); P8_MMA(1,0,At,B0); P8_BAR; P8_SCHED;
;     P8_STAGE(P8_SB(0,1),Bt,bcol+128,t+2);
;     P8_WAIT_V(6); P8_BAR; P8_MMA(1,1,At,B1); P8_BAR;
.LBB0_286:
	ds_read_b128 v[174:177], v157
	ds_read_b128 v[178:181], v157 offset:1024
	ds_read_b128 v[182:185], v157 offset:2048
	ds_read_b128 v[186:189], v157 offset:3072
	v_add_u32_e32 v171, 0xc000, v143
	v_add_u32_e32 v172, 0xe000, v143
	v_add_u32_e32 v158, s54, v140
	s_add_i32 m0, s100, 0xc000
	ds_read_b128 v[160:163], v147
	ds_read_b128 v[190:193], v147 offset:1024
	ds_read_b128 v[196:199], v146
	ds_read_b128 v[200:203], v146 offset:1024
	ds_read_b128 v[204:207], v145
	ds_read_b128 v[208:211], v145 offset:1024
	ds_read_b128 v[212:215], v144
	ds_read_b128 v[216:219], v144 offset:1024
	global_load_lds_dwordx4 v158, s[86:87]
	v_add_u32_e32 v158, s54, v138
	s_add_i32 m0, s100, 0xe000
	s_nop 0
	global_load_lds_dwordx4 v158, s[86:87]
	s_waitcnt lgkmcnt(8)
	s_barrier
	s_waitcnt lgkmcnt(0)
	s_setprio 1
	s_waitcnt lgkmcnt(0)
	v_mfma_f32_16x16x32_bf16 v[124:127], v[160:163], v[174:177], v[124:127]
	v_mfma_f32_16x16x32_bf16 v[120:123], v[160:163], v[182:185], v[120:123]
	v_mfma_f32_16x16x32_bf16 v[116:119], v[196:199], v[174:177], v[116:119]
	v_mfma_f32_16x16x32_bf16 v[112:115], v[196:199], v[182:185], v[112:115]
	v_mfma_f32_16x16x32_bf16 v[108:111], v[204:207], v[174:177], v[108:111]
	v_mfma_f32_16x16x32_bf16 v[104:107], v[204:207], v[182:185], v[104:107]
	v_mfma_f32_16x16x32_bf16 v[100:103], v[212:215], v[174:177], v[100:103]
	v_mfma_f32_16x16x32_bf16 v[96:99], v[212:215], v[182:185], v[96:99]
	v_mfma_f32_16x16x32_bf16 v[124:127], v[190:193], v[178:181], v[124:127]
	v_mfma_f32_16x16x32_bf16 v[120:123], v[190:193], v[186:189], v[120:123]
	v_mfma_f32_16x16x32_bf16 v[116:119], v[200:203], v[178:181], v[116:119]
	v_mfma_f32_16x16x32_bf16 v[112:115], v[200:203], v[186:189], v[112:115]
	v_mfma_f32_16x16x32_bf16 v[108:111], v[208:211], v[178:181], v[108:111]
	v_mfma_f32_16x16x32_bf16 v[104:107], v[208:211], v[186:189], v[104:107]
	v_mfma_f32_16x16x32_bf16 v[100:103], v[216:219], v[178:181], v[100:103]
	v_mfma_f32_16x16x32_bf16 v[96:99], v[216:219], v[186:189], v[96:99]
	s_setprio 0
	s_barrier
	v_add_u32_e32 v158, 0x10000, v143
	v_add_u32_e32 v159, 0x12000, v143
	v_add_u32_e32 v236, s66, v136
	s_add_i32 m0, s100, 0x10000
	ds_read_b128 v[220:223], v155
	ds_read_b128 v[224:227], v155 offset:1024
	ds_read_b128 v[228:231], v155 offset:2048
	ds_read_b128 v[232:235], v155 offset:3072
	global_load_lds_dwordx4 v236, s[86:87]
	v_add_u32_e32 v236, s66, v134
	s_add_i32 m0, s100, 0x12000
	s_nop 0
	global_load_lds_dwordx4 v236, s[86:87]
	s_barrier
	s_waitcnt lgkmcnt(0)
	s_setprio 1
	s_waitcnt lgkmcnt(0)
	v_mfma_f32_16x16x32_bf16 v[92:95], v[160:163], v[220:223], v[92:95]
	v_mfma_f32_16x16x32_bf16 v[88:91], v[160:163], v[228:231], v[88:91]
	v_mfma_f32_16x16x32_bf16 v[84:87], v[196:199], v[220:223], v[84:87]
	v_mfma_f32_16x16x32_bf16 v[80:83], v[196:199], v[228:231], v[80:83]
	v_mfma_f32_16x16x32_bf16 v[76:79], v[204:207], v[220:223], v[76:79]
	v_mfma_f32_16x16x32_bf16 v[72:75], v[204:207], v[228:231], v[72:75]
	v_mfma_f32_16x16x32_bf16 v[68:71], v[212:215], v[220:223], v[68:71]
	v_mfma_f32_16x16x32_bf16 v[64:67], v[212:215], v[228:231], v[64:67]
	v_mfma_f32_16x16x32_bf16 v[92:95], v[190:193], v[224:227], v[92:95]
	v_mfma_f32_16x16x32_bf16 v[88:91], v[190:193], v[232:235], v[88:91]
	v_mfma_f32_16x16x32_bf16 v[84:87], v[200:203], v[224:227], v[84:87]
	v_mfma_f32_16x16x32_bf16 v[80:83], v[200:203], v[232:235], v[80:83]
	v_mfma_f32_16x16x32_bf16 v[76:79], v[208:211], v[224:227], v[76:79]
	v_mfma_f32_16x16x32_bf16 v[72:75], v[208:211], v[232:235], v[72:75]
	v_mfma_f32_16x16x32_bf16 v[68:71], v[216:219], v[224:227], v[68:71]
	v_mfma_f32_16x16x32_bf16 v[64:67], v[216:219], v[232:235], v[64:67]
	s_setprio 0
	v_add_u32_e32 v160, s60, v140
	s_mov_b32 m0, s100
	s_barrier
	ds_read_b128 v[190:193], v147 offset:16384
	ds_read_b128 v[196:199], v147 offset:17408
	ds_read_b128 v[200:203], v146 offset:16384
	ds_read_b128 v[204:207], v146 offset:17408
	ds_read_b128 v[208:211], v145 offset:16384
	ds_read_b128 v[212:215], v145 offset:17408
	ds_read_b128 v[216:219], v144 offset:16384
	ds_read_b128 v[236:239], v144 offset:17408
	global_load_lds_dwordx4 v160, s[86:87]
	v_add_u32_e32 v160, 0x2000, v143
	v_add_u32_e32 v162, s60, v138
	s_add_i32 m0, s100, 0x2000
	s_nop 0
	global_load_lds_dwordx4 v162, s[86:87]
	s_barrier
	s_waitcnt lgkmcnt(0)
	s_setprio 1
	s_waitcnt lgkmcnt(0)
	v_mfma_f32_16x16x32_bf16 v[60:63], v[190:193], v[174:177], v[60:63]
	v_mfma_f32_16x16x32_bf16 v[56:59], v[190:193], v[182:185], v[56:59]
	v_mfma_f32_16x16x32_bf16 v[52:55], v[200:203], v[174:177], v[52:55]
	v_mfma_f32_16x16x32_bf16 v[48:51], v[200:203], v[182:185], v[48:51]
	v_mfma_f32_16x16x32_bf16 v[44:47], v[208:211], v[174:177], v[44:47]
	v_mfma_f32_16x16x32_bf16 v[40:43], v[208:211], v[182:185], v[40:43]
	v_mfma_f32_16x16x32_bf16 v[36:39], v[216:219], v[174:177], v[36:39]
	v_mfma_f32_16x16x32_bf16 v[32:35], v[216:219], v[182:185], v[32:35]
	v_mfma_f32_16x16x32_bf16 v[60:63], v[196:199], v[178:181], v[60:63]
	v_mfma_f32_16x16x32_bf16 v[56:59], v[196:199], v[186:189], v[56:59]
	v_mfma_f32_16x16x32_bf16 v[52:55], v[204:207], v[178:181], v[52:55]
	v_mfma_f32_16x16x32_bf16 v[48:51], v[204:207], v[186:189], v[48:51]
	v_mfma_f32_16x16x32_bf16 v[44:47], v[212:215], v[178:181], v[44:47]
	v_mfma_f32_16x16x32_bf16 v[40:43], v[212:215], v[186:189], v[40:43]
	v_mfma_f32_16x16x32_bf16 v[36:39], v[236:239], v[178:181], v[36:39]
	v_mfma_f32_16x16x32_bf16 v[32:35], v[236:239], v[186:189], v[32:35]
	s_setprio 0
	s_barrier
	v_add_u32_e32 v161, 0x14000, v143
	v_add_u32_e32 v162, s70, v136
	s_add_i32 m0, s100, 0x14000
	v_add_u32_e32 v174, s70, v134
	global_load_lds_dwordx4 v162, s[86:87]
	v_add_u32_e32 v162, 0x16000, v143
	s_nop 0
	s_add_i32 m0, s100, 0x16000
	s_nop 0
	global_load_lds_dwordx4 v174, s[86:87]
	s_waitcnt vmcnt(6)
	s_barrier
; #define P8_STAGE(P,BASE,br,kt) do{const bfr* _ub=(BASE)+((long)(br)*K+(long)(kt)*BK); \
;     __builtin_amdgcn_global_load_lds((const unsigned*)(_ub+so0),(unsigned*)((char*)(P)+wid*1024),16,0,0); \
;     __builtin_amdgcn_global_load_lds((const unsigned*)(_ub+so1),(unsigned*)((char*)(P)+wid*1024+8192),16,0,0);}while(0)
; #define P8_LDA(dst,b,h) _Pragma("unroll") for(int m=0;m<4;++m) _Pragma("unroll") for(int k=0;k<2;++k) \
;     dst[m][k]=*reinterpret_cast<const bf16x8*>((char*)P8_SA(b,h)+lds_byte(wr*64+m*16+fr,k*32+fq*8))
; #define P8_LDB(dst,b,h) _Pragma("unroll") for(int n=0;n<2;++n) _Pragma("unroll") for(int k=0;k<2;++k) \
;     dst[n][k]=*reinterpret_cast<const bf16x8*>((char*)P8_SB(b,h)+lds_byte(wc*32+n*16+fr,k*32+fq*8))
; #define P8_MMA(ai,bj,At,Bt) do{__builtin_amdgcn_s_setprio(1); \
;     _Pragma("unroll") for(int m=0;m<4;++m) _Pragma("unroll") for(int n=0;n<2;++n) _Pragma("unroll") for(int k=0;k<2;++k) \
;       acc[ai][bj][m][n]=__builtin_amdgcn_mfma_f32_16x16x32_bf16(At[m][k],Bt[n][k],acc[ai][bj][m][n],0,0,0); \
;     __builtin_amdgcn_s_setprio(0);}while(0)
; #define P8_WAIT_V(n) asm volatile("s_waitcnt vmcnt(" #n ")":::"memory")
; #define P8_WAIT_L(n) asm volatile("s_waitcnt lgkmcnt(" #n ")":::"memory")
; #define P8_BAR __builtin_amdgcn_s_barrier()
; #define P8_SCHED __builtin_amdgcn_sched_barrier(0)
; template <class EPI>
; DEVI void gemm8_tile(const bfr* __restrict__ A, const bfr* __restrict__ Bt, int K, int brow, int bcol, int nbrow, int nbcol, char* shmc, EPI epi) {
;     ...
;     P8_WAIT_V(6); P8_BAR; P8_MMA(1,1,At,B1); P8_BAR;
;     P8_LDB(B0,1,0); P8_SCHED; P8_LDA(At,1,0); P8_STAGE(P8_SA(0,1),A,brow+128,t+2);
;     P8_WAIT_L(8); P8_BAR; P8_WAIT_L(0); P8_MMA(0,0,At,B0); P8_BAR; P8_SCHED;
;     P8_LDB(B1,1,1); P8_STAGE(P8_SB(1,0),Bt,bcol,t+3);
;     P8_BAR; P8_WAIT_L(0); P8_MMA(0,1,At,B1); P8_BAR;
;     P8_LDA(At,1,1); P8_STAGE(P8_SA(1,0),A,brow,t+3);
;     P8_BAR; P8_WAIT_L(0); P8_MMA(1,0,At,B0); P8_BAR; P8_SCHED;
	s_setprio 1
	v_mfma_f32_16x16x32_bf16 v[28:31], v[190:193], v[220:223], v[28:31]
	v_mfma_f32_16x16x32_bf16 v[24:27], v[190:193], v[228:231], v[24:27]
	v_mfma_f32_16x16x32_bf16 v[20:23], v[200:203], v[220:223], v[20:23]
	v_mfma_f32_16x16x32_bf16 v[16:19], v[200:203], v[228:231], v[16:19]
	v_mfma_f32_16x16x32_bf16 v[12:15], v[208:211], v[220:223], v[12:15]
	v_mfma_f32_16x16x32_bf16 v[8:11], v[208:211], v[228:231], v[8:11]
	v_mfma_f32_16x16x32_bf16 v[4:7], v[216:219], v[220:223], v[4:7]
	v_mfma_f32_16x16x32_bf16 v[0:3], v[216:219], v[228:231], v[0:3]
	v_mfma_f32_16x16x32_bf16 v[28:31], v[196:199], v[224:227], v[28:31]
	v_mfma_f32_16x16x32_bf16 v[24:27], v[196:199], v[232:235], v[24:27]
	v_mfma_f32_16x16x32_bf16 v[20:23], v[204:207], v[224:227], v[20:23]
	v_mfma_f32_16x16x32_bf16 v[16:19], v[204:207], v[232:235], v[16:19]
	v_mfma_f32_16x16x32_bf16 v[12:15], v[212:215], v[224:227], v[12:15]
	v_mfma_f32_16x16x32_bf16 v[8:11], v[212:215], v[232:235], v[8:11]
	v_mfma_f32_16x16x32_bf16 v[4:7], v[236:239], v[224:227], v[4:7]
	v_mfma_f32_16x16x32_bf16 v[0:3], v[236:239], v[232:235], v[0:3]
	s_setprio 0
	s_barrier
	ds_read_b128 v[174:177], v149
	ds_read_b128 v[178:181], v149 offset:1024
	ds_read_b128 v[182:185], v149 offset:2048
	ds_read_b128 v[186:189], v149 offset:3072
	v_add_u32_e32 v163, 0x4000, v143
	v_add_u32_e32 v170, 0x6000, v143
	v_add_u32_e32 v224, s82, v140
	s_add_i32 m0, s100, 0x4000
	ds_read_b128 v[190:193], v147 offset:32768
	ds_read_b128 v[196:199], v147 offset:33792
	ds_read_b128 v[200:203], v146 offset:32768
	ds_read_b128 v[204:207], v146 offset:33792
	ds_read_b128 v[208:211], v145 offset:32768
	ds_read_b128 v[212:215], v145 offset:33792
	ds_read_b128 v[216:219], v144 offset:32768
	ds_read_b128 v[220:223], v144 offset:33792
	global_load_lds_dwordx4 v224, s[86:87]
	v_add_u32_e32 v224, s82, v138
	s_add_i32 m0, s100, 0x6000
	s_nop 0
	global_load_lds_dwordx4 v224, s[86:87]
	s_waitcnt lgkmcnt(8)
	s_barrier
	s_waitcnt lgkmcnt(0)
	s_setprio 1
	s_waitcnt lgkmcnt(0)
	v_mfma_f32_16x16x32_bf16 v[124:127], v[190:193], v[174:177], v[124:127]
	v_mfma_f32_16x16x32_bf16 v[120:123], v[190:193], v[182:185], v[120:123]
	v_mfma_f32_16x16x32_bf16 v[116:119], v[200:203], v[174:177], v[116:119]
	v_mfma_f32_16x16x32_bf16 v[112:115], v[200:203], v[182:185], v[112:115]
	v_mfma_f32_16x16x32_bf16 v[108:111], v[208:211], v[174:177], v[108:111]
	v_mfma_f32_16x16x32_bf16 v[104:107], v[208:211], v[182:185], v[104:107]
	v_mfma_f32_16x16x32_bf16 v[100:103], v[216:219], v[174:177], v[100:103]
	v_mfma_f32_16x16x32_bf16 v[96:99], v[216:219], v[182:185], v[96:99]
	v_mfma_f32_16x16x32_bf16 v[124:127], v[196:199], v[178:181], v[124:127]
	v_mfma_f32_16x16x32_bf16 v[120:123], v[196:199], v[186:189], v[120:123]
	v_mfma_f32_16x16x32_bf16 v[116:119], v[204:207], v[178:181], v[116:119]
	v_mfma_f32_16x16x32_bf16 v[112:115], v[204:207], v[186:189], v[112:115]
	v_mfma_f32_16x16x32_bf16 v[108:111], v[212:215], v[178:181], v[108:111]
	v_mfma_f32_16x16x32_bf16 v[104:107], v[212:215], v[186:189], v[104:107]
	v_mfma_f32_16x16x32_bf16 v[100:103], v[220:223], v[178:181], v[100:103]
	v_mfma_f32_16x16x32_bf16 v[96:99], v[220:223], v[186:189], v[96:99]
	s_setprio 0
	s_barrier
	v_add_u32_e32 v248, s74, v136
	s_add_i32 m0, s100, 0x18000
	ds_read_b128 v[224:227], v148
	ds_read_b128 v[228:231], v148 offset:1024
	ds_read_b128 v[232:235], v148 offset:2048
	ds_read_b128 v[236:239], v148 offset:3072
	global_load_lds_dwordx4 v248, s[86:87]
	v_add_u32_e32 v248, s74, v134
	s_add_i32 m0, s100, 0x1a000
	s_nop 0
	global_load_lds_dwordx4 v248, s[86:87]
	s_barrier
	s_waitcnt lgkmcnt(0)
	s_setprio 1
	s_waitcnt lgkmcnt(0)
	v_mfma_f32_16x16x32_bf16 v[92:95], v[190:193], v[224:227], v[92:95]
	v_mfma_f32_16x16x32_bf16 v[88:91], v[190:193], v[232:235], v[88:91]
	v_mfma_f32_16x16x32_bf16 v[84:87], v[200:203], v[224:227], v[84:87]
	v_mfma_f32_16x16x32_bf16 v[80:83], v[200:203], v[232:235], v[80:83]
	v_mfma_f32_16x16x32_bf16 v[76:79], v[208:211], v[224:227], v[76:79]
	v_mfma_f32_16x16x32_bf16 v[72:75], v[208:211], v[232:235], v[72:75]
	v_mfma_f32_16x16x32_bf16 v[68:71], v[216:219], v[224:227], v[68:71]
	v_mfma_f32_16x16x32_bf16 v[64:67], v[216:219], v[232:235], v[64:67]
	v_mfma_f32_16x16x32_bf16 v[92:95], v[196:199], v[228:231], v[92:95]
	v_mfma_f32_16x16x32_bf16 v[88:91], v[196:199], v[236:239], v[88:91]
	v_mfma_f32_16x16x32_bf16 v[84:87], v[204:207], v[228:231], v[84:87]
	v_mfma_f32_16x16x32_bf16 v[80:83], v[204:207], v[236:239], v[80:83]
	v_mfma_f32_16x16x32_bf16 v[76:79], v[212:215], v[228:231], v[76:79]
	v_mfma_f32_16x16x32_bf16 v[72:75], v[212:215], v[236:239], v[72:75]
	v_mfma_f32_16x16x32_bf16 v[68:71], v[220:223], v[228:231], v[68:71]
	v_mfma_f32_16x16x32_bf16 v[64:67], v[220:223], v[236:239], v[64:67]
	s_setprio 0
	v_add_u32_e32 v240, s92, v140
	s_add_i32 m0, s100, 0x8000
	s_barrier
	ds_read_b128 v[190:193], v147 offset:49152
	ds_read_b128 v[196:199], v147 offset:50176
	ds_read_b128 v[200:203], v146 offset:49152
	ds_read_b128 v[204:207], v146 offset:50176
	ds_read_b128 v[208:211], v145 offset:49152
	ds_read_b128 v[212:215], v145 offset:50176
	ds_read_b128 v[216:219], v144 offset:49152
	ds_read_b128 v[220:223], v144 offset:50176
	global_load_lds_dwordx4 v240, s[86:87]
	v_add_u32_e32 v240, s92, v138
	s_add_i32 m0, s100, 0xa000
	s_nop 0
	global_load_lds_dwordx4 v240, s[86:87]
	s_barrier
; #define P8_STAGE(P,BASE,br,kt) do{const bfr* _ub=(BASE)+((long)(br)*K+(long)(kt)*BK); \
;     __builtin_amdgcn_global_load_lds((const unsigned*)(_ub+so0),(unsigned*)((char*)(P)+wid*1024),16,0,0); \
;     __builtin_amdgcn_global_load_lds((const unsigned*)(_ub+so1),(unsigned*)((char*)(P)+wid*1024+8192),16,0,0);}while(0)
; #define P8_LDA(dst,b,h) _Pragma("unroll") for(int m=0;m<4;++m) _Pragma("unroll") for(int k=0;k<2;++k) \
;     dst[m][k]=*reinterpret_cast<const bf16x8*>((char*)P8_SA(b,h)+lds_byte(wr*64+m*16+fr,k*32+fq*8))
; #define P8_LDB(dst,b,h) _Pragma("unroll") for(int n=0;n<2;++n) _Pragma("unroll") for(int k=0;k<2;++k) \
;     dst[n][k]=*reinterpret_cast<const bf16x8*>((char*)P8_SB(b,h)+lds_byte(wc*32+n*16+fr,k*32+fq*8))
; #define P8_MMA(ai,bj,At,Bt) do{__builtin_amdgcn_s_setprio(1); \
;     _Pragma("unroll") for(int m=0;m<4;++m) _Pragma("unroll") for(int n=0;n<2;++n) _Pragma("unroll") for(int k=0;k<2;++k) \
;       acc[ai][bj][m][n]=__builtin_amdgcn_mfma_f32_16x16x32_bf16(At[m][k],Bt[n][k],acc[ai][bj][m][n],0,0,0); \
;     __builtin_amdgcn_s_setprio(0);}while(0)
; #define P8_WAIT_V(n) asm volatile("s_waitcnt vmcnt(" #n ")":::"memory")
; #define P8_WAIT_L(n) asm volatile("s_waitcnt lgkmcnt(" #n ")":::"memory")
; #define P8_BAR __builtin_amdgcn_s_barrier()
; #define P8_SCHED __builtin_amdgcn_sched_barrier(0)
; template <class EPI>
; DEVI void gemm8_tile(const bfr* __restrict__ A, const bfr* __restrict__ Bt, int K, int brow, int bcol, int nbrow, int nbcol, char* shmc, EPI epi) {
;     ...
;     P8_BAR; P8_WAIT_L(0); P8_MMA(1,0,At,B0); P8_BAR; P8_SCHED;
;     P8_STAGE(P8_SB(1,1),Bt,bcol+128,t+3);
;     P8_WAIT_V(6); P8_BAR; P8_MMA(1,1,At,B1); P8_BAR;
;   }
;   { P8_LDB(B0,0,0); P8_LDA(At,0,0); P8_STAGE(P8_SA(1,1),A,brow+128,nt-1);
;     P8_BAR; P8_WAIT_L(0); P8_MMA(0,0,At,B0); P8_BAR;
	s_waitcnt lgkmcnt(0)
	s_setprio 1
	s_waitcnt lgkmcnt(0)
	v_mfma_f32_16x16x32_bf16 v[60:63], v[190:193], v[174:177], v[60:63]
	v_mfma_f32_16x16x32_bf16 v[56:59], v[190:193], v[182:185], v[56:59]
	v_mfma_f32_16x16x32_bf16 v[52:55], v[200:203], v[174:177], v[52:55]
	v_mfma_f32_16x16x32_bf16 v[48:51], v[200:203], v[182:185], v[48:51]
	v_mfma_f32_16x16x32_bf16 v[44:47], v[208:211], v[174:177], v[44:47]
	v_mfma_f32_16x16x32_bf16 v[40:43], v[208:211], v[182:185], v[40:43]
	v_mfma_f32_16x16x32_bf16 v[36:39], v[216:219], v[174:177], v[36:39]
	v_mfma_f32_16x16x32_bf16 v[32:35], v[216:219], v[182:185], v[32:35]
	v_mfma_f32_16x16x32_bf16 v[60:63], v[196:199], v[178:181], v[60:63]
	v_mfma_f32_16x16x32_bf16 v[56:59], v[196:199], v[186:189], v[56:59]
	v_mfma_f32_16x16x32_bf16 v[52:55], v[204:207], v[178:181], v[52:55]
	v_mfma_f32_16x16x32_bf16 v[48:51], v[204:207], v[186:189], v[48:51]
	v_mfma_f32_16x16x32_bf16 v[44:47], v[212:215], v[178:181], v[44:47]
	v_mfma_f32_16x16x32_bf16 v[40:43], v[212:215], v[186:189], v[40:43]
	v_mfma_f32_16x16x32_bf16 v[36:39], v[220:223], v[178:181], v[36:39]
	v_mfma_f32_16x16x32_bf16 v[32:35], v[220:223], v[186:189], v[32:35]
	s_setprio 0
	s_barrier
	v_add_u32_e32 v174, s78, v136
	s_add_i32 m0, s100, 0x1c000
	s_nop 0
	global_load_lds_dwordx4 v174, s[86:87]
	v_add_u32_e32 v174, s78, v134
	s_add_i32 m0, s100, 0x1e000
	s_nop 0
	global_load_lds_dwordx4 v174, s[86:87]
	s_waitcnt vmcnt(6)
	s_barrier
	s_setprio 1
	v_mfma_f32_16x16x32_bf16 v[28:31], v[190:193], v[224:227], v[28:31]
	v_mfma_f32_16x16x32_bf16 v[24:27], v[190:193], v[232:235], v[24:27]
	v_mfma_f32_16x16x32_bf16 v[20:23], v[200:203], v[224:227], v[20:23]
	v_mfma_f32_16x16x32_bf16 v[16:19], v[200:203], v[232:235], v[16:19]
	v_mfma_f32_16x16x32_bf16 v[12:15], v[208:211], v[224:227], v[12:15]
	v_mfma_f32_16x16x32_bf16 v[8:11], v[208:211], v[232:235], v[8:11]
	v_mfma_f32_16x16x32_bf16 v[4:7], v[216:219], v[224:227], v[4:7]
	v_mfma_f32_16x16x32_bf16 v[0:3], v[216:219], v[232:235], v[0:3]
	v_mfma_f32_16x16x32_bf16 v[28:31], v[196:199], v[228:231], v[28:31]
	v_mfma_f32_16x16x32_bf16 v[24:27], v[196:199], v[236:239], v[24:27]
	v_mfma_f32_16x16x32_bf16 v[20:23], v[204:207], v[228:231], v[20:23]
	v_mfma_f32_16x16x32_bf16 v[16:19], v[204:207], v[236:239], v[16:19]
	v_mfma_f32_16x16x32_bf16 v[12:15], v[212:215], v[228:231], v[12:15]
	v_mfma_f32_16x16x32_bf16 v[8:11], v[212:215], v[236:239], v[8:11]
	v_mfma_f32_16x16x32_bf16 v[4:7], v[220:223], v[228:231], v[4:7]
	v_mfma_f32_16x16x32_bf16 v[0:3], v[220:223], v[236:239], v[0:3]
	s_setprio 0
	s_add_i32 s0, s0, 2
	v_lshl_add_u64 v[134:135], v[134:135], 0, s[80:81]
	v_lshl_add_u64 v[136:137], v[136:137], 0, s[80:81]
	v_lshl_add_u64 v[138:139], v[138:139], 0, s[80:81]
	s_cmp_lt_u32 s0, 28
	v_lshl_add_u64 v[140:141], v[140:141], 0, s[80:81]
	s_barrier
	s_cbranch_scc1 .LBB0_286
	s_or_b32 s0, s8, 0x80
	s_ashr_i32 s1, s0, 31
	s_lshl_b64 s[0:1], s[0:1], 12
	s_add_u32 s0, s29, s0
	s_addc_u32 s1, s68, s1
	ds_read_b128 v[134:137], v157
	ds_read_b128 v[138:141], v157 offset:1024
	ds_read_b128 v[150:153], v157 offset:2048
	ds_read_b128 v[174:177], v157 offset:3072
	ds_read_b128 v[178:181], v147
	ds_read_b128 v[182:185], v147 offset:1024
	ds_read_b128 v[186:189], v146
	ds_read_b128 v[190:193], v146 offset:1024
	ds_read_b128 v[196:199], v145
	ds_read_b128 v[200:203], v145 offset:1024
	ds_read_b128 v[204:207], v144
	ds_read_b128 v[208:211], v144 offset:1024
	v_lshl_add_u64 v[156:157], v[166:167], 1, s[0:1]
	s_mov_b64 s[54:55], 0xf80
	v_lshl_add_u64 v[156:157], v[156:157], 0, s[54:55]
	s_add_i32 m0, s100, 0xc000
	v_lshl_add_u64 v[132:133], v[132:133], 1, s[0:1]
	global_load_lds_dwordx4 v[156:157], off
	v_lshl_add_u64 v[132:133], v[132:133], 0, s[54:55]
	s_add_i32 m0, s100, 0xe000
	s_nop 0
	global_load_lds_dwordx4 v[132:133], off
	s_barrier
	s_waitcnt lgkmcnt(0)
	s_setprio 1
	s_waitcnt lgkmcnt(0)
	v_mfma_f32_16x16x32_bf16 v[124:127], v[178:181], v[134:137], v[124:127]
	v_mfma_f32_16x16x32_bf16 v[116:119], v[186:189], v[134:137], v[116:119]
	v_mfma_f32_16x16x32_bf16 v[112:115], v[186:189], v[150:153], v[112:115]
	v_mfma_f32_16x16x32_bf16 v[96:99], v[204:207], v[150:153], v[96:99]
	v_mfma_f32_16x16x32_bf16 v[124:127], v[182:185], v[138:141], v[124:127]
	v_mfma_f32_16x16x32_bf16 v[120:123], v[178:181], v[150:153], v[120:123]
	v_mfma_f32_16x16x32_bf16 v[116:119], v[190:193], v[138:141], v[116:119]
	v_mfma_f32_16x16x32_bf16 v[112:115], v[190:193], v[174:177], v[112:115]
	v_mfma_f32_16x16x32_bf16 v[108:111], v[196:199], v[134:137], v[108:111]
	v_mfma_f32_16x16x32_bf16 v[104:107], v[196:199], v[150:153], v[104:107]
	v_mfma_f32_16x16x32_bf16 v[100:103], v[204:207], v[134:137], v[100:103]
	v_mfma_f32_16x16x32_bf16 v[96:99], v[208:211], v[174:177], v[96:99]
	v_mfma_f32_16x16x32_bf16 v[212:215], v[182:185], v[174:177], v[120:123]
	v_mfma_f32_16x16x32_bf16 v[216:219], v[200:203], v[138:141], v[108:111]
	v_mfma_f32_16x16x32_bf16 v[220:223], v[200:203], v[174:177], v[104:107]
	v_mfma_f32_16x16x32_bf16 v[224:227], v[208:211], v[138:141], v[100:103]
	s_setprio 0
	s_barrier
	s_nop 0
	ds_read_b128 v[100:103], v155
	ds_read_b128 v[104:107], v155 offset:1024
	ds_read_b128 v[108:111], v155 offset:2048
	ds_read_b128 v[120:123], v155 offset:3072
	s_barrier
; #define P8_LDA(dst,b,h) _Pragma("unroll") for(int m=0;m<4;++m) _Pragma("unroll") for(int k=0;k<2;++k) \
;     dst[m][k]=*reinterpret_cast<const bf16x8*>((char*)P8_SA(b,h)+lds_byte(wr*64+m*16+fr,k*32+fq*8))
; #define P8_LDB(dst,b,h) _Pragma("unroll") for(int n=0;n<2;++n) _Pragma("unroll") for(int k=0;k<2;++k) \
;     dst[n][k]=*reinterpret_cast<const bf16x8*>((char*)P8_SB(b,h)+lds_byte(wc*32+n*16+fr,k*32+fq*8))
; #define P8_MMA(ai,bj,At,Bt) do{__builtin_amdgcn_s_setprio(1); \
;     _Pragma("unroll") for(int m=0;m<4;++m) _Pragma("unroll") for(int n=0;n<2;++n) _Pragma("unroll") for(int k=0;k<2;++k) \
;       acc[ai][bj][m][n]=__builtin_amdgcn_mfma_f32_16x16x32_bf16(At[m][k],Bt[n][k],acc[ai][bj][m][n],0,0,0); \
;     __builtin_amdgcn_s_setprio(0);}while(0)
; #define P8_WAIT_V(n) asm volatile("s_waitcnt vmcnt(" #n ")":::"memory")
; #define P8_WAIT_L(n) asm volatile("s_waitcnt lgkmcnt(" #n ")":::"memory")
; #define P8_BAR __builtin_amdgcn_s_barrier()
; template <class EPI>
; DEVI void gemm8_tile(const bfr* __restrict__ A, const bfr* __restrict__ Bt, int K, int brow, int bcol, int nbrow, int nbcol, char* shmc, EPI epi) {
;     ...
;     P8_LDB(B1,0,1); P8_BAR; P8_WAIT_L(0); P8_MMA(0,1,At,B1); P8_BAR;
;     P8_LDA(At,0,1); P8_WAIT_V(4); P8_BAR; P8_WAIT_L(0); P8_MMA(1,0,At,B0); P8_MMA(1,1,At,B1); P8_BAR; }
;   { P8_LDB(B0,1,0); P8_LDA(At,1,0); P8_WAIT_V(2); P8_BAR; P8_WAIT_L(0); P8_MMA(0,0,At,B0); P8_BAR;
;     P8_LDB(B1,1,1); P8_WAIT_V(0); P8_BAR; P8_WAIT_L(0); P8_MMA(0,1,At,B1); P8_BAR;
	s_waitcnt lgkmcnt(0)
	s_setprio 1
	s_waitcnt lgkmcnt(0)
	v_mfma_f32_16x16x32_bf16 v[92:95], v[178:181], v[100:103], v[92:95]
	v_mfma_f32_16x16x32_bf16 v[84:87], v[186:189], v[100:103], v[84:87]
	v_mfma_f32_16x16x32_bf16 v[80:83], v[186:189], v[108:111], v[80:83]
	v_mfma_f32_16x16x32_bf16 v[64:67], v[204:207], v[108:111], v[64:67]
	v_mfma_f32_16x16x32_bf16 v[92:95], v[182:185], v[104:107], v[92:95]
	v_mfma_f32_16x16x32_bf16 v[88:91], v[178:181], v[108:111], v[88:91]
	v_mfma_f32_16x16x32_bf16 v[84:87], v[190:193], v[104:107], v[84:87]
	v_mfma_f32_16x16x32_bf16 v[80:83], v[190:193], v[120:123], v[80:83]
	v_mfma_f32_16x16x32_bf16 v[76:79], v[196:199], v[100:103], v[76:79]
	v_mfma_f32_16x16x32_bf16 v[72:75], v[196:199], v[108:111], v[72:75]
	v_mfma_f32_16x16x32_bf16 v[68:71], v[204:207], v[100:103], v[68:71]
	v_mfma_f32_16x16x32_bf16 v[64:67], v[208:211], v[120:123], v[64:67]
	v_mfma_f32_16x16x32_bf16 v[154:157], v[182:185], v[120:123], v[88:91]
	v_mfma_f32_16x16x32_bf16 v[178:181], v[200:203], v[104:107], v[76:79]
	v_mfma_f32_16x16x32_bf16 v[182:185], v[200:203], v[120:123], v[72:75]
	v_mfma_f32_16x16x32_bf16 v[186:189], v[208:211], v[104:107], v[68:71]
	s_setprio 0
	s_barrier
	s_nop 0
	ds_read_b128 v[68:71], v147 offset:16384
	ds_read_b128 v[72:75], v147 offset:17408
	ds_read_b128 v[76:79], v146 offset:16384
	ds_read_b128 v[88:91], v146 offset:17408
	ds_read_b128 v[190:193], v145 offset:16384
	ds_read_b128 v[196:199], v145 offset:17408
	ds_read_b128 v[200:203], v144 offset:16384
	ds_read_b128 v[204:207], v144 offset:17408
	s_waitcnt vmcnt(4)
	s_barrier
	s_waitcnt lgkmcnt(0)
	s_setprio 1
	s_waitcnt lgkmcnt(0)
	v_mfma_f32_16x16x32_bf16 v[60:63], v[68:71], v[134:137], v[60:63]
	v_mfma_f32_16x16x32_bf16 v[52:55], v[76:79], v[134:137], v[52:55]
	v_mfma_f32_16x16x32_bf16 v[48:51], v[76:79], v[150:153], v[48:51]
	v_mfma_f32_16x16x32_bf16 v[32:35], v[200:203], v[150:153], v[32:35]
	v_mfma_f32_16x16x32_bf16 v[60:63], v[72:75], v[138:141], v[60:63]
	v_mfma_f32_16x16x32_bf16 v[56:59], v[68:71], v[150:153], v[56:59]
	v_mfma_f32_16x16x32_bf16 v[52:55], v[88:91], v[138:141], v[52:55]
	v_mfma_f32_16x16x32_bf16 v[48:51], v[88:91], v[174:177], v[48:51]
	v_mfma_f32_16x16x32_bf16 v[44:47], v[190:193], v[134:137], v[44:47]
	v_mfma_f32_16x16x32_bf16 v[40:43], v[190:193], v[150:153], v[40:43]
	v_mfma_f32_16x16x32_bf16 v[36:39], v[200:203], v[134:137], v[36:39]
	v_mfma_f32_16x16x32_bf16 v[32:35], v[204:207], v[174:177], v[32:35]
	v_mfma_f32_16x16x32_bf16 v[208:211], v[72:75], v[174:177], v[56:59]
	v_mfma_f32_16x16x32_bf16 v[228:231], v[196:199], v[138:141], v[44:47]
	v_mfma_f32_16x16x32_bf16 v[232:235], v[196:199], v[174:177], v[40:43]
	v_mfma_f32_16x16x32_bf16 v[132:135], v[204:207], v[138:141], v[36:39]
	s_setprio 0
	s_setprio 1
	v_mfma_f32_16x16x32_bf16 v[28:31], v[68:71], v[100:103], v[28:31]
	v_mfma_f32_16x16x32_bf16 v[20:23], v[76:79], v[100:103], v[20:23]
	v_mfma_f32_16x16x32_bf16 v[16:19], v[76:79], v[108:111], v[16:19]
	v_mfma_f32_16x16x32_bf16 v[0:3], v[200:203], v[108:111], v[0:3]
	v_mfma_f32_16x16x32_bf16 v[28:31], v[72:75], v[104:107], v[28:31]
	v_mfma_f32_16x16x32_bf16 v[24:27], v[68:71], v[108:111], v[24:27]
	v_mfma_f32_16x16x32_bf16 v[20:23], v[88:91], v[104:107], v[20:23]
	v_mfma_f32_16x16x32_bf16 v[16:19], v[88:91], v[120:123], v[16:19]
	v_mfma_f32_16x16x32_bf16 v[12:15], v[190:193], v[100:103], v[12:15]
	v_mfma_f32_16x16x32_bf16 v[8:11], v[190:193], v[108:111], v[8:11]
	v_mfma_f32_16x16x32_bf16 v[4:7], v[200:203], v[100:103], v[4:7]
	v_mfma_f32_16x16x32_bf16 v[0:3], v[204:207], v[120:123], v[0:3]
	v_mfma_f32_16x16x32_bf16 v[136:139], v[72:75], v[120:123], v[24:27]
	v_mfma_f32_16x16x32_bf16 v[150:153], v[196:199], v[104:107], v[12:15]
	v_mfma_f32_16x16x32_bf16 v[172:175], v[196:199], v[120:123], v[8:11]
	v_mfma_f32_16x16x32_bf16 v[190:193], v[204:207], v[104:107], v[4:7]
	s_setprio 0
	s_barrier
	s_nop 0
	ds_read_b128 v[4:7], v149
	ds_read_b128 v[8:11], v149 offset:1024
	ds_read_b128 v[12:15], v149 offset:2048
	ds_read_b128 v[24:27], v149 offset:3072
	ds_read_b128 v[36:39], v147 offset:32768
	ds_read_b128 v[40:43], v147 offset:33792
	ds_read_b128 v[44:47], v146 offset:32768
	ds_read_b128 v[56:59], v146 offset:33792
	ds_read_b128 v[68:71], v145 offset:32768
	ds_read_b128 v[196:199], v145 offset:33792
	ds_read_b128 v[200:203], v144 offset:32768
	ds_read_b128 v[204:207], v144 offset:33792
	s_waitcnt vmcnt(2)
	s_barrier
	s_waitcnt lgkmcnt(0)
	s_setprio 1
	s_waitcnt lgkmcnt(0)
	v_mfma_f32_16x16x32_bf16 v[72:75], v[36:39], v[4:7], v[124:127]
	v_mfma_f32_16x16x32_bf16 v[120:123], v[40:43], v[8:11], v[72:75]
	v_mfma_f32_16x16x32_bf16 v[72:75], v[36:39], v[12:15], v[212:215]
	v_mfma_f32_16x16x32_bf16 v[104:107], v[40:43], v[24:27], v[72:75]
	v_mfma_f32_16x16x32_bf16 v[72:75], v[44:47], v[4:7], v[116:119]
	v_mfma_f32_16x16x32_bf16 v[124:127], v[56:59], v[8:11], v[72:75]
	v_mfma_f32_16x16x32_bf16 v[72:75], v[44:47], v[12:15], v[112:115]
	v_mfma_f32_16x16x32_bf16 v[108:111], v[56:59], v[24:27], v[72:75]
	v_mfma_f32_16x16x32_bf16 v[72:75], v[68:71], v[4:7], v[216:219]
	v_mfma_f32_16x16x32_bf16 v[112:115], v[196:199], v[8:11], v[72:75]
	v_mfma_f32_16x16x32_bf16 v[72:75], v[68:71], v[12:15], v[220:223]
	v_mfma_f32_16x16x32_bf16 v[100:103], v[196:199], v[24:27], v[72:75]
	v_mfma_f32_16x16x32_bf16 v[72:75], v[200:203], v[4:7], v[224:227]
	v_mfma_f32_16x16x32_bf16 v[116:119], v[204:207], v[8:11], v[72:75]
	v_mfma_f32_16x16x32_bf16 v[72:75], v[200:203], v[12:15], v[96:99]
	v_mfma_f32_16x16x32_bf16 v[96:99], v[204:207], v[24:27], v[72:75]
	s_setprio 0
	s_barrier
	ds_read_b128 v[212:215], v148
	ds_read_b128 v[216:219], v148 offset:1024
	ds_read_b128 v[220:223], v148 offset:2048
	ds_read_b128 v[224:227], v148 offset:3072
	s_waitcnt vmcnt(0)
	s_barrier
; DEVI int nblk() { int n = NBLK; asm volatile("" : "+s"(n)); return n; }
; #define P8_STAGE(P,BASE,br,kt) do{const bfr* _ub=(BASE)+((long)(br)*K+(long)(kt)*BK); \
;     __builtin_amdgcn_global_load_lds((const unsigned*)(_ub+so0),(unsigned*)((char*)(P)+wid*1024),16,0,0); \
;     __builtin_amdgcn_global_load_lds((const unsigned*)(_ub+so1),(unsigned*)((char*)(P)+wid*1024+8192),16,0,0);}while(0)
; #define P8_LDA(dst,b,h) _Pragma("unroll") for(int m=0;m<4;++m) _Pragma("unroll") for(int k=0;k<2;++k) \
;     dst[m][k]=*reinterpret_cast<const bf16x8*>((char*)P8_SA(b,h)+lds_byte(wr*64+m*16+fr,k*32+fq*8))
; #define P8_LDB(dst,b,h) _Pragma("unroll") for(int n=0;n<2;++n) _Pragma("unroll") for(int k=0;k<2;++k) \
;     dst[n][k]=*reinterpret_cast<const bf16x8*>((char*)P8_SB(b,h)+lds_byte(wc*32+n*16+fr,k*32+fq*8))
; #define P8_MMA(ai,bj,At,Bt) do{__builtin_amdgcn_s_setprio(1); \
;     _Pragma("unroll") for(int m=0;m<4;++m) _Pragma("unroll") for(int n=0;n<2;++n) _Pragma("unroll") for(int k=0;k<2;++k) \
;       acc[ai][bj][m][n]=__builtin_amdgcn_mfma_f32_16x16x32_bf16(At[m][k],Bt[n][k],acc[ai][bj][m][n],0,0,0); \
;     __builtin_amdgcn_s_setprio(0);}while(0)
; #define P8_WAIT_V(n) asm volatile("s_waitcnt vmcnt(" #n ")":::"memory")
; #define P8_BAR __builtin_amdgcn_s_barrier()
; template <class EPI>
; DEVI void gemm8_tile(const bfr* __restrict__ A, const bfr* __restrict__ Bt, int K, int brow, int bcol, int nbrow, int nbcol, char* shmc, EPI epi) {
;     ...
;   { P8_LDB(B0,1,0); P8_LDA(At,1,0); P8_WAIT_V(2); P8_BAR; P8_WAIT_L(0); P8_MMA(0,0,At,B0); P8_BAR;
;     P8_LDB(B1,1,1); P8_WAIT_V(0); P8_BAR; P8_WAIT_L(0); P8_MMA(0,1,At,B1); P8_BAR;
;     P8_LDA(At,1,1); P8_BAR; P8_WAIT_L(0); P8_MMA(1,0,At,B0); P8_MMA(1,1,At,B1); P8_BAR; }
;   if(wr==0)P8_BAR;
;   if (nbrow >= 0) {
;     P8_STAGE(P8_SB(0,0),Bt,nbcol,0); P8_STAGE(P8_SA(0,0),A,nbrow,0);
;     P8_STAGE(P8_SB(0,1),Bt,nbcol+128,0); P8_STAGE(P8_SA(0,1),A,nbrow+128,0);
;   }
; template <class EPI>
; DEVI void gemm8_linear(const bfr* A, int ntA, const bfr* B, int ntB, int K, char* shm, EPI epi) {
;     ...
;   while (t < ntiles) {
;     const int tn = t + nblk(); int pan = 0, pbn = 0; const bool hn = tn < ntiles;
;     if (hn) tile_decode(tn, ntiles, ntA, pan, pbn);
;     gemm8_tile(A, B, K, pa * 256, pb * 256, hn ? pan * 256 : -1, pbn * 256, shm, [&](f32x4 (&acc)[2][2][4][2]) { epi(acc, pa, pb); });
;     t = tn; pa = pan; pb = pbn;
	s_waitcnt lgkmcnt(0)
	s_setprio 1
	s_waitcnt lgkmcnt(0)
	v_mfma_f32_16x16x32_bf16 v[72:75], v[36:39], v[212:215], v[92:95]
	v_mfma_f32_16x16x32_bf16 v[36:39], v[36:39], v[220:223], v[154:157]
	v_mfma_f32_16x16x32_bf16 v[88:91], v[40:43], v[216:219], v[72:75]
	v_mfma_f32_16x16x32_bf16 v[72:75], v[40:43], v[224:227], v[36:39]
	v_mfma_f32_16x16x32_bf16 v[36:39], v[44:47], v[212:215], v[84:87]
	v_mfma_f32_16x16x32_bf16 v[92:95], v[56:59], v[216:219], v[36:39]
	v_mfma_f32_16x16x32_bf16 v[36:39], v[44:47], v[220:223], v[80:83]
	v_mfma_f32_16x16x32_bf16 v[76:79], v[56:59], v[224:227], v[36:39]
	v_mfma_f32_16x16x32_bf16 v[36:39], v[68:71], v[212:215], v[178:181]
	v_mfma_f32_16x16x32_bf16 v[80:83], v[196:199], v[216:219], v[36:39]
	v_mfma_f32_16x16x32_bf16 v[36:39], v[68:71], v[220:223], v[182:185]
	v_mfma_f32_16x16x32_bf16 v[68:71], v[196:199], v[224:227], v[36:39]
	v_mfma_f32_16x16x32_bf16 v[36:39], v[200:203], v[212:215], v[186:189]
	v_mfma_f32_16x16x32_bf16 v[84:87], v[204:207], v[216:219], v[36:39]
	v_mfma_f32_16x16x32_bf16 v[36:39], v[200:203], v[220:223], v[64:67]
	v_mfma_f32_16x16x32_bf16 v[64:67], v[204:207], v[224:227], v[36:39]
	s_setprio 0
	s_barrier
	ds_read_b128 v[154:157], v147 offset:49152
	ds_read_b128 v[176:179], v147 offset:50176
	ds_read_b128 v[180:183], v146 offset:49152
	ds_read_b128 v[146:149], v146 offset:50176
	ds_read_b128 v[184:187], v145 offset:49152
	ds_read_b128 v[196:199], v145 offset:50176
	ds_read_b128 v[200:203], v144 offset:49152
	ds_read_b128 v[204:207], v144 offset:50176
	s_barrier
	s_waitcnt lgkmcnt(0)
	s_setprio 1
	s_waitcnt lgkmcnt(0)
	v_mfma_f32_16x16x32_bf16 v[36:39], v[154:157], v[4:7], v[60:63]
	v_mfma_f32_16x16x32_bf16 v[56:59], v[176:179], v[8:11], v[36:39]
	v_mfma_f32_16x16x32_bf16 v[36:39], v[154:157], v[12:15], v[208:211]
	v_mfma_f32_16x16x32_bf16 v[40:43], v[176:179], v[24:27], v[36:39]
	v_mfma_f32_16x16x32_bf16 v[36:39], v[180:183], v[4:7], v[52:55]
	v_mfma_f32_16x16x32_bf16 v[60:63], v[146:149], v[8:11], v[36:39]
	v_mfma_f32_16x16x32_bf16 v[36:39], v[180:183], v[12:15], v[48:51]
	v_mfma_f32_16x16x32_bf16 v[44:47], v[146:149], v[24:27], v[36:39]
	v_mfma_f32_16x16x32_bf16 v[36:39], v[184:187], v[4:7], v[228:231]
	v_mfma_f32_16x16x32_bf16 v[4:7], v[200:203], v[4:7], v[132:135]
	v_mfma_f32_16x16x32_bf16 v[48:51], v[196:199], v[8:11], v[36:39]
	v_mfma_f32_16x16x32_bf16 v[36:39], v[184:187], v[12:15], v[232:235]
	v_mfma_f32_16x16x32_bf16 v[52:55], v[204:207], v[8:11], v[4:7]
	v_mfma_f32_16x16x32_bf16 v[4:7], v[200:203], v[12:15], v[32:35]
	v_mfma_f32_16x16x32_bf16 v[36:39], v[196:199], v[24:27], v[36:39]
	v_mfma_f32_16x16x32_bf16 v[32:35], v[204:207], v[24:27], v[4:7]
	s_setprio 0
	s_setprio 1
	v_mfma_f32_16x16x32_bf16 v[4:7], v[154:157], v[212:215], v[28:31]
	v_mfma_f32_16x16x32_bf16 v[24:27], v[176:179], v[216:219], v[4:7]
	v_mfma_f32_16x16x32_bf16 v[4:7], v[154:157], v[220:223], v[136:139]
	v_mfma_f32_16x16x32_bf16 v[8:11], v[176:179], v[224:227], v[4:7]
	v_mfma_f32_16x16x32_bf16 v[4:7], v[180:183], v[212:215], v[20:23]
	v_mfma_f32_16x16x32_bf16 v[28:31], v[146:149], v[216:219], v[4:7]
	v_mfma_f32_16x16x32_bf16 v[4:7], v[180:183], v[220:223], v[16:19]
	v_mfma_f32_16x16x32_bf16 v[12:15], v[146:149], v[224:227], v[4:7]
	v_mfma_f32_16x16x32_bf16 v[4:7], v[184:187], v[212:215], v[150:153]
	v_mfma_f32_16x16x32_bf16 v[16:19], v[196:199], v[216:219], v[4:7]
	v_mfma_f32_16x16x32_bf16 v[4:7], v[184:187], v[220:223], v[172:175]
	v_mfma_f32_16x16x32_bf16 v[20:23], v[200:203], v[212:215], v[190:193]
	v_mfma_f32_16x16x32_bf16 v[0:3], v[200:203], v[220:223], v[0:3]
	v_mfma_f32_16x16x32_bf16 v[4:7], v[196:199], v[224:227], v[4:7]
	v_mfma_f32_16x16x32_bf16 v[20:23], v[204:207], v[216:219], v[20:23]
	v_mfma_f32_16x16x32_bf16 v[0:3], v[204:207], v[224:227], v[0:3]
	s_setprio 0
	v_cmp_gt_u32_e32 vcc, s57, v142
	s_barrier
	s_and_saveexec_b64 s[0:1], vcc
	s_cbranch_execz .LBB0_289
	s_barrier
.LBB0_289:
	s_or_b64 exec, exec, s[0:1]
	s_lshl_b32 s2, s69, 8
	s_and_b64 s[0:1], s[34:35], exec
	s_cselect_b32 s58, s2, -1
	s_cmp_lt_i32 s58, 0
	s_cbranch_scc1 .LBB0_278
	s_lshl_b32 s0, s72, 8
	s_ashr_i32 s1, s0, 31
	s_lshl_b64 s[34:35], s[0:1], 12
	s_add_u32 s34, s84, s34
	s_addc_u32 s35, s85, s35
	v_lshl_add_u64 v[132:133], s[34:35], 0, v[128:129]
	s_add_i32 m0, s100, 0x10000
	v_readfirstlane_b32 s1, v159
	global_load_lds_dwordx4 v[132:133], off
	v_lshl_add_u64 v[132:133], s[34:35], 0, v[130:131]
	s_lshl_b64 s[34:35], s[58:59], 12
	s_add_u32 s34, s29, s34
	s_mov_b32 m0, s1
	s_addc_u32 s35, s68, s35
	global_load_lds_dwordx4 v[132:133], off
	v_lshl_add_u64 v[132:133], s[34:35], 0, v[128:129]
	s_mov_b32 m0, s100
	s_bitset1_b32 s0, 7
	global_load_lds_dwordx4 v[132:133], off
	s_add_i32 m0, s100, 0x2000
	s_ashr_i32 s1, s0, 31
	s_lshl_b64 s[0:1], s[0:1], 12
	s_add_u32 s0, s84, s0
	v_lshl_add_u64 v[132:133], s[34:35], 0, v[130:131]
	s_addc_u32 s1, s85, s1
	global_load_lds_dwordx4 v[132:133], off
	v_lshl_add_u64 v[132:133], s[0:1], 0, v[128:129]
	s_add_i32 m0, s100, 0x14000
	s_addk_i32 s58, 0x80
	global_load_lds_dwordx4 v[132:133], off
	v_lshl_add_u64 v[132:133], s[0:1], 0, v[130:131]
	s_add_i32 m0, s100, 0x16000
	s_lshl_b64 s[0:1], s[58:59], 12
	s_add_u32 s0, s29, s0
	s_addc_u32 s1, s68, s1
	v_readfirstlane_b32 s2, v163
	global_load_lds_dwordx4 v[132:133], off
	v_lshl_add_u64 v[128:129], s[0:1], 0, v[128:129]
	s_mov_b32 m0, s2
	s_nop 0
	global_load_lds_dwordx4 v[128:129], off
	v_lshl_add_u64 v[128:129], s[0:1], 0, v[130:131]
	v_readfirstlane_b32 s0, v170
	s_mov_b32 m0, s0
	s_nop 0
	global_load_lds_dwordx4 v[128:129], off
	s_branch .LBB0_278

; #define P8_STAGE(P,BASE,br,kt) do{const bfr* _ub=(BASE)+((long)(br)*K+(long)(kt)*BK); \
;     __builtin_amdgcn_global_load_lds((const unsigned*)(_ub+so0),(unsigned*)((char*)(P)+wid*1024),16,0,0); \
;     __builtin_amdgcn_global_load_lds((const unsigned*)(_ub+so1),(unsigned*)((char*)(P)+wid*1024+8192),16,0,0);}while(0)
; #define P8_WAIT_V(n) asm volatile("s_waitcnt vmcnt(" #n ")":::"memory")
; #define P8_BAR __builtin_amdgcn_s_barrier()
; template <class EPI>
; DEVI void gemm8_tile(const bfr* __restrict__ A, const bfr* __restrict__ Bt, int K, int brow, int bcol, int nbrow, int nbcol, char* shmc, EPI epi) {
;     ...
;   unsigned so0, so1;
;   { int _r, _c; stage_rc(tid * 16, _r, _c); so0 = (unsigned)(_r * K + _c); stage_rc(tid * 16 + 8192, _r, _c); so1 = (unsigned)(_r * K + _c); }
;   f32x4 acc[2][2][4][2];
; #pragma unroll
;   for (int a = 0; a < 2; ++a)
; #pragma unroll
;     for (int b = 0; b < 2; ++b)
; #pragma unroll
;       for (int m = 0; m < 4; ++m)
; #pragma unroll
;         for (int n = 0; n < 2; ++n) acc[a][b][m][n] = f32x4{0.f, 0.f, 0.f, 0.f};
;   bf16x8 At[4][2], B0[2][2], B1[2][2];
;   const int nt = K / BK;
;   if(wr==1)P8_BAR;
;   P8_WAIT_V(4); P8_BAR;
;   P8_STAGE(P8_SB(1,0),Bt,bcol,1); P8_STAGE(P8_SA(1,0),A,brow,1); P8_STAGE(P8_SB(1,1),Bt,bcol+128,1);
;   P8_WAIT_V(6); P8_BAR;
.LBB0_381:
	s_or_b64 exec, exec, s[0:1]
	v_lshlrev_b32_e32 v2, 4, v142
	v_and_b32_e32 v3, 32, v142
	s_lshl_b32 s34, s11, 8
	v_lshrrev_b32_e32 v7, 1, v142
	v_bitop3_b32 v3, v2, v3, 48 bitop3:0x6c
	v_add_u32_e32 v2, 0x2000, v2
	v_ashrrev_i32_e32 v4, 3, v142
	v_bfe_u32 v5, v142, 2, 4
	s_mov_b32 s0, 0x7fff0
	v_lshrrev_b32_e32 v8, 1, v3
	v_ashrrev_i32_e32 v9, 7, v2
	v_and_b32_e32 v7, 32, v7
	s_ashr_i32 s35, s34, 31
	s_lshl_b32 s10, s2, 8
	v_ashrrev_i32_e32 v1, 6, v142
	v_and_or_b32 v6, v4, s0, v5
	v_and_or_b32 v2, v9, s0, v5
	v_or_b32_e32 v3, v8, v7
	s_lshl_b64 s[0:1], s[34:35], 14
	v_lshl_or_b32 v166, v6, 13, v3
	s_add_u32 s54, s65, s0
	v_lshlrev_b32_e32 v143, 10, v1
	s_nop 0
	v_readfirstlane_b32 s100, v143
	s_nop 3
	s_addc_u32 s55, s68, s1
	v_lshlrev_b64 v[128:129], 1, v[166:167]
	v_add_u32_e32 v150, 0x18000, v143
	v_lshl_or_b32 v132, v2, 13, v3
	v_lshl_add_u64 v[2:3], s[54:55], 0, v[128:129]
	v_mov_b32_e32 v133, v167
	v_lshl_add_u64 v[2:3], v[2:3], 0, s[62:63]
	s_add_i32 m0, s100, 0x18000
	v_lshlrev_b64 v[130:131], 1, v[132:133]
	s_ashr_i32 s11, s10, 31
	s_waitcnt vmcnt(4)
	s_barrier
	global_load_lds_dwordx4 v[2:3], off
	v_lshl_add_u64 v[2:3], s[54:55], 0, v[130:131]
	v_add_u32_e32 v151, 0x1a000, v143
	s_lshl_b64 s[54:55], s[10:11], 14
	v_readfirstlane_b32 s2, v151
	s_add_u32 s60, s31, s54
	v_lshl_add_u64 v[2:3], v[2:3], 0, s[62:63]
	s_mov_b32 m0, s2
	s_addc_u32 s61, s64, s55
	v_add_u32_e32 v152, 0x8000, v143
	global_load_lds_dwordx4 v[2:3], off
	v_lshl_add_u64 v[2:3], s[60:61], 0, v[128:129]
	v_lshl_add_u64 v[2:3], v[2:3], 0, s[62:63]
	s_add_i32 m0, s100, 0x8000
	v_add_u32_e32 v153, 0xa000, v143
	global_load_lds_dwordx4 v[2:3], off
	v_lshl_add_u64 v[2:3], s[60:61], 0, v[130:131]
	s_or_b32 s60, s34, 0x80
	s_ashr_i32 s61, s60, 31
	s_lshl_b64 s[60:61], s[60:61], 14
	v_readfirstlane_b32 s2, v153
	s_add_u32 s60, s65, s60
	v_lshl_add_u64 v[2:3], v[2:3], 0, s[62:63]
	s_mov_b32 m0, s2
	s_addc_u32 s61, s68, s61
	v_add_u32_e32 v155, 0x1c000, v143
	global_load_lds_dwordx4 v[2:3], off
	v_lshl_add_u64 v[2:3], s[60:61], 0, v[128:129]
	v_lshl_add_u64 v[2:3], v[2:3], 0, s[62:63]
	s_add_i32 m0, s100, 0x1c000
	v_add_u32_e32 v156, 0x1e000, v143
	global_load_lds_dwordx4 v[2:3], off
	v_lshl_add_u64 v[2:3], s[60:61], 0, v[130:131]
	v_lshl_add_u64 v[2:3], v[2:3], 0, s[62:63]
	s_add_i32 m0, s100, 0x1e000
	v_and_b32_e32 v10, 15, v142
	global_load_lds_dwordx4 v[2:3], off
	v_lshlrev_b32_e32 v1, 12, v1
	v_and_b32_e32 v11, 48, v142
	v_and_b32_e32 v6, 0x3000, v1
	v_lshlrev_b32_e32 v1, 6, v10
	v_lshlrev_b32_e32 v3, 2, v142
	v_or_b32_e32 v2, v1, v11
	v_and_b32_e32 v3, 32, v3
	s_mov_b32 s2, 0x14000
	v_bitop3_b32 v13, v2, s2, v3 bitop3:0xde
	s_mov_b32 s2, 0x18000
	v_lshlrev_b32_e32 v16, 13, v0
	v_lshlrev_b32_e32 v0, 6, v142
	v_bitop3_b32 v14, v2, s2, v3 bitop3:0xde
	s_mov_b32 s2, 0x1c000
	v_and_b32_e32 v0, 0x3c0, v0
	v_bitop3_b32 v10, v1, v3, v11 bitop3:0x36
	v_bitop3_b32 v12, v2, s3, v3 bitop3:0xde
	v_bitop3_b32 v15, v2, s2, v3 bitop3:0xde
	v_bitop3_b32 v11, v0, v3, v11 bitop3:0x36
	v_lshlrev_b32_e32 v0, 13, v9
	s_mov_b32 s2, 0xfffe0000
	v_lshlrev_b32_e32 v3, 13, v4
	v_and_or_b32 v0, v0, s2, v8
	v_lshlrev_b32_e32 v2, 13, v5
	v_and_or_b32 v3, v3, s2, v8
	v_or3_b32 v0, v0, v2, v7
	v_mov_b32_e32 v1, v167
	v_or3_b32 v2, v3, v2, v7
	v_mov_b32_e32 v3, v167
	v_lshlrev_b64 v[0:1], 1, v[0:1]
	v_lshlrev_b64 v[2:3], 1, v[2:3]
	v_lshl_add_u64 v[134:135], s[0:1], 0, v[0:1]
	v_lshl_add_u64 v[136:137], s[0:1], 0, v[2:3]
	s_add_u32 s0, s6, s54
	s_waitcnt vmcnt(6)
	s_addc_u32 s1, s7, s55
	v_or_b32_e32 v17, 0x800, v16
	v_or_b32_e32 v18, 0x1000, v16
	v_or_b32_e32 v19, 0x1800, v16
	v_lshl_add_u64 v[138:139], s[0:1], 0, v[0:1]
	v_mov_b32_e32 v0, 0
	v_lshl_add_u64 v[140:141], s[0:1], 0, v[2:3]
	s_mov_b32 s0, -2
	v_add_u32_e32 v157, v12, v6
	v_add_u32_e32 v147, v10, v16
	v_add_u32_e32 v146, v11, v17
	v_add_u32_e32 v145, v11, v18
	v_add_u32_e32 v144, v11, v19
	v_add_u32_e32 v154, v13, v6
	v_add_u32_e32 v149, v14, v6
	v_add_u32_e32 v148, v15, v6
	v_mov_b32_e32 v1, v0
	v_mov_b32_e32 v2, v0
	v_mov_b32_e32 v3, v0
	v_mov_b32_e32 v4, v0
	v_mov_b32_e32 v5, v0
	v_mov_b32_e32 v6, v0
	v_mov_b32_e32 v7, v0
	v_mov_b32_e32 v8, v0
	v_mov_b32_e32 v9, v0
	v_mov_b32_e32 v10, v0
	v_mov_b32_e32 v11, v0
	v_mov_b32_e32 v12, v0
	v_mov_b32_e32 v13, v0
	v_mov_b32_e32 v14, v0
	v_mov_b32_e32 v15, v0
	v_mov_b32_e32 v16, v0
	v_mov_b32_e32 v17, v0
	v_mov_b32_e32 v18, v0
	v_mov_b32_e32 v19, v0
	v_mov_b32_e32 v20, v0
	v_mov_b32_e32 v21, v0
	v_mov_b32_e32 v22, v0
	v_mov_b32_e32 v23, v0
	v_mov_b32_e32 v24, v0
	v_mov_b32_e32 v25, v0
	v_mov_b32_e32 v26, v0
	v_mov_b32_e32 v27, v0
	v_mov_b32_e32 v28, v0
	v_mov_b32_e32 v29, v0
	v_mov_b32_e32 v30, v0
	v_mov_b32_e32 v31, v0
	v_mov_b32_e32 v32, v0
	v_mov_b32_e32 v33, v0
	v_mov_b32_e32 v34, v0
	v_mov_b32_e32 v35, v0
	v_mov_b32_e32 v36, v0
	v_mov_b32_e32 v37, v0
	v_mov_b32_e32 v38, v0
	v_mov_b32_e32 v39, v0
	v_mov_b32_e32 v40, v0
	v_mov_b32_e32 v41, v0
	v_mov_b32_e32 v42, v0
	v_mov_b32_e32 v43, v0
	v_mov_b32_e32 v44, v0
	v_mov_b32_e32 v45, v0
	v_mov_b32_e32 v46, v0
	v_mov_b32_e32 v47, v0
	v_mov_b32_e32 v48, v0
	v_mov_b32_e32 v49, v0
	v_mov_b32_e32 v50, v0
	v_mov_b32_e32 v51, v0
	v_mov_b32_e32 v52, v0
	v_mov_b32_e32 v53, v0
	v_mov_b32_e32 v54, v0
	v_mov_b32_e32 v55, v0
	v_mov_b32_e32 v56, v0
	v_mov_b32_e32 v57, v0
	v_mov_b32_e32 v58, v0
	v_mov_b32_e32 v59, v0
	v_mov_b32_e32 v60, v0
	v_mov_b32_e32 v61, v0
	v_mov_b32_e32 v62, v0
	v_mov_b32_e32 v63, v0
	v_mov_b32_e32 v64, v0
	v_mov_b32_e32 v65, v0
	v_mov_b32_e32 v66, v0
	v_mov_b32_e32 v67, v0
	v_mov_b32_e32 v68, v0
	v_mov_b32_e32 v69, v0
	v_mov_b32_e32 v70, v0
	v_mov_b32_e32 v71, v0
	v_mov_b32_e32 v72, v0
	v_mov_b32_e32 v73, v0
; #define P8_STAGE(P,BASE,br,kt) do{const bfr* _ub=(BASE)+((long)(br)*K+(long)(kt)*BK); \
;     __builtin_amdgcn_global_load_lds((const unsigned*)(_ub+so0),(unsigned*)((char*)(P)+wid*1024),16,0,0); \
;     __builtin_amdgcn_global_load_lds((const unsigned*)(_ub+so1),(unsigned*)((char*)(P)+wid*1024+8192),16,0,0);}while(0)
; #define P8_LDA(dst,b,h) _Pragma("unroll") for(int m=0;m<4;++m) _Pragma("unroll") for(int k=0;k<2;++k) \
;     dst[m][k]=*reinterpret_cast<const bf16x8*>((char*)P8_SA(b,h)+lds_byte(wr*64+m*16+fr,k*32+fq*8))
; #define P8_LDB(dst,b,h) _Pragma("unroll") for(int n=0;n<2;++n) _Pragma("unroll") for(int k=0;k<2;++k) \
;     dst[n][k]=*reinterpret_cast<const bf16x8*>((char*)P8_SB(b,h)+lds_byte(wc*32+n*16+fr,k*32+fq*8))
; #define P8_MMA(ai,bj,At,Bt) do{__builtin_amdgcn_s_setprio(1); \
;     _Pragma("unroll") for(int m=0;m<4;++m) _Pragma("unroll") for(int n=0;n<2;++n) _Pragma("unroll") for(int k=0;k<2;++k) \
;       acc[ai][bj][m][n]=__builtin_amdgcn_mfma_f32_16x16x32_bf16(At[m][k],Bt[n][k],acc[ai][bj][m][n],0,0,0); \
;     __builtin_amdgcn_s_setprio(0);}while(0)
; #define P8_WAIT_L(n) asm volatile("s_waitcnt lgkmcnt(" #n ")":::"memory")
; #define P8_BAR __builtin_amdgcn_s_barrier()
; #define P8_SCHED __builtin_amdgcn_sched_barrier(0)
; template <class EPI>
; DEVI void gemm8_tile(const bfr* __restrict__ A, const bfr* __restrict__ Bt, int K, int brow, int bcol, int nbrow, int nbcol, char* shmc, EPI epi) {
;     ...
;       for (int m = 0; m < 4; ++m)
; #pragma unroll
;         for (int n = 0; n < 2; ++n) acc[a][b][m][n] = f32x4{0.f, 0.f, 0.f, 0.f};
;     ...
;   for(int t=0;t<nt-2;t+=2){
;     P8_LDB(B0,0,0); P8_SCHED; P8_LDA(At,0,0); P8_STAGE(P8_SA(1,1),A,brow+128,t+1);
;     P8_WAIT_L(8); P8_BAR; P8_WAIT_L(0); P8_MMA(0,0,At,B0); P8_BAR; P8_SCHED;
;     P8_LDB(B1,0,1); P8_STAGE(P8_SB(0,0),Bt,bcol,t+2);
;     P8_BAR; P8_WAIT_L(0); P8_MMA(0,1,At,B1); P8_BAR;
;     P8_LDA(At,0,1); P8_STAGE(P8_SA(0,0),A,brow,t+2);
;     P8_BAR; P8_WAIT_L(0); P8_MMA(1,0,At,B0); P8_BAR; P8_SCHED;
	v_mov_b32_e32 v74, v0
	v_mov_b32_e32 v75, v0
	v_mov_b32_e32 v76, v0
	v_mov_b32_e32 v77, v0
	v_mov_b32_e32 v78, v0
	v_mov_b32_e32 v79, v0
	v_mov_b32_e32 v80, v0
	v_mov_b32_e32 v81, v0
	v_mov_b32_e32 v82, v0
	v_mov_b32_e32 v83, v0
	v_mov_b32_e32 v84, v0
	v_mov_b32_e32 v85, v0
	v_mov_b32_e32 v86, v0
	v_mov_b32_e32 v87, v0
	v_mov_b32_e32 v88, v0
	v_mov_b32_e32 v89, v0
	v_mov_b32_e32 v90, v0
	v_mov_b32_e32 v91, v0
	v_mov_b32_e32 v92, v0
	v_mov_b32_e32 v93, v0
	v_mov_b32_e32 v94, v0
	v_mov_b32_e32 v95, v0
	v_mov_b32_e32 v96, v0
	v_mov_b32_e32 v97, v0
	v_mov_b32_e32 v98, v0
	v_mov_b32_e32 v99, v0
	v_mov_b32_e32 v100, v0
	v_mov_b32_e32 v101, v0
	v_mov_b32_e32 v102, v0
	v_mov_b32_e32 v103, v0
	v_mov_b32_e32 v104, v0
	v_mov_b32_e32 v105, v0
	v_mov_b32_e32 v106, v0
	v_mov_b32_e32 v107, v0
	v_mov_b32_e32 v108, v0
	v_mov_b32_e32 v109, v0
	v_mov_b32_e32 v110, v0
	v_mov_b32_e32 v111, v0
	v_mov_b32_e32 v112, v0
	v_mov_b32_e32 v113, v0
	v_mov_b32_e32 v114, v0
	v_mov_b32_e32 v115, v0
	v_mov_b32_e32 v116, v0
	v_mov_b32_e32 v117, v0
	v_mov_b32_e32 v118, v0
	v_mov_b32_e32 v119, v0
	v_mov_b32_e32 v120, v0
	v_mov_b32_e32 v121, v0
	v_mov_b32_e32 v122, v0
	v_mov_b32_e32 v123, v0
	v_mov_b32_e32 v124, v0
	v_mov_b32_e32 v125, v0
	v_mov_b32_e32 v126, v0
	v_mov_b32_e32 v127, v0
	s_mov_b64 s[54:55], 0xbc00080
	s_mov_b64 s[60:61], 0x1be90100
	s_mov_b64 s[82:83], 0xba00100
	s_mov_b64 s[92:93], 0x1c090100
	s_mov_b64 s[94:95], 0xbc00100
	s_mov_b64 s[96:97], 0x1be90180
	s_mov_b64 vcc, 0xba00180
	s_mov_b64 s[28:29], 0x1c090180
	s_barrier
.LBB0_382:
	ds_read_b128 v[174:177], v157
	ds_read_b128 v[178:181], v157 offset:1024
	ds_read_b128 v[182:185], v157 offset:2048
	ds_read_b128 v[186:189], v157 offset:3072
	v_add_u32_e32 v171, 0xc000, v143
	v_add_u32_e32 v172, 0xe000, v143
	v_add_u32_e32 v158, s54, v140
	s_add_i32 m0, s100, 0xc000
	ds_read_b128 v[160:163], v147
	ds_read_b128 v[190:193], v147 offset:1024
	ds_read_b128 v[196:199], v146
	ds_read_b128 v[208:211], v146 offset:1024
	ds_read_b128 v[212:215], v145
	ds_read_b128 v[216:219], v145 offset:1024
	ds_read_b128 v[220:223], v144
	ds_read_b128 v[224:227], v144 offset:1024
	global_load_lds_dwordx4 v158, s[86:87]
	v_add_u32_e32 v158, s54, v138
	s_add_i32 m0, s100, 0xe000
	s_nop 0
	global_load_lds_dwordx4 v158, s[86:87]
	s_waitcnt lgkmcnt(8)
	s_barrier
	s_waitcnt lgkmcnt(0)
	s_setprio 1
	s_waitcnt lgkmcnt(0)
	v_mfma_f32_16x16x32_bf16 v[124:127], v[160:163], v[174:177], v[124:127]
	v_mfma_f32_16x16x32_bf16 v[120:123], v[160:163], v[182:185], v[120:123]
	v_mfma_f32_16x16x32_bf16 v[116:119], v[196:199], v[174:177], v[116:119]
	v_mfma_f32_16x16x32_bf16 v[112:115], v[196:199], v[182:185], v[112:115]
	v_mfma_f32_16x16x32_bf16 v[108:111], v[212:215], v[174:177], v[108:111]
	v_mfma_f32_16x16x32_bf16 v[104:107], v[212:215], v[182:185], v[104:107]
	v_mfma_f32_16x16x32_bf16 v[100:103], v[220:223], v[174:177], v[100:103]
	v_mfma_f32_16x16x32_bf16 v[96:99], v[220:223], v[182:185], v[96:99]
	v_mfma_f32_16x16x32_bf16 v[124:127], v[190:193], v[178:181], v[124:127]
	v_mfma_f32_16x16x32_bf16 v[120:123], v[190:193], v[186:189], v[120:123]
	v_mfma_f32_16x16x32_bf16 v[116:119], v[208:211], v[178:181], v[116:119]
	v_mfma_f32_16x16x32_bf16 v[112:115], v[208:211], v[186:189], v[112:115]
	v_mfma_f32_16x16x32_bf16 v[108:111], v[216:219], v[178:181], v[108:111]
	v_mfma_f32_16x16x32_bf16 v[104:107], v[216:219], v[186:189], v[104:107]
	v_mfma_f32_16x16x32_bf16 v[100:103], v[224:227], v[178:181], v[100:103]
	v_mfma_f32_16x16x32_bf16 v[96:99], v[224:227], v[186:189], v[96:99]
	s_setprio 0
	s_barrier
	v_add_u32_e32 v158, 0x10000, v143
	v_add_u32_e32 v206, s60, v136
	s_add_i32 m0, s100, 0x10000
	v_add_u32_e32 v159, 0x12000, v143
	ds_read_b128 v[228:231], v154
	ds_read_b128 v[232:235], v154 offset:1024
	ds_read_b128 v[236:239], v154 offset:2048
	ds_read_b128 v[240:243], v154 offset:3072
	global_load_lds_dwordx4 v206, s[86:87]
	v_add_u32_e32 v244, s60, v134
	s_add_i32 m0, s100, 0x12000
	s_nop 0
	global_load_lds_dwordx4 v244, s[86:87]
	s_barrier
	s_waitcnt lgkmcnt(0)
	s_setprio 1
	s_waitcnt lgkmcnt(0)
	v_mfma_f32_16x16x32_bf16 v[92:95], v[160:163], v[228:231], v[92:95]
	v_mfma_f32_16x16x32_bf16 v[88:91], v[160:163], v[236:239], v[88:91]
	v_mfma_f32_16x16x32_bf16 v[84:87], v[196:199], v[228:231], v[84:87]
	v_mfma_f32_16x16x32_bf16 v[80:83], v[196:199], v[236:239], v[80:83]
	v_mfma_f32_16x16x32_bf16 v[76:79], v[212:215], v[228:231], v[76:79]
	v_mfma_f32_16x16x32_bf16 v[72:75], v[212:215], v[236:239], v[72:75]
	v_mfma_f32_16x16x32_bf16 v[68:71], v[220:223], v[228:231], v[68:71]
	v_mfma_f32_16x16x32_bf16 v[64:67], v[220:223], v[236:239], v[64:67]
	v_mfma_f32_16x16x32_bf16 v[92:95], v[190:193], v[232:235], v[92:95]
	v_mfma_f32_16x16x32_bf16 v[88:91], v[190:193], v[240:243], v[88:91]
	v_mfma_f32_16x16x32_bf16 v[84:87], v[208:211], v[232:235], v[84:87]
	v_mfma_f32_16x16x32_bf16 v[80:83], v[208:211], v[240:243], v[80:83]
	v_mfma_f32_16x16x32_bf16 v[76:79], v[216:219], v[232:235], v[76:79]
	v_mfma_f32_16x16x32_bf16 v[72:75], v[216:219], v[240:243], v[72:75]
	v_mfma_f32_16x16x32_bf16 v[68:71], v[224:227], v[232:235], v[68:71]
	v_mfma_f32_16x16x32_bf16 v[64:67], v[224:227], v[240:243], v[64:67]
	s_setprio 0
	v_add_u32_e32 v160, s82, v140
	s_mov_b32 m0, s100
	s_barrier
	ds_read_b128 v[190:193], v147 offset:16384
	ds_read_b128 v[196:199], v147 offset:17408
	ds_read_b128 v[208:211], v146 offset:16384
	ds_read_b128 v[212:215], v146 offset:17408
	ds_read_b128 v[216:219], v145 offset:16384
	ds_read_b128 v[220:223], v145 offset:17408
	ds_read_b128 v[224:227], v144 offset:16384
	ds_read_b128 v[244:247], v144 offset:17408
	global_load_lds_dwordx4 v160, s[86:87]
	v_add_u32_e32 v160, 0x2000, v143
	v_add_u32_e32 v162, s82, v138
	s_add_i32 m0, s100, 0x2000
	s_nop 0
	global_load_lds_dwordx4 v162, s[86:87]
	s_barrier
; #define P8_STAGE(P,BASE,br,kt) do{const bfr* _ub=(BASE)+((long)(br)*K+(long)(kt)*BK); \
;     __builtin_amdgcn_global_load_lds((const unsigned*)(_ub+so0),(unsigned*)((char*)(P)+wid*1024),16,0,0); \
;     __builtin_amdgcn_global_load_lds((const unsigned*)(_ub+so1),(unsigned*)((char*)(P)+wid*1024+8192),16,0,0);}while(0)
; #define P8_LDA(dst,b,h) _Pragma("unroll") for(int m=0;m<4;++m) _Pragma("unroll") for(int k=0;k<2;++k) \
;     dst[m][k]=*reinterpret_cast<const bf16x8*>((char*)P8_SA(b,h)+lds_byte(wr*64+m*16+fr,k*32+fq*8))
; #define P8_LDB(dst,b,h) _Pragma("unroll") for(int n=0;n<2;++n) _Pragma("unroll") for(int k=0;k<2;++k) \
;     dst[n][k]=*reinterpret_cast<const bf16x8*>((char*)P8_SB(b,h)+lds_byte(wc*32+n*16+fr,k*32+fq*8))
; #define P8_MMA(ai,bj,At,Bt) do{__builtin_amdgcn_s_setprio(1); \
;     _Pragma("unroll") for(int m=0;m<4;++m) _Pragma("unroll") for(int n=0;n<2;++n) _Pragma("unroll") for(int k=0;k<2;++k) \
;       acc[ai][bj][m][n]=__builtin_amdgcn_mfma_f32_16x16x32_bf16(At[m][k],Bt[n][k],acc[ai][bj][m][n],0,0,0); \
;     __builtin_amdgcn_s_setprio(0);}while(0)
; #define P8_WAIT_V(n) asm volatile("s_waitcnt vmcnt(" #n ")":::"memory")
; #define P8_WAIT_L(n) asm volatile("s_waitcnt lgkmcnt(" #n ")":::"memory")
; #define P8_BAR __builtin_amdgcn_s_barrier()
; #define P8_SCHED __builtin_amdgcn_sched_barrier(0)
; template <class EPI>
; DEVI void gemm8_tile(const bfr* __restrict__ A, const bfr* __restrict__ Bt, int K, int brow, int bcol, int nbrow, int nbcol, char* shmc, EPI epi) {
;     ...
;     P8_BAR; P8_WAIT_L(0); P8_MMA(1,0,At,B0); P8_BAR; P8_SCHED;
;     P8_STAGE(P8_SB(0,1),Bt,bcol+128,t+2);
;     P8_WAIT_V(6); P8_BAR; P8_MMA(1,1,At,B1); P8_BAR;
;     P8_LDB(B0,1,0); P8_SCHED; P8_LDA(At,1,0); P8_STAGE(P8_SA(0,1),A,brow+128,t+2);
;     P8_WAIT_L(8); P8_BAR; P8_WAIT_L(0); P8_MMA(0,0,At,B0); P8_BAR; P8_SCHED;
;     P8_LDB(B1,1,1); P8_STAGE(P8_SB(1,0),Bt,bcol,t+3);
;     P8_BAR; P8_WAIT_L(0); P8_MMA(0,1,At,B1); P8_BAR;
;     P8_LDA(At,1,1); P8_STAGE(P8_SA(1,0),A,brow,t+3);
	s_waitcnt lgkmcnt(0)
	s_setprio 1
	s_waitcnt lgkmcnt(0)
	v_mfma_f32_16x16x32_bf16 v[60:63], v[190:193], v[174:177], v[60:63]
	v_mfma_f32_16x16x32_bf16 v[56:59], v[190:193], v[182:185], v[56:59]
	v_mfma_f32_16x16x32_bf16 v[52:55], v[208:211], v[174:177], v[52:55]
	v_mfma_f32_16x16x32_bf16 v[48:51], v[208:211], v[182:185], v[48:51]
	v_mfma_f32_16x16x32_bf16 v[44:47], v[216:219], v[174:177], v[44:47]
	v_mfma_f32_16x16x32_bf16 v[40:43], v[216:219], v[182:185], v[40:43]
	v_mfma_f32_16x16x32_bf16 v[36:39], v[224:227], v[174:177], v[36:39]
	v_mfma_f32_16x16x32_bf16 v[32:35], v[224:227], v[182:185], v[32:35]
	v_mfma_f32_16x16x32_bf16 v[60:63], v[196:199], v[178:181], v[60:63]
	v_mfma_f32_16x16x32_bf16 v[56:59], v[196:199], v[186:189], v[56:59]
	v_mfma_f32_16x16x32_bf16 v[52:55], v[212:215], v[178:181], v[52:55]
	v_mfma_f32_16x16x32_bf16 v[48:51], v[212:215], v[186:189], v[48:51]
	v_mfma_f32_16x16x32_bf16 v[44:47], v[220:223], v[178:181], v[44:47]
	v_mfma_f32_16x16x32_bf16 v[40:43], v[220:223], v[186:189], v[40:43]
	v_mfma_f32_16x16x32_bf16 v[36:39], v[244:247], v[178:181], v[36:39]
	v_mfma_f32_16x16x32_bf16 v[32:35], v[244:247], v[186:189], v[32:35]
	s_setprio 0
	s_barrier
	v_add_u32_e32 v161, 0x14000, v143
	v_add_u32_e32 v162, s92, v136
	s_add_i32 m0, s100, 0x14000
	v_add_u32_e32 v174, s92, v134
	global_load_lds_dwordx4 v162, s[86:87]
	v_add_u32_e32 v162, 0x16000, v143
	s_nop 0
	s_add_i32 m0, s100, 0x16000
	s_nop 0
	global_load_lds_dwordx4 v174, s[86:87]
	s_waitcnt vmcnt(6)
	s_barrier
	s_setprio 1
	v_mfma_f32_16x16x32_bf16 v[28:31], v[190:193], v[228:231], v[28:31]
	v_mfma_f32_16x16x32_bf16 v[24:27], v[190:193], v[236:239], v[24:27]
	v_mfma_f32_16x16x32_bf16 v[20:23], v[208:211], v[228:231], v[20:23]
	v_mfma_f32_16x16x32_bf16 v[16:19], v[208:211], v[236:239], v[16:19]
	v_mfma_f32_16x16x32_bf16 v[12:15], v[216:219], v[228:231], v[12:15]
	v_mfma_f32_16x16x32_bf16 v[8:11], v[216:219], v[236:239], v[8:11]
	v_mfma_f32_16x16x32_bf16 v[4:7], v[224:227], v[228:231], v[4:7]
	v_mfma_f32_16x16x32_bf16 v[0:3], v[224:227], v[236:239], v[0:3]
	v_mfma_f32_16x16x32_bf16 v[28:31], v[196:199], v[232:235], v[28:31]
	v_mfma_f32_16x16x32_bf16 v[24:27], v[196:199], v[240:243], v[24:27]
	v_mfma_f32_16x16x32_bf16 v[20:23], v[212:215], v[232:235], v[20:23]
	v_mfma_f32_16x16x32_bf16 v[16:19], v[212:215], v[240:243], v[16:19]
	v_mfma_f32_16x16x32_bf16 v[12:15], v[220:223], v[232:235], v[12:15]
	v_mfma_f32_16x16x32_bf16 v[8:11], v[220:223], v[240:243], v[8:11]
	v_mfma_f32_16x16x32_bf16 v[4:7], v[244:247], v[232:235], v[4:7]
	v_mfma_f32_16x16x32_bf16 v[0:3], v[244:247], v[240:243], v[0:3]
	s_setprio 0
	s_barrier
	ds_read_b128 v[174:177], v149
	ds_read_b128 v[178:181], v149 offset:1024
	ds_read_b128 v[182:185], v149 offset:2048
	ds_read_b128 v[186:189], v149 offset:3072
	v_add_u32_e32 v163, 0x4000, v143
	v_add_u32_e32 v170, 0x6000, v143
	v_add_u32_e32 v232, s94, v140
	s_add_i32 m0, s100, 0x4000
	ds_read_b128 v[190:193], v147 offset:32768
	ds_read_b128 v[196:199], v147 offset:33792
	ds_read_b128 v[208:211], v146 offset:32768
	ds_read_b128 v[212:215], v146 offset:33792
	ds_read_b128 v[216:219], v145 offset:32768
	ds_read_b128 v[220:223], v145 offset:33792
	ds_read_b128 v[224:227], v144 offset:32768
	ds_read_b128 v[228:231], v144 offset:33792
	global_load_lds_dwordx4 v232, s[86:87]
	v_add_u32_e32 v232, s94, v138
	s_add_i32 m0, s100, 0x6000
	s_nop 0
	global_load_lds_dwordx4 v232, s[86:87]
	s_waitcnt lgkmcnt(8)
	s_barrier
	s_waitcnt lgkmcnt(0)
	s_setprio 1
	s_waitcnt lgkmcnt(0)
	v_mfma_f32_16x16x32_bf16 v[124:127], v[190:193], v[174:177], v[124:127]
	v_mfma_f32_16x16x32_bf16 v[120:123], v[190:193], v[182:185], v[120:123]
	v_mfma_f32_16x16x32_bf16 v[116:119], v[208:211], v[174:177], v[116:119]
	v_mfma_f32_16x16x32_bf16 v[112:115], v[208:211], v[182:185], v[112:115]
	v_mfma_f32_16x16x32_bf16 v[108:111], v[216:219], v[174:177], v[108:111]
	v_mfma_f32_16x16x32_bf16 v[104:107], v[216:219], v[182:185], v[104:107]
	v_mfma_f32_16x16x32_bf16 v[100:103], v[224:227], v[174:177], v[100:103]
	v_mfma_f32_16x16x32_bf16 v[96:99], v[224:227], v[182:185], v[96:99]
	v_mfma_f32_16x16x32_bf16 v[124:127], v[196:199], v[178:181], v[124:127]
	v_mfma_f32_16x16x32_bf16 v[120:123], v[196:199], v[186:189], v[120:123]
	v_mfma_f32_16x16x32_bf16 v[116:119], v[212:215], v[178:181], v[116:119]
	v_mfma_f32_16x16x32_bf16 v[112:115], v[212:215], v[186:189], v[112:115]
	v_mfma_f32_16x16x32_bf16 v[108:111], v[220:223], v[178:181], v[108:111]
	v_mfma_f32_16x16x32_bf16 v[104:107], v[220:223], v[186:189], v[104:107]
	v_mfma_f32_16x16x32_bf16 v[100:103], v[228:231], v[178:181], v[100:103]
	v_mfma_f32_16x16x32_bf16 v[96:99], v[228:231], v[186:189], v[96:99]
	s_setprio 0
	s_barrier
	v_add_u32_e32 v248, s96, v136
	s_add_i32 m0, s100, 0x18000
	ds_read_b128 v[232:235], v148
	ds_read_b128 v[236:239], v148 offset:1024
	ds_read_b128 v[240:243], v148 offset:2048
	ds_read_b128 v[244:247], v148 offset:3072
	global_load_lds_dwordx4 v248, s[86:87]
	v_add_u32_e32 v248, s96, v134
	s_add_i32 m0, s100, 0x1a000
	s_nop 0
	global_load_lds_dwordx4 v248, s[86:87]
	s_barrier
; #define P8_STAGE(P,BASE,br,kt) do{const bfr* _ub=(BASE)+((long)(br)*K+(long)(kt)*BK); \
;     __builtin_amdgcn_global_load_lds((const unsigned*)(_ub+so0),(unsigned*)((char*)(P)+wid*1024),16,0,0); \
;     __builtin_amdgcn_global_load_lds((const unsigned*)(_ub+so1),(unsigned*)((char*)(P)+wid*1024+8192),16,0,0);}while(0)
; #define P8_LDA(dst,b,h) _Pragma("unroll") for(int m=0;m<4;++m) _Pragma("unroll") for(int k=0;k<2;++k) \
;     dst[m][k]=*reinterpret_cast<const bf16x8*>((char*)P8_SA(b,h)+lds_byte(wr*64+m*16+fr,k*32+fq*8))
; #define P8_LDB(dst,b,h) _Pragma("unroll") for(int n=0;n<2;++n) _Pragma("unroll") for(int k=0;k<2;++k) \
;     dst[n][k]=*reinterpret_cast<const bf16x8*>((char*)P8_SB(b,h)+lds_byte(wc*32+n*16+fr,k*32+fq*8))
; #define P8_MMA(ai,bj,At,Bt) do{__builtin_amdgcn_s_setprio(1); \
;     _Pragma("unroll") for(int m=0;m<4;++m) _Pragma("unroll") for(int n=0;n<2;++n) _Pragma("unroll") for(int k=0;k<2;++k) \
;       acc[ai][bj][m][n]=__builtin_amdgcn_mfma_f32_16x16x32_bf16(At[m][k],Bt[n][k],acc[ai][bj][m][n],0,0,0); \
;     __builtin_amdgcn_s_setprio(0);}while(0)
; #define P8_WAIT_V(n) asm volatile("s_waitcnt vmcnt(" #n ")":::"memory")
; #define P8_WAIT_L(n) asm volatile("s_waitcnt lgkmcnt(" #n ")":::"memory")
; #define P8_BAR __builtin_amdgcn_s_barrier()
; #define P8_SCHED __builtin_amdgcn_sched_barrier(0)
; template <class EPI>
; DEVI void gemm8_tile(const bfr* __restrict__ A, const bfr* __restrict__ Bt, int K, int brow, int bcol, int nbrow, int nbcol, char* shmc, EPI epi) {
;     ...
;     P8_LDA(At,1,1); P8_STAGE(P8_SA(1,0),A,brow,t+3);
;     P8_BAR; P8_WAIT_L(0); P8_MMA(1,0,At,B0); P8_BAR; P8_SCHED;
;     P8_STAGE(P8_SB(1,1),Bt,bcol+128,t+3);
;     P8_WAIT_V(6); P8_BAR; P8_MMA(1,1,At,B1); P8_BAR;
;   }
;   { P8_LDB(B0,0,0); P8_LDA(At,0,0); P8_STAGE(P8_SA(1,1),A,brow+128,nt-1);
	s_waitcnt lgkmcnt(0)
	s_setprio 1
	s_waitcnt lgkmcnt(0)
	v_mfma_f32_16x16x32_bf16 v[92:95], v[190:193], v[232:235], v[92:95]
	v_mfma_f32_16x16x32_bf16 v[88:91], v[190:193], v[240:243], v[88:91]
	v_mfma_f32_16x16x32_bf16 v[84:87], v[208:211], v[232:235], v[84:87]
	v_mfma_f32_16x16x32_bf16 v[80:83], v[208:211], v[240:243], v[80:83]
	v_mfma_f32_16x16x32_bf16 v[76:79], v[216:219], v[232:235], v[76:79]
	v_mfma_f32_16x16x32_bf16 v[72:75], v[216:219], v[240:243], v[72:75]
	v_mfma_f32_16x16x32_bf16 v[68:71], v[224:227], v[232:235], v[68:71]
	v_mfma_f32_16x16x32_bf16 v[64:67], v[224:227], v[240:243], v[64:67]
	v_mfma_f32_16x16x32_bf16 v[92:95], v[196:199], v[236:239], v[92:95]
	v_mfma_f32_16x16x32_bf16 v[88:91], v[196:199], v[244:247], v[88:91]
	v_mfma_f32_16x16x32_bf16 v[84:87], v[212:215], v[236:239], v[84:87]
	v_mfma_f32_16x16x32_bf16 v[80:83], v[212:215], v[244:247], v[80:83]
	v_mfma_f32_16x16x32_bf16 v[76:79], v[220:223], v[236:239], v[76:79]
	v_mfma_f32_16x16x32_bf16 v[72:75], v[220:223], v[244:247], v[72:75]
	v_mfma_f32_16x16x32_bf16 v[68:71], v[228:231], v[236:239], v[68:71]
	v_mfma_f32_16x16x32_bf16 v[64:67], v[228:231], v[244:247], v[64:67]
	s_setprio 0
	v_add_u32_e32 v200, vcc_lo, v140
	s_add_i32 m0, s100, 0x8000
	s_barrier
	ds_read_b128 v[190:193], v147 offset:49152
	ds_read_b128 v[196:199], v147 offset:50176
	ds_read_b128 v[208:211], v146 offset:49152
	ds_read_b128 v[212:215], v146 offset:50176
	ds_read_b128 v[216:219], v145 offset:49152
	ds_read_b128 v[220:223], v145 offset:50176
	ds_read_b128 v[224:227], v144 offset:49152
	ds_read_b128 v[228:231], v144 offset:50176
	global_load_lds_dwordx4 v200, s[86:87]
	v_add_u32_e32 v200, vcc_lo, v138
	s_add_i32 m0, s100, 0xa000
	s_nop 0
	global_load_lds_dwordx4 v200, s[86:87]
	s_barrier
	s_waitcnt lgkmcnt(0)
	s_setprio 1
	s_waitcnt lgkmcnt(0)
	v_mfma_f32_16x16x32_bf16 v[60:63], v[190:193], v[174:177], v[60:63]
	v_mfma_f32_16x16x32_bf16 v[56:59], v[190:193], v[182:185], v[56:59]
	v_mfma_f32_16x16x32_bf16 v[52:55], v[208:211], v[174:177], v[52:55]
	v_mfma_f32_16x16x32_bf16 v[48:51], v[208:211], v[182:185], v[48:51]
	v_mfma_f32_16x16x32_bf16 v[44:47], v[216:219], v[174:177], v[44:47]
	v_mfma_f32_16x16x32_bf16 v[40:43], v[216:219], v[182:185], v[40:43]
	v_mfma_f32_16x16x32_bf16 v[36:39], v[224:227], v[174:177], v[36:39]
	v_mfma_f32_16x16x32_bf16 v[32:35], v[224:227], v[182:185], v[32:35]
	v_mfma_f32_16x16x32_bf16 v[60:63], v[196:199], v[178:181], v[60:63]
	v_mfma_f32_16x16x32_bf16 v[56:59], v[196:199], v[186:189], v[56:59]
	v_mfma_f32_16x16x32_bf16 v[52:55], v[212:215], v[178:181], v[52:55]
	v_mfma_f32_16x16x32_bf16 v[48:51], v[212:215], v[186:189], v[48:51]
	v_mfma_f32_16x16x32_bf16 v[44:47], v[220:223], v[178:181], v[44:47]
	v_mfma_f32_16x16x32_bf16 v[40:43], v[220:223], v[186:189], v[40:43]
	v_mfma_f32_16x16x32_bf16 v[36:39], v[228:231], v[178:181], v[36:39]
	v_mfma_f32_16x16x32_bf16 v[32:35], v[228:231], v[186:189], v[32:35]
	s_setprio 0
	s_barrier
	v_add_u32_e32 v174, s28, v136
	s_add_i32 m0, s100, 0x1c000
	s_nop 0
	global_load_lds_dwordx4 v174, s[86:87]
	v_add_u32_e32 v174, s28, v134
	s_add_i32 m0, s100, 0x1e000
	s_nop 0
	global_load_lds_dwordx4 v174, s[86:87]
	s_waitcnt vmcnt(6)
	s_barrier
	s_setprio 1
	v_mfma_f32_16x16x32_bf16 v[28:31], v[190:193], v[232:235], v[28:31]
	v_mfma_f32_16x16x32_bf16 v[24:27], v[190:193], v[240:243], v[24:27]
	v_mfma_f32_16x16x32_bf16 v[20:23], v[208:211], v[232:235], v[20:23]
	v_mfma_f32_16x16x32_bf16 v[16:19], v[208:211], v[240:243], v[16:19]
	v_mfma_f32_16x16x32_bf16 v[12:15], v[216:219], v[232:235], v[12:15]
	v_mfma_f32_16x16x32_bf16 v[8:11], v[216:219], v[240:243], v[8:11]
	v_mfma_f32_16x16x32_bf16 v[4:7], v[224:227], v[232:235], v[4:7]
	v_mfma_f32_16x16x32_bf16 v[0:3], v[224:227], v[240:243], v[0:3]
	v_mfma_f32_16x16x32_bf16 v[28:31], v[196:199], v[236:239], v[28:31]
	v_mfma_f32_16x16x32_bf16 v[24:27], v[196:199], v[244:247], v[24:27]
	v_mfma_f32_16x16x32_bf16 v[20:23], v[212:215], v[236:239], v[20:23]
	v_mfma_f32_16x16x32_bf16 v[16:19], v[212:215], v[244:247], v[16:19]
	v_mfma_f32_16x16x32_bf16 v[12:15], v[220:223], v[236:239], v[12:15]
	v_mfma_f32_16x16x32_bf16 v[8:11], v[220:223], v[244:247], v[8:11]
	v_mfma_f32_16x16x32_bf16 v[4:7], v[228:231], v[236:239], v[4:7]
	v_mfma_f32_16x16x32_bf16 v[0:3], v[228:231], v[244:247], v[0:3]
	s_setprio 0
	s_add_i32 s0, s0, 2
	v_lshl_add_u64 v[134:135], v[134:135], 0, s[80:81]
	v_lshl_add_u64 v[136:137], v[136:137], 0, s[80:81]
	v_lshl_add_u64 v[138:139], v[138:139], 0, s[80:81]
	s_cmpk_lt_u32 s0, 0x7c
	v_lshl_add_u64 v[140:141], v[140:141], 0, s[80:81]
	s_barrier
	s_cbranch_scc1 .LBB0_382
	s_or_b32 s0, s10, 0x80
	s_ashr_i32 s1, s0, 31
	s_lshl_b64 s[0:1], s[0:1], 14
	s_add_u32 s0, s31, s0
	s_addc_u32 s1, s64, s1
	s_add_u32 s0, s0, 0x3f80
	s_addc_u32 s1, s1, 0
	ds_read_b128 v[134:137], v157
	ds_read_b128 v[138:141], v157 offset:1024
	ds_read_b128 v[150:153], v157 offset:2048
	ds_read_b128 v[174:177], v157 offset:3072
	ds_read_b128 v[178:181], v147
	ds_read_b128 v[182:185], v147 offset:1024
	ds_read_b128 v[186:189], v146
	ds_read_b128 v[190:193], v146 offset:1024
	ds_read_b128 v[196:199], v145
	ds_read_b128 v[208:211], v145 offset:1024
	ds_read_b128 v[212:215], v144
	ds_read_b128 v[216:219], v144 offset:1024
	v_lshl_add_u64 v[156:157], v[166:167], 1, s[0:1]
	s_add_i32 m0, s100, 0xc000
	v_lshl_add_u64 v[132:133], v[132:133], 1, s[0:1]
	global_load_lds_dwordx4 v[156:157], off
	s_add_i32 m0, s100, 0xe000
	s_nop 0
	global_load_lds_dwordx4 v[132:133], off
	s_barrier
; #define P8_STAGE(P,BASE,br,kt) do{const bfr* _ub=(BASE)+((long)(br)*K+(long)(kt)*BK); \
;     __builtin_amdgcn_global_load_lds((const unsigned*)(_ub+so0),(unsigned*)((char*)(P)+wid*1024),16,0,0); \
;     __builtin_amdgcn_global_load_lds((const unsigned*)(_ub+so1),(unsigned*)((char*)(P)+wid*1024+8192),16,0,0);}while(0)
; #define P8_LDA(dst,b,h) _Pragma("unroll") for(int m=0;m<4;++m) _Pragma("unroll") for(int k=0;k<2;++k) \
;     dst[m][k]=*reinterpret_cast<const bf16x8*>((char*)P8_SA(b,h)+lds_byte(wr*64+m*16+fr,k*32+fq*8))
; #define P8_LDB(dst,b,h) _Pragma("unroll") for(int n=0;n<2;++n) _Pragma("unroll") for(int k=0;k<2;++k) \
;     dst[n][k]=*reinterpret_cast<const bf16x8*>((char*)P8_SB(b,h)+lds_byte(wc*32+n*16+fr,k*32+fq*8))
; #define P8_MMA(ai,bj,At,Bt) do{__builtin_amdgcn_s_setprio(1); \
;     _Pragma("unroll") for(int m=0;m<4;++m) _Pragma("unroll") for(int n=0;n<2;++n) _Pragma("unroll") for(int k=0;k<2;++k) \
;       acc[ai][bj][m][n]=__builtin_amdgcn_mfma_f32_16x16x32_bf16(At[m][k],Bt[n][k],acc[ai][bj][m][n],0,0,0); \
;     __builtin_amdgcn_s_setprio(0);}while(0)
; #define P8_WAIT_V(n) asm volatile("s_waitcnt vmcnt(" #n ")":::"memory")
; #define P8_WAIT_L(n) asm volatile("s_waitcnt lgkmcnt(" #n ")":::"memory")
; #define P8_BAR __builtin_amdgcn_s_barrier()
; template <class EPI>
; DEVI void gemm8_tile(const bfr* __restrict__ A, const bfr* __restrict__ Bt, int K, int brow, int bcol, int nbrow, int nbcol, char* shmc, EPI epi) {
;     ...
;   { P8_LDB(B0,0,0); P8_LDA(At,0,0); P8_STAGE(P8_SA(1,1),A,brow+128,nt-1);
;     P8_BAR; P8_WAIT_L(0); P8_MMA(0,0,At,B0); P8_BAR;
;     P8_LDB(B1,0,1); P8_BAR; P8_WAIT_L(0); P8_MMA(0,1,At,B1); P8_BAR;
;     P8_LDA(At,0,1); P8_WAIT_V(4); P8_BAR; P8_WAIT_L(0); P8_MMA(1,0,At,B0); P8_MMA(1,1,At,B1); P8_BAR; }
;   { P8_LDB(B0,1,0); P8_LDA(At,1,0); P8_WAIT_V(2); P8_BAR; P8_WAIT_L(0); P8_MMA(0,0,At,B0); P8_BAR;
	s_waitcnt lgkmcnt(0)
	s_setprio 1
	s_waitcnt lgkmcnt(0)
	v_mfma_f32_16x16x32_bf16 v[124:127], v[178:181], v[134:137], v[124:127]
	v_mfma_f32_16x16x32_bf16 v[116:119], v[186:189], v[134:137], v[116:119]
	v_mfma_f32_16x16x32_bf16 v[112:115], v[186:189], v[150:153], v[112:115]
	v_mfma_f32_16x16x32_bf16 v[96:99], v[212:215], v[150:153], v[96:99]
	v_mfma_f32_16x16x32_bf16 v[124:127], v[182:185], v[138:141], v[124:127]
	v_mfma_f32_16x16x32_bf16 v[120:123], v[178:181], v[150:153], v[120:123]
	v_mfma_f32_16x16x32_bf16 v[116:119], v[190:193], v[138:141], v[116:119]
	v_mfma_f32_16x16x32_bf16 v[112:115], v[190:193], v[174:177], v[112:115]
	v_mfma_f32_16x16x32_bf16 v[108:111], v[196:199], v[134:137], v[108:111]
	v_mfma_f32_16x16x32_bf16 v[104:107], v[196:199], v[150:153], v[104:107]
	v_mfma_f32_16x16x32_bf16 v[100:103], v[212:215], v[134:137], v[100:103]
	v_mfma_f32_16x16x32_bf16 v[96:99], v[216:219], v[174:177], v[96:99]
	v_mfma_f32_16x16x32_bf16 v[220:223], v[182:185], v[174:177], v[120:123]
	v_mfma_f32_16x16x32_bf16 v[224:227], v[208:211], v[138:141], v[108:111]
	v_mfma_f32_16x16x32_bf16 v[228:231], v[208:211], v[174:177], v[104:107]
	v_mfma_f32_16x16x32_bf16 v[232:235], v[216:219], v[138:141], v[100:103]
	s_setprio 0
	s_barrier
	s_nop 0
	ds_read_b128 v[100:103], v154
	ds_read_b128 v[104:107], v154 offset:1024
	ds_read_b128 v[108:111], v154 offset:2048
	ds_read_b128 v[120:123], v154 offset:3072
	s_barrier
	s_waitcnt lgkmcnt(0)
	s_setprio 1
	s_waitcnt lgkmcnt(0)
	v_mfma_f32_16x16x32_bf16 v[92:95], v[178:181], v[100:103], v[92:95]
	v_mfma_f32_16x16x32_bf16 v[84:87], v[186:189], v[100:103], v[84:87]
	v_mfma_f32_16x16x32_bf16 v[80:83], v[186:189], v[108:111], v[80:83]
	v_mfma_f32_16x16x32_bf16 v[64:67], v[212:215], v[108:111], v[64:67]
	v_mfma_f32_16x16x32_bf16 v[92:95], v[182:185], v[104:107], v[92:95]
	v_mfma_f32_16x16x32_bf16 v[88:91], v[178:181], v[108:111], v[88:91]
	v_mfma_f32_16x16x32_bf16 v[84:87], v[190:193], v[104:107], v[84:87]
	v_mfma_f32_16x16x32_bf16 v[80:83], v[190:193], v[120:123], v[80:83]
	v_mfma_f32_16x16x32_bf16 v[76:79], v[196:199], v[100:103], v[76:79]
	v_mfma_f32_16x16x32_bf16 v[72:75], v[196:199], v[108:111], v[72:75]
	v_mfma_f32_16x16x32_bf16 v[68:71], v[212:215], v[100:103], v[68:71]
	v_mfma_f32_16x16x32_bf16 v[64:67], v[216:219], v[120:123], v[64:67]
	v_mfma_f32_16x16x32_bf16 v[154:157], v[182:185], v[120:123], v[88:91]
	v_mfma_f32_16x16x32_bf16 v[178:181], v[208:211], v[104:107], v[76:79]
	v_mfma_f32_16x16x32_bf16 v[182:185], v[208:211], v[120:123], v[72:75]
	v_mfma_f32_16x16x32_bf16 v[186:189], v[216:219], v[104:107], v[68:71]
	s_setprio 0
	s_barrier
	s_nop 0
	ds_read_b128 v[68:71], v147 offset:16384
	ds_read_b128 v[72:75], v147 offset:17408
	ds_read_b128 v[76:79], v146 offset:16384
	ds_read_b128 v[88:91], v146 offset:17408
	ds_read_b128 v[190:193], v145 offset:16384
	ds_read_b128 v[196:199], v145 offset:17408
	ds_read_b128 v[208:211], v144 offset:16384
	ds_read_b128 v[212:215], v144 offset:17408
	s_waitcnt vmcnt(4)
	s_barrier
	s_waitcnt lgkmcnt(0)
	s_setprio 1
	s_waitcnt lgkmcnt(0)
	v_mfma_f32_16x16x32_bf16 v[60:63], v[68:71], v[134:137], v[60:63]
	v_mfma_f32_16x16x32_bf16 v[52:55], v[76:79], v[134:137], v[52:55]
	v_mfma_f32_16x16x32_bf16 v[48:51], v[76:79], v[150:153], v[48:51]
	v_mfma_f32_16x16x32_bf16 v[32:35], v[208:211], v[150:153], v[32:35]
	v_mfma_f32_16x16x32_bf16 v[60:63], v[72:75], v[138:141], v[60:63]
	v_mfma_f32_16x16x32_bf16 v[56:59], v[68:71], v[150:153], v[56:59]
	v_mfma_f32_16x16x32_bf16 v[52:55], v[88:91], v[138:141], v[52:55]
	v_mfma_f32_16x16x32_bf16 v[48:51], v[88:91], v[174:177], v[48:51]
	v_mfma_f32_16x16x32_bf16 v[44:47], v[190:193], v[134:137], v[44:47]
	v_mfma_f32_16x16x32_bf16 v[40:43], v[190:193], v[150:153], v[40:43]
	v_mfma_f32_16x16x32_bf16 v[36:39], v[208:211], v[134:137], v[36:39]
	v_mfma_f32_16x16x32_bf16 v[32:35], v[212:215], v[174:177], v[32:35]
	v_mfma_f32_16x16x32_bf16 v[216:219], v[72:75], v[174:177], v[56:59]
	v_mfma_f32_16x16x32_bf16 v[236:239], v[196:199], v[138:141], v[44:47]
	v_mfma_f32_16x16x32_bf16 v[240:243], v[196:199], v[174:177], v[40:43]
	v_mfma_f32_16x16x32_bf16 v[132:135], v[212:215], v[138:141], v[36:39]
	s_setprio 0
	s_setprio 1
	v_mfma_f32_16x16x32_bf16 v[28:31], v[68:71], v[100:103], v[28:31]
	v_mfma_f32_16x16x32_bf16 v[20:23], v[76:79], v[100:103], v[20:23]
	v_mfma_f32_16x16x32_bf16 v[16:19], v[76:79], v[108:111], v[16:19]
	v_mfma_f32_16x16x32_bf16 v[0:3], v[208:211], v[108:111], v[0:3]
	v_mfma_f32_16x16x32_bf16 v[28:31], v[72:75], v[104:107], v[28:31]
	v_mfma_f32_16x16x32_bf16 v[24:27], v[68:71], v[108:111], v[24:27]
	v_mfma_f32_16x16x32_bf16 v[20:23], v[88:91], v[104:107], v[20:23]
	v_mfma_f32_16x16x32_bf16 v[16:19], v[88:91], v[120:123], v[16:19]
	v_mfma_f32_16x16x32_bf16 v[12:15], v[190:193], v[100:103], v[12:15]
	v_mfma_f32_16x16x32_bf16 v[8:11], v[190:193], v[108:111], v[8:11]
	v_mfma_f32_16x16x32_bf16 v[4:7], v[208:211], v[100:103], v[4:7]
	v_mfma_f32_16x16x32_bf16 v[0:3], v[212:215], v[120:123], v[0:3]
	v_mfma_f32_16x16x32_bf16 v[136:139], v[72:75], v[120:123], v[24:27]
	v_mfma_f32_16x16x32_bf16 v[150:153], v[196:199], v[104:107], v[12:15]
	v_mfma_f32_16x16x32_bf16 v[172:175], v[196:199], v[120:123], v[8:11]
	v_mfma_f32_16x16x32_bf16 v[190:193], v[212:215], v[104:107], v[4:7]
	s_setprio 0
	s_barrier
	s_nop 0
	ds_read_b128 v[4:7], v149
	ds_read_b128 v[8:11], v149 offset:1024
	ds_read_b128 v[12:15], v149 offset:2048
	ds_read_b128 v[24:27], v149 offset:3072
	ds_read_b128 v[36:39], v147 offset:32768
	ds_read_b128 v[40:43], v147 offset:33792
	ds_read_b128 v[44:47], v146 offset:32768
	ds_read_b128 v[56:59], v146 offset:33792
	ds_read_b128 v[68:71], v145 offset:32768
	ds_read_b128 v[196:199], v145 offset:33792
	ds_read_b128 v[208:211], v144 offset:32768
	ds_read_b128 v[212:215], v144 offset:33792
	s_waitcnt vmcnt(2)
	s_barrier
; #define P8_STAGE(P,BASE,br,kt) do{const bfr* _ub=(BASE)+((long)(br)*K+(long)(kt)*BK); \
;     __builtin_amdgcn_global_load_lds((const unsigned*)(_ub+so0),(unsigned*)((char*)(P)+wid*1024),16,0,0); \
;     __builtin_amdgcn_global_load_lds((const unsigned*)(_ub+so1),(unsigned*)((char*)(P)+wid*1024+8192),16,0,0);}while(0)
; #define P8_LDA(dst,b,h) _Pragma("unroll") for(int m=0;m<4;++m) _Pragma("unroll") for(int k=0;k<2;++k) \
;     dst[m][k]=*reinterpret_cast<const bf16x8*>((char*)P8_SA(b,h)+lds_byte(wr*64+m*16+fr,k*32+fq*8))
; #define P8_LDB(dst,b,h) _Pragma("unroll") for(int n=0;n<2;++n) _Pragma("unroll") for(int k=0;k<2;++k) \
;     dst[n][k]=*reinterpret_cast<const bf16x8*>((char*)P8_SB(b,h)+lds_byte(wc*32+n*16+fr,k*32+fq*8))
; #define P8_MMA(ai,bj,At,Bt) do{__builtin_amdgcn_s_setprio(1); \
;     _Pragma("unroll") for(int m=0;m<4;++m) _Pragma("unroll") for(int n=0;n<2;++n) _Pragma("unroll") for(int k=0;k<2;++k) \
;       acc[ai][bj][m][n]=__builtin_amdgcn_mfma_f32_16x16x32_bf16(At[m][k],Bt[n][k],acc[ai][bj][m][n],0,0,0); \
;     __builtin_amdgcn_s_setprio(0);}while(0)
; #define P8_WAIT_V(n) asm volatile("s_waitcnt vmcnt(" #n ")":::"memory")
; #define P8_WAIT_L(n) asm volatile("s_waitcnt lgkmcnt(" #n ")":::"memory")
; #define P8_BAR __builtin_amdgcn_s_barrier()
; template <class EPI>
; DEVI void gemm8_tile(const bfr* __restrict__ A, const bfr* __restrict__ Bt, int K, int brow, int bcol, int nbrow, int nbcol, char* shmc, EPI epi) {
;     ...
;     P8_LDA(At,0,1); P8_WAIT_V(4); P8_BAR; P8_WAIT_L(0); P8_MMA(1,0,At,B0); P8_MMA(1,1,At,B1); P8_BAR; }
;   { P8_LDB(B0,1,0); P8_LDA(At,1,0); P8_WAIT_V(2); P8_BAR; P8_WAIT_L(0); P8_MMA(0,0,At,B0); P8_BAR;
;     P8_LDB(B1,1,1); P8_WAIT_V(0); P8_BAR; P8_WAIT_L(0); P8_MMA(0,1,At,B1); P8_BAR;
;     P8_LDA(At,1,1); P8_BAR; P8_WAIT_L(0); P8_MMA(1,0,At,B0); P8_MMA(1,1,At,B1); P8_BAR; }
;   if(wr==0)P8_BAR;
;   if (nbrow >= 0) {
;     P8_STAGE(P8_SB(0,0),Bt,nbcol,0); P8_STAGE(P8_SA(0,0),A,nbrow,0);
;     P8_STAGE(P8_SB(0,1),Bt,nbcol+128,0); P8_STAGE(P8_SA(0,1),A,nbrow+128,0);
;   }
	s_waitcnt lgkmcnt(0)
	s_setprio 1
	s_waitcnt lgkmcnt(0)
	v_mfma_f32_16x16x32_bf16 v[72:75], v[36:39], v[4:7], v[124:127]
	v_mfma_f32_16x16x32_bf16 v[120:123], v[40:43], v[8:11], v[72:75]
	v_mfma_f32_16x16x32_bf16 v[72:75], v[36:39], v[12:15], v[220:223]
	v_mfma_f32_16x16x32_bf16 v[104:107], v[40:43], v[24:27], v[72:75]
	v_mfma_f32_16x16x32_bf16 v[72:75], v[44:47], v[4:7], v[116:119]
	v_mfma_f32_16x16x32_bf16 v[124:127], v[56:59], v[8:11], v[72:75]
	v_mfma_f32_16x16x32_bf16 v[72:75], v[44:47], v[12:15], v[112:115]
	v_mfma_f32_16x16x32_bf16 v[108:111], v[56:59], v[24:27], v[72:75]
	v_mfma_f32_16x16x32_bf16 v[72:75], v[68:71], v[4:7], v[224:227]
	v_mfma_f32_16x16x32_bf16 v[112:115], v[196:199], v[8:11], v[72:75]
	v_mfma_f32_16x16x32_bf16 v[72:75], v[68:71], v[12:15], v[228:231]
	v_mfma_f32_16x16x32_bf16 v[100:103], v[196:199], v[24:27], v[72:75]
	v_mfma_f32_16x16x32_bf16 v[72:75], v[208:211], v[4:7], v[232:235]
	v_mfma_f32_16x16x32_bf16 v[116:119], v[212:215], v[8:11], v[72:75]
	v_mfma_f32_16x16x32_bf16 v[72:75], v[208:211], v[12:15], v[96:99]
	v_mfma_f32_16x16x32_bf16 v[96:99], v[212:215], v[24:27], v[72:75]
	s_setprio 0
	s_barrier
	ds_read_b128 v[220:223], v148
	ds_read_b128 v[224:227], v148 offset:1024
	ds_read_b128 v[228:231], v148 offset:2048
	ds_read_b128 v[232:235], v148 offset:3072
	s_waitcnt vmcnt(0)
	s_barrier
	s_waitcnt lgkmcnt(0)
	s_setprio 1
	s_waitcnt lgkmcnt(0)
	v_mfma_f32_16x16x32_bf16 v[72:75], v[36:39], v[220:223], v[92:95]
	v_mfma_f32_16x16x32_bf16 v[36:39], v[36:39], v[228:231], v[154:157]
	v_mfma_f32_16x16x32_bf16 v[88:91], v[40:43], v[224:227], v[72:75]
	v_mfma_f32_16x16x32_bf16 v[72:75], v[40:43], v[232:235], v[36:39]
	v_mfma_f32_16x16x32_bf16 v[36:39], v[44:47], v[220:223], v[84:87]
	v_mfma_f32_16x16x32_bf16 v[92:95], v[56:59], v[224:227], v[36:39]
	v_mfma_f32_16x16x32_bf16 v[36:39], v[44:47], v[228:231], v[80:83]
	v_mfma_f32_16x16x32_bf16 v[76:79], v[56:59], v[232:235], v[36:39]
	v_mfma_f32_16x16x32_bf16 v[36:39], v[68:71], v[220:223], v[178:181]
	v_mfma_f32_16x16x32_bf16 v[80:83], v[196:199], v[224:227], v[36:39]
	v_mfma_f32_16x16x32_bf16 v[36:39], v[68:71], v[228:231], v[182:185]
	v_mfma_f32_16x16x32_bf16 v[68:71], v[196:199], v[232:235], v[36:39]
	v_mfma_f32_16x16x32_bf16 v[36:39], v[208:211], v[220:223], v[186:189]
	v_mfma_f32_16x16x32_bf16 v[84:87], v[212:215], v[224:227], v[36:39]
	v_mfma_f32_16x16x32_bf16 v[36:39], v[208:211], v[228:231], v[64:67]
	v_mfma_f32_16x16x32_bf16 v[64:67], v[212:215], v[232:235], v[36:39]
	s_setprio 0
	s_barrier
	ds_read_b128 v[154:157], v147 offset:49152
	ds_read_b128 v[176:179], v147 offset:50176
	ds_read_b128 v[180:183], v146 offset:49152
	ds_read_b128 v[146:149], v146 offset:50176
	ds_read_b128 v[184:187], v145 offset:49152
	ds_read_b128 v[196:199], v145 offset:50176
	ds_read_b128 v[208:211], v144 offset:49152
	ds_read_b128 v[212:215], v144 offset:50176
	s_barrier
	s_waitcnt lgkmcnt(0)
	s_setprio 1
	s_waitcnt lgkmcnt(0)
	v_mfma_f32_16x16x32_bf16 v[36:39], v[154:157], v[4:7], v[60:63]
	v_mfma_f32_16x16x32_bf16 v[56:59], v[176:179], v[8:11], v[36:39]
	v_mfma_f32_16x16x32_bf16 v[36:39], v[154:157], v[12:15], v[216:219]
	v_mfma_f32_16x16x32_bf16 v[40:43], v[176:179], v[24:27], v[36:39]
	v_mfma_f32_16x16x32_bf16 v[36:39], v[180:183], v[4:7], v[52:55]
	v_mfma_f32_16x16x32_bf16 v[60:63], v[146:149], v[8:11], v[36:39]
	v_mfma_f32_16x16x32_bf16 v[36:39], v[180:183], v[12:15], v[48:51]
	v_mfma_f32_16x16x32_bf16 v[44:47], v[146:149], v[24:27], v[36:39]
	v_mfma_f32_16x16x32_bf16 v[36:39], v[184:187], v[4:7], v[236:239]
	v_mfma_f32_16x16x32_bf16 v[4:7], v[208:211], v[4:7], v[132:135]
	v_mfma_f32_16x16x32_bf16 v[48:51], v[196:199], v[8:11], v[36:39]
	v_mfma_f32_16x16x32_bf16 v[36:39], v[184:187], v[12:15], v[240:243]
	v_mfma_f32_16x16x32_bf16 v[52:55], v[212:215], v[8:11], v[4:7]
	v_mfma_f32_16x16x32_bf16 v[4:7], v[208:211], v[12:15], v[32:35]
	v_mfma_f32_16x16x32_bf16 v[36:39], v[196:199], v[24:27], v[36:39]
	v_mfma_f32_16x16x32_bf16 v[32:35], v[212:215], v[24:27], v[4:7]
	s_setprio 0
	s_setprio 1
	v_mfma_f32_16x16x32_bf16 v[4:7], v[154:157], v[220:223], v[28:31]
	v_mfma_f32_16x16x32_bf16 v[24:27], v[176:179], v[224:227], v[4:7]
	v_mfma_f32_16x16x32_bf16 v[4:7], v[154:157], v[228:231], v[136:139]
	v_mfma_f32_16x16x32_bf16 v[8:11], v[176:179], v[232:235], v[4:7]
	v_mfma_f32_16x16x32_bf16 v[4:7], v[180:183], v[220:223], v[20:23]
	v_mfma_f32_16x16x32_bf16 v[28:31], v[146:149], v[224:227], v[4:7]
	v_mfma_f32_16x16x32_bf16 v[4:7], v[180:183], v[228:231], v[16:19]
	v_mfma_f32_16x16x32_bf16 v[12:15], v[146:149], v[232:235], v[4:7]
	v_mfma_f32_16x16x32_bf16 v[4:7], v[184:187], v[220:223], v[150:153]
	v_mfma_f32_16x16x32_bf16 v[16:19], v[196:199], v[224:227], v[4:7]
	v_mfma_f32_16x16x32_bf16 v[4:7], v[184:187], v[228:231], v[172:175]
	v_mfma_f32_16x16x32_bf16 v[20:23], v[208:211], v[220:223], v[190:193]
	v_mfma_f32_16x16x32_bf16 v[0:3], v[208:211], v[228:231], v[0:3]
	v_mfma_f32_16x16x32_bf16 v[4:7], v[196:199], v[232:235], v[4:7]
	v_mfma_f32_16x16x32_bf16 v[20:23], v[212:215], v[224:227], v[20:23]
	v_mfma_f32_16x16x32_bf16 v[0:3], v[212:215], v[232:235], v[0:3]
	s_setprio 0
	v_cmp_gt_u32_e32 vcc, s57, v142
	s_barrier
	s_and_saveexec_b64 s[0:1], vcc
	s_cbranch_execz .LBB0_385
	s_barrier
.LBB0_385:
	s_or_b64 exec, exec, s[0:1]
	s_lshl_b32 s2, s69, 8
	s_and_b64 s[0:1], s[4:5], exec
	s_cselect_b32 s58, s2, -1
	s_cmp_lt_i32 s58, 0
	s_cbranch_scc1 .LBB0_374
	s_lshl_b32 s0, s72, 8
	s_ashr_i32 s1, s0, 31
	s_lshl_b64 s[4:5], s[0:1], 14
	s_add_u32 s4, s65, s4
	s_addc_u32 s5, s68, s5
	v_lshl_add_u64 v[132:133], s[4:5], 0, v[128:129]
	s_add_i32 m0, s100, 0x10000
	v_readfirstlane_b32 s1, v159
	global_load_lds_dwordx4 v[132:133], off
	v_lshl_add_u64 v[132:133], s[4:5], 0, v[130:131]
	s_lshl_b64 s[4:5], s[58:59], 14
	s_add_u32 s4, s31, s4
	s_mov_b32 m0, s1
	s_addc_u32 s5, s64, s5
	global_load_lds_dwordx4 v[132:133], off
	v_lshl_add_u64 v[132:133], s[4:5], 0, v[128:129]
	s_mov_b32 m0, s100
	s_bitset1_b32 s0, 7
	global_load_lds_dwordx4 v[132:133], off
	s_add_i32 m0, s100, 0x2000
	s_ashr_i32 s1, s0, 31
	s_lshl_b64 s[0:1], s[0:1], 14
	s_add_u32 s0, s65, s0
	v_lshl_add_u64 v[132:133], s[4:5], 0, v[130:131]
	s_addc_u32 s1, s68, s1
	global_load_lds_dwordx4 v[132:133], off
	v_lshl_add_u64 v[132:133], s[0:1], 0, v[128:129]
	s_add_i32 m0, s100, 0x14000
	s_addk_i32 s58, 0x80
	global_load_lds_dwordx4 v[132:133], off
	v_lshl_add_u64 v[132:133], s[0:1], 0, v[130:131]
	s_add_i32 m0, s100, 0x16000
	s_lshl_b64 s[0:1], s[58:59], 14
	s_add_u32 s0, s31, s0
	s_addc_u32 s1, s64, s1
	v_readfirstlane_b32 s2, v163
	global_load_lds_dwordx4 v[132:133], off
	v_lshl_add_u64 v[128:129], s[0:1], 0, v[128:129]
	s_mov_b32 m0, s2
	s_nop 0
	global_load_lds_dwordx4 v[128:129], off
	v_lshl_add_u64 v[128:129], s[0:1], 0, v[130:131]
	v_readfirstlane_b32 s0, v170
	s_mov_b32 m0, s0
	s_nop 0
	global_load_lds_dwordx4 v[128:129], off
	s_branch .LBB0_374

; #define P8_STAGE(P,BASE,br,kt) do{const bfr* _ub=(BASE)+((long)(br)*K+(long)(kt)*BK); \
;     __builtin_amdgcn_global_load_lds((const unsigned*)(_ub+so0),(unsigned*)((char*)(P)+wid*1024),16,0,0); \
;     __builtin_amdgcn_global_load_lds((const unsigned*)(_ub+so1),(unsigned*)((char*)(P)+wid*1024+8192),16,0,0);}while(0)
; #define P8_WAIT_V(n) asm volatile("s_waitcnt vmcnt(" #n ")":::"memory")
; #define P8_BAR __builtin_amdgcn_s_barrier()
; template <class EPI>
; DEVI void gemm8_tile(const bfr* __restrict__ A, const bfr* __restrict__ Bt, int K, int brow, int bcol, int nbrow, int nbcol, char* shmc, EPI epi) {
;     ...
;   unsigned so0, so1;
;   { int _r, _c; stage_rc(tid * 16, _r, _c); so0 = (unsigned)(_r * K + _c); stage_rc(tid * 16 + 8192, _r, _c); so1 = (unsigned)(_r * K + _c); }
;   f32x4 acc[2][2][4][2];
; #pragma unroll
;   for (int a = 0; a < 2; ++a)
; #pragma unroll
;     for (int b = 0; b < 2; ++b)
; #pragma unroll
;       for (int m = 0; m < 4; ++m)
; #pragma unroll
;         for (int n = 0; n < 2; ++n) acc[a][b][m][n] = f32x4{0.f, 0.f, 0.f, 0.f};
;   bf16x8 At[4][2], B0[2][2], B1[2][2];
;   const int nt = K / BK;
;   if(wr==1)P8_BAR;
;   P8_WAIT_V(4); P8_BAR;
;   P8_STAGE(P8_SB(1,0),Bt,bcol,1); P8_STAGE(P8_SA(1,0),A,brow,1); P8_STAGE(P8_SB(1,1),Bt,bcol+128,1);
;   P8_WAIT_V(6); P8_BAR;
.LBB0_400:
	s_or_b64 exec, exec, s[0:1]
	v_lshlrev_b32_e32 v2, 4, v142
	v_and_b32_e32 v3, 32, v142
	s_lshl_b32 s82, s35, 8
	v_lshrrev_b32_e32 v7, 1, v142
	v_bitop3_b32 v3, v2, v3, 48 bitop3:0x6c
	v_add_u32_e32 v2, 0x2000, v2
	v_ashrrev_i32_e32 v4, 3, v142
	v_bfe_u32 v5, v142, 2, 4
	s_mov_b32 s0, 0x1ffff0
	v_lshrrev_b32_e32 v8, 1, v3
	v_ashrrev_i32_e32 v9, 7, v2
	v_and_b32_e32 v7, 32, v7
	s_ashr_i32 s83, s82, 31
	s_lshl_b32 s34, s2, 8
	v_ashrrev_i32_e32 v1, 6, v142
	v_and_or_b32 v6, v4, s0, v5
	v_and_or_b32 v2, v9, s0, v5
	v_or_b32_e32 v3, v8, v7
	s_lshl_b64 s[0:1], s[82:83], 12
	v_lshl_or_b32 v166, v6, 11, v3
	s_add_u32 s54, s84, s0
	v_lshlrev_b32_e32 v143, 10, v1
	s_nop 0
	v_readfirstlane_b32 s100, v143
	s_nop 3
	s_addc_u32 s55, s85, s1
	v_lshlrev_b64 v[128:129], 1, v[166:167]
	v_add_u32_e32 v150, 0x18000, v143
	v_lshl_or_b32 v132, v2, 11, v3
	v_lshl_add_u64 v[2:3], s[54:55], 0, v[128:129]
	v_mov_b32_e32 v133, v167
	v_lshl_add_u64 v[2:3], v[2:3], 0, s[62:63]
	s_add_i32 m0, s100, 0x18000
	v_lshlrev_b64 v[130:131], 1, v[132:133]
	s_ashr_i32 s35, s34, 31
	s_waitcnt vmcnt(4)
	s_barrier
	global_load_lds_dwordx4 v[2:3], off
	v_lshl_add_u64 v[2:3], s[54:55], 0, v[130:131]
	v_add_u32_e32 v151, 0x1a000, v143
	s_lshl_b64 s[54:55], s[34:35], 12
	v_readfirstlane_b32 s2, v151
	s_add_u32 s60, s31, s54
	v_lshl_add_u64 v[2:3], v[2:3], 0, s[62:63]
	s_mov_b32 m0, s2
	s_addc_u32 s61, s64, s55
	v_add_u32_e32 v152, 0x8000, v143
	global_load_lds_dwordx4 v[2:3], off
	v_lshl_add_u64 v[2:3], s[60:61], 0, v[128:129]
	v_lshl_add_u64 v[2:3], v[2:3], 0, s[62:63]
	s_add_i32 m0, s100, 0x8000
	v_add_u32_e32 v153, 0xa000, v143
	global_load_lds_dwordx4 v[2:3], off
	v_lshl_add_u64 v[2:3], s[60:61], 0, v[130:131]
	s_or_b32 s60, s82, 0x80
	s_ashr_i32 s61, s60, 31
	s_lshl_b64 s[60:61], s[60:61], 12
	v_readfirstlane_b32 s2, v153
	s_add_u32 s60, s84, s60
	v_lshl_add_u64 v[2:3], v[2:3], 0, s[62:63]
	s_mov_b32 m0, s2
	s_addc_u32 s61, s85, s61
	v_add_u32_e32 v154, 0x1c000, v143
	global_load_lds_dwordx4 v[2:3], off
	v_lshl_add_u64 v[2:3], s[60:61], 0, v[128:129]
	v_lshl_add_u64 v[2:3], v[2:3], 0, s[62:63]
	s_add_i32 m0, s100, 0x1c000
	v_add_u32_e32 v156, 0x1e000, v143
	global_load_lds_dwordx4 v[2:3], off
	v_lshl_add_u64 v[2:3], s[60:61], 0, v[130:131]
	v_lshl_add_u64 v[2:3], v[2:3], 0, s[62:63]
	s_add_i32 m0, s100, 0x1e000
	v_and_b32_e32 v10, 15, v142
	global_load_lds_dwordx4 v[2:3], off
	v_lshlrev_b32_e32 v1, 12, v1
	v_and_b32_e32 v11, 48, v142
	v_and_b32_e32 v6, 0x3000, v1
	v_lshlrev_b32_e32 v1, 6, v10
	v_lshlrev_b32_e32 v3, 2, v142
	v_or_b32_e32 v2, v1, v11
	v_and_b32_e32 v3, 32, v3
	s_mov_b32 s2, 0x14000
	v_bitop3_b32 v13, v2, s2, v3 bitop3:0xde
	s_mov_b32 s2, 0x18000
	v_lshlrev_b32_e32 v16, 13, v0
	v_lshlrev_b32_e32 v0, 6, v142
	v_bitop3_b32 v14, v2, s2, v3 bitop3:0xde
	s_mov_b32 s2, 0x1c000
	v_and_b32_e32 v0, 0x3c0, v0
	v_bitop3_b32 v10, v1, v3, v11 bitop3:0x36
	v_bitop3_b32 v15, v2, s2, v3 bitop3:0xde
	v_bitop3_b32 v11, v0, v3, v11 bitop3:0x36
	v_lshlrev_b32_e32 v0, 11, v9
	s_movk_i32 s2, 0x8000
	v_bitop3_b32 v12, v2, s3, v3 bitop3:0xde
	v_and_or_b32 v0, v0, s2, v8
	v_lshlrev_b32_e32 v2, 11, v5
	v_lshlrev_b32_e32 v3, 11, v4
	s_add_u32 s54, s8, s54
	v_or3_b32 v0, v0, v2, v7
	v_mov_b32_e32 v1, v167
	v_and_or_b32 v3, v3, s2, v8
	s_waitcnt vmcnt(6)
	s_addc_u32 s55, s9, s55
	v_lshlrev_b64 v[0:1], 1, v[0:1]
	v_or3_b32 v2, v3, v2, v7
	v_mov_b32_e32 v3, v167
	v_or_b32_e32 v17, 0x800, v16
	v_or_b32_e32 v18, 0x1000, v16
	v_or_b32_e32 v19, 0x1800, v16
	v_lshl_add_u64 v[134:135], s[54:55], 0, v[0:1]
	v_lshlrev_b64 v[2:3], 1, v[2:3]
	v_lshl_add_u64 v[138:139], s[0:1], 0, v[0:1]
	v_mov_b32_e32 v0, 0
	v_lshl_add_u64 v[136:137], s[54:55], 0, v[2:3]
	v_lshl_add_u64 v[140:141], s[0:1], 0, v[2:3]
	s_mov_b32 s0, -2
	v_add_u32_e32 v157, v12, v6
	v_add_u32_e32 v147, v10, v16
	v_add_u32_e32 v146, v11, v17
	v_add_u32_e32 v145, v11, v18
	v_add_u32_e32 v144, v11, v19
	v_add_u32_e32 v155, v13, v6
	v_add_u32_e32 v149, v14, v6
	v_add_u32_e32 v148, v15, v6
	v_mov_b32_e32 v1, v0
	v_mov_b32_e32 v2, v0
	v_mov_b32_e32 v3, v0
	v_mov_b32_e32 v4, v0
	v_mov_b32_e32 v5, v0
	v_mov_b32_e32 v6, v0
	v_mov_b32_e32 v7, v0
	v_mov_b32_e32 v8, v0
	v_mov_b32_e32 v9, v0
	v_mov_b32_e32 v10, v0
	v_mov_b32_e32 v11, v0
	v_mov_b32_e32 v12, v0
	v_mov_b32_e32 v13, v0
	v_mov_b32_e32 v14, v0
	v_mov_b32_e32 v15, v0
	v_mov_b32_e32 v16, v0
	v_mov_b32_e32 v17, v0
	v_mov_b32_e32 v18, v0
	v_mov_b32_e32 v19, v0
	v_mov_b32_e32 v20, v0
	v_mov_b32_e32 v21, v0
	v_mov_b32_e32 v22, v0
	v_mov_b32_e32 v23, v0
	v_mov_b32_e32 v24, v0
	v_mov_b32_e32 v25, v0
	v_mov_b32_e32 v26, v0
	v_mov_b32_e32 v27, v0
	v_mov_b32_e32 v28, v0
	v_mov_b32_e32 v29, v0
	v_mov_b32_e32 v30, v0
	v_mov_b32_e32 v31, v0
	v_mov_b32_e32 v32, v0
	v_mov_b32_e32 v33, v0
	v_mov_b32_e32 v34, v0
	v_mov_b32_e32 v35, v0
	v_mov_b32_e32 v36, v0
	v_mov_b32_e32 v37, v0
	v_mov_b32_e32 v38, v0
	v_mov_b32_e32 v39, v0
	v_mov_b32_e32 v40, v0
	v_mov_b32_e32 v41, v0
	v_mov_b32_e32 v42, v0
	v_mov_b32_e32 v43, v0
	v_mov_b32_e32 v44, v0
	v_mov_b32_e32 v45, v0
	v_mov_b32_e32 v46, v0
	v_mov_b32_e32 v47, v0
	v_mov_b32_e32 v48, v0
	v_mov_b32_e32 v49, v0
	v_mov_b32_e32 v50, v0
	v_mov_b32_e32 v51, v0
	v_mov_b32_e32 v52, v0
	v_mov_b32_e32 v53, v0
	v_mov_b32_e32 v54, v0
	v_mov_b32_e32 v55, v0
	v_mov_b32_e32 v56, v0
	v_mov_b32_e32 v57, v0
	v_mov_b32_e32 v58, v0
	v_mov_b32_e32 v59, v0
	v_mov_b32_e32 v60, v0
	v_mov_b32_e32 v61, v0
	v_mov_b32_e32 v62, v0
	v_mov_b32_e32 v63, v0
	v_mov_b32_e32 v64, v0
	v_mov_b32_e32 v65, v0
	v_mov_b32_e32 v66, v0
	v_mov_b32_e32 v67, v0
	v_mov_b32_e32 v68, v0
	v_mov_b32_e32 v69, v0
	v_mov_b32_e32 v70, v0
	v_mov_b32_e32 v71, v0
	v_mov_b32_e32 v72, v0
	v_mov_b32_e32 v73, v0
	v_mov_b32_e32 v74, v0
	v_mov_b32_e32 v75, v0
	v_mov_b32_e32 v76, v0
	v_mov_b32_e32 v77, v0
	v_mov_b32_e32 v78, v0
	v_mov_b32_e32 v79, v0
	v_mov_b32_e32 v80, v0
	v_mov_b32_e32 v81, v0
	v_mov_b32_e32 v82, v0
	v_mov_b32_e32 v83, v0
	v_mov_b32_e32 v84, v0
	v_mov_b32_e32 v85, v0
	v_mov_b32_e32 v86, v0
	v_mov_b32_e32 v87, v0
	v_mov_b32_e32 v88, v0
	v_mov_b32_e32 v89, v0
	v_mov_b32_e32 v90, v0
	v_mov_b32_e32 v91, v0
	v_mov_b32_e32 v92, v0
	v_mov_b32_e32 v93, v0
	v_mov_b32_e32 v94, v0
	v_mov_b32_e32 v95, v0
	v_mov_b32_e32 v96, v0
	v_mov_b32_e32 v97, v0
	v_mov_b32_e32 v98, v0
	v_mov_b32_e32 v99, v0
	v_mov_b32_e32 v100, v0
	v_mov_b32_e32 v101, v0
	v_mov_b32_e32 v102, v0
	v_mov_b32_e32 v103, v0
	v_mov_b32_e32 v104, v0
	v_mov_b32_e32 v105, v0
	v_mov_b32_e32 v106, v0
	v_mov_b32_e32 v107, v0
	v_mov_b32_e32 v108, v0
	v_mov_b32_e32 v109, v0
	v_mov_b32_e32 v110, v0
	v_mov_b32_e32 v111, v0
	v_mov_b32_e32 v112, v0
	v_mov_b32_e32 v113, v0
	v_mov_b32_e32 v114, v0
	v_mov_b32_e32 v115, v0
	v_mov_b32_e32 v116, v0
	v_mov_b32_e32 v117, v0
	v_mov_b32_e32 v118, v0
	v_mov_b32_e32 v119, v0
	v_mov_b32_e32 v120, v0
	v_mov_b32_e32 v121, v0
	v_mov_b32_e32 v122, v0
	v_mov_b32_e32 v123, v0
	v_mov_b32_e32 v124, v0
	v_mov_b32_e32 v125, v0
	v_mov_b32_e32 v126, v0
	v_mov_b32_e32 v127, v0
	s_mov_b64 s[54:55], 0x3a80080
	s_mov_b64 s[60:61], 0x3a00100
	s_mov_b64 s[68:69], 0x3a80100
	s_mov_b64 s[72:73], 0x3a00180
	s_barrier
; #define P8_STAGE(P,BASE,br,kt) do{const bfr* _ub=(BASE)+((long)(br)*K+(long)(kt)*BK); \
;     __builtin_amdgcn_global_load_lds((const unsigned*)(_ub+so0),(unsigned*)((char*)(P)+wid*1024),16,0,0); \
;     __builtin_amdgcn_global_load_lds((const unsigned*)(_ub+so1),(unsigned*)((char*)(P)+wid*1024+8192),16,0,0);}while(0)
; #define P8_LDA(dst,b,h) _Pragma("unroll") for(int m=0;m<4;++m) _Pragma("unroll") for(int k=0;k<2;++k) \
;     dst[m][k]=*reinterpret_cast<const bf16x8*>((char*)P8_SA(b,h)+lds_byte(wr*64+m*16+fr,k*32+fq*8))
; #define P8_LDB(dst,b,h) _Pragma("unroll") for(int n=0;n<2;++n) _Pragma("unroll") for(int k=0;k<2;++k) \
;     dst[n][k]=*reinterpret_cast<const bf16x8*>((char*)P8_SB(b,h)+lds_byte(wc*32+n*16+fr,k*32+fq*8))
; #define P8_MMA(ai,bj,At,Bt) do{__builtin_amdgcn_s_setprio(1); \
;     _Pragma("unroll") for(int m=0;m<4;++m) _Pragma("unroll") for(int n=0;n<2;++n) _Pragma("unroll") for(int k=0;k<2;++k) \
;       acc[ai][bj][m][n]=__builtin_amdgcn_mfma_f32_16x16x32_bf16(At[m][k],Bt[n][k],acc[ai][bj][m][n],0,0,0); \
;     __builtin_amdgcn_s_setprio(0);}while(0)
; #define P8_WAIT_V(n) asm volatile("s_waitcnt vmcnt(" #n ")":::"memory")
; #define P8_WAIT_L(n) asm volatile("s_waitcnt lgkmcnt(" #n ")":::"memory")
; #define P8_BAR __builtin_amdgcn_s_barrier()
; #define P8_SCHED __builtin_amdgcn_sched_barrier(0)
; template <class EPI>
; DEVI void gemm8_tile(const bfr* __restrict__ A, const bfr* __restrict__ Bt, int K, int brow, int bcol, int nbrow, int nbcol, char* shmc, EPI epi) {
;     ...
;     P8_LDB(B0,0,0); P8_SCHED; P8_LDA(At,0,0); P8_STAGE(P8_SA(1,1),A,brow+128,t+1);
;     P8_WAIT_L(8); P8_BAR; P8_WAIT_L(0); P8_MMA(0,0,At,B0); P8_BAR; P8_SCHED;
;     P8_LDB(B1,0,1); P8_STAGE(P8_SB(0,0),Bt,bcol,t+2);
;     P8_BAR; P8_WAIT_L(0); P8_MMA(0,1,At,B1); P8_BAR;
;     P8_LDA(At,0,1); P8_STAGE(P8_SA(0,0),A,brow,t+2);
;     P8_BAR; P8_WAIT_L(0); P8_MMA(1,0,At,B0); P8_BAR; P8_SCHED;
;     P8_STAGE(P8_SB(0,1),Bt,bcol+128,t+2);
;     P8_WAIT_V(6); P8_BAR; P8_MMA(1,1,At,B1); P8_BAR;
.LBB0_401:
	ds_read_b128 v[174:177], v157
	ds_read_b128 v[178:181], v157 offset:1024
	ds_read_b128 v[182:185], v157 offset:2048
	ds_read_b128 v[186:189], v157 offset:3072
	v_add_u32_e32 v171, 0xc000, v143
	v_add_u32_e32 v172, 0xe000, v143
	v_add_u32_e32 v158, s54, v136
	s_add_i32 m0, s100, 0xc000
	ds_read_b128 v[160:163], v147
	ds_read_b128 v[190:193], v147 offset:1024
	ds_read_b128 v[196:199], v146
	ds_read_b128 v[208:211], v146 offset:1024
	ds_read_b128 v[212:215], v145
	ds_read_b128 v[216:219], v145 offset:1024
	ds_read_b128 v[220:223], v144
	ds_read_b128 v[224:227], v144 offset:1024
	global_load_lds_dwordx4 v158, s[86:87]
	v_add_u32_e32 v158, s54, v134
	s_add_i32 m0, s100, 0xe000
	s_nop 0
	global_load_lds_dwordx4 v158, s[86:87]
	s_waitcnt lgkmcnt(8)
	s_barrier
	s_waitcnt lgkmcnt(0)
	s_setprio 1
	s_waitcnt lgkmcnt(0)
	v_mfma_f32_16x16x32_bf16 v[124:127], v[160:163], v[174:177], v[124:127]
	v_mfma_f32_16x16x32_bf16 v[120:123], v[160:163], v[182:185], v[120:123]
	v_mfma_f32_16x16x32_bf16 v[116:119], v[196:199], v[174:177], v[116:119]
	v_mfma_f32_16x16x32_bf16 v[112:115], v[196:199], v[182:185], v[112:115]
	v_mfma_f32_16x16x32_bf16 v[108:111], v[212:215], v[174:177], v[108:111]
	v_mfma_f32_16x16x32_bf16 v[104:107], v[212:215], v[182:185], v[104:107]
	v_mfma_f32_16x16x32_bf16 v[100:103], v[220:223], v[174:177], v[100:103]
	v_mfma_f32_16x16x32_bf16 v[96:99], v[220:223], v[182:185], v[96:99]
	v_mfma_f32_16x16x32_bf16 v[124:127], v[190:193], v[178:181], v[124:127]
	v_mfma_f32_16x16x32_bf16 v[120:123], v[190:193], v[186:189], v[120:123]
	v_mfma_f32_16x16x32_bf16 v[116:119], v[208:211], v[178:181], v[116:119]
	v_mfma_f32_16x16x32_bf16 v[112:115], v[208:211], v[186:189], v[112:115]
	v_mfma_f32_16x16x32_bf16 v[108:111], v[216:219], v[178:181], v[108:111]
	v_mfma_f32_16x16x32_bf16 v[104:107], v[216:219], v[186:189], v[104:107]
	v_mfma_f32_16x16x32_bf16 v[100:103], v[224:227], v[178:181], v[100:103]
	v_mfma_f32_16x16x32_bf16 v[96:99], v[224:227], v[186:189], v[96:99]
	s_setprio 0
	s_barrier
	v_add_u32_e32 v158, 0x10000, v143
	v_add_u32_e32 v206, s66, v140
	s_add_i32 m0, s100, 0x10000
	v_add_u32_e32 v159, 0x12000, v143
	ds_read_b128 v[228:231], v155
	ds_read_b128 v[232:235], v155 offset:1024
	ds_read_b128 v[236:239], v155 offset:2048
	ds_read_b128 v[240:243], v155 offset:3072
	global_load_lds_dwordx4 v206, s[86:87]
	v_add_u32_e32 v244, s66, v138
	s_add_i32 m0, s100, 0x12000
	s_nop 0
	global_load_lds_dwordx4 v244, s[86:87]
	s_barrier
	s_waitcnt lgkmcnt(0)
	s_setprio 1
	s_waitcnt lgkmcnt(0)
	v_mfma_f32_16x16x32_bf16 v[92:95], v[160:163], v[228:231], v[92:95]
	v_mfma_f32_16x16x32_bf16 v[88:91], v[160:163], v[236:239], v[88:91]
	v_mfma_f32_16x16x32_bf16 v[84:87], v[196:199], v[228:231], v[84:87]
	v_mfma_f32_16x16x32_bf16 v[80:83], v[196:199], v[236:239], v[80:83]
	v_mfma_f32_16x16x32_bf16 v[76:79], v[212:215], v[228:231], v[76:79]
	v_mfma_f32_16x16x32_bf16 v[72:75], v[212:215], v[236:239], v[72:75]
	v_mfma_f32_16x16x32_bf16 v[68:71], v[220:223], v[228:231], v[68:71]
	v_mfma_f32_16x16x32_bf16 v[64:67], v[220:223], v[236:239], v[64:67]
	v_mfma_f32_16x16x32_bf16 v[92:95], v[190:193], v[232:235], v[92:95]
	v_mfma_f32_16x16x32_bf16 v[88:91], v[190:193], v[240:243], v[88:91]
	v_mfma_f32_16x16x32_bf16 v[84:87], v[208:211], v[232:235], v[84:87]
	v_mfma_f32_16x16x32_bf16 v[80:83], v[208:211], v[240:243], v[80:83]
	v_mfma_f32_16x16x32_bf16 v[76:79], v[216:219], v[232:235], v[76:79]
	v_mfma_f32_16x16x32_bf16 v[72:75], v[216:219], v[240:243], v[72:75]
	v_mfma_f32_16x16x32_bf16 v[68:71], v[224:227], v[232:235], v[68:71]
	v_mfma_f32_16x16x32_bf16 v[64:67], v[224:227], v[240:243], v[64:67]
	s_setprio 0
	v_add_u32_e32 v160, s60, v136
	s_mov_b32 m0, s100
	s_barrier
	ds_read_b128 v[190:193], v147 offset:16384
	ds_read_b128 v[196:199], v147 offset:17408
	ds_read_b128 v[208:211], v146 offset:16384
	ds_read_b128 v[212:215], v146 offset:17408
	ds_read_b128 v[216:219], v145 offset:16384
	ds_read_b128 v[220:223], v145 offset:17408
	ds_read_b128 v[224:227], v144 offset:16384
	ds_read_b128 v[244:247], v144 offset:17408
	global_load_lds_dwordx4 v160, s[86:87]
	v_add_u32_e32 v160, 0x2000, v143
	v_add_u32_e32 v162, s60, v134
	s_add_i32 m0, s100, 0x2000
	s_nop 0
	global_load_lds_dwordx4 v162, s[86:87]
	s_barrier
	s_waitcnt lgkmcnt(0)
	s_setprio 1
	s_waitcnt lgkmcnt(0)
	v_mfma_f32_16x16x32_bf16 v[60:63], v[190:193], v[174:177], v[60:63]
	v_mfma_f32_16x16x32_bf16 v[56:59], v[190:193], v[182:185], v[56:59]
	v_mfma_f32_16x16x32_bf16 v[52:55], v[208:211], v[174:177], v[52:55]
	v_mfma_f32_16x16x32_bf16 v[48:51], v[208:211], v[182:185], v[48:51]
	v_mfma_f32_16x16x32_bf16 v[44:47], v[216:219], v[174:177], v[44:47]
	v_mfma_f32_16x16x32_bf16 v[40:43], v[216:219], v[182:185], v[40:43]
	v_mfma_f32_16x16x32_bf16 v[36:39], v[224:227], v[174:177], v[36:39]
	v_mfma_f32_16x16x32_bf16 v[32:35], v[224:227], v[182:185], v[32:35]
	v_mfma_f32_16x16x32_bf16 v[60:63], v[196:199], v[178:181], v[60:63]
	v_mfma_f32_16x16x32_bf16 v[56:59], v[196:199], v[186:189], v[56:59]
	v_mfma_f32_16x16x32_bf16 v[52:55], v[212:215], v[178:181], v[52:55]
	v_mfma_f32_16x16x32_bf16 v[48:51], v[212:215], v[186:189], v[48:51]
	v_mfma_f32_16x16x32_bf16 v[44:47], v[220:223], v[178:181], v[44:47]
	v_mfma_f32_16x16x32_bf16 v[40:43], v[220:223], v[186:189], v[40:43]
	v_mfma_f32_16x16x32_bf16 v[36:39], v[244:247], v[178:181], v[36:39]
	v_mfma_f32_16x16x32_bf16 v[32:35], v[244:247], v[186:189], v[32:35]
	s_setprio 0
	s_barrier
	v_add_u32_e32 v161, 0x14000, v143
	v_add_u32_e32 v162, s70, v140
	s_add_i32 m0, s100, 0x14000
	v_add_u32_e32 v174, s70, v138
	global_load_lds_dwordx4 v162, s[86:87]
	v_add_u32_e32 v162, 0x16000, v143
	s_nop 0
	s_add_i32 m0, s100, 0x16000
	s_nop 0
	global_load_lds_dwordx4 v174, s[86:87]
	s_waitcnt vmcnt(6)
	s_barrier
; #define P8_STAGE(P,BASE,br,kt) do{const bfr* _ub=(BASE)+((long)(br)*K+(long)(kt)*BK); \
;     __builtin_amdgcn_global_load_lds((const unsigned*)(_ub+so0),(unsigned*)((char*)(P)+wid*1024),16,0,0); \
;     __builtin_amdgcn_global_load_lds((const unsigned*)(_ub+so1),(unsigned*)((char*)(P)+wid*1024+8192),16,0,0);}while(0)
; #define P8_LDA(dst,b,h) _Pragma("unroll") for(int m=0;m<4;++m) _Pragma("unroll") for(int k=0;k<2;++k) \
;     dst[m][k]=*reinterpret_cast<const bf16x8*>((char*)P8_SA(b,h)+lds_byte(wr*64+m*16+fr,k*32+fq*8))
; #define P8_LDB(dst,b,h) _Pragma("unroll") for(int n=0;n<2;++n) _Pragma("unroll") for(int k=0;k<2;++k) \
;     dst[n][k]=*reinterpret_cast<const bf16x8*>((char*)P8_SB(b,h)+lds_byte(wc*32+n*16+fr,k*32+fq*8))
; #define P8_MMA(ai,bj,At,Bt) do{__builtin_amdgcn_s_setprio(1); \
;     _Pragma("unroll") for(int m=0;m<4;++m) _Pragma("unroll") for(int n=0;n<2;++n) _Pragma("unroll") for(int k=0;k<2;++k) \
;       acc[ai][bj][m][n]=__builtin_amdgcn_mfma_f32_16x16x32_bf16(At[m][k],Bt[n][k],acc[ai][bj][m][n],0,0,0); \
;     __builtin_amdgcn_s_setprio(0);}while(0)
; #define P8_WAIT_V(n) asm volatile("s_waitcnt vmcnt(" #n ")":::"memory")
; #define P8_WAIT_L(n) asm volatile("s_waitcnt lgkmcnt(" #n ")":::"memory")
; #define P8_BAR __builtin_amdgcn_s_barrier()
; #define P8_SCHED __builtin_amdgcn_sched_barrier(0)
; template <class EPI>
; DEVI void gemm8_tile(const bfr* __restrict__ A, const bfr* __restrict__ Bt, int K, int brow, int bcol, int nbrow, int nbcol, char* shmc, EPI epi) {
;     ...
;     P8_WAIT_V(6); P8_BAR; P8_MMA(1,1,At,B1); P8_BAR;
;     P8_LDB(B0,1,0); P8_SCHED; P8_LDA(At,1,0); P8_STAGE(P8_SA(0,1),A,brow+128,t+2);
;     P8_WAIT_L(8); P8_BAR; P8_WAIT_L(0); P8_MMA(0,0,At,B0); P8_BAR; P8_SCHED;
;     P8_LDB(B1,1,1); P8_STAGE(P8_SB(1,0),Bt,bcol,t+3);
;     P8_BAR; P8_WAIT_L(0); P8_MMA(0,1,At,B1); P8_BAR;
;     P8_LDA(At,1,1); P8_STAGE(P8_SA(1,0),A,brow,t+3);
;     P8_BAR; P8_WAIT_L(0); P8_MMA(1,0,At,B0); P8_BAR; P8_SCHED;
	s_setprio 1
	v_mfma_f32_16x16x32_bf16 v[28:31], v[190:193], v[228:231], v[28:31]
	v_mfma_f32_16x16x32_bf16 v[24:27], v[190:193], v[236:239], v[24:27]
	v_mfma_f32_16x16x32_bf16 v[20:23], v[208:211], v[228:231], v[20:23]
	v_mfma_f32_16x16x32_bf16 v[16:19], v[208:211], v[236:239], v[16:19]
	v_mfma_f32_16x16x32_bf16 v[12:15], v[216:219], v[228:231], v[12:15]
	v_mfma_f32_16x16x32_bf16 v[8:11], v[216:219], v[236:239], v[8:11]
	v_mfma_f32_16x16x32_bf16 v[4:7], v[224:227], v[228:231], v[4:7]
	v_mfma_f32_16x16x32_bf16 v[0:3], v[224:227], v[236:239], v[0:3]
	v_mfma_f32_16x16x32_bf16 v[28:31], v[196:199], v[232:235], v[28:31]
	v_mfma_f32_16x16x32_bf16 v[24:27], v[196:199], v[240:243], v[24:27]
	v_mfma_f32_16x16x32_bf16 v[20:23], v[212:215], v[232:235], v[20:23]
	v_mfma_f32_16x16x32_bf16 v[16:19], v[212:215], v[240:243], v[16:19]
	v_mfma_f32_16x16x32_bf16 v[12:15], v[220:223], v[232:235], v[12:15]
	v_mfma_f32_16x16x32_bf16 v[8:11], v[220:223], v[240:243], v[8:11]
	v_mfma_f32_16x16x32_bf16 v[4:7], v[244:247], v[232:235], v[4:7]
	v_mfma_f32_16x16x32_bf16 v[0:3], v[244:247], v[240:243], v[0:3]
	s_setprio 0
	s_barrier
	ds_read_b128 v[174:177], v149
	ds_read_b128 v[178:181], v149 offset:1024
	ds_read_b128 v[182:185], v149 offset:2048
	ds_read_b128 v[186:189], v149 offset:3072
	v_add_u32_e32 v163, 0x4000, v143
	v_add_u32_e32 v170, 0x6000, v143
	v_add_u32_e32 v232, s68, v136
	s_add_i32 m0, s100, 0x4000
	ds_read_b128 v[190:193], v147 offset:32768
	ds_read_b128 v[196:199], v147 offset:33792
	ds_read_b128 v[208:211], v146 offset:32768
	ds_read_b128 v[212:215], v146 offset:33792
	ds_read_b128 v[216:219], v145 offset:32768
	ds_read_b128 v[220:223], v145 offset:33792
	ds_read_b128 v[224:227], v144 offset:32768
	ds_read_b128 v[228:231], v144 offset:33792
	global_load_lds_dwordx4 v232, s[86:87]
	v_add_u32_e32 v232, s68, v134
	s_add_i32 m0, s100, 0x6000
	s_nop 0
	global_load_lds_dwordx4 v232, s[86:87]
	s_waitcnt lgkmcnt(8)
	s_barrier
	s_waitcnt lgkmcnt(0)
	s_setprio 1
	s_waitcnt lgkmcnt(0)
	v_mfma_f32_16x16x32_bf16 v[124:127], v[190:193], v[174:177], v[124:127]
	v_mfma_f32_16x16x32_bf16 v[120:123], v[190:193], v[182:185], v[120:123]
	v_mfma_f32_16x16x32_bf16 v[116:119], v[208:211], v[174:177], v[116:119]
	v_mfma_f32_16x16x32_bf16 v[112:115], v[208:211], v[182:185], v[112:115]
	v_mfma_f32_16x16x32_bf16 v[108:111], v[216:219], v[174:177], v[108:111]
	v_mfma_f32_16x16x32_bf16 v[104:107], v[216:219], v[182:185], v[104:107]
	v_mfma_f32_16x16x32_bf16 v[100:103], v[224:227], v[174:177], v[100:103]
	v_mfma_f32_16x16x32_bf16 v[96:99], v[224:227], v[182:185], v[96:99]
	v_mfma_f32_16x16x32_bf16 v[124:127], v[196:199], v[178:181], v[124:127]
	v_mfma_f32_16x16x32_bf16 v[120:123], v[196:199], v[186:189], v[120:123]
	v_mfma_f32_16x16x32_bf16 v[116:119], v[212:215], v[178:181], v[116:119]
	v_mfma_f32_16x16x32_bf16 v[112:115], v[212:215], v[186:189], v[112:115]
	v_mfma_f32_16x16x32_bf16 v[108:111], v[220:223], v[178:181], v[108:111]
	v_mfma_f32_16x16x32_bf16 v[104:107], v[220:223], v[186:189], v[104:107]
	v_mfma_f32_16x16x32_bf16 v[100:103], v[228:231], v[178:181], v[100:103]
	v_mfma_f32_16x16x32_bf16 v[96:99], v[228:231], v[186:189], v[96:99]
	s_setprio 0
	s_barrier
	v_add_u32_e32 v248, s74, v140
	s_add_i32 m0, s100, 0x18000
	ds_read_b128 v[232:235], v148
	ds_read_b128 v[236:239], v148 offset:1024
	ds_read_b128 v[240:243], v148 offset:2048
	ds_read_b128 v[244:247], v148 offset:3072
	global_load_lds_dwordx4 v248, s[86:87]
	v_add_u32_e32 v248, s74, v138
	s_add_i32 m0, s100, 0x1a000
	s_nop 0
	global_load_lds_dwordx4 v248, s[86:87]
	s_barrier
	s_waitcnt lgkmcnt(0)
	s_setprio 1
	s_waitcnt lgkmcnt(0)
	v_mfma_f32_16x16x32_bf16 v[92:95], v[190:193], v[232:235], v[92:95]
	v_mfma_f32_16x16x32_bf16 v[88:91], v[190:193], v[240:243], v[88:91]
	v_mfma_f32_16x16x32_bf16 v[84:87], v[208:211], v[232:235], v[84:87]
	v_mfma_f32_16x16x32_bf16 v[80:83], v[208:211], v[240:243], v[80:83]
	v_mfma_f32_16x16x32_bf16 v[76:79], v[216:219], v[232:235], v[76:79]
	v_mfma_f32_16x16x32_bf16 v[72:75], v[216:219], v[240:243], v[72:75]
	v_mfma_f32_16x16x32_bf16 v[68:71], v[224:227], v[232:235], v[68:71]
	v_mfma_f32_16x16x32_bf16 v[64:67], v[224:227], v[240:243], v[64:67]
	v_mfma_f32_16x16x32_bf16 v[92:95], v[196:199], v[236:239], v[92:95]
	v_mfma_f32_16x16x32_bf16 v[88:91], v[196:199], v[244:247], v[88:91]
	v_mfma_f32_16x16x32_bf16 v[84:87], v[212:215], v[236:239], v[84:87]
	v_mfma_f32_16x16x32_bf16 v[80:83], v[212:215], v[244:247], v[80:83]
	v_mfma_f32_16x16x32_bf16 v[76:79], v[220:223], v[236:239], v[76:79]
	v_mfma_f32_16x16x32_bf16 v[72:75], v[220:223], v[244:247], v[72:75]
	v_mfma_f32_16x16x32_bf16 v[68:71], v[228:231], v[236:239], v[68:71]
	v_mfma_f32_16x16x32_bf16 v[64:67], v[228:231], v[244:247], v[64:67]
	s_setprio 0
	v_add_u32_e32 v200, s72, v136
	s_add_i32 m0, s100, 0x8000
	s_barrier
	ds_read_b128 v[190:193], v147 offset:49152
	ds_read_b128 v[196:199], v147 offset:50176
	ds_read_b128 v[208:211], v146 offset:49152
	ds_read_b128 v[212:215], v146 offset:50176
	ds_read_b128 v[216:219], v145 offset:49152
	ds_read_b128 v[220:223], v145 offset:50176
	ds_read_b128 v[224:227], v144 offset:49152
	ds_read_b128 v[228:231], v144 offset:50176
	global_load_lds_dwordx4 v200, s[86:87]
	v_add_u32_e32 v200, s72, v134
	s_add_i32 m0, s100, 0xa000
	s_nop 0
	global_load_lds_dwordx4 v200, s[86:87]
	s_barrier
; #define P8_STAGE(P,BASE,br,kt) do{const bfr* _ub=(BASE)+((long)(br)*K+(long)(kt)*BK); \
;     __builtin_amdgcn_global_load_lds((const unsigned*)(_ub+so0),(unsigned*)((char*)(P)+wid*1024),16,0,0); \
;     __builtin_amdgcn_global_load_lds((const unsigned*)(_ub+so1),(unsigned*)((char*)(P)+wid*1024+8192),16,0,0);}while(0)
; #define P8_LDA(dst,b,h) _Pragma("unroll") for(int m=0;m<4;++m) _Pragma("unroll") for(int k=0;k<2;++k) \
;     dst[m][k]=*reinterpret_cast<const bf16x8*>((char*)P8_SA(b,h)+lds_byte(wr*64+m*16+fr,k*32+fq*8))
; #define P8_LDB(dst,b,h) _Pragma("unroll") for(int n=0;n<2;++n) _Pragma("unroll") for(int k=0;k<2;++k) \
;     dst[n][k]=*reinterpret_cast<const bf16x8*>((char*)P8_SB(b,h)+lds_byte(wc*32+n*16+fr,k*32+fq*8))
; #define P8_MMA(ai,bj,At,Bt) do{__builtin_amdgcn_s_setprio(1); \
;     _Pragma("unroll") for(int m=0;m<4;++m) _Pragma("unroll") for(int n=0;n<2;++n) _Pragma("unroll") for(int k=0;k<2;++k) \
;       acc[ai][bj][m][n]=__builtin_amdgcn_mfma_f32_16x16x32_bf16(At[m][k],Bt[n][k],acc[ai][bj][m][n],0,0,0); \
;     __builtin_amdgcn_s_setprio(0);}while(0)
; #define P8_WAIT_V(n) asm volatile("s_waitcnt vmcnt(" #n ")":::"memory")
; #define P8_WAIT_L(n) asm volatile("s_waitcnt lgkmcnt(" #n ")":::"memory")
; #define P8_BAR __builtin_amdgcn_s_barrier()
; #define P8_SCHED __builtin_amdgcn_sched_barrier(0)
; template <class EPI>
; DEVI void gemm8_tile(const bfr* __restrict__ A, const bfr* __restrict__ Bt, int K, int brow, int bcol, int nbrow, int nbcol, char* shmc, EPI epi) {
;     ...
;     P8_BAR; P8_WAIT_L(0); P8_MMA(1,0,At,B0); P8_BAR; P8_SCHED;
;     P8_STAGE(P8_SB(1,1),Bt,bcol+128,t+3);
;     P8_WAIT_V(6); P8_BAR; P8_MMA(1,1,At,B1); P8_BAR;
;   }
;   { P8_LDB(B0,0,0); P8_LDA(At,0,0); P8_STAGE(P8_SA(1,1),A,brow+128,nt-1);
;     P8_BAR; P8_WAIT_L(0); P8_MMA(0,0,At,B0); P8_BAR;
	s_waitcnt lgkmcnt(0)
	s_setprio 1
	s_waitcnt lgkmcnt(0)
	v_mfma_f32_16x16x32_bf16 v[60:63], v[190:193], v[174:177], v[60:63]
	v_mfma_f32_16x16x32_bf16 v[56:59], v[190:193], v[182:185], v[56:59]
	v_mfma_f32_16x16x32_bf16 v[52:55], v[208:211], v[174:177], v[52:55]
	v_mfma_f32_16x16x32_bf16 v[48:51], v[208:211], v[182:185], v[48:51]
	v_mfma_f32_16x16x32_bf16 v[44:47], v[216:219], v[174:177], v[44:47]
	v_mfma_f32_16x16x32_bf16 v[40:43], v[216:219], v[182:185], v[40:43]
	v_mfma_f32_16x16x32_bf16 v[36:39], v[224:227], v[174:177], v[36:39]
	v_mfma_f32_16x16x32_bf16 v[32:35], v[224:227], v[182:185], v[32:35]
	v_mfma_f32_16x16x32_bf16 v[60:63], v[196:199], v[178:181], v[60:63]
	v_mfma_f32_16x16x32_bf16 v[56:59], v[196:199], v[186:189], v[56:59]
	v_mfma_f32_16x16x32_bf16 v[52:55], v[212:215], v[178:181], v[52:55]
	v_mfma_f32_16x16x32_bf16 v[48:51], v[212:215], v[186:189], v[48:51]
	v_mfma_f32_16x16x32_bf16 v[44:47], v[220:223], v[178:181], v[44:47]
	v_mfma_f32_16x16x32_bf16 v[40:43], v[220:223], v[186:189], v[40:43]
	v_mfma_f32_16x16x32_bf16 v[36:39], v[228:231], v[178:181], v[36:39]
	v_mfma_f32_16x16x32_bf16 v[32:35], v[228:231], v[186:189], v[32:35]
	s_setprio 0
	s_barrier
	v_add_u32_e32 v174, s78, v140
	s_add_i32 m0, s100, 0x1c000
	s_nop 0
	global_load_lds_dwordx4 v174, s[86:87]
	v_add_u32_e32 v174, s78, v138
	s_add_i32 m0, s100, 0x1e000
	s_nop 0
	global_load_lds_dwordx4 v174, s[86:87]
	s_waitcnt vmcnt(6)
	s_barrier
	s_setprio 1
	v_mfma_f32_16x16x32_bf16 v[28:31], v[190:193], v[232:235], v[28:31]
	v_mfma_f32_16x16x32_bf16 v[24:27], v[190:193], v[240:243], v[24:27]
	v_mfma_f32_16x16x32_bf16 v[20:23], v[208:211], v[232:235], v[20:23]
	v_mfma_f32_16x16x32_bf16 v[16:19], v[208:211], v[240:243], v[16:19]
	v_mfma_f32_16x16x32_bf16 v[12:15], v[216:219], v[232:235], v[12:15]
	v_mfma_f32_16x16x32_bf16 v[8:11], v[216:219], v[240:243], v[8:11]
	v_mfma_f32_16x16x32_bf16 v[4:7], v[224:227], v[232:235], v[4:7]
	v_mfma_f32_16x16x32_bf16 v[0:3], v[224:227], v[240:243], v[0:3]
	v_mfma_f32_16x16x32_bf16 v[28:31], v[196:199], v[236:239], v[28:31]
	v_mfma_f32_16x16x32_bf16 v[24:27], v[196:199], v[244:247], v[24:27]
	v_mfma_f32_16x16x32_bf16 v[20:23], v[212:215], v[236:239], v[20:23]
	v_mfma_f32_16x16x32_bf16 v[16:19], v[212:215], v[244:247], v[16:19]
	v_mfma_f32_16x16x32_bf16 v[12:15], v[220:223], v[236:239], v[12:15]
	v_mfma_f32_16x16x32_bf16 v[8:11], v[220:223], v[244:247], v[8:11]
	v_mfma_f32_16x16x32_bf16 v[4:7], v[228:231], v[236:239], v[4:7]
	v_mfma_f32_16x16x32_bf16 v[0:3], v[228:231], v[244:247], v[0:3]
	s_setprio 0
	s_add_i32 s0, s0, 2
	v_lshl_add_u64 v[134:135], v[134:135], 0, s[80:81]
	v_lshl_add_u64 v[136:137], v[136:137], 0, s[80:81]
	v_lshl_add_u64 v[138:139], v[138:139], 0, s[80:81]
	s_cmp_lt_u32 s0, 28
	v_lshl_add_u64 v[140:141], v[140:141], 0, s[80:81]
	s_barrier
	s_cbranch_scc1 .LBB0_401
	s_or_b32 s0, s34, 0x80
	s_ashr_i32 s1, s0, 31
	s_lshl_b64 s[0:1], s[0:1], 12
	s_add_u32 s0, s31, s0
	s_addc_u32 s1, s64, s1
	ds_read_b128 v[134:137], v157
	ds_read_b128 v[138:141], v157 offset:1024
	ds_read_b128 v[150:153], v157 offset:2048
	ds_read_b128 v[174:177], v157 offset:3072
	ds_read_b128 v[178:181], v147
	ds_read_b128 v[182:185], v147 offset:1024
	ds_read_b128 v[186:189], v146
	ds_read_b128 v[190:193], v146 offset:1024
	ds_read_b128 v[196:199], v145
	ds_read_b128 v[208:211], v145 offset:1024
	ds_read_b128 v[212:215], v144
	ds_read_b128 v[216:219], v144 offset:1024
	v_lshl_add_u64 v[156:157], v[166:167], 1, s[0:1]
	s_mov_b64 s[54:55], 0xf80
	v_lshl_add_u64 v[156:157], v[156:157], 0, s[54:55]
	s_add_i32 m0, s100, 0xc000
	v_lshl_add_u64 v[132:133], v[132:133], 1, s[0:1]
	global_load_lds_dwordx4 v[156:157], off
	v_lshl_add_u64 v[132:133], v[132:133], 0, s[54:55]
	s_add_i32 m0, s100, 0xe000
	s_nop 0
	global_load_lds_dwordx4 v[132:133], off
	s_barrier
	s_waitcnt lgkmcnt(0)
	s_setprio 1
	s_waitcnt lgkmcnt(0)
	v_mfma_f32_16x16x32_bf16 v[124:127], v[178:181], v[134:137], v[124:127]
	v_mfma_f32_16x16x32_bf16 v[116:119], v[186:189], v[134:137], v[116:119]
	v_mfma_f32_16x16x32_bf16 v[112:115], v[186:189], v[150:153], v[112:115]
	v_mfma_f32_16x16x32_bf16 v[100:103], v[212:215], v[134:137], v[100:103]
	v_mfma_f32_16x16x32_bf16 v[124:127], v[182:185], v[138:141], v[124:127]
	v_mfma_f32_16x16x32_bf16 v[120:123], v[178:181], v[150:153], v[120:123]
	v_mfma_f32_16x16x32_bf16 v[116:119], v[190:193], v[138:141], v[116:119]
	v_mfma_f32_16x16x32_bf16 v[112:115], v[190:193], v[174:177], v[112:115]
	v_mfma_f32_16x16x32_bf16 v[108:111], v[196:199], v[134:137], v[108:111]
	v_mfma_f32_16x16x32_bf16 v[104:107], v[196:199], v[150:153], v[104:107]
	v_mfma_f32_16x16x32_bf16 v[100:103], v[216:219], v[138:141], v[100:103]
	v_mfma_f32_16x16x32_bf16 v[96:99], v[212:215], v[150:153], v[96:99]
	v_mfma_f32_16x16x32_bf16 v[220:223], v[182:185], v[174:177], v[120:123]
	v_mfma_f32_16x16x32_bf16 v[224:227], v[208:211], v[138:141], v[108:111]
	v_mfma_f32_16x16x32_bf16 v[228:231], v[208:211], v[174:177], v[104:107]
	v_mfma_f32_16x16x32_bf16 v[232:235], v[216:219], v[174:177], v[96:99]
	s_setprio 0
	s_barrier
	s_nop 1
	ds_read_b128 v[96:99], v155
	ds_read_b128 v[104:107], v155 offset:1024
	ds_read_b128 v[108:111], v155 offset:2048
	ds_read_b128 v[120:123], v155 offset:3072
	s_barrier
; #define P8_LDA(dst,b,h) _Pragma("unroll") for(int m=0;m<4;++m) _Pragma("unroll") for(int k=0;k<2;++k) \
;     dst[m][k]=*reinterpret_cast<const bf16x8*>((char*)P8_SA(b,h)+lds_byte(wr*64+m*16+fr,k*32+fq*8))
; #define P8_LDB(dst,b,h) _Pragma("unroll") for(int n=0;n<2;++n) _Pragma("unroll") for(int k=0;k<2;++k) \
;     dst[n][k]=*reinterpret_cast<const bf16x8*>((char*)P8_SB(b,h)+lds_byte(wc*32+n*16+fr,k*32+fq*8))
; #define P8_MMA(ai,bj,At,Bt) do{__builtin_amdgcn_s_setprio(1); \
;     _Pragma("unroll") for(int m=0;m<4;++m) _Pragma("unroll") for(int n=0;n<2;++n) _Pragma("unroll") for(int k=0;k<2;++k) \
;       acc[ai][bj][m][n]=__builtin_amdgcn_mfma_f32_16x16x32_bf16(At[m][k],Bt[n][k],acc[ai][bj][m][n],0,0,0); \
;     __builtin_amdgcn_s_setprio(0);}while(0)
; #define P8_WAIT_V(n) asm volatile("s_waitcnt vmcnt(" #n ")":::"memory")
; #define P8_WAIT_L(n) asm volatile("s_waitcnt lgkmcnt(" #n ")":::"memory")
; #define P8_BAR __builtin_amdgcn_s_barrier()
; template <class EPI>
; DEVI void gemm8_tile(const bfr* __restrict__ A, const bfr* __restrict__ Bt, int K, int brow, int bcol, int nbrow, int nbcol, char* shmc, EPI epi) {
;     ...
;     P8_BAR; P8_WAIT_L(0); P8_MMA(0,0,At,B0); P8_BAR;
;     P8_LDB(B1,0,1); P8_BAR; P8_WAIT_L(0); P8_MMA(0,1,At,B1); P8_BAR;
;     P8_LDA(At,0,1); P8_WAIT_V(4); P8_BAR; P8_WAIT_L(0); P8_MMA(1,0,At,B0); P8_MMA(1,1,At,B1); P8_BAR; }
;   { P8_LDB(B0,1,0); P8_LDA(At,1,0); P8_WAIT_V(2); P8_BAR; P8_WAIT_L(0); P8_MMA(0,0,At,B0); P8_BAR;
;     P8_LDB(B1,1,1); P8_WAIT_V(0); P8_BAR; P8_WAIT_L(0); P8_MMA(0,1,At,B1); P8_BAR;
	s_waitcnt lgkmcnt(0)
	s_setprio 1
	s_waitcnt lgkmcnt(0)
	v_mfma_f32_16x16x32_bf16 v[92:95], v[178:181], v[96:99], v[92:95]
	v_mfma_f32_16x16x32_bf16 v[84:87], v[186:189], v[96:99], v[84:87]
	v_mfma_f32_16x16x32_bf16 v[80:83], v[186:189], v[108:111], v[80:83]
	v_mfma_f32_16x16x32_bf16 v[68:71], v[212:215], v[96:99], v[68:71]
	v_mfma_f32_16x16x32_bf16 v[92:95], v[182:185], v[104:107], v[92:95]
	v_mfma_f32_16x16x32_bf16 v[88:91], v[178:181], v[108:111], v[88:91]
	v_mfma_f32_16x16x32_bf16 v[84:87], v[190:193], v[104:107], v[84:87]
	v_mfma_f32_16x16x32_bf16 v[80:83], v[190:193], v[120:123], v[80:83]
	v_mfma_f32_16x16x32_bf16 v[76:79], v[196:199], v[96:99], v[76:79]
	v_mfma_f32_16x16x32_bf16 v[72:75], v[196:199], v[108:111], v[72:75]
	v_mfma_f32_16x16x32_bf16 v[68:71], v[216:219], v[104:107], v[68:71]
	v_mfma_f32_16x16x32_bf16 v[64:67], v[212:215], v[108:111], v[64:67]
	v_mfma_f32_16x16x32_bf16 v[154:157], v[182:185], v[120:123], v[88:91]
	v_mfma_f32_16x16x32_bf16 v[178:181], v[208:211], v[104:107], v[76:79]
	v_mfma_f32_16x16x32_bf16 v[182:185], v[208:211], v[120:123], v[72:75]
	v_mfma_f32_16x16x32_bf16 v[186:189], v[216:219], v[120:123], v[64:67]
	s_setprio 0
	s_barrier
	s_nop 1
	ds_read_b128 v[64:67], v147 offset:16384
	ds_read_b128 v[72:75], v147 offset:17408
	ds_read_b128 v[76:79], v146 offset:16384
	ds_read_b128 v[88:91], v146 offset:17408
	ds_read_b128 v[190:193], v145 offset:16384
	ds_read_b128 v[196:199], v145 offset:17408
	ds_read_b128 v[208:211], v144 offset:16384
	ds_read_b128 v[212:215], v144 offset:17408
	s_waitcnt vmcnt(4)
	s_barrier
	s_waitcnt lgkmcnt(0)
	s_setprio 1
	s_waitcnt lgkmcnt(0)
	v_mfma_f32_16x16x32_bf16 v[60:63], v[64:67], v[134:137], v[60:63]
	v_mfma_f32_16x16x32_bf16 v[52:55], v[76:79], v[134:137], v[52:55]
	v_mfma_f32_16x16x32_bf16 v[48:51], v[76:79], v[150:153], v[48:51]
	v_mfma_f32_16x16x32_bf16 v[36:39], v[208:211], v[134:137], v[36:39]
	v_mfma_f32_16x16x32_bf16 v[60:63], v[72:75], v[138:141], v[60:63]
	v_mfma_f32_16x16x32_bf16 v[56:59], v[64:67], v[150:153], v[56:59]
	v_mfma_f32_16x16x32_bf16 v[52:55], v[88:91], v[138:141], v[52:55]
	v_mfma_f32_16x16x32_bf16 v[48:51], v[88:91], v[174:177], v[48:51]
	v_mfma_f32_16x16x32_bf16 v[44:47], v[190:193], v[134:137], v[44:47]
	v_mfma_f32_16x16x32_bf16 v[40:43], v[190:193], v[150:153], v[40:43]
	v_mfma_f32_16x16x32_bf16 v[36:39], v[212:215], v[138:141], v[36:39]
	v_mfma_f32_16x16x32_bf16 v[32:35], v[208:211], v[150:153], v[32:35]
	v_mfma_f32_16x16x32_bf16 v[216:219], v[72:75], v[174:177], v[56:59]
	v_mfma_f32_16x16x32_bf16 v[236:239], v[196:199], v[138:141], v[44:47]
	v_mfma_f32_16x16x32_bf16 v[240:243], v[196:199], v[174:177], v[40:43]
	v_mfma_f32_16x16x32_bf16 v[132:135], v[212:215], v[174:177], v[32:35]
	s_setprio 0
	s_setprio 1
	v_mfma_f32_16x16x32_bf16 v[28:31], v[64:67], v[96:99], v[28:31]
	v_mfma_f32_16x16x32_bf16 v[20:23], v[76:79], v[96:99], v[20:23]
	v_mfma_f32_16x16x32_bf16 v[16:19], v[76:79], v[108:111], v[16:19]
	v_mfma_f32_16x16x32_bf16 v[4:7], v[208:211], v[96:99], v[4:7]
	v_mfma_f32_16x16x32_bf16 v[28:31], v[72:75], v[104:107], v[28:31]
	v_mfma_f32_16x16x32_bf16 v[24:27], v[64:67], v[108:111], v[24:27]
	v_mfma_f32_16x16x32_bf16 v[20:23], v[88:91], v[104:107], v[20:23]
	v_mfma_f32_16x16x32_bf16 v[16:19], v[88:91], v[120:123], v[16:19]
	v_mfma_f32_16x16x32_bf16 v[12:15], v[190:193], v[96:99], v[12:15]
	v_mfma_f32_16x16x32_bf16 v[8:11], v[190:193], v[108:111], v[8:11]
	v_mfma_f32_16x16x32_bf16 v[4:7], v[212:215], v[104:107], v[4:7]
	v_mfma_f32_16x16x32_bf16 v[0:3], v[208:211], v[108:111], v[0:3]
	v_mfma_f32_16x16x32_bf16 v[136:139], v[72:75], v[120:123], v[24:27]
	v_mfma_f32_16x16x32_bf16 v[150:153], v[196:199], v[104:107], v[12:15]
	v_mfma_f32_16x16x32_bf16 v[172:175], v[196:199], v[120:123], v[8:11]
	v_mfma_f32_16x16x32_bf16 v[190:193], v[212:215], v[120:123], v[0:3]
	s_setprio 0
	s_barrier
	s_nop 1
	ds_read_b128 v[0:3], v149
	ds_read_b128 v[8:11], v149 offset:1024
	ds_read_b128 v[12:15], v149 offset:2048
	ds_read_b128 v[24:27], v149 offset:3072
	ds_read_b128 v[32:35], v147 offset:32768
	ds_read_b128 v[40:43], v147 offset:33792
	ds_read_b128 v[44:47], v146 offset:32768
	ds_read_b128 v[56:59], v146 offset:33792
	ds_read_b128 v[64:67], v145 offset:32768
	ds_read_b128 v[196:199], v145 offset:33792
	ds_read_b128 v[208:211], v144 offset:32768
	ds_read_b128 v[212:215], v144 offset:33792
	s_waitcnt vmcnt(2)
	s_barrier
	s_waitcnt lgkmcnt(0)
	s_setprio 1
	s_waitcnt lgkmcnt(0)
	v_mfma_f32_16x16x32_bf16 v[72:75], v[32:35], v[0:3], v[124:127]
	v_mfma_f32_16x16x32_bf16 v[120:123], v[40:43], v[8:11], v[72:75]
	v_mfma_f32_16x16x32_bf16 v[72:75], v[32:35], v[12:15], v[220:223]
	v_mfma_f32_16x16x32_bf16 v[104:107], v[40:43], v[24:27], v[72:75]
	v_mfma_f32_16x16x32_bf16 v[72:75], v[44:47], v[0:3], v[116:119]
	v_mfma_f32_16x16x32_bf16 v[124:127], v[56:59], v[8:11], v[72:75]
	v_mfma_f32_16x16x32_bf16 v[72:75], v[44:47], v[12:15], v[112:115]
	v_mfma_f32_16x16x32_bf16 v[108:111], v[56:59], v[24:27], v[72:75]
	v_mfma_f32_16x16x32_bf16 v[72:75], v[64:67], v[0:3], v[224:227]
	v_mfma_f32_16x16x32_bf16 v[112:115], v[196:199], v[8:11], v[72:75]
	v_mfma_f32_16x16x32_bf16 v[72:75], v[64:67], v[12:15], v[228:231]
	v_mfma_f32_16x16x32_bf16 v[96:99], v[196:199], v[24:27], v[72:75]
	v_mfma_f32_16x16x32_bf16 v[72:75], v[208:211], v[0:3], v[100:103]
	v_mfma_f32_16x16x32_bf16 v[116:119], v[212:215], v[8:11], v[72:75]
	v_mfma_f32_16x16x32_bf16 v[72:75], v[208:211], v[12:15], v[232:235]
	v_mfma_f32_16x16x32_bf16 v[100:103], v[212:215], v[24:27], v[72:75]
	s_setprio 0
	s_barrier
; #define P8_STAGE(P,BASE,br,kt) do{const bfr* _ub=(BASE)+((long)(br)*K+(long)(kt)*BK); \
;     __builtin_amdgcn_global_load_lds((const unsigned*)(_ub+so0),(unsigned*)((char*)(P)+wid*1024),16,0,0); \
;     __builtin_amdgcn_global_load_lds((const unsigned*)(_ub+so1),(unsigned*)((char*)(P)+wid*1024+8192),16,0,0);}while(0)
; #define P8_LDA(dst,b,h) _Pragma("unroll") for(int m=0;m<4;++m) _Pragma("unroll") for(int k=0;k<2;++k) \
;     dst[m][k]=*reinterpret_cast<const bf16x8*>((char*)P8_SA(b,h)+lds_byte(wr*64+m*16+fr,k*32+fq*8))
; #define P8_LDB(dst,b,h) _Pragma("unroll") for(int n=0;n<2;++n) _Pragma("unroll") for(int k=0;k<2;++k) \
;     dst[n][k]=*reinterpret_cast<const bf16x8*>((char*)P8_SB(b,h)+lds_byte(wc*32+n*16+fr,k*32+fq*8))
; #define P8_MMA(ai,bj,At,Bt) do{__builtin_amdgcn_s_setprio(1); \
;     _Pragma("unroll") for(int m=0;m<4;++m) _Pragma("unroll") for(int n=0;n<2;++n) _Pragma("unroll") for(int k=0;k<2;++k) \
;       acc[ai][bj][m][n]=__builtin_amdgcn_mfma_f32_16x16x32_bf16(At[m][k],Bt[n][k],acc[ai][bj][m][n],0,0,0); \
;     __builtin_amdgcn_s_setprio(0);}while(0)
; #define P8_WAIT_V(n) asm volatile("s_waitcnt vmcnt(" #n ")":::"memory")
; #define P8_WAIT_L(n) asm volatile("s_waitcnt lgkmcnt(" #n ")":::"memory")
; #define P8_BAR __builtin_amdgcn_s_barrier()
; template <class EPI>
; DEVI void gemm8_tile(const bfr* __restrict__ A, const bfr* __restrict__ Bt, int K, int brow, int bcol, int nbrow, int nbcol, char* shmc, EPI epi) {
;     ...
;   { P8_LDB(B0,1,0); P8_LDA(At,1,0); P8_WAIT_V(2); P8_BAR; P8_WAIT_L(0); P8_MMA(0,0,At,B0); P8_BAR;
;     P8_LDB(B1,1,1); P8_WAIT_V(0); P8_BAR; P8_WAIT_L(0); P8_MMA(0,1,At,B1); P8_BAR;
;     P8_LDA(At,1,1); P8_BAR; P8_WAIT_L(0); P8_MMA(1,0,At,B0); P8_MMA(1,1,At,B1); P8_BAR; }
;   if(wr==0)P8_BAR;
;   if (nbrow >= 0) {
;     P8_STAGE(P8_SB(0,0),Bt,nbcol,0); P8_STAGE(P8_SA(0,0),A,nbrow,0);
;     P8_STAGE(P8_SB(0,1),Bt,nbcol+128,0); P8_STAGE(P8_SA(0,1),A,nbrow+128,0);
;   }
	ds_read_b128 v[220:223], v148
	ds_read_b128 v[224:227], v148 offset:1024
	ds_read_b128 v[228:231], v148 offset:2048
	ds_read_b128 v[232:235], v148 offset:3072
	s_waitcnt vmcnt(0)
	s_barrier
	s_waitcnt lgkmcnt(0)
	s_setprio 1
	s_waitcnt lgkmcnt(0)
	v_mfma_f32_16x16x32_bf16 v[72:75], v[32:35], v[220:223], v[92:95]
	v_mfma_f32_16x16x32_bf16 v[32:35], v[32:35], v[228:231], v[154:157]
	v_mfma_f32_16x16x32_bf16 v[88:91], v[40:43], v[224:227], v[72:75]
	v_mfma_f32_16x16x32_bf16 v[72:75], v[40:43], v[232:235], v[32:35]
	v_mfma_f32_16x16x32_bf16 v[32:35], v[44:47], v[220:223], v[84:87]
	v_mfma_f32_16x16x32_bf16 v[92:95], v[56:59], v[224:227], v[32:35]
	v_mfma_f32_16x16x32_bf16 v[32:35], v[44:47], v[228:231], v[80:83]
	v_mfma_f32_16x16x32_bf16 v[76:79], v[56:59], v[232:235], v[32:35]
	v_mfma_f32_16x16x32_bf16 v[32:35], v[64:67], v[220:223], v[178:181]
	v_mfma_f32_16x16x32_bf16 v[80:83], v[196:199], v[224:227], v[32:35]
	v_mfma_f32_16x16x32_bf16 v[32:35], v[64:67], v[228:231], v[182:185]
	v_mfma_f32_16x16x32_bf16 v[64:67], v[196:199], v[232:235], v[32:35]
	v_mfma_f32_16x16x32_bf16 v[32:35], v[208:211], v[220:223], v[68:71]
	v_mfma_f32_16x16x32_bf16 v[84:87], v[212:215], v[224:227], v[32:35]
	v_mfma_f32_16x16x32_bf16 v[32:35], v[208:211], v[228:231], v[186:189]
	v_mfma_f32_16x16x32_bf16 v[68:71], v[212:215], v[232:235], v[32:35]
	s_setprio 0
	s_barrier
	ds_read_b128 v[154:157], v147 offset:49152
	ds_read_b128 v[176:179], v147 offset:50176
	ds_read_b128 v[180:183], v146 offset:49152
	ds_read_b128 v[146:149], v146 offset:50176
	ds_read_b128 v[184:187], v145 offset:49152
	ds_read_b128 v[196:199], v145 offset:50176
	ds_read_b128 v[208:211], v144 offset:49152
	ds_read_b128 v[212:215], v144 offset:50176
	s_barrier
	s_waitcnt lgkmcnt(0)
	s_setprio 1
	s_waitcnt lgkmcnt(0)
	v_mfma_f32_16x16x32_bf16 v[32:35], v[154:157], v[0:3], v[60:63]
	v_mfma_f32_16x16x32_bf16 v[56:59], v[176:179], v[8:11], v[32:35]
	v_mfma_f32_16x16x32_bf16 v[32:35], v[154:157], v[12:15], v[216:219]
	v_mfma_f32_16x16x32_bf16 v[40:43], v[176:179], v[24:27], v[32:35]
	v_mfma_f32_16x16x32_bf16 v[32:35], v[180:183], v[0:3], v[52:55]
	v_mfma_f32_16x16x32_bf16 v[60:63], v[146:149], v[8:11], v[32:35]
	v_mfma_f32_16x16x32_bf16 v[32:35], v[180:183], v[12:15], v[48:51]
	v_mfma_f32_16x16x32_bf16 v[44:47], v[146:149], v[24:27], v[32:35]
	v_mfma_f32_16x16x32_bf16 v[32:35], v[184:187], v[0:3], v[236:239]
	v_mfma_f32_16x16x32_bf16 v[0:3], v[208:211], v[0:3], v[36:39]
	v_mfma_f32_16x16x32_bf16 v[48:51], v[196:199], v[8:11], v[32:35]
	v_mfma_f32_16x16x32_bf16 v[32:35], v[184:187], v[12:15], v[240:243]
	v_mfma_f32_16x16x32_bf16 v[52:55], v[212:215], v[8:11], v[0:3]
	v_mfma_f32_16x16x32_bf16 v[0:3], v[208:211], v[12:15], v[132:135]
	v_mfma_f32_16x16x32_bf16 v[32:35], v[196:199], v[24:27], v[32:35]
	v_mfma_f32_16x16x32_bf16 v[36:39], v[212:215], v[24:27], v[0:3]
	s_setprio 0
	s_setprio 1
	v_mfma_f32_16x16x32_bf16 v[0:3], v[154:157], v[220:223], v[28:31]
	v_mfma_f32_16x16x32_bf16 v[24:27], v[176:179], v[224:227], v[0:3]
	v_mfma_f32_16x16x32_bf16 v[0:3], v[154:157], v[228:231], v[136:139]
	v_mfma_f32_16x16x32_bf16 v[8:11], v[176:179], v[232:235], v[0:3]
	v_mfma_f32_16x16x32_bf16 v[0:3], v[180:183], v[220:223], v[20:23]
	v_mfma_f32_16x16x32_bf16 v[28:31], v[146:149], v[224:227], v[0:3]
	v_mfma_f32_16x16x32_bf16 v[0:3], v[180:183], v[228:231], v[16:19]
	v_mfma_f32_16x16x32_bf16 v[12:15], v[146:149], v[232:235], v[0:3]
	v_mfma_f32_16x16x32_bf16 v[0:3], v[184:187], v[220:223], v[150:153]
	v_mfma_f32_16x16x32_bf16 v[4:7], v[208:211], v[220:223], v[4:7]
	v_mfma_f32_16x16x32_bf16 v[16:19], v[196:199], v[224:227], v[0:3]
	v_mfma_f32_16x16x32_bf16 v[0:3], v[184:187], v[228:231], v[172:175]
	v_mfma_f32_16x16x32_bf16 v[20:23], v[212:215], v[224:227], v[4:7]
	v_mfma_f32_16x16x32_bf16 v[4:7], v[208:211], v[228:231], v[190:193]
	v_mfma_f32_16x16x32_bf16 v[0:3], v[196:199], v[232:235], v[0:3]
	v_mfma_f32_16x16x32_bf16 v[4:7], v[212:215], v[232:235], v[4:7]
	s_setprio 0
	v_cmp_gt_u32_e32 vcc, s57, v142
	s_barrier
	s_and_saveexec_b64 s[0:1], vcc
	s_cbranch_execz .LBB0_404
	s_barrier
.LBB0_404:
	s_or_b64 exec, exec, s[0:1]
	s_lshl_b32 s2, s28, 8
	s_and_b64 s[0:1], s[4:5], exec
	s_cselect_b32 s58, s2, -1
	s_cmp_lt_i32 s58, 0
	s_cbranch_scc1 .LBB0_393
	s_lshl_b32 s0, s29, 8
	s_ashr_i32 s1, s0, 31
	s_lshl_b64 s[4:5], s[0:1], 12
	s_add_u32 s4, s84, s4
	s_addc_u32 s5, s85, s5
	v_lshl_add_u64 v[132:133], s[4:5], 0, v[128:129]
	s_add_i32 m0, s100, 0x10000
	v_readfirstlane_b32 s1, v159
	global_load_lds_dwordx4 v[132:133], off
	v_lshl_add_u64 v[132:133], s[4:5], 0, v[130:131]
	s_lshl_b64 s[4:5], s[58:59], 12
	s_add_u32 s4, s31, s4
	s_mov_b32 m0, s1
	s_addc_u32 s5, s64, s5
	global_load_lds_dwordx4 v[132:133], off
	v_lshl_add_u64 v[132:133], s[4:5], 0, v[128:129]
	s_mov_b32 m0, s100
	s_bitset1_b32 s0, 7
	global_load_lds_dwordx4 v[132:133], off
	s_add_i32 m0, s100, 0x2000
	s_ashr_i32 s1, s0, 31
	s_lshl_b64 s[0:1], s[0:1], 12
	s_add_u32 s0, s84, s0
	v_lshl_add_u64 v[132:133], s[4:5], 0, v[130:131]
	s_addc_u32 s1, s85, s1
	global_load_lds_dwordx4 v[132:133], off
	v_lshl_add_u64 v[132:133], s[0:1], 0, v[128:129]
	s_add_i32 m0, s100, 0x14000
	s_addk_i32 s58, 0x80
	global_load_lds_dwordx4 v[132:133], off
	v_lshl_add_u64 v[132:133], s[0:1], 0, v[130:131]
	s_add_i32 m0, s100, 0x16000
	s_lshl_b64 s[0:1], s[58:59], 12
	s_add_u32 s0, s31, s0
	s_addc_u32 s1, s64, s1
	v_readfirstlane_b32 s2, v163
	global_load_lds_dwordx4 v[132:133], off
	v_lshl_add_u64 v[128:129], s[0:1], 0, v[128:129]
	s_mov_b32 m0, s2
	s_nop 0
	global_load_lds_dwordx4 v[128:129], off
	v_lshl_add_u64 v[128:129], s[0:1], 0, v[130:131]
	v_readfirstlane_b32 s0, v170
	s_mov_b32 m0, s0
	s_nop 0
	global_load_lds_dwordx4 v[128:129], off
	s_branch .LBB0_393
